# speedup vs baseline: 1.0110x; 1.0015x over previous
; #define WAIT_V(n) asm volatile("s_waitcnt vmcnt(" #n ")" ::: "memory")
; #define WAIT_L(n) asm volatile("s_waitcnt lgkmcnt(" #n ")" ::: "memory")
; #define BAR __builtin_amdgcn_s_barrier()
; #define SCHED __builtin_amdgcn_sched_barrier(0)
; #define LDA(dst, b, h)                                                                            \
;   _Pragma("unroll") for (int m = 0; m < 4; ++m) _Pragma("unroll") for (int k = 0; k < 2; ++k)                                         \
;     dst[m][k] = *reinterpret_cast<const bf16x8*>((char*)SA(b, h) + lds_byte(wr * 64 + m * 16 + fr, k * 32 + fq * 8))
; #define LDB(dst, b, h)                                                                            \
;   _Pragma("unroll") for (int n = 0; n < 2; ++n) _Pragma("unroll") for (int k = 0; k < 2; ++k)                                         \
;     dst[n][k] = *reinterpret_cast<const bf16x8*>((char*)SB(b, h) + lds_byte(wc * 32 + n * 16 + fr, k * 32 + fq * 8))
; template <int K, bool SWAP>
; __device__ __forceinline__ void gemm_kloop(const bf16* __restrict__ A, const bf16* __restrict__ Bt,
;                                            f32x4 (&acc)[2][2][4][2], bool pref = false) {
;     ...
;   for (int t = 0; t < nt - 2; t += 2) {
;     LDB(B0, 0, 0); SCHED; LDA(At, 0, 0); STAGE(SA(1, 1), A, HALF, t + 1);
;     WAIT_L(8); BAR; WAIT_L(0); MMA(0, 0, At, B0); BAR; SCHED;
;     LDB(B1, 0, 1); STAGE(SB(0, 0), Bt, 0, t + 2);
;     BAR; WAIT_L(0); MMA(0, 1, At, B1); BAR;
;     LDA(At, 0, 1); STAGE(SA(0, 0), A, 0, t + 2);
;     BAR; WAIT_L(0); MMA(1, 0, At, B0); BAR; SCHED;
;     STAGE(SB(0, 1), Bt, HALF, t + 2);
;     WAIT_V(6); BAR; MMA(1, 1, At, B1); BAR;
;     LDB(B0, 1, 0); SCHED; LDA(At, 1, 0); STAGE(SA(0, 1), A, HALF, t + 2);
;     WAIT_L(8); BAR; WAIT_L(0); MMA(0, 0, At, B0); BAR; SCHED;
;     LDB(B1, 1, 1); STAGE(SB(1, 0), Bt, 0, t + 3);
;     BAR; WAIT_L(0); MMA(0, 1, At, B1); BAR;
;     LDA(At, 1, 1); STAGE(SA(1, 0), A, 0, t + 3);
;     BAR; WAIT_L(0); MMA(1, 0, At, B0); BAR; SCHED;
;     STAGE(SB(1, 1), Bt, HALF, t + 3);
;     WAIT_V(6); BAR; MMA(1, 1, At, B1); BAR;
.LBB0_271:
	ds_read_b128 v[162:165], v159
	ds_read_b128 v[166:169], v159 offset:1024
	ds_read_b128 v[170:173], v159 offset:2048
	ds_read_b128 v[174:177], v159 offset:3072
	v_add_u32_e32 v160, 0xc000, v146
	v_lshl_add_u64 v[178:179], s[58:59], 0, v[140:141]
	v_readfirstlane_b32 s5, v160
	v_lshl_add_u64 v[188:189], v[178:179], 0, s[42:43]
	s_mov_b32 m0, s5
	v_add_u32_e32 v161, 0xe000, v146
	ds_read_b128 v[198:201], v151
	ds_read_b128 v[202:205], v151 offset:1024
	ds_read_b128 v[206:209], v150
	ds_read_b128 v[210:213], v150 offset:1024
	ds_read_b128 v[214:217], v149
	ds_read_b128 v[218:221], v149 offset:1024
	ds_read_b128 v[222:225], v148
	ds_read_b128 v[226:229], v148 offset:1024
	global_load_lds_dwordx4 v[188:189], off
	v_lshl_add_u64 v[188:189], s[58:59], 0, v[142:143]
	v_readfirstlane_b32 s5, v161
	v_lshl_add_u64 v[230:231], v[188:189], 0, s[42:43]
	s_mov_b32 m0, s5
	s_nop 0
	global_load_lds_dwordx4 v[230:231], off
	s_waitcnt lgkmcnt(8)
	s_barrier
	s_waitcnt lgkmcnt(0)
	s_setprio 1
	s_waitcnt lgkmcnt(0)
	v_mfma_f32_16x16x32_bf16 v[124:127], v[198:201], v[162:165], v[124:127]
	v_mfma_f32_16x16x32_bf16 v[120:123], v[198:201], v[170:173], v[120:123]
	v_mfma_f32_16x16x32_bf16 v[112:115], v[206:209], v[170:173], v[112:115]
	v_mfma_f32_16x16x32_bf16 v[116:119], v[206:209], v[162:165], v[116:119]
	v_mfma_f32_16x16x32_bf16 v[108:111], v[214:217], v[162:165], v[108:111]
	v_mfma_f32_16x16x32_bf16 v[104:107], v[214:217], v[170:173], v[104:107]
	v_mfma_f32_16x16x32_bf16 v[96:99], v[222:225], v[170:173], v[96:99]
	v_mfma_f32_16x16x32_bf16 v[100:103], v[222:225], v[162:165], v[100:103]
	v_mfma_f32_16x16x32_bf16 v[124:127], v[202:205], v[166:169], v[124:127]
	v_mfma_f32_16x16x32_bf16 v[120:123], v[202:205], v[174:177], v[120:123]
	v_mfma_f32_16x16x32_bf16 v[112:115], v[210:213], v[174:177], v[112:115]
	v_mfma_f32_16x16x32_bf16 v[116:119], v[210:213], v[166:169], v[116:119]
	v_mfma_f32_16x16x32_bf16 v[108:111], v[218:221], v[166:169], v[108:111]
	v_mfma_f32_16x16x32_bf16 v[104:107], v[218:221], v[174:177], v[104:107]
	v_mfma_f32_16x16x32_bf16 v[96:99], v[226:229], v[174:177], v[96:99]
	v_mfma_f32_16x16x32_bf16 v[100:103], v[226:229], v[166:169], v[100:103]
	s_setprio 0
	s_barrier
	v_add_u32_e32 v186, s7, v145
	v_lshl_add_u64 v[246:247], s[58:59], 0, v[136:137]
	v_readfirstlane_b32 s5, v186
	v_lshl_add_u64 v[248:249], v[246:247], 0, s[44:45]
	s_mov_b32 m0, s5
	v_add_u32_e32 v186, 0x2000, v186
	ds_read_b128 v[230:233], v158
	ds_read_b128 v[234:237], v158 offset:1024
	ds_read_b128 v[238:241], v158 offset:2048
	ds_read_b128 v[242:245], v158 offset:3072
	global_load_lds_dwordx4 v[248:249], off
	v_lshl_add_u64 v[248:249], s[58:59], 0, v[138:139]
	v_readfirstlane_b32 s5, v186
	v_lshl_add_u64 v[250:251], v[248:249], 0, s[44:45]
	s_mov_b32 m0, s5
	s_nop 0
	global_load_lds_dwordx4 v[250:251], off
	s_barrier
	s_waitcnt lgkmcnt(0)
	s_setprio 1
	s_waitcnt lgkmcnt(0)
	v_mfma_f32_16x16x32_bf16 v[92:95], v[198:201], v[230:233], v[92:95]
	v_mfma_f32_16x16x32_bf16 v[88:91], v[198:201], v[238:241], v[88:91]
	v_mfma_f32_16x16x32_bf16 v[80:83], v[206:209], v[238:241], v[80:83]
	v_mfma_f32_16x16x32_bf16 v[84:87], v[206:209], v[230:233], v[84:87]
	v_mfma_f32_16x16x32_bf16 v[76:79], v[214:217], v[230:233], v[76:79]
	v_mfma_f32_16x16x32_bf16 v[72:75], v[214:217], v[238:241], v[72:75]
	v_mfma_f32_16x16x32_bf16 v[64:67], v[222:225], v[238:241], v[64:67]
	v_mfma_f32_16x16x32_bf16 v[68:71], v[222:225], v[230:233], v[68:71]
	v_mfma_f32_16x16x32_bf16 v[92:95], v[202:205], v[234:237], v[92:95]
	v_mfma_f32_16x16x32_bf16 v[88:91], v[202:205], v[242:245], v[88:91]
	v_mfma_f32_16x16x32_bf16 v[80:83], v[210:213], v[242:245], v[80:83]
	v_mfma_f32_16x16x32_bf16 v[84:87], v[210:213], v[234:237], v[84:87]
	v_mfma_f32_16x16x32_bf16 v[76:79], v[218:221], v[234:237], v[76:79]
	v_mfma_f32_16x16x32_bf16 v[72:75], v[218:221], v[242:245], v[72:75]
	v_mfma_f32_16x16x32_bf16 v[64:67], v[226:229], v[242:245], v[64:67]
	v_mfma_f32_16x16x32_bf16 v[68:71], v[226:229], v[234:237], v[68:71]
	s_setprio 0
	v_readfirstlane_b32 s5, v146
	v_add_u32_e32 v186, 0x2000, v146
	v_lshl_add_u64 v[250:251], v[178:179], 0, s[46:47]
	s_mov_b32 m0, s5
	v_readfirstlane_b32 s5, v186
	s_barrier
	ds_read_b128 v[198:201], v151 offset:16384
	ds_read_b128 v[202:205], v151 offset:17408
	ds_read_b128 v[206:209], v150 offset:16384
	ds_read_b128 v[210:213], v150 offset:17408
	ds_read_b128 v[214:217], v149 offset:16384
	ds_read_b128 v[218:221], v149 offset:17408
	ds_read_b128 v[222:225], v148 offset:16384
	ds_read_b128 v[226:229], v148 offset:17408
	global_load_lds_dwordx4 v[250:251], off
	v_lshl_add_u64 v[250:251], v[188:189], 0, s[46:47]
	s_mov_b32 m0, s5
	s_nop 0
	global_load_lds_dwordx4 v[250:251], off
	s_barrier
	s_waitcnt lgkmcnt(0)
	s_setprio 1
	s_waitcnt lgkmcnt(0)
	v_mfma_f32_16x16x32_bf16 v[60:63], v[198:201], v[162:165], v[60:63]
	v_mfma_f32_16x16x32_bf16 v[56:59], v[198:201], v[170:173], v[56:59]
	v_mfma_f32_16x16x32_bf16 v[48:51], v[206:209], v[170:173], v[48:51]
	v_mfma_f32_16x16x32_bf16 v[52:55], v[206:209], v[162:165], v[52:55]
	v_mfma_f32_16x16x32_bf16 v[44:47], v[214:217], v[162:165], v[44:47]
	v_mfma_f32_16x16x32_bf16 v[40:43], v[214:217], v[170:173], v[40:43]
	v_mfma_f32_16x16x32_bf16 v[32:35], v[222:225], v[170:173], v[32:35]
	v_mfma_f32_16x16x32_bf16 v[36:39], v[222:225], v[162:165], v[36:39]
	v_mfma_f32_16x16x32_bf16 v[60:63], v[202:205], v[166:169], v[60:63]
	v_mfma_f32_16x16x32_bf16 v[56:59], v[202:205], v[174:177], v[56:59]
	v_mfma_f32_16x16x32_bf16 v[48:51], v[210:213], v[174:177], v[48:51]
	v_mfma_f32_16x16x32_bf16 v[52:55], v[210:213], v[166:169], v[52:55]
	v_mfma_f32_16x16x32_bf16 v[44:47], v[218:221], v[166:169], v[44:47]
	v_mfma_f32_16x16x32_bf16 v[40:43], v[218:221], v[174:177], v[40:43]
	v_mfma_f32_16x16x32_bf16 v[32:35], v[226:229], v[174:177], v[32:35]
	v_mfma_f32_16x16x32_bf16 v[36:39], v[226:229], v[166:169], v[36:39]
	s_setprio 0
	s_barrier
; #define WAIT_V(n) asm volatile("s_waitcnt vmcnt(" #n ")" ::: "memory")
; #define WAIT_L(n) asm volatile("s_waitcnt lgkmcnt(" #n ")" ::: "memory")
; #define BAR __builtin_amdgcn_s_barrier()
; #define SCHED __builtin_amdgcn_sched_barrier(0)
; #define LDA(dst, b, h)                                                                            \
;   _Pragma("unroll") for (int m = 0; m < 4; ++m) _Pragma("unroll") for (int k = 0; k < 2; ++k)                                         \
;     dst[m][k] = *reinterpret_cast<const bf16x8*>((char*)SA(b, h) + lds_byte(wr * 64 + m * 16 + fr, k * 32 + fq * 8))
; #define LDB(dst, b, h)                                                                            \
;   _Pragma("unroll") for (int n = 0; n < 2; ++n) _Pragma("unroll") for (int k = 0; k < 2; ++k)                                         \
;     dst[n][k] = *reinterpret_cast<const bf16x8*>((char*)SB(b, h) + lds_byte(wc * 32 + n * 16 + fr, k * 32 + fq * 8))
; template <int K, bool SWAP>
; __device__ __forceinline__ void gemm_kloop(const bf16* __restrict__ A, const bf16* __restrict__ Bt,
;                                            f32x4 (&acc)[2][2][4][2], bool pref = false) {
;     ...
;     STAGE(SB(0, 1), Bt, HALF, t + 2);
;     WAIT_V(6); BAR; MMA(1, 1, At, B1); BAR;
;     LDB(B0, 1, 0); SCHED; LDA(At, 1, 0); STAGE(SA(0, 1), A, HALF, t + 2);
;     WAIT_L(8); BAR; WAIT_L(0); MMA(0, 0, At, B0); BAR; SCHED;
;     LDB(B1, 1, 1); STAGE(SB(1, 0), Bt, 0, t + 3);
;     BAR; WAIT_L(0); MMA(0, 1, At, B1); BAR;
	v_readfirstlane_b32 s5, v147
	v_add_u32_e32 v164, 0x2000, v147
	v_lshl_add_u64 v[162:163], v[246:247], 0, s[48:49]
	s_mov_b32 m0, s5
	v_readfirstlane_b32 s5, v164
	global_load_lds_dwordx4 v[162:163], off
	v_lshl_add_u64 v[162:163], v[248:249], 0, s[48:49]
	s_mov_b32 m0, s5
	s_nop 0
	global_load_lds_dwordx4 v[162:163], off
	s_waitcnt vmcnt(6)
	s_barrier
	s_setprio 1
	v_mfma_f32_16x16x32_bf16 v[28:31], v[198:201], v[230:233], v[28:31]
	v_mfma_f32_16x16x32_bf16 v[24:27], v[198:201], v[238:241], v[24:27]
	v_mfma_f32_16x16x32_bf16 v[16:19], v[206:209], v[238:241], v[16:19]
	v_mfma_f32_16x16x32_bf16 v[20:23], v[206:209], v[230:233], v[20:23]
	v_mfma_f32_16x16x32_bf16 v[12:15], v[214:217], v[230:233], v[12:15]
	v_mfma_f32_16x16x32_bf16 v[8:11], v[214:217], v[238:241], v[8:11]
	v_mfma_f32_16x16x32_bf16 v[0:3], v[222:225], v[238:241], v[0:3]
	v_mfma_f32_16x16x32_bf16 v[4:7], v[222:225], v[230:233], v[4:7]
	v_mfma_f32_16x16x32_bf16 v[28:31], v[202:205], v[234:237], v[28:31]
	v_mfma_f32_16x16x32_bf16 v[24:27], v[202:205], v[242:245], v[24:27]
	v_mfma_f32_16x16x32_bf16 v[16:19], v[210:213], v[242:245], v[16:19]
	v_mfma_f32_16x16x32_bf16 v[20:23], v[210:213], v[234:237], v[20:23]
	v_mfma_f32_16x16x32_bf16 v[12:15], v[218:221], v[234:237], v[12:15]
	v_mfma_f32_16x16x32_bf16 v[8:11], v[218:221], v[242:245], v[8:11]
	v_mfma_f32_16x16x32_bf16 v[0:3], v[226:229], v[242:245], v[0:3]
	v_mfma_f32_16x16x32_bf16 v[4:7], v[226:229], v[234:237], v[4:7]
	s_setprio 0
	s_barrier
	ds_read_b128 v[162:165], v153
	ds_read_b128 v[166:169], v153 offset:1024
	ds_read_b128 v[170:173], v153 offset:2048
	ds_read_b128 v[174:177], v153 offset:3072
	v_add_u32_e32 v186, 0x4000, v146
	v_lshl_add_u64 v[230:231], v[178:179], 0, s[50:51]
	v_readfirstlane_b32 s5, v186
	v_add_u32_e32 v186, 0x6000, v146
	s_mov_b32 m0, s5
	v_readfirstlane_b32 s5, v186
	ds_read_b128 v[198:201], v151 offset:32768
	ds_read_b128 v[202:205], v151 offset:33792
	ds_read_b128 v[206:209], v150 offset:32768
	ds_read_b128 v[210:213], v150 offset:33792
	ds_read_b128 v[214:217], v149 offset:32768
	ds_read_b128 v[218:221], v149 offset:33792
	ds_read_b128 v[222:225], v148 offset:32768
	ds_read_b128 v[226:229], v148 offset:33792
	global_load_lds_dwordx4 v[230:231], off
	v_lshl_add_u64 v[230:231], v[188:189], 0, s[50:51]
	s_mov_b32 m0, s5
	s_nop 0
	global_load_lds_dwordx4 v[230:231], off
	s_waitcnt lgkmcnt(8)
	s_barrier
	s_waitcnt lgkmcnt(0)
	s_setprio 1
	s_waitcnt lgkmcnt(0)
	v_mfma_f32_16x16x32_bf16 v[124:127], v[198:201], v[162:165], v[124:127]
	v_mfma_f32_16x16x32_bf16 v[120:123], v[198:201], v[170:173], v[120:123]
	v_mfma_f32_16x16x32_bf16 v[112:115], v[206:209], v[170:173], v[112:115]
	v_mfma_f32_16x16x32_bf16 v[116:119], v[206:209], v[162:165], v[116:119]
	v_mfma_f32_16x16x32_bf16 v[108:111], v[214:217], v[162:165], v[108:111]
	v_mfma_f32_16x16x32_bf16 v[104:107], v[214:217], v[170:173], v[104:107]
	v_mfma_f32_16x16x32_bf16 v[96:99], v[222:225], v[170:173], v[96:99]
	v_mfma_f32_16x16x32_bf16 v[100:103], v[222:225], v[162:165], v[100:103]
	v_mfma_f32_16x16x32_bf16 v[124:127], v[202:205], v[166:169], v[124:127]
	v_mfma_f32_16x16x32_bf16 v[120:123], v[202:205], v[174:177], v[120:123]
	v_mfma_f32_16x16x32_bf16 v[112:115], v[210:213], v[174:177], v[112:115]
	v_mfma_f32_16x16x32_bf16 v[116:119], v[210:213], v[166:169], v[116:119]
	v_mfma_f32_16x16x32_bf16 v[108:111], v[218:221], v[166:169], v[108:111]
	v_mfma_f32_16x16x32_bf16 v[104:107], v[218:221], v[174:177], v[104:107]
	v_mfma_f32_16x16x32_bf16 v[96:99], v[226:229], v[174:177], v[96:99]
	v_mfma_f32_16x16x32_bf16 v[100:103], v[226:229], v[166:169], v[100:103]
	s_setprio 0
	s_barrier
	v_readfirstlane_b32 s5, v154
	v_add_u32_e32 v186, 0x2000, v154
	v_lshl_add_u64 v[250:251], v[246:247], 0, s[52:53]
	s_mov_b32 m0, s5
	v_readfirstlane_b32 s5, v186
	ds_read_b128 v[230:233], v152
	ds_read_b128 v[234:237], v152 offset:1024
	ds_read_b128 v[238:241], v152 offset:2048
	ds_read_b128 v[242:245], v152 offset:3072
	global_load_lds_dwordx4 v[250:251], off
	v_lshl_add_u64 v[250:251], v[248:249], 0, s[52:53]
	s_mov_b32 m0, s5
	s_nop 0
	global_load_lds_dwordx4 v[250:251], off
	s_barrier
	s_waitcnt lgkmcnt(0)
	s_setprio 1
	s_waitcnt lgkmcnt(0)
	v_mfma_f32_16x16x32_bf16 v[92:95], v[198:201], v[230:233], v[92:95]
	v_mfma_f32_16x16x32_bf16 v[88:91], v[198:201], v[238:241], v[88:91]
	v_mfma_f32_16x16x32_bf16 v[80:83], v[206:209], v[238:241], v[80:83]
	v_mfma_f32_16x16x32_bf16 v[84:87], v[206:209], v[230:233], v[84:87]
	v_mfma_f32_16x16x32_bf16 v[76:79], v[214:217], v[230:233], v[76:79]
	v_mfma_f32_16x16x32_bf16 v[72:75], v[214:217], v[238:241], v[72:75]
	v_mfma_f32_16x16x32_bf16 v[64:67], v[222:225], v[238:241], v[64:67]
	v_mfma_f32_16x16x32_bf16 v[68:71], v[222:225], v[230:233], v[68:71]
	v_mfma_f32_16x16x32_bf16 v[92:95], v[202:205], v[234:237], v[92:95]
	v_mfma_f32_16x16x32_bf16 v[88:91], v[202:205], v[242:245], v[88:91]
	v_mfma_f32_16x16x32_bf16 v[80:83], v[210:213], v[242:245], v[80:83]
	v_mfma_f32_16x16x32_bf16 v[84:87], v[210:213], v[234:237], v[84:87]
	v_mfma_f32_16x16x32_bf16 v[76:79], v[218:221], v[234:237], v[76:79]
	v_mfma_f32_16x16x32_bf16 v[72:75], v[218:221], v[242:245], v[72:75]
	v_mfma_f32_16x16x32_bf16 v[64:67], v[226:229], v[242:245], v[64:67]
	v_mfma_f32_16x16x32_bf16 v[68:71], v[226:229], v[234:237], v[68:71]
	s_setprio 0
	v_readfirstlane_b32 s5, v155
	v_lshl_add_u64 v[178:179], v[178:179], 0, s[54:55]
	s_mov_b32 m0, s5
	v_readfirstlane_b32 s5, v156
	s_barrier
; #define WAIT_V(n) asm volatile("s_waitcnt vmcnt(" #n ")" ::: "memory")
; #define WAIT_L(n) asm volatile("s_waitcnt lgkmcnt(" #n ")" ::: "memory")
; #define BAR __builtin_amdgcn_s_barrier()
; #define SCHED __builtin_amdgcn_sched_barrier(0)
; #define LDA(dst, b, h)                                                                            \
;   _Pragma("unroll") for (int m = 0; m < 4; ++m) _Pragma("unroll") for (int k = 0; k < 2; ++k)                                         \
;     dst[m][k] = *reinterpret_cast<const bf16x8*>((char*)SA(b, h) + lds_byte(wr * 64 + m * 16 + fr, k * 32 + fq * 8))
; #define LDB(dst, b, h)                                                                            \
;   _Pragma("unroll") for (int n = 0; n < 2; ++n) _Pragma("unroll") for (int k = 0; k < 2; ++k)                                         \
;     dst[n][k] = *reinterpret_cast<const bf16x8*>((char*)SB(b, h) + lds_byte(wc * 32 + n * 16 + fr, k * 32 + fq * 8))
; template <int K, bool SWAP>
; __device__ __forceinline__ void gemm_kloop(const bf16* __restrict__ A, const bf16* __restrict__ Bt,
;                                            f32x4 (&acc)[2][2][4][2], bool pref = false) {
;     ...
;     LDA(At, 1, 1); STAGE(SA(1, 0), A, 0, t + 3);
;     BAR; WAIT_L(0); MMA(1, 0, At, B0); BAR; SCHED;
;     STAGE(SB(1, 1), Bt, HALF, t + 3);
;     WAIT_V(6); BAR; MMA(1, 1, At, B1); BAR;
;   }
;   { LDB(B0, 0, 0); LDA(At, 0, 0); STAGE(SA(1, 1), A, HALF, nt - 1);
;     BAR; WAIT_L(0); MMA(0, 0, At, B0); BAR;
	ds_read_b128 v[198:201], v151 offset:49152
	ds_read_b128 v[202:205], v151 offset:50176
	ds_read_b128 v[206:209], v150 offset:49152
	ds_read_b128 v[210:213], v150 offset:50176
	ds_read_b128 v[214:217], v149 offset:49152
	ds_read_b128 v[218:221], v149 offset:50176
	ds_read_b128 v[222:225], v148 offset:49152
	ds_read_b128 v[226:229], v148 offset:50176
	global_load_lds_dwordx4 v[178:179], off
	v_lshl_add_u64 v[178:179], v[188:189], 0, s[54:55]
	s_mov_b32 m0, s5
	s_nop 0
	global_load_lds_dwordx4 v[178:179], off
	s_barrier
	s_waitcnt lgkmcnt(0)
	s_setprio 1
	s_waitcnt lgkmcnt(0)
	v_mfma_f32_16x16x32_bf16 v[60:63], v[198:201], v[162:165], v[60:63]
	v_mfma_f32_16x16x32_bf16 v[56:59], v[198:201], v[170:173], v[56:59]
	v_mfma_f32_16x16x32_bf16 v[48:51], v[206:209], v[170:173], v[48:51]
	v_mfma_f32_16x16x32_bf16 v[52:55], v[206:209], v[162:165], v[52:55]
	v_mfma_f32_16x16x32_bf16 v[44:47], v[214:217], v[162:165], v[44:47]
	v_mfma_f32_16x16x32_bf16 v[40:43], v[214:217], v[170:173], v[40:43]
	v_mfma_f32_16x16x32_bf16 v[32:35], v[222:225], v[170:173], v[32:35]
	v_mfma_f32_16x16x32_bf16 v[36:39], v[222:225], v[162:165], v[36:39]
	v_mfma_f32_16x16x32_bf16 v[60:63], v[202:205], v[166:169], v[60:63]
	v_mfma_f32_16x16x32_bf16 v[56:59], v[202:205], v[174:177], v[56:59]
	v_mfma_f32_16x16x32_bf16 v[48:51], v[210:213], v[174:177], v[48:51]
	v_mfma_f32_16x16x32_bf16 v[52:55], v[210:213], v[166:169], v[52:55]
	v_mfma_f32_16x16x32_bf16 v[44:47], v[218:221], v[166:169], v[44:47]
	v_mfma_f32_16x16x32_bf16 v[40:43], v[218:221], v[174:177], v[40:43]
	v_mfma_f32_16x16x32_bf16 v[32:35], v[226:229], v[174:177], v[32:35]
	v_mfma_f32_16x16x32_bf16 v[36:39], v[226:229], v[166:169], v[36:39]
	s_setprio 0
	s_barrier
	v_readfirstlane_b32 s5, v157
	v_add_u32_e32 v164, 0x2000, v157
	v_lshl_add_u64 v[162:163], v[246:247], 0, s[56:57]
	s_mov_b32 m0, s5
	v_readfirstlane_b32 s5, v164
	global_load_lds_dwordx4 v[162:163], off
	v_lshl_add_u64 v[162:163], v[248:249], 0, s[56:57]
	s_mov_b32 m0, s5
	s_nop 0
	global_load_lds_dwordx4 v[162:163], off
	s_waitcnt vmcnt(6)
	s_barrier
	s_setprio 1
	v_mfma_f32_16x16x32_bf16 v[28:31], v[198:201], v[230:233], v[28:31]
	v_mfma_f32_16x16x32_bf16 v[24:27], v[198:201], v[238:241], v[24:27]
	v_mfma_f32_16x16x32_bf16 v[16:19], v[206:209], v[238:241], v[16:19]
	v_mfma_f32_16x16x32_bf16 v[20:23], v[206:209], v[230:233], v[20:23]
	v_mfma_f32_16x16x32_bf16 v[12:15], v[214:217], v[230:233], v[12:15]
	v_mfma_f32_16x16x32_bf16 v[8:11], v[214:217], v[238:241], v[8:11]
	v_mfma_f32_16x16x32_bf16 v[0:3], v[222:225], v[238:241], v[0:3]
	v_mfma_f32_16x16x32_bf16 v[4:7], v[222:225], v[230:233], v[4:7]
	v_mfma_f32_16x16x32_bf16 v[28:31], v[202:205], v[234:237], v[28:31]
	v_mfma_f32_16x16x32_bf16 v[24:27], v[202:205], v[242:245], v[24:27]
	v_mfma_f32_16x16x32_bf16 v[16:19], v[210:213], v[242:245], v[16:19]
	v_mfma_f32_16x16x32_bf16 v[20:23], v[210:213], v[234:237], v[20:23]
	v_mfma_f32_16x16x32_bf16 v[12:15], v[218:221], v[234:237], v[12:15]
	v_mfma_f32_16x16x32_bf16 v[8:11], v[218:221], v[242:245], v[8:11]
	v_mfma_f32_16x16x32_bf16 v[0:3], v[226:229], v[242:245], v[0:3]
	v_mfma_f32_16x16x32_bf16 v[4:7], v[226:229], v[234:237], v[4:7]
	s_setprio 0
	s_add_i32 s4, s4, 2
	v_lshl_add_u64 v[136:137], v[136:137], 0, s[44:45]
	v_lshl_add_u64 v[138:139], v[138:139], 0, s[44:45]
	v_lshl_add_u64 v[140:141], v[140:141], 0, s[44:45]
	s_cmp_lt_u32 s4, 12
	v_lshl_add_u64 v[142:143], v[142:143], 0, s[44:45]
	s_barrier
	s_cbranch_scc1 .LBB0_271
	s_add_u32 s0, s0, 0x40780
	s_addc_u32 s1, s1, 0
	v_lshl_add_u64 v[130:131], s[0:1], 0, v[130:131]
	v_readfirstlane_b32 s4, v160
	v_lshl_add_u64 v[128:129], v[128:129], 1, v[130:131]
	s_mov_b32 m0, s4
	ds_read_b128 v[136:139], v159
	ds_read_b128 v[140:143], v159 offset:1024
	ds_read_b128 v[154:157], v159 offset:2048
	ds_read_b128 v[162:165], v159 offset:3072
	ds_read_b128 v[166:169], v151
	ds_read_b128 v[170:173], v151 offset:1024
	ds_read_b128 v[174:177], v150
	ds_read_b128 v[198:201], v150 offset:1024
	ds_read_b128 v[202:205], v149
	ds_read_b128 v[206:209], v149 offset:1024
	ds_read_b128 v[210:213], v148
	ds_read_b128 v[214:217], v148 offset:1024
	global_load_lds_dwordx4 v[128:129], off
	v_lshl_add_u64 v[128:129], s[0:1], 0, v[134:135]
	v_readfirstlane_b32 s0, v161
	v_lshl_add_u64 v[128:129], v[132:133], 1, v[128:129]
	s_mov_b32 m0, s0
	s_nop 0
	global_load_lds_dwordx4 v[128:129], off
	s_barrier
	s_waitcnt lgkmcnt(0)
	s_setprio 1
	s_waitcnt lgkmcnt(0)
	v_mfma_f32_16x16x32_bf16 v[124:127], v[166:169], v[136:139], v[124:127]
	v_mfma_f32_16x16x32_bf16 v[116:119], v[174:177], v[136:139], v[116:119]
	v_mfma_f32_16x16x32_bf16 v[108:111], v[202:205], v[136:139], v[108:111]
	v_mfma_f32_16x16x32_bf16 v[100:103], v[210:213], v[136:139], v[100:103]
	v_mfma_f32_16x16x32_bf16 v[124:127], v[170:173], v[140:143], v[124:127]
	v_mfma_f32_16x16x32_bf16 v[120:123], v[166:169], v[154:157], v[120:123]
	v_mfma_f32_16x16x32_bf16 v[116:119], v[198:201], v[140:143], v[116:119]
	v_mfma_f32_16x16x32_bf16 v[112:115], v[174:177], v[154:157], v[112:115]
	v_mfma_f32_16x16x32_bf16 v[108:111], v[206:209], v[140:143], v[108:111]
	v_mfma_f32_16x16x32_bf16 v[104:107], v[202:205], v[154:157], v[104:107]
	v_mfma_f32_16x16x32_bf16 v[100:103], v[214:217], v[140:143], v[100:103]
	v_mfma_f32_16x16x32_bf16 v[96:99], v[210:213], v[154:157], v[96:99]
	v_mfma_f32_16x16x32_bf16 v[128:131], v[170:173], v[162:165], v[120:123]
	v_mfma_f32_16x16x32_bf16 v[132:135], v[198:201], v[162:165], v[112:115]
	v_mfma_f32_16x16x32_bf16 v[218:221], v[206:209], v[162:165], v[104:107]
	v_mfma_f32_16x16x32_bf16 v[222:225], v[214:217], v[162:165], v[96:99]
	s_setprio 0
	s_barrier
; #define WAIT_V(n) asm volatile("s_waitcnt vmcnt(" #n ")" ::: "memory")
; #define WAIT_L(n) asm volatile("s_waitcnt lgkmcnt(" #n ")" ::: "memory")
; #define BAR __builtin_amdgcn_s_barrier()
; #define LDA(dst, b, h)                                                                            \
;   _Pragma("unroll") for (int m = 0; m < 4; ++m) _Pragma("unroll") for (int k = 0; k < 2; ++k)                                         \
;     dst[m][k] = *reinterpret_cast<const bf16x8*>((char*)SA(b, h) + lds_byte(wr * 64 + m * 16 + fr, k * 32 + fq * 8))
; #define LDB(dst, b, h)                                                                            \
;   _Pragma("unroll") for (int n = 0; n < 2; ++n) _Pragma("unroll") for (int k = 0; k < 2; ++k)                                         \
;     dst[n][k] = *reinterpret_cast<const bf16x8*>((char*)SB(b, h) + lds_byte(wc * 32 + n * 16 + fr, k * 32 + fq * 8))
; template <int K, bool SWAP>
; __device__ __forceinline__ void gemm_kloop(const bf16* __restrict__ A, const bf16* __restrict__ Bt,
;                                            f32x4 (&acc)[2][2][4][2], bool pref = false) {
;     ...
;     LDB(B1, 0, 1); BAR; WAIT_L(0); MMA(0, 1, At, B1); BAR;
;     LDA(At, 0, 1); WAIT_V(4); BAR; WAIT_L(0); MMA(1, 0, At, B0); MMA(1, 1, At, B1); BAR; }
;   { LDB(B0, 1, 0); LDA(At, 1, 0); WAIT_V(2); BAR; WAIT_L(0); MMA(0, 0, At, B0); BAR;
	s_nop 1
	ds_read_b128 v[96:99], v158
	ds_read_b128 v[104:107], v158 offset:1024
	ds_read_b128 v[112:115], v158 offset:2048
	ds_read_b128 v[120:123], v158 offset:3072
	s_barrier
	s_waitcnt lgkmcnt(0)
	s_setprio 1
	s_waitcnt lgkmcnt(0)
	v_mfma_f32_16x16x32_bf16 v[92:95], v[166:169], v[96:99], v[92:95]
	v_mfma_f32_16x16x32_bf16 v[84:87], v[174:177], v[96:99], v[84:87]
	v_mfma_f32_16x16x32_bf16 v[76:79], v[202:205], v[96:99], v[76:79]
	v_mfma_f32_16x16x32_bf16 v[68:71], v[210:213], v[96:99], v[68:71]
	v_mfma_f32_16x16x32_bf16 v[92:95], v[170:173], v[104:107], v[92:95]
	v_mfma_f32_16x16x32_bf16 v[88:91], v[166:169], v[112:115], v[88:91]
	v_mfma_f32_16x16x32_bf16 v[84:87], v[198:201], v[104:107], v[84:87]
	v_mfma_f32_16x16x32_bf16 v[80:83], v[174:177], v[112:115], v[80:83]
	v_mfma_f32_16x16x32_bf16 v[76:79], v[206:209], v[104:107], v[76:79]
	v_mfma_f32_16x16x32_bf16 v[72:75], v[202:205], v[112:115], v[72:75]
	v_mfma_f32_16x16x32_bf16 v[68:71], v[214:217], v[104:107], v[68:71]
	v_mfma_f32_16x16x32_bf16 v[64:67], v[210:213], v[112:115], v[64:67]
	v_mfma_f32_16x16x32_bf16 v[158:161], v[170:173], v[120:123], v[88:91]
	v_mfma_f32_16x16x32_bf16 v[166:169], v[198:201], v[120:123], v[80:83]
	v_mfma_f32_16x16x32_bf16 v[170:173], v[206:209], v[120:123], v[72:75]
	v_mfma_f32_16x16x32_bf16 v[174:177], v[214:217], v[120:123], v[64:67]
	s_setprio 0
	s_barrier
	s_nop 1
	ds_read_b128 v[64:67], v151 offset:16384
	ds_read_b128 v[72:75], v151 offset:17408
	ds_read_b128 v[80:83], v150 offset:16384
	ds_read_b128 v[88:91], v150 offset:17408
	ds_read_b128 v[198:201], v149 offset:16384
	ds_read_b128 v[202:205], v149 offset:17408
	ds_read_b128 v[206:209], v148 offset:16384
	ds_read_b128 v[210:213], v148 offset:17408
	s_waitcnt vmcnt(4)
	s_barrier
	s_waitcnt lgkmcnt(0)
	s_setprio 1
	s_waitcnt lgkmcnt(0)
	v_mfma_f32_16x16x32_bf16 v[60:63], v[64:67], v[136:139], v[60:63]
	v_mfma_f32_16x16x32_bf16 v[52:55], v[80:83], v[136:139], v[52:55]
	v_mfma_f32_16x16x32_bf16 v[44:47], v[198:201], v[136:139], v[44:47]
	v_mfma_f32_16x16x32_bf16 v[36:39], v[206:209], v[136:139], v[36:39]
	v_mfma_f32_16x16x32_bf16 v[60:63], v[72:75], v[140:143], v[60:63]
	v_mfma_f32_16x16x32_bf16 v[56:59], v[64:67], v[154:157], v[56:59]
	v_mfma_f32_16x16x32_bf16 v[52:55], v[88:91], v[140:143], v[52:55]
	v_mfma_f32_16x16x32_bf16 v[48:51], v[80:83], v[154:157], v[48:51]
	v_mfma_f32_16x16x32_bf16 v[44:47], v[202:205], v[140:143], v[44:47]
	v_mfma_f32_16x16x32_bf16 v[40:43], v[198:201], v[154:157], v[40:43]
	v_mfma_f32_16x16x32_bf16 v[36:39], v[210:213], v[140:143], v[36:39]
	v_mfma_f32_16x16x32_bf16 v[32:35], v[206:209], v[154:157], v[32:35]
	v_mfma_f32_16x16x32_bf16 v[214:217], v[72:75], v[162:165], v[56:59]
	v_mfma_f32_16x16x32_bf16 v[226:229], v[88:91], v[162:165], v[48:51]
	v_mfma_f32_16x16x32_bf16 v[230:233], v[202:205], v[162:165], v[40:43]
	v_mfma_f32_16x16x32_bf16 v[136:139], v[210:213], v[162:165], v[32:35]
	s_setprio 0
	s_setprio 1
	v_mfma_f32_16x16x32_bf16 v[28:31], v[64:67], v[96:99], v[28:31]
	v_mfma_f32_16x16x32_bf16 v[20:23], v[80:83], v[96:99], v[20:23]
	v_mfma_f32_16x16x32_bf16 v[12:15], v[198:201], v[96:99], v[12:15]
	v_mfma_f32_16x16x32_bf16 v[4:7], v[206:209], v[96:99], v[4:7]
	v_mfma_f32_16x16x32_bf16 v[28:31], v[72:75], v[104:107], v[28:31]
	v_mfma_f32_16x16x32_bf16 v[24:27], v[64:67], v[112:115], v[24:27]
	v_mfma_f32_16x16x32_bf16 v[20:23], v[88:91], v[104:107], v[20:23]
	v_mfma_f32_16x16x32_bf16 v[16:19], v[80:83], v[112:115], v[16:19]
	v_mfma_f32_16x16x32_bf16 v[12:15], v[202:205], v[104:107], v[12:15]
	v_mfma_f32_16x16x32_bf16 v[8:11], v[198:201], v[112:115], v[8:11]
	v_mfma_f32_16x16x32_bf16 v[4:7], v[210:213], v[104:107], v[4:7]
	v_mfma_f32_16x16x32_bf16 v[0:3], v[206:209], v[112:115], v[0:3]
	v_mfma_f32_16x16x32_bf16 v[140:143], v[72:75], v[120:123], v[24:27]
	v_mfma_f32_16x16x32_bf16 v[154:157], v[88:91], v[120:123], v[16:19]
	v_mfma_f32_16x16x32_bf16 v[162:165], v[202:205], v[120:123], v[8:11]
	v_mfma_f32_16x16x32_bf16 v[198:201], v[210:213], v[120:123], v[0:3]
	s_setprio 0
	s_barrier
	s_nop 1
	ds_read_b128 v[0:3], v153
	ds_read_b128 v[8:11], v153 offset:1024
	ds_read_b128 v[16:19], v153 offset:2048
	ds_read_b128 v[24:27], v153 offset:3072
	ds_read_b128 v[32:35], v151 offset:32768
	ds_read_b128 v[40:43], v151 offset:33792
	ds_read_b128 v[48:51], v150 offset:32768
	ds_read_b128 v[56:59], v150 offset:33792
	ds_read_b128 v[64:67], v149 offset:32768
	ds_read_b128 v[202:205], v149 offset:33792
	ds_read_b128 v[206:209], v148 offset:32768
	ds_read_b128 v[210:213], v148 offset:33792
	s_waitcnt vmcnt(2)
	s_barrier
; #define WAIT_V(n) asm volatile("s_waitcnt vmcnt(" #n ")" ::: "memory")
; #define WAIT_L(n) asm volatile("s_waitcnt lgkmcnt(" #n ")" ::: "memory")
; #define BAR __builtin_amdgcn_s_barrier()
; #define LDA(dst, b, h)                                                                            \
;   _Pragma("unroll") for (int m = 0; m < 4; ++m) _Pragma("unroll") for (int k = 0; k < 2; ++k)                                         \
;     dst[m][k] = *reinterpret_cast<const bf16x8*>((char*)SA(b, h) + lds_byte(wr * 64 + m * 16 + fr, k * 32 + fq * 8))
; #define LDB(dst, b, h)                                                                            \
;   _Pragma("unroll") for (int n = 0; n < 2; ++n) _Pragma("unroll") for (int k = 0; k < 2; ++k)                                         \
;     dst[n][k] = *reinterpret_cast<const bf16x8*>((char*)SB(b, h) + lds_byte(wc * 32 + n * 16 + fr, k * 32 + fq * 8))
; template <int K, bool SWAP>
; __device__ __forceinline__ void gemm_kloop(const bf16* __restrict__ A, const bf16* __restrict__ Bt,
;                                            f32x4 (&acc)[2][2][4][2], bool pref = false) {
;     ...
;   { LDB(B0, 1, 0); LDA(At, 1, 0); WAIT_V(2); BAR; WAIT_L(0); MMA(0, 0, At, B0); BAR;
;     LDB(B1, 1, 1); WAIT_V(0); BAR; WAIT_L(0); MMA(0, 1, At, B1); BAR;
;     LDA(At, 1, 1); BAR; WAIT_L(0); MMA(1, 0, At, B0); MMA(1, 1, At, B1); BAR; }
;   if (wr == 0) BAR;
	s_waitcnt lgkmcnt(0)
	s_setprio 1
	s_waitcnt lgkmcnt(0)
	v_mfma_f32_16x16x32_bf16 v[72:75], v[32:35], v[0:3], v[124:127]
	v_mfma_f32_16x16x32_bf16 v[120:123], v[40:43], v[8:11], v[72:75]
	v_mfma_f32_16x16x32_bf16 v[72:75], v[32:35], v[16:19], v[128:131]
	v_mfma_f32_16x16x32_bf16 v[124:127], v[40:43], v[24:27], v[72:75]
	v_mfma_f32_16x16x32_bf16 v[72:75], v[48:51], v[0:3], v[116:119]
	v_mfma_f32_16x16x32_bf16 v[112:115], v[56:59], v[8:11], v[72:75]
	v_mfma_f32_16x16x32_bf16 v[72:75], v[48:51], v[16:19], v[132:135]
	v_mfma_f32_16x16x32_bf16 v[116:119], v[56:59], v[24:27], v[72:75]
	v_mfma_f32_16x16x32_bf16 v[72:75], v[64:67], v[0:3], v[108:111]
	v_mfma_f32_16x16x32_bf16 v[104:107], v[202:205], v[8:11], v[72:75]
	v_mfma_f32_16x16x32_bf16 v[72:75], v[64:67], v[16:19], v[218:221]
	v_mfma_f32_16x16x32_bf16 v[108:111], v[202:205], v[24:27], v[72:75]
	v_mfma_f32_16x16x32_bf16 v[72:75], v[206:209], v[0:3], v[100:103]
	v_mfma_f32_16x16x32_bf16 v[96:99], v[210:213], v[8:11], v[72:75]
	v_mfma_f32_16x16x32_bf16 v[72:75], v[206:209], v[16:19], v[222:225]
	v_mfma_f32_16x16x32_bf16 v[100:103], v[210:213], v[24:27], v[72:75]
	s_setprio 0
	s_barrier
	ds_read_b128 v[128:131], v152
	ds_read_b128 v[132:135], v152 offset:1024
	ds_read_b128 v[218:221], v152 offset:2048
	ds_read_b128 v[222:225], v152 offset:3072
	s_waitcnt vmcnt(0)
	s_barrier
	s_waitcnt lgkmcnt(0)
	s_setprio 1
	s_waitcnt lgkmcnt(0)
	v_mfma_f32_16x16x32_bf16 v[72:75], v[32:35], v[128:131], v[92:95]
	v_mfma_f32_16x16x32_bf16 v[32:35], v[32:35], v[218:221], v[158:161]
	v_mfma_f32_16x16x32_bf16 v[92:95], v[40:43], v[222:225], v[32:35]
	v_mfma_f32_16x16x32_bf16 v[32:35], v[48:51], v[128:131], v[84:87]
	v_mfma_f32_16x16x32_bf16 v[80:83], v[56:59], v[132:135], v[32:35]
	v_mfma_f32_16x16x32_bf16 v[32:35], v[48:51], v[218:221], v[166:169]
	v_mfma_f32_16x16x32_bf16 v[84:87], v[56:59], v[222:225], v[32:35]
	v_mfma_f32_16x16x32_bf16 v[32:35], v[64:67], v[128:131], v[76:79]
	v_mfma_f32_16x16x32_bf16 v[88:91], v[40:43], v[132:135], v[72:75]
	v_mfma_f32_16x16x32_bf16 v[72:75], v[202:205], v[132:135], v[32:35]
	v_mfma_f32_16x16x32_bf16 v[32:35], v[64:67], v[218:221], v[170:173]
	v_mfma_f32_16x16x32_bf16 v[76:79], v[202:205], v[222:225], v[32:35]
	v_mfma_f32_16x16x32_bf16 v[32:35], v[206:209], v[128:131], v[68:71]
	v_mfma_f32_16x16x32_bf16 v[64:67], v[210:213], v[132:135], v[32:35]
	v_mfma_f32_16x16x32_bf16 v[32:35], v[206:209], v[218:221], v[174:177]
	v_mfma_f32_16x16x32_bf16 v[68:71], v[210:213], v[222:225], v[32:35]
	s_setprio 0
	s_barrier
	ds_read_b128 v[158:161], v151 offset:49152
	ds_read_b128 v[166:169], v151 offset:50176
	ds_read_b128 v[170:173], v150 offset:49152
	ds_read_b128 v[150:153], v150 offset:50176
	ds_read_b128 v[174:177], v149 offset:49152
	ds_read_b128 v[202:205], v149 offset:50176
	ds_read_b128 v[206:209], v148 offset:49152
	ds_read_b128 v[146:149], v148 offset:50176
	s_barrier
	s_waitcnt lgkmcnt(0)
	s_setprio 1
	s_waitcnt lgkmcnt(0)
	v_mfma_f32_16x16x32_bf16 v[32:35], v[158:161], v[0:3], v[60:63]
	v_mfma_f32_16x16x32_bf16 v[56:59], v[166:169], v[8:11], v[32:35]
	v_mfma_f32_16x16x32_bf16 v[32:35], v[158:161], v[16:19], v[214:217]
	v_mfma_f32_16x16x32_bf16 v[60:63], v[166:169], v[24:27], v[32:35]
	v_mfma_f32_16x16x32_bf16 v[32:35], v[170:173], v[0:3], v[52:55]
	v_mfma_f32_16x16x32_bf16 v[48:51], v[150:153], v[8:11], v[32:35]
	v_mfma_f32_16x16x32_bf16 v[32:35], v[170:173], v[16:19], v[226:229]
	v_mfma_f32_16x16x32_bf16 v[52:55], v[150:153], v[24:27], v[32:35]
	v_mfma_f32_16x16x32_bf16 v[32:35], v[174:177], v[0:3], v[44:47]
	v_mfma_f32_16x16x32_bf16 v[40:43], v[202:205], v[8:11], v[32:35]
	v_mfma_f32_16x16x32_bf16 v[32:35], v[174:177], v[16:19], v[230:233]
	v_mfma_f32_16x16x32_bf16 v[0:3], v[206:209], v[0:3], v[36:39]
	v_mfma_f32_16x16x32_bf16 v[44:47], v[202:205], v[24:27], v[32:35]
	v_mfma_f32_16x16x32_bf16 v[32:35], v[146:149], v[8:11], v[0:3]
	v_mfma_f32_16x16x32_bf16 v[0:3], v[206:209], v[16:19], v[136:139]
	v_mfma_f32_16x16x32_bf16 v[36:39], v[146:149], v[24:27], v[0:3]
	s_setprio 0
	s_setprio 1
	v_mfma_f32_16x16x32_bf16 v[0:3], v[158:161], v[128:131], v[28:31]
	v_mfma_f32_16x16x32_bf16 v[24:27], v[166:169], v[132:135], v[0:3]
	v_mfma_f32_16x16x32_bf16 v[0:3], v[158:161], v[218:221], v[140:143]
	v_mfma_f32_16x16x32_bf16 v[28:31], v[166:169], v[222:225], v[0:3]
	v_mfma_f32_16x16x32_bf16 v[0:3], v[170:173], v[128:131], v[20:23]
	v_mfma_f32_16x16x32_bf16 v[16:19], v[150:153], v[132:135], v[0:3]
	v_mfma_f32_16x16x32_bf16 v[0:3], v[170:173], v[218:221], v[154:157]
	v_mfma_f32_16x16x32_bf16 v[20:23], v[150:153], v[222:225], v[0:3]
	v_mfma_f32_16x16x32_bf16 v[0:3], v[174:177], v[128:131], v[12:15]
	v_mfma_f32_16x16x32_bf16 v[8:11], v[202:205], v[132:135], v[0:3]
	v_mfma_f32_16x16x32_bf16 v[0:3], v[174:177], v[218:221], v[162:165]
	v_mfma_f32_16x16x32_bf16 v[12:15], v[202:205], v[222:225], v[0:3]
	v_mfma_f32_16x16x32_bf16 v[0:3], v[206:209], v[128:131], v[4:7]
	v_mfma_f32_16x16x32_bf16 v[4:7], v[206:209], v[218:221], v[198:201]
	v_mfma_f32_16x16x32_bf16 v[0:3], v[146:149], v[132:135], v[0:3]
	v_mfma_f32_16x16x32_bf16 v[4:7], v[146:149], v[222:225], v[4:7]
	s_setprio 0
	s_movk_i32 s0, 0x100
	v_cmp_gt_u32_e32 vcc, s0, v144
	s_barrier
	s_and_saveexec_b64 s[0:1], vcc
	s_cbranch_execz .LBB0_274
	s_barrier

; #define WAIT_L(n) asm volatile("s_waitcnt lgkmcnt(" #n ")" ::: "memory")
; #define BAR __builtin_amdgcn_s_barrier()
; #define SCHED __builtin_amdgcn_sched_barrier(0)
; #define LDA(dst, b, h)                                                                            \
;   _Pragma("unroll") for (int m = 0; m < 4; ++m) _Pragma("unroll") for (int k = 0; k < 2; ++k)                                         \
;     dst[m][k] = *reinterpret_cast<const bf16x8*>((char*)SA(b, h) + lds_byte(wr * 64 + m * 16 + fr, k * 32 + fq * 8))
; #define LDB(dst, b, h)                                                                            \
;   _Pragma("unroll") for (int n = 0; n < 2; ++n) _Pragma("unroll") for (int k = 0; k < 2; ++k)                                         \
;     dst[n][k] = *reinterpret_cast<const bf16x8*>((char*)SB(b, h) + lds_byte(wc * 32 + n * 16 + fr, k * 32 + fq * 8))
; template <int K, bool SWAP>
; __device__ __forceinline__ void gemm_kloop(const bf16* __restrict__ A, const bf16* __restrict__ Bt,
;                                            f32x4 (&acc)[2][2][4][2], bool pref = false) {
;     ...
;     LDB(B0, 0, 0); SCHED; LDA(At, 0, 0); STAGE(SA(1, 1), A, HALF, t + 1);
;     WAIT_L(8); BAR; WAIT_L(0); MMA(0, 0, At, B0); BAR; SCHED;
;     LDB(B1, 0, 1); STAGE(SB(0, 0), Bt, 0, t + 2);
;     BAR; WAIT_L(0); MMA(0, 1, At, B1); BAR;
;     LDA(At, 0, 1); STAGE(SA(0, 0), A, 0, t + 2);
;     BAR; WAIT_L(0); MMA(1, 0, At, B0); BAR; SCHED;
.LBB0_449:
	ds_read_b128 v[162:165], v159
	ds_read_b128 v[166:169], v159 offset:1024
	ds_read_b128 v[170:173], v159 offset:2048
	ds_read_b128 v[174:177], v159 offset:3072
	v_add_u32_e32 v160, 0xc000, v146
	v_lshl_add_u64 v[178:179], s[58:59], 0, v[140:141]
	v_readfirstlane_b32 s7, v160
	v_lshl_add_u64 v[188:189], v[178:179], 0, s[42:43]
	s_mov_b32 m0, s7
	v_add_u32_e32 v161, 0xe000, v146
	ds_read_b128 v[198:201], v151
	ds_read_b128 v[202:205], v151 offset:1024
	ds_read_b128 v[206:209], v150
	ds_read_b128 v[210:213], v150 offset:1024
	ds_read_b128 v[214:217], v149
	ds_read_b128 v[218:221], v149 offset:1024
	ds_read_b128 v[222:225], v148
	ds_read_b128 v[226:229], v148 offset:1024
	global_load_lds_dwordx4 v[188:189], off
	v_lshl_add_u64 v[188:189], s[58:59], 0, v[142:143]
	v_readfirstlane_b32 s7, v161
	v_lshl_add_u64 v[230:231], v[188:189], 0, s[42:43]
	s_mov_b32 m0, s7
	s_nop 0
	global_load_lds_dwordx4 v[230:231], off
	s_waitcnt lgkmcnt(8)
	s_barrier
	s_waitcnt lgkmcnt(0)
	s_setprio 1
	s_waitcnt lgkmcnt(0)
	v_mfma_f32_16x16x32_bf16 v[124:127], v[198:201], v[162:165], v[124:127]
	v_mfma_f32_16x16x32_bf16 v[120:123], v[198:201], v[170:173], v[120:123]
	v_mfma_f32_16x16x32_bf16 v[112:115], v[206:209], v[170:173], v[112:115]
	v_mfma_f32_16x16x32_bf16 v[116:119], v[206:209], v[162:165], v[116:119]
	v_mfma_f32_16x16x32_bf16 v[108:111], v[214:217], v[162:165], v[108:111]
	v_mfma_f32_16x16x32_bf16 v[104:107], v[214:217], v[170:173], v[104:107]
	v_mfma_f32_16x16x32_bf16 v[96:99], v[222:225], v[170:173], v[96:99]
	v_mfma_f32_16x16x32_bf16 v[100:103], v[222:225], v[162:165], v[100:103]
	v_mfma_f32_16x16x32_bf16 v[124:127], v[202:205], v[166:169], v[124:127]
	v_mfma_f32_16x16x32_bf16 v[120:123], v[202:205], v[174:177], v[120:123]
	v_mfma_f32_16x16x32_bf16 v[112:115], v[210:213], v[174:177], v[112:115]
	v_mfma_f32_16x16x32_bf16 v[116:119], v[210:213], v[166:169], v[116:119]
	v_mfma_f32_16x16x32_bf16 v[108:111], v[218:221], v[166:169], v[108:111]
	v_mfma_f32_16x16x32_bf16 v[104:107], v[218:221], v[174:177], v[104:107]
	v_mfma_f32_16x16x32_bf16 v[96:99], v[226:229], v[174:177], v[96:99]
	v_mfma_f32_16x16x32_bf16 v[100:103], v[226:229], v[166:169], v[100:103]
	s_setprio 0
	s_barrier
	v_add_u32_e32 v186, s1, v145
	v_lshl_add_u64 v[246:247], s[58:59], 0, v[136:137]
	v_readfirstlane_b32 s7, v186
	v_lshl_add_u64 v[248:249], v[246:247], 0, s[44:45]
	s_mov_b32 m0, s7
	v_add_u32_e32 v186, 0x2000, v186
	ds_read_b128 v[230:233], v158
	ds_read_b128 v[234:237], v158 offset:1024
	ds_read_b128 v[238:241], v158 offset:2048
	ds_read_b128 v[242:245], v158 offset:3072
	global_load_lds_dwordx4 v[248:249], off
	v_lshl_add_u64 v[248:249], s[58:59], 0, v[138:139]
	v_readfirstlane_b32 s7, v186
	v_lshl_add_u64 v[250:251], v[248:249], 0, s[44:45]
	s_mov_b32 m0, s7
	s_nop 0
	global_load_lds_dwordx4 v[250:251], off
	s_barrier
	s_waitcnt lgkmcnt(0)
	s_setprio 1
	s_waitcnt lgkmcnt(0)
	v_mfma_f32_16x16x32_bf16 v[92:95], v[198:201], v[230:233], v[92:95]
	v_mfma_f32_16x16x32_bf16 v[88:91], v[198:201], v[238:241], v[88:91]
	v_mfma_f32_16x16x32_bf16 v[80:83], v[206:209], v[238:241], v[80:83]
	v_mfma_f32_16x16x32_bf16 v[84:87], v[206:209], v[230:233], v[84:87]
	v_mfma_f32_16x16x32_bf16 v[76:79], v[214:217], v[230:233], v[76:79]
	v_mfma_f32_16x16x32_bf16 v[72:75], v[214:217], v[238:241], v[72:75]
	v_mfma_f32_16x16x32_bf16 v[64:67], v[222:225], v[238:241], v[64:67]
	v_mfma_f32_16x16x32_bf16 v[68:71], v[222:225], v[230:233], v[68:71]
	v_mfma_f32_16x16x32_bf16 v[92:95], v[202:205], v[234:237], v[92:95]
	v_mfma_f32_16x16x32_bf16 v[88:91], v[202:205], v[242:245], v[88:91]
	v_mfma_f32_16x16x32_bf16 v[80:83], v[210:213], v[242:245], v[80:83]
	v_mfma_f32_16x16x32_bf16 v[84:87], v[210:213], v[234:237], v[84:87]
	v_mfma_f32_16x16x32_bf16 v[76:79], v[218:221], v[234:237], v[76:79]
	v_mfma_f32_16x16x32_bf16 v[72:75], v[218:221], v[242:245], v[72:75]
	v_mfma_f32_16x16x32_bf16 v[64:67], v[226:229], v[242:245], v[64:67]
	v_mfma_f32_16x16x32_bf16 v[68:71], v[226:229], v[234:237], v[68:71]
	s_setprio 0
	v_readfirstlane_b32 s7, v146
	v_add_u32_e32 v186, 0x2000, v146
	v_lshl_add_u64 v[250:251], v[178:179], 0, s[46:47]
	s_mov_b32 m0, s7
	v_readfirstlane_b32 s7, v186
	s_barrier
	ds_read_b128 v[198:201], v151 offset:16384
	ds_read_b128 v[202:205], v151 offset:17408
	ds_read_b128 v[206:209], v150 offset:16384
	ds_read_b128 v[210:213], v150 offset:17408
	ds_read_b128 v[214:217], v149 offset:16384
	ds_read_b128 v[218:221], v149 offset:17408
	ds_read_b128 v[222:225], v148 offset:16384
	ds_read_b128 v[226:229], v148 offset:17408
	global_load_lds_dwordx4 v[250:251], off
	v_lshl_add_u64 v[250:251], v[188:189], 0, s[46:47]
	s_mov_b32 m0, s7
	s_nop 0
	global_load_lds_dwordx4 v[250:251], off
	s_barrier
	s_waitcnt lgkmcnt(0)
	s_setprio 1
	s_waitcnt lgkmcnt(0)
	v_mfma_f32_16x16x32_bf16 v[60:63], v[198:201], v[162:165], v[60:63]
	v_mfma_f32_16x16x32_bf16 v[56:59], v[198:201], v[170:173], v[56:59]
	v_mfma_f32_16x16x32_bf16 v[48:51], v[206:209], v[170:173], v[48:51]
	v_mfma_f32_16x16x32_bf16 v[52:55], v[206:209], v[162:165], v[52:55]
	v_mfma_f32_16x16x32_bf16 v[44:47], v[214:217], v[162:165], v[44:47]
	v_mfma_f32_16x16x32_bf16 v[40:43], v[214:217], v[170:173], v[40:43]
	v_mfma_f32_16x16x32_bf16 v[32:35], v[222:225], v[170:173], v[32:35]
	v_mfma_f32_16x16x32_bf16 v[36:39], v[222:225], v[162:165], v[36:39]
	v_mfma_f32_16x16x32_bf16 v[60:63], v[202:205], v[166:169], v[60:63]
	v_mfma_f32_16x16x32_bf16 v[56:59], v[202:205], v[174:177], v[56:59]
	v_mfma_f32_16x16x32_bf16 v[48:51], v[210:213], v[174:177], v[48:51]
	v_mfma_f32_16x16x32_bf16 v[52:55], v[210:213], v[166:169], v[52:55]
	v_mfma_f32_16x16x32_bf16 v[44:47], v[218:221], v[166:169], v[44:47]
	v_mfma_f32_16x16x32_bf16 v[40:43], v[218:221], v[174:177], v[40:43]
	v_mfma_f32_16x16x32_bf16 v[32:35], v[226:229], v[174:177], v[32:35]
	v_mfma_f32_16x16x32_bf16 v[36:39], v[226:229], v[166:169], v[36:39]
	s_setprio 0
	s_barrier
; #define WAIT_V(n) asm volatile("s_waitcnt vmcnt(" #n ")" ::: "memory")
; #define WAIT_L(n) asm volatile("s_waitcnt lgkmcnt(" #n ")" ::: "memory")
; #define BAR __builtin_amdgcn_s_barrier()
; #define SCHED __builtin_amdgcn_sched_barrier(0)
; #define LDA(dst, b, h)                                                                            \
;   _Pragma("unroll") for (int m = 0; m < 4; ++m) _Pragma("unroll") for (int k = 0; k < 2; ++k)                                         \
;     dst[m][k] = *reinterpret_cast<const bf16x8*>((char*)SA(b, h) + lds_byte(wr * 64 + m * 16 + fr, k * 32 + fq * 8))
; #define LDB(dst, b, h)                                                                            \
;   _Pragma("unroll") for (int n = 0; n < 2; ++n) _Pragma("unroll") for (int k = 0; k < 2; ++k)                                         \
;     dst[n][k] = *reinterpret_cast<const bf16x8*>((char*)SB(b, h) + lds_byte(wc * 32 + n * 16 + fr, k * 32 + fq * 8))
; template <int K, bool SWAP>
; __device__ __forceinline__ void gemm_kloop(const bf16* __restrict__ A, const bf16* __restrict__ Bt,
;                                            f32x4 (&acc)[2][2][4][2], bool pref = false) {
;     ...
;     STAGE(SB(0, 1), Bt, HALF, t + 2);
;     WAIT_V(6); BAR; MMA(1, 1, At, B1); BAR;
;     LDB(B0, 1, 0); SCHED; LDA(At, 1, 0); STAGE(SA(0, 1), A, HALF, t + 2);
;     WAIT_L(8); BAR; WAIT_L(0); MMA(0, 0, At, B0); BAR; SCHED;
;     LDB(B1, 1, 1); STAGE(SB(1, 0), Bt, 0, t + 3);
;     BAR; WAIT_L(0); MMA(0, 1, At, B1); BAR;
	v_readfirstlane_b32 s7, v147
	v_add_u32_e32 v164, 0x2000, v147
	v_lshl_add_u64 v[162:163], v[246:247], 0, s[48:49]
	s_mov_b32 m0, s7
	v_readfirstlane_b32 s7, v164
	global_load_lds_dwordx4 v[162:163], off
	v_lshl_add_u64 v[162:163], v[248:249], 0, s[48:49]
	s_mov_b32 m0, s7
	s_nop 0
	global_load_lds_dwordx4 v[162:163], off
	s_waitcnt vmcnt(6)
	s_barrier
	s_setprio 1
	v_mfma_f32_16x16x32_bf16 v[28:31], v[198:201], v[230:233], v[28:31]
	v_mfma_f32_16x16x32_bf16 v[24:27], v[198:201], v[238:241], v[24:27]
	v_mfma_f32_16x16x32_bf16 v[16:19], v[206:209], v[238:241], v[16:19]
	v_mfma_f32_16x16x32_bf16 v[20:23], v[206:209], v[230:233], v[20:23]
	v_mfma_f32_16x16x32_bf16 v[12:15], v[214:217], v[230:233], v[12:15]
	v_mfma_f32_16x16x32_bf16 v[8:11], v[214:217], v[238:241], v[8:11]
	v_mfma_f32_16x16x32_bf16 v[0:3], v[222:225], v[238:241], v[0:3]
	v_mfma_f32_16x16x32_bf16 v[4:7], v[222:225], v[230:233], v[4:7]
	v_mfma_f32_16x16x32_bf16 v[28:31], v[202:205], v[234:237], v[28:31]
	v_mfma_f32_16x16x32_bf16 v[24:27], v[202:205], v[242:245], v[24:27]
	v_mfma_f32_16x16x32_bf16 v[16:19], v[210:213], v[242:245], v[16:19]
	v_mfma_f32_16x16x32_bf16 v[20:23], v[210:213], v[234:237], v[20:23]
	v_mfma_f32_16x16x32_bf16 v[12:15], v[218:221], v[234:237], v[12:15]
	v_mfma_f32_16x16x32_bf16 v[8:11], v[218:221], v[242:245], v[8:11]
	v_mfma_f32_16x16x32_bf16 v[0:3], v[226:229], v[242:245], v[0:3]
	v_mfma_f32_16x16x32_bf16 v[4:7], v[226:229], v[234:237], v[4:7]
	s_setprio 0
	s_barrier
	ds_read_b128 v[162:165], v153
	ds_read_b128 v[166:169], v153 offset:1024
	ds_read_b128 v[170:173], v153 offset:2048
	ds_read_b128 v[174:177], v153 offset:3072
	v_add_u32_e32 v186, 0x4000, v146
	v_lshl_add_u64 v[230:231], v[178:179], 0, s[50:51]
	v_readfirstlane_b32 s7, v186
	v_add_u32_e32 v186, 0x6000, v146
	s_mov_b32 m0, s7
	v_readfirstlane_b32 s7, v186
	ds_read_b128 v[198:201], v151 offset:32768
	ds_read_b128 v[202:205], v151 offset:33792
	ds_read_b128 v[206:209], v150 offset:32768
	ds_read_b128 v[210:213], v150 offset:33792
	ds_read_b128 v[214:217], v149 offset:32768
	ds_read_b128 v[218:221], v149 offset:33792
	ds_read_b128 v[222:225], v148 offset:32768
	ds_read_b128 v[226:229], v148 offset:33792
	global_load_lds_dwordx4 v[230:231], off
	v_lshl_add_u64 v[230:231], v[188:189], 0, s[50:51]
	s_mov_b32 m0, s7
	s_nop 0
	global_load_lds_dwordx4 v[230:231], off
	s_waitcnt lgkmcnt(8)
	s_barrier
	s_waitcnt lgkmcnt(0)
	s_setprio 1
	s_waitcnt lgkmcnt(0)
	v_mfma_f32_16x16x32_bf16 v[124:127], v[198:201], v[162:165], v[124:127]
	v_mfma_f32_16x16x32_bf16 v[120:123], v[198:201], v[170:173], v[120:123]
	v_mfma_f32_16x16x32_bf16 v[112:115], v[206:209], v[170:173], v[112:115]
	v_mfma_f32_16x16x32_bf16 v[116:119], v[206:209], v[162:165], v[116:119]
	v_mfma_f32_16x16x32_bf16 v[108:111], v[214:217], v[162:165], v[108:111]
	v_mfma_f32_16x16x32_bf16 v[104:107], v[214:217], v[170:173], v[104:107]
	v_mfma_f32_16x16x32_bf16 v[96:99], v[222:225], v[170:173], v[96:99]
	v_mfma_f32_16x16x32_bf16 v[100:103], v[222:225], v[162:165], v[100:103]
	v_mfma_f32_16x16x32_bf16 v[124:127], v[202:205], v[166:169], v[124:127]
	v_mfma_f32_16x16x32_bf16 v[120:123], v[202:205], v[174:177], v[120:123]
	v_mfma_f32_16x16x32_bf16 v[112:115], v[210:213], v[174:177], v[112:115]
	v_mfma_f32_16x16x32_bf16 v[116:119], v[210:213], v[166:169], v[116:119]
	v_mfma_f32_16x16x32_bf16 v[108:111], v[218:221], v[166:169], v[108:111]
	v_mfma_f32_16x16x32_bf16 v[104:107], v[218:221], v[174:177], v[104:107]
	v_mfma_f32_16x16x32_bf16 v[96:99], v[226:229], v[174:177], v[96:99]
	v_mfma_f32_16x16x32_bf16 v[100:103], v[226:229], v[166:169], v[100:103]
	s_setprio 0
	s_barrier
	v_readfirstlane_b32 s7, v154
	v_add_u32_e32 v186, 0x2000, v154
	v_lshl_add_u64 v[250:251], v[246:247], 0, s[52:53]
	s_mov_b32 m0, s7
	v_readfirstlane_b32 s7, v186
	ds_read_b128 v[230:233], v152
	ds_read_b128 v[234:237], v152 offset:1024
	ds_read_b128 v[238:241], v152 offset:2048
	ds_read_b128 v[242:245], v152 offset:3072
	global_load_lds_dwordx4 v[250:251], off
	v_lshl_add_u64 v[250:251], v[248:249], 0, s[52:53]
	s_mov_b32 m0, s7
	s_nop 0
	global_load_lds_dwordx4 v[250:251], off
	s_barrier
	s_waitcnt lgkmcnt(0)
	s_setprio 1
	s_waitcnt lgkmcnt(0)
	v_mfma_f32_16x16x32_bf16 v[92:95], v[198:201], v[230:233], v[92:95]
	v_mfma_f32_16x16x32_bf16 v[88:91], v[198:201], v[238:241], v[88:91]
	v_mfma_f32_16x16x32_bf16 v[80:83], v[206:209], v[238:241], v[80:83]
	v_mfma_f32_16x16x32_bf16 v[84:87], v[206:209], v[230:233], v[84:87]
	v_mfma_f32_16x16x32_bf16 v[76:79], v[214:217], v[230:233], v[76:79]
	v_mfma_f32_16x16x32_bf16 v[72:75], v[214:217], v[238:241], v[72:75]
	v_mfma_f32_16x16x32_bf16 v[64:67], v[222:225], v[238:241], v[64:67]
	v_mfma_f32_16x16x32_bf16 v[68:71], v[222:225], v[230:233], v[68:71]
	v_mfma_f32_16x16x32_bf16 v[92:95], v[202:205], v[234:237], v[92:95]
	v_mfma_f32_16x16x32_bf16 v[88:91], v[202:205], v[242:245], v[88:91]
	v_mfma_f32_16x16x32_bf16 v[80:83], v[210:213], v[242:245], v[80:83]
	v_mfma_f32_16x16x32_bf16 v[84:87], v[210:213], v[234:237], v[84:87]
	v_mfma_f32_16x16x32_bf16 v[76:79], v[218:221], v[234:237], v[76:79]
	v_mfma_f32_16x16x32_bf16 v[72:75], v[218:221], v[242:245], v[72:75]
	v_mfma_f32_16x16x32_bf16 v[64:67], v[226:229], v[242:245], v[64:67]
	v_mfma_f32_16x16x32_bf16 v[68:71], v[226:229], v[234:237], v[68:71]
	s_setprio 0
	v_readfirstlane_b32 s7, v155
	v_lshl_add_u64 v[178:179], v[178:179], 0, s[54:55]
	s_mov_b32 m0, s7
	v_readfirstlane_b32 s7, v156
	s_barrier
; #define WAIT_V(n) asm volatile("s_waitcnt vmcnt(" #n ")" ::: "memory")
; #define WAIT_L(n) asm volatile("s_waitcnt lgkmcnt(" #n ")" ::: "memory")
; #define BAR __builtin_amdgcn_s_barrier()
; #define SCHED __builtin_amdgcn_sched_barrier(0)
; #define LDA(dst, b, h)                                                                            \
;   _Pragma("unroll") for (int m = 0; m < 4; ++m) _Pragma("unroll") for (int k = 0; k < 2; ++k)                                         \
;     dst[m][k] = *reinterpret_cast<const bf16x8*>((char*)SA(b, h) + lds_byte(wr * 64 + m * 16 + fr, k * 32 + fq * 8))
; #define LDB(dst, b, h)                                                                            \
;   _Pragma("unroll") for (int n = 0; n < 2; ++n) _Pragma("unroll") for (int k = 0; k < 2; ++k)                                         \
;     dst[n][k] = *reinterpret_cast<const bf16x8*>((char*)SB(b, h) + lds_byte(wc * 32 + n * 16 + fr, k * 32 + fq * 8))
; template <int K, bool SWAP>
; __device__ __forceinline__ void gemm_kloop(const bf16* __restrict__ A, const bf16* __restrict__ Bt,
;                                            f32x4 (&acc)[2][2][4][2], bool pref = false) {
;     ...
;     LDA(At, 1, 1); STAGE(SA(1, 0), A, 0, t + 3);
;     BAR; WAIT_L(0); MMA(1, 0, At, B0); BAR; SCHED;
;     STAGE(SB(1, 1), Bt, HALF, t + 3);
;     WAIT_V(6); BAR; MMA(1, 1, At, B1); BAR;
;   }
;   { LDB(B0, 0, 0); LDA(At, 0, 0); STAGE(SA(1, 1), A, HALF, nt - 1);
;     BAR; WAIT_L(0); MMA(0, 0, At, B0); BAR;
	ds_read_b128 v[198:201], v151 offset:49152
	ds_read_b128 v[202:205], v151 offset:50176
	ds_read_b128 v[206:209], v150 offset:49152
	ds_read_b128 v[210:213], v150 offset:50176
	ds_read_b128 v[214:217], v149 offset:49152
	ds_read_b128 v[218:221], v149 offset:50176
	ds_read_b128 v[222:225], v148 offset:49152
	ds_read_b128 v[226:229], v148 offset:50176
	global_load_lds_dwordx4 v[178:179], off
	v_lshl_add_u64 v[178:179], v[188:189], 0, s[54:55]
	s_mov_b32 m0, s7
	s_nop 0
	global_load_lds_dwordx4 v[178:179], off
	s_barrier
	s_waitcnt lgkmcnt(0)
	s_setprio 1
	s_waitcnt lgkmcnt(0)
	v_mfma_f32_16x16x32_bf16 v[60:63], v[198:201], v[162:165], v[60:63]
	v_mfma_f32_16x16x32_bf16 v[56:59], v[198:201], v[170:173], v[56:59]
	v_mfma_f32_16x16x32_bf16 v[48:51], v[206:209], v[170:173], v[48:51]
	v_mfma_f32_16x16x32_bf16 v[52:55], v[206:209], v[162:165], v[52:55]
	v_mfma_f32_16x16x32_bf16 v[44:47], v[214:217], v[162:165], v[44:47]
	v_mfma_f32_16x16x32_bf16 v[40:43], v[214:217], v[170:173], v[40:43]
	v_mfma_f32_16x16x32_bf16 v[32:35], v[222:225], v[170:173], v[32:35]
	v_mfma_f32_16x16x32_bf16 v[36:39], v[222:225], v[162:165], v[36:39]
	v_mfma_f32_16x16x32_bf16 v[60:63], v[202:205], v[166:169], v[60:63]
	v_mfma_f32_16x16x32_bf16 v[56:59], v[202:205], v[174:177], v[56:59]
	v_mfma_f32_16x16x32_bf16 v[48:51], v[210:213], v[174:177], v[48:51]
	v_mfma_f32_16x16x32_bf16 v[52:55], v[210:213], v[166:169], v[52:55]
	v_mfma_f32_16x16x32_bf16 v[44:47], v[218:221], v[166:169], v[44:47]
	v_mfma_f32_16x16x32_bf16 v[40:43], v[218:221], v[174:177], v[40:43]
	v_mfma_f32_16x16x32_bf16 v[32:35], v[226:229], v[174:177], v[32:35]
	v_mfma_f32_16x16x32_bf16 v[36:39], v[226:229], v[166:169], v[36:39]
	s_setprio 0
	s_barrier
	v_readfirstlane_b32 s7, v157
	v_add_u32_e32 v164, 0x2000, v157
	v_lshl_add_u64 v[162:163], v[246:247], 0, s[56:57]
	s_mov_b32 m0, s7
	v_readfirstlane_b32 s7, v164
	global_load_lds_dwordx4 v[162:163], off
	v_lshl_add_u64 v[162:163], v[248:249], 0, s[56:57]
	s_mov_b32 m0, s7
	s_nop 0
	global_load_lds_dwordx4 v[162:163], off
	s_waitcnt vmcnt(6)
	s_barrier
	s_setprio 1
	v_mfma_f32_16x16x32_bf16 v[28:31], v[198:201], v[230:233], v[28:31]
	v_mfma_f32_16x16x32_bf16 v[24:27], v[198:201], v[238:241], v[24:27]
	v_mfma_f32_16x16x32_bf16 v[16:19], v[206:209], v[238:241], v[16:19]
	v_mfma_f32_16x16x32_bf16 v[20:23], v[206:209], v[230:233], v[20:23]
	v_mfma_f32_16x16x32_bf16 v[12:15], v[214:217], v[230:233], v[12:15]
	v_mfma_f32_16x16x32_bf16 v[8:11], v[214:217], v[238:241], v[8:11]
	v_mfma_f32_16x16x32_bf16 v[0:3], v[222:225], v[238:241], v[0:3]
	v_mfma_f32_16x16x32_bf16 v[4:7], v[222:225], v[230:233], v[4:7]
	v_mfma_f32_16x16x32_bf16 v[28:31], v[202:205], v[234:237], v[28:31]
	v_mfma_f32_16x16x32_bf16 v[24:27], v[202:205], v[242:245], v[24:27]
	v_mfma_f32_16x16x32_bf16 v[16:19], v[210:213], v[242:245], v[16:19]
	v_mfma_f32_16x16x32_bf16 v[20:23], v[210:213], v[234:237], v[20:23]
	v_mfma_f32_16x16x32_bf16 v[12:15], v[218:221], v[234:237], v[12:15]
	v_mfma_f32_16x16x32_bf16 v[8:11], v[218:221], v[242:245], v[8:11]
	v_mfma_f32_16x16x32_bf16 v[0:3], v[226:229], v[242:245], v[0:3]
	v_mfma_f32_16x16x32_bf16 v[4:7], v[226:229], v[234:237], v[4:7]
	s_setprio 0
	s_add_i32 s6, s6, 2
	v_lshl_add_u64 v[136:137], v[136:137], 0, s[44:45]
	v_lshl_add_u64 v[138:139], v[138:139], 0, s[44:45]
	v_lshl_add_u64 v[140:141], v[140:141], 0, s[44:45]
	s_cmp_lt_u32 s6, 12
	v_lshl_add_u64 v[142:143], v[142:143], 0, s[44:45]
	s_barrier
	s_cbranch_scc1 .LBB0_449
	s_add_u32 s4, s4, 0x40780
	s_addc_u32 s5, s5, 0
	v_lshl_add_u64 v[130:131], s[4:5], 0, v[130:131]
	v_readfirstlane_b32 s6, v160
	v_lshl_add_u64 v[128:129], v[128:129], 1, v[130:131]
	s_mov_b32 m0, s6
	ds_read_b128 v[136:139], v159
	ds_read_b128 v[140:143], v159 offset:1024
	ds_read_b128 v[154:157], v159 offset:2048
	ds_read_b128 v[162:165], v159 offset:3072
	ds_read_b128 v[166:169], v151
	ds_read_b128 v[170:173], v151 offset:1024
	ds_read_b128 v[174:177], v150
	ds_read_b128 v[198:201], v150 offset:1024
	ds_read_b128 v[202:205], v149
	ds_read_b128 v[206:209], v149 offset:1024
	ds_read_b128 v[210:213], v148
	ds_read_b128 v[214:217], v148 offset:1024
	global_load_lds_dwordx4 v[128:129], off
	v_lshl_add_u64 v[128:129], s[4:5], 0, v[134:135]
	v_readfirstlane_b32 s4, v161
	v_lshl_add_u64 v[128:129], v[132:133], 1, v[128:129]
	s_mov_b32 m0, s4
	s_nop 0
	global_load_lds_dwordx4 v[128:129], off
	s_barrier
	s_waitcnt lgkmcnt(0)
	s_setprio 1
	s_waitcnt lgkmcnt(0)
	v_mfma_f32_16x16x32_bf16 v[124:127], v[166:169], v[136:139], v[124:127]
	v_mfma_f32_16x16x32_bf16 v[116:119], v[174:177], v[136:139], v[116:119]
	v_mfma_f32_16x16x32_bf16 v[108:111], v[202:205], v[136:139], v[108:111]
	v_mfma_f32_16x16x32_bf16 v[100:103], v[210:213], v[136:139], v[100:103]
	v_mfma_f32_16x16x32_bf16 v[124:127], v[170:173], v[140:143], v[124:127]
	v_mfma_f32_16x16x32_bf16 v[120:123], v[166:169], v[154:157], v[120:123]
	v_mfma_f32_16x16x32_bf16 v[116:119], v[198:201], v[140:143], v[116:119]
	v_mfma_f32_16x16x32_bf16 v[112:115], v[174:177], v[154:157], v[112:115]
	v_mfma_f32_16x16x32_bf16 v[108:111], v[206:209], v[140:143], v[108:111]
	v_mfma_f32_16x16x32_bf16 v[104:107], v[202:205], v[154:157], v[104:107]
	v_mfma_f32_16x16x32_bf16 v[100:103], v[214:217], v[140:143], v[100:103]
	v_mfma_f32_16x16x32_bf16 v[96:99], v[210:213], v[154:157], v[96:99]
	v_mfma_f32_16x16x32_bf16 v[128:131], v[170:173], v[162:165], v[120:123]
	v_mfma_f32_16x16x32_bf16 v[132:135], v[198:201], v[162:165], v[112:115]
	v_mfma_f32_16x16x32_bf16 v[218:221], v[206:209], v[162:165], v[104:107]
	v_mfma_f32_16x16x32_bf16 v[222:225], v[214:217], v[162:165], v[96:99]
	s_setprio 0
	s_barrier
; #define WAIT_V(n) asm volatile("s_waitcnt vmcnt(" #n ")" ::: "memory")
; #define WAIT_L(n) asm volatile("s_waitcnt lgkmcnt(" #n ")" ::: "memory")
; #define BAR __builtin_amdgcn_s_barrier()
; #define LDA(dst, b, h)                                                                            \
;   _Pragma("unroll") for (int m = 0; m < 4; ++m) _Pragma("unroll") for (int k = 0; k < 2; ++k)                                         \
;     dst[m][k] = *reinterpret_cast<const bf16x8*>((char*)SA(b, h) + lds_byte(wr * 64 + m * 16 + fr, k * 32 + fq * 8))
; #define LDB(dst, b, h)                                                                            \
;   _Pragma("unroll") for (int n = 0; n < 2; ++n) _Pragma("unroll") for (int k = 0; k < 2; ++k)                                         \
;     dst[n][k] = *reinterpret_cast<const bf16x8*>((char*)SB(b, h) + lds_byte(wc * 32 + n * 16 + fr, k * 32 + fq * 8))
; template <int K, bool SWAP>
; __device__ __forceinline__ void gemm_kloop(const bf16* __restrict__ A, const bf16* __restrict__ Bt,
;                                            f32x4 (&acc)[2][2][4][2], bool pref = false) {
;     ...
;     LDB(B1, 0, 1); BAR; WAIT_L(0); MMA(0, 1, At, B1); BAR;
;     LDA(At, 0, 1); WAIT_V(4); BAR; WAIT_L(0); MMA(1, 0, At, B0); MMA(1, 1, At, B1); BAR; }
;   { LDB(B0, 1, 0); LDA(At, 1, 0); WAIT_V(2); BAR; WAIT_L(0); MMA(0, 0, At, B0); BAR;
	s_nop 1
	ds_read_b128 v[96:99], v158
	ds_read_b128 v[104:107], v158 offset:1024
	ds_read_b128 v[112:115], v158 offset:2048
	ds_read_b128 v[120:123], v158 offset:3072
	s_barrier
	s_waitcnt lgkmcnt(0)
	s_setprio 1
	s_waitcnt lgkmcnt(0)
	v_mfma_f32_16x16x32_bf16 v[92:95], v[166:169], v[96:99], v[92:95]
	v_mfma_f32_16x16x32_bf16 v[84:87], v[174:177], v[96:99], v[84:87]
	v_mfma_f32_16x16x32_bf16 v[76:79], v[202:205], v[96:99], v[76:79]
	v_mfma_f32_16x16x32_bf16 v[68:71], v[210:213], v[96:99], v[68:71]
	v_mfma_f32_16x16x32_bf16 v[92:95], v[170:173], v[104:107], v[92:95]
	v_mfma_f32_16x16x32_bf16 v[88:91], v[166:169], v[112:115], v[88:91]
	v_mfma_f32_16x16x32_bf16 v[84:87], v[198:201], v[104:107], v[84:87]
	v_mfma_f32_16x16x32_bf16 v[80:83], v[174:177], v[112:115], v[80:83]
	v_mfma_f32_16x16x32_bf16 v[76:79], v[206:209], v[104:107], v[76:79]
	v_mfma_f32_16x16x32_bf16 v[72:75], v[202:205], v[112:115], v[72:75]
	v_mfma_f32_16x16x32_bf16 v[68:71], v[214:217], v[104:107], v[68:71]
	v_mfma_f32_16x16x32_bf16 v[64:67], v[210:213], v[112:115], v[64:67]
	v_mfma_f32_16x16x32_bf16 v[158:161], v[170:173], v[120:123], v[88:91]
	v_mfma_f32_16x16x32_bf16 v[166:169], v[198:201], v[120:123], v[80:83]
	v_mfma_f32_16x16x32_bf16 v[170:173], v[206:209], v[120:123], v[72:75]
	v_mfma_f32_16x16x32_bf16 v[174:177], v[214:217], v[120:123], v[64:67]
	s_setprio 0
	s_barrier
	s_nop 1
	ds_read_b128 v[64:67], v151 offset:16384
	ds_read_b128 v[72:75], v151 offset:17408
	ds_read_b128 v[80:83], v150 offset:16384
	ds_read_b128 v[88:91], v150 offset:17408
	ds_read_b128 v[198:201], v149 offset:16384
	ds_read_b128 v[202:205], v149 offset:17408
	ds_read_b128 v[206:209], v148 offset:16384
	ds_read_b128 v[210:213], v148 offset:17408
	s_waitcnt vmcnt(4)
	s_barrier
	s_waitcnt lgkmcnt(0)
	s_setprio 1
	s_waitcnt lgkmcnt(0)
	v_mfma_f32_16x16x32_bf16 v[60:63], v[64:67], v[136:139], v[60:63]
	v_mfma_f32_16x16x32_bf16 v[52:55], v[80:83], v[136:139], v[52:55]
	v_mfma_f32_16x16x32_bf16 v[44:47], v[198:201], v[136:139], v[44:47]
	v_mfma_f32_16x16x32_bf16 v[36:39], v[206:209], v[136:139], v[36:39]
	v_mfma_f32_16x16x32_bf16 v[60:63], v[72:75], v[140:143], v[60:63]
	v_mfma_f32_16x16x32_bf16 v[56:59], v[64:67], v[154:157], v[56:59]
	v_mfma_f32_16x16x32_bf16 v[52:55], v[88:91], v[140:143], v[52:55]
	v_mfma_f32_16x16x32_bf16 v[48:51], v[80:83], v[154:157], v[48:51]
	v_mfma_f32_16x16x32_bf16 v[44:47], v[202:205], v[140:143], v[44:47]
	v_mfma_f32_16x16x32_bf16 v[40:43], v[198:201], v[154:157], v[40:43]
	v_mfma_f32_16x16x32_bf16 v[36:39], v[210:213], v[140:143], v[36:39]
	v_mfma_f32_16x16x32_bf16 v[32:35], v[206:209], v[154:157], v[32:35]
	v_mfma_f32_16x16x32_bf16 v[214:217], v[72:75], v[162:165], v[56:59]
	v_mfma_f32_16x16x32_bf16 v[226:229], v[88:91], v[162:165], v[48:51]
	v_mfma_f32_16x16x32_bf16 v[230:233], v[202:205], v[162:165], v[40:43]
	v_mfma_f32_16x16x32_bf16 v[136:139], v[210:213], v[162:165], v[32:35]
	s_setprio 0
	s_setprio 1
	v_mfma_f32_16x16x32_bf16 v[28:31], v[64:67], v[96:99], v[28:31]
	v_mfma_f32_16x16x32_bf16 v[20:23], v[80:83], v[96:99], v[20:23]
	v_mfma_f32_16x16x32_bf16 v[12:15], v[198:201], v[96:99], v[12:15]
	v_mfma_f32_16x16x32_bf16 v[4:7], v[206:209], v[96:99], v[4:7]
	v_mfma_f32_16x16x32_bf16 v[28:31], v[72:75], v[104:107], v[28:31]
	v_mfma_f32_16x16x32_bf16 v[24:27], v[64:67], v[112:115], v[24:27]
	v_mfma_f32_16x16x32_bf16 v[20:23], v[88:91], v[104:107], v[20:23]
	v_mfma_f32_16x16x32_bf16 v[16:19], v[80:83], v[112:115], v[16:19]
	v_mfma_f32_16x16x32_bf16 v[12:15], v[202:205], v[104:107], v[12:15]
	v_mfma_f32_16x16x32_bf16 v[8:11], v[198:201], v[112:115], v[8:11]
	v_mfma_f32_16x16x32_bf16 v[4:7], v[210:213], v[104:107], v[4:7]
	v_mfma_f32_16x16x32_bf16 v[0:3], v[206:209], v[112:115], v[0:3]
	v_mfma_f32_16x16x32_bf16 v[140:143], v[72:75], v[120:123], v[24:27]
	v_mfma_f32_16x16x32_bf16 v[154:157], v[88:91], v[120:123], v[16:19]
	v_mfma_f32_16x16x32_bf16 v[162:165], v[202:205], v[120:123], v[8:11]
	v_mfma_f32_16x16x32_bf16 v[198:201], v[210:213], v[120:123], v[0:3]
	s_setprio 0
	s_barrier
	ds_read_b128 v[202:205], v153
	ds_read_b128 v[206:209], v153 offset:1024
	ds_read_b128 v[210:213], v153 offset:2048
	ds_read_b128 v[234:237], v153 offset:3072
	ds_read_b128 v[0:3], v151 offset:32768
	ds_read_b128 v[8:11], v151 offset:33792
	ds_read_b128 v[16:19], v150 offset:32768
	ds_read_b128 v[24:27], v150 offset:33792
	ds_read_b128 v[238:241], v149 offset:32768
	ds_read_b128 v[242:245], v149 offset:33792
	ds_read_b128 v[246:249], v148 offset:32768
	ds_read_b128 v[250:253], v148 offset:33792
	s_waitcnt vmcnt(2)
	s_barrier
; #define WAIT_V(n) asm volatile("s_waitcnt vmcnt(" #n ")" ::: "memory")
; #define WAIT_L(n) asm volatile("s_waitcnt lgkmcnt(" #n ")" ::: "memory")
; #define BAR __builtin_amdgcn_s_barrier()
; #define LDA(dst, b, h)                                                                            \
;   _Pragma("unroll") for (int m = 0; m < 4; ++m) _Pragma("unroll") for (int k = 0; k < 2; ++k)                                         \
;     dst[m][k] = *reinterpret_cast<const bf16x8*>((char*)SA(b, h) + lds_byte(wr * 64 + m * 16 + fr, k * 32 + fq * 8))
; #define LDB(dst, b, h)                                                                            \
;   _Pragma("unroll") for (int n = 0; n < 2; ++n) _Pragma("unroll") for (int k = 0; k < 2; ++k)                                         \
;     dst[n][k] = *reinterpret_cast<const bf16x8*>((char*)SB(b, h) + lds_byte(wc * 32 + n * 16 + fr, k * 32 + fq * 8))
; template <int K, bool SWAP>
; __device__ __forceinline__ void gemm_kloop(const bf16* __restrict__ A, const bf16* __restrict__ Bt,
;                                            f32x4 (&acc)[2][2][4][2], bool pref = false) {
;     ...
;   { LDB(B0, 1, 0); LDA(At, 1, 0); WAIT_V(2); BAR; WAIT_L(0); MMA(0, 0, At, B0); BAR;
;     LDB(B1, 1, 1); WAIT_V(0); BAR; WAIT_L(0); MMA(0, 1, At, B1); BAR;
;     LDA(At, 1, 1); BAR; WAIT_L(0); MMA(1, 0, At, B0); MMA(1, 1, At, B1); BAR; }
;   if (wr == 0) BAR;
	s_waitcnt lgkmcnt(0)
	s_setprio 1
	s_waitcnt lgkmcnt(0)
	v_mfma_f32_16x16x32_bf16 v[32:35], v[0:3], v[202:205], v[124:127]
	v_mfma_f32_16x16x32_bf16 v[120:123], v[8:11], v[206:209], v[32:35]
	v_mfma_f32_16x16x32_bf16 v[32:35], v[0:3], v[210:213], v[128:131]
	v_mfma_f32_16x16x32_bf16 v[112:115], v[8:11], v[234:237], v[32:35]
	v_mfma_f32_16x16x32_bf16 v[32:35], v[16:19], v[202:205], v[116:119]
	v_mfma_f32_16x16x32_bf16 v[104:107], v[24:27], v[206:209], v[32:35]
	v_mfma_f32_16x16x32_bf16 v[32:35], v[16:19], v[210:213], v[132:135]
	v_mfma_f32_16x16x32_bf16 v[96:99], v[24:27], v[234:237], v[32:35]
	v_mfma_f32_16x16x32_bf16 v[32:35], v[238:241], v[202:205], v[108:111]
	v_mfma_f32_16x16x32_bf16 v[88:91], v[242:245], v[206:209], v[32:35]
	v_mfma_f32_16x16x32_bf16 v[32:35], v[238:241], v[210:213], v[218:221]
	v_mfma_f32_16x16x32_bf16 v[80:83], v[242:245], v[234:237], v[32:35]
	v_mfma_f32_16x16x32_bf16 v[32:35], v[246:249], v[202:205], v[100:103]
	v_mfma_f32_16x16x32_bf16 v[72:75], v[250:253], v[206:209], v[32:35]
	v_mfma_f32_16x16x32_bf16 v[32:35], v[246:249], v[210:213], v[222:225]
	v_mfma_f32_16x16x32_bf16 v[64:67], v[250:253], v[234:237], v[32:35]
	s_setprio 0
	s_barrier
	ds_read_b128 v[128:131], v152
	ds_read_b128 v[132:135], v152 offset:1024
	ds_read_b128 v[218:221], v152 offset:2048
	ds_read_b128 v[222:225], v152 offset:3072
	s_waitcnt vmcnt(0)
	s_barrier
	s_waitcnt lgkmcnt(0)
	s_setprio 1
	s_waitcnt lgkmcnt(0)
	v_mfma_f32_16x16x32_bf16 v[32:35], v[0:3], v[128:131], v[92:95]
	v_mfma_f32_16x16x32_bf16 v[0:3], v[0:3], v[218:221], v[158:161]
	v_mfma_f32_16x16x32_bf16 v[48:51], v[8:11], v[222:225], v[0:3]
	v_mfma_f32_16x16x32_bf16 v[0:3], v[16:19], v[128:131], v[84:87]
	v_mfma_f32_16x16x32_bf16 v[40:43], v[24:27], v[132:135], v[0:3]
	v_mfma_f32_16x16x32_bf16 v[0:3], v[16:19], v[218:221], v[166:169]
	v_mfma_f32_16x16x32_bf16 v[56:59], v[8:11], v[132:135], v[32:35]
	v_mfma_f32_16x16x32_bf16 v[32:35], v[24:27], v[222:225], v[0:3]
	v_mfma_f32_16x16x32_bf16 v[0:3], v[238:241], v[128:131], v[76:79]
	v_mfma_f32_16x16x32_bf16 v[24:27], v[242:245], v[132:135], v[0:3]
	v_mfma_f32_16x16x32_bf16 v[0:3], v[238:241], v[218:221], v[170:173]
	v_mfma_f32_16x16x32_bf16 v[16:19], v[242:245], v[222:225], v[0:3]
	v_mfma_f32_16x16x32_bf16 v[0:3], v[246:249], v[128:131], v[68:71]
	v_mfma_f32_16x16x32_bf16 v[8:11], v[250:253], v[132:135], v[0:3]
	v_mfma_f32_16x16x32_bf16 v[0:3], v[246:249], v[218:221], v[174:177]
	v_mfma_f32_16x16x32_bf16 v[0:3], v[250:253], v[222:225], v[0:3]
	s_setprio 0
	s_barrier
	ds_read_b128 v[158:161], v151 offset:49152
	ds_read_b128 v[166:169], v151 offset:50176
	ds_read_b128 v[170:173], v150 offset:49152
	ds_read_b128 v[150:153], v150 offset:50176
	ds_read_b128 v[174:177], v149 offset:49152
	ds_read_b128 v[238:241], v149 offset:50176
	ds_read_b128 v[242:245], v148 offset:49152
	ds_read_b128 v[146:149], v148 offset:50176
	s_barrier
	s_waitcnt lgkmcnt(0)
	s_setprio 1
	s_waitcnt lgkmcnt(0)
	v_mfma_f32_16x16x32_bf16 v[60:63], v[158:161], v[202:205], v[60:63]
	v_mfma_f32_16x16x32_bf16 v[52:55], v[170:173], v[202:205], v[52:55]
	v_mfma_f32_16x16x32_bf16 v[44:47], v[174:177], v[202:205], v[44:47]
	v_mfma_f32_16x16x32_bf16 v[36:39], v[242:245], v[202:205], v[36:39]
	v_mfma_f32_16x16x32_bf16 v[124:127], v[166:169], v[206:209], v[60:63]
	v_mfma_f32_16x16x32_bf16 v[60:63], v[158:161], v[210:213], v[214:217]
	v_mfma_f32_16x16x32_bf16 v[108:111], v[150:153], v[206:209], v[52:55]
	v_mfma_f32_16x16x32_bf16 v[52:55], v[170:173], v[210:213], v[226:229]
	v_mfma_f32_16x16x32_bf16 v[92:95], v[238:241], v[206:209], v[44:47]
	v_mfma_f32_16x16x32_bf16 v[44:47], v[174:177], v[210:213], v[230:233]
	v_mfma_f32_16x16x32_bf16 v[76:79], v[146:149], v[206:209], v[36:39]
	v_mfma_f32_16x16x32_bf16 v[36:39], v[242:245], v[210:213], v[136:139]
	v_mfma_f32_16x16x32_bf16 v[116:119], v[166:169], v[234:237], v[60:63]
	v_mfma_f32_16x16x32_bf16 v[100:103], v[150:153], v[234:237], v[52:55]
	v_mfma_f32_16x16x32_bf16 v[84:87], v[238:241], v[234:237], v[44:47]
	v_mfma_f32_16x16x32_bf16 v[68:71], v[146:149], v[234:237], v[36:39]
	s_setprio 0
	s_setprio 1
	v_mfma_f32_16x16x32_bf16 v[28:31], v[158:161], v[128:131], v[28:31]
	v_mfma_f32_16x16x32_bf16 v[60:63], v[166:169], v[132:135], v[28:31]
	v_mfma_f32_16x16x32_bf16 v[28:31], v[158:161], v[218:221], v[140:143]
	v_mfma_f32_16x16x32_bf16 v[20:23], v[170:173], v[128:131], v[20:23]
	v_mfma_f32_16x16x32_bf16 v[12:15], v[174:177], v[128:131], v[12:15]
	v_mfma_f32_16x16x32_bf16 v[52:55], v[166:169], v[222:225], v[28:31]
	v_mfma_f32_16x16x32_bf16 v[44:47], v[150:153], v[132:135], v[20:23]
	v_mfma_f32_16x16x32_bf16 v[20:23], v[170:173], v[218:221], v[154:157]
	v_mfma_f32_16x16x32_bf16 v[28:31], v[238:241], v[132:135], v[12:15]
	v_mfma_f32_16x16x32_bf16 v[12:15], v[174:177], v[218:221], v[162:165]
	v_mfma_f32_16x16x32_bf16 v[4:7], v[242:245], v[128:131], v[4:7]
	v_mfma_f32_16x16x32_bf16 v[36:39], v[150:153], v[222:225], v[20:23]
	v_mfma_f32_16x16x32_bf16 v[20:23], v[238:241], v[222:225], v[12:15]
	v_mfma_f32_16x16x32_bf16 v[12:15], v[146:149], v[132:135], v[4:7]
	v_mfma_f32_16x16x32_bf16 v[4:7], v[242:245], v[218:221], v[198:201]
	v_mfma_f32_16x16x32_bf16 v[4:7], v[146:149], v[222:225], v[4:7]
	s_setprio 0
	s_movk_i32 s4, 0x100
	v_cmp_gt_u32_e32 vcc, s4, v144
	s_barrier
	s_and_saveexec_b64 s[4:5], vcc
	s_cbranch_execz .LBB0_452
	s_barrier

; #define WAIT_L(n) asm volatile("s_waitcnt lgkmcnt(" #n ")" ::: "memory")
; #define BAR __builtin_amdgcn_s_barrier()
; #define SCHED __builtin_amdgcn_sched_barrier(0)
; #define LDA(dst, b, h)                                                                            \
;   _Pragma("unroll") for (int m = 0; m < 4; ++m) _Pragma("unroll") for (int k = 0; k < 2; ++k)                                         \
;     dst[m][k] = *reinterpret_cast<const bf16x8*>((char*)SA(b, h) + lds_byte(wr * 64 + m * 16 + fr, k * 32 + fq * 8))
; #define LDB(dst, b, h)                                                                            \
;   _Pragma("unroll") for (int n = 0; n < 2; ++n) _Pragma("unroll") for (int k = 0; k < 2; ++k)                                         \
;     dst[n][k] = *reinterpret_cast<const bf16x8*>((char*)SB(b, h) + lds_byte(wc * 32 + n * 16 + fr, k * 32 + fq * 8))
; template <int K, bool SWAP>
; __device__ __forceinline__ void gemm_kloop(const bf16* __restrict__ A, const bf16* __restrict__ Bt,
;                                            f32x4 (&acc)[2][2][4][2], bool pref = false) {
;     ...
;     LDB(B0, 0, 0); SCHED; LDA(At, 0, 0); STAGE(SA(1, 1), A, HALF, t + 1);
;     WAIT_L(8); BAR; WAIT_L(0); MMA(0, 0, At, B0); BAR; SCHED;
;     LDB(B1, 0, 1); STAGE(SB(0, 0), Bt, 0, t + 2);
;     BAR; WAIT_L(0); MMA(0, 1, At, B1); BAR;
;     LDA(At, 0, 1); STAGE(SA(0, 0), A, 0, t + 2);
;     BAR; WAIT_L(0); MMA(1, 0, At, B0); BAR; SCHED;
.LBB0_514:
	ds_read_b128 v[162:165], v159
	ds_read_b128 v[166:169], v159 offset:1024
	ds_read_b128 v[170:173], v159 offset:2048
	ds_read_b128 v[174:177], v159 offset:3072
	v_add_u32_e32 v160, 0xc000, v146
	v_lshl_add_u64 v[178:179], s[58:59], 0, v[140:141]
	v_readfirstlane_b32 s9, v160
	v_lshl_add_u64 v[188:189], v[178:179], 0, s[42:43]
	s_mov_b32 m0, s9
	v_add_u32_e32 v161, 0xe000, v146
	ds_read_b128 v[198:201], v151
	ds_read_b128 v[202:205], v151 offset:1024
	ds_read_b128 v[206:209], v150
	ds_read_b128 v[210:213], v150 offset:1024
	ds_read_b128 v[214:217], v149
	ds_read_b128 v[218:221], v149 offset:1024
	ds_read_b128 v[222:225], v148
	ds_read_b128 v[226:229], v148 offset:1024
	global_load_lds_dwordx4 v[188:189], off
	v_lshl_add_u64 v[188:189], s[58:59], 0, v[142:143]
	v_readfirstlane_b32 s9, v161
	v_lshl_add_u64 v[230:231], v[188:189], 0, s[42:43]
	s_mov_b32 m0, s9
	s_nop 0
	global_load_lds_dwordx4 v[230:231], off
	s_waitcnt lgkmcnt(8)
	s_barrier
	s_waitcnt lgkmcnt(0)
	s_setprio 1
	s_waitcnt lgkmcnt(0)
	v_mfma_f32_16x16x32_bf16 v[124:127], v[162:165], v[198:201], v[124:127]
	v_mfma_f32_16x16x32_bf16 v[120:123], v[170:173], v[198:201], v[120:123]
	v_mfma_f32_16x16x32_bf16 v[112:115], v[170:173], v[206:209], v[112:115]
	v_mfma_f32_16x16x32_bf16 v[116:119], v[162:165], v[206:209], v[116:119]
	v_mfma_f32_16x16x32_bf16 v[108:111], v[162:165], v[214:217], v[108:111]
	v_mfma_f32_16x16x32_bf16 v[104:107], v[170:173], v[214:217], v[104:107]
	v_mfma_f32_16x16x32_bf16 v[96:99], v[170:173], v[222:225], v[96:99]
	v_mfma_f32_16x16x32_bf16 v[100:103], v[162:165], v[222:225], v[100:103]
	v_mfma_f32_16x16x32_bf16 v[124:127], v[166:169], v[202:205], v[124:127]
	v_mfma_f32_16x16x32_bf16 v[120:123], v[174:177], v[202:205], v[120:123]
	v_mfma_f32_16x16x32_bf16 v[112:115], v[174:177], v[210:213], v[112:115]
	v_mfma_f32_16x16x32_bf16 v[116:119], v[166:169], v[210:213], v[116:119]
	v_mfma_f32_16x16x32_bf16 v[108:111], v[166:169], v[218:221], v[108:111]
	v_mfma_f32_16x16x32_bf16 v[104:107], v[174:177], v[218:221], v[104:107]
	v_mfma_f32_16x16x32_bf16 v[96:99], v[174:177], v[226:229], v[96:99]
	v_mfma_f32_16x16x32_bf16 v[100:103], v[166:169], v[226:229], v[100:103]
	s_setprio 0
	s_barrier
	v_add_u32_e32 v186, s7, v145
	v_lshl_add_u64 v[246:247], s[58:59], 0, v[136:137]
	v_readfirstlane_b32 s9, v186
	v_lshl_add_u64 v[248:249], v[246:247], 0, s[44:45]
	s_mov_b32 m0, s9
	v_add_u32_e32 v186, 0x2000, v186
	ds_read_b128 v[230:233], v158
	ds_read_b128 v[234:237], v158 offset:1024
	ds_read_b128 v[238:241], v158 offset:2048
	ds_read_b128 v[242:245], v158 offset:3072
	global_load_lds_dwordx4 v[248:249], off
	v_lshl_add_u64 v[248:249], s[58:59], 0, v[138:139]
	v_readfirstlane_b32 s9, v186
	v_lshl_add_u64 v[250:251], v[248:249], 0, s[44:45]
	s_mov_b32 m0, s9
	s_nop 0
	global_load_lds_dwordx4 v[250:251], off
	s_barrier
	s_waitcnt lgkmcnt(0)
	s_setprio 1
	s_waitcnt lgkmcnt(0)
	v_mfma_f32_16x16x32_bf16 v[92:95], v[230:233], v[198:201], v[92:95]
	v_mfma_f32_16x16x32_bf16 v[88:91], v[238:241], v[198:201], v[88:91]
	v_mfma_f32_16x16x32_bf16 v[72:75], v[238:241], v[206:209], v[72:75]
	v_mfma_f32_16x16x32_bf16 v[84:87], v[230:233], v[206:209], v[84:87]
	v_mfma_f32_16x16x32_bf16 v[60:63], v[230:233], v[214:217], v[60:63]
	v_mfma_f32_16x16x32_bf16 v[56:59], v[238:241], v[214:217], v[56:59]
	v_mfma_f32_16x16x32_bf16 v[48:51], v[238:241], v[222:225], v[48:51]
	v_mfma_f32_16x16x32_bf16 v[52:55], v[230:233], v[222:225], v[52:55]
	v_mfma_f32_16x16x32_bf16 v[92:95], v[234:237], v[202:205], v[92:95]
	v_mfma_f32_16x16x32_bf16 v[88:91], v[242:245], v[202:205], v[88:91]
	v_mfma_f32_16x16x32_bf16 v[72:75], v[242:245], v[210:213], v[72:75]
	v_mfma_f32_16x16x32_bf16 v[84:87], v[234:237], v[210:213], v[84:87]
	v_mfma_f32_16x16x32_bf16 v[60:63], v[234:237], v[218:221], v[60:63]
	v_mfma_f32_16x16x32_bf16 v[56:59], v[242:245], v[218:221], v[56:59]
	v_mfma_f32_16x16x32_bf16 v[48:51], v[242:245], v[226:229], v[48:51]
	v_mfma_f32_16x16x32_bf16 v[52:55], v[234:237], v[226:229], v[52:55]
	s_setprio 0
	v_readfirstlane_b32 s9, v146
	v_add_u32_e32 v186, 0x2000, v146
	v_lshl_add_u64 v[250:251], v[178:179], 0, s[46:47]
	s_mov_b32 m0, s9
	v_readfirstlane_b32 s9, v186
	s_barrier
	ds_read_b128 v[198:201], v151 offset:16384
	ds_read_b128 v[202:205], v151 offset:17408
	ds_read_b128 v[206:209], v150 offset:16384
	ds_read_b128 v[210:213], v150 offset:17408
	ds_read_b128 v[214:217], v149 offset:16384
	ds_read_b128 v[218:221], v149 offset:17408
	ds_read_b128 v[222:225], v148 offset:16384
	ds_read_b128 v[226:229], v148 offset:17408
	global_load_lds_dwordx4 v[250:251], off
	v_lshl_add_u64 v[250:251], v[188:189], 0, s[46:47]
	s_mov_b32 m0, s9
	s_nop 0
	global_load_lds_dwordx4 v[250:251], off
	s_barrier
	s_waitcnt lgkmcnt(0)
	s_setprio 1
	s_waitcnt lgkmcnt(0)
	v_mfma_f32_16x16x32_bf16 v[44:47], v[162:165], v[198:201], v[44:47]
	v_mfma_f32_16x16x32_bf16 v[40:43], v[170:173], v[198:201], v[40:43]
	v_mfma_f32_16x16x32_bf16 v[32:35], v[170:173], v[206:209], v[32:35]
	v_mfma_f32_16x16x32_bf16 v[36:39], v[162:165], v[206:209], v[36:39]
	v_mfma_f32_16x16x32_bf16 v[28:31], v[162:165], v[214:217], v[28:31]
	v_mfma_f32_16x16x32_bf16 v[24:27], v[170:173], v[214:217], v[24:27]
	v_mfma_f32_16x16x32_bf16 v[16:19], v[170:173], v[222:225], v[16:19]
	v_mfma_f32_16x16x32_bf16 v[20:23], v[162:165], v[222:225], v[20:23]
	v_mfma_f32_16x16x32_bf16 v[44:47], v[166:169], v[202:205], v[44:47]
	v_mfma_f32_16x16x32_bf16 v[40:43], v[174:177], v[202:205], v[40:43]
	v_mfma_f32_16x16x32_bf16 v[32:35], v[174:177], v[210:213], v[32:35]
	v_mfma_f32_16x16x32_bf16 v[36:39], v[166:169], v[210:213], v[36:39]
	v_mfma_f32_16x16x32_bf16 v[28:31], v[166:169], v[218:221], v[28:31]
	v_mfma_f32_16x16x32_bf16 v[24:27], v[174:177], v[218:221], v[24:27]
	v_mfma_f32_16x16x32_bf16 v[16:19], v[174:177], v[226:229], v[16:19]
	v_mfma_f32_16x16x32_bf16 v[20:23], v[166:169], v[226:229], v[20:23]
	s_setprio 0
	s_barrier
; #define WAIT_V(n) asm volatile("s_waitcnt vmcnt(" #n ")" ::: "memory")
; #define WAIT_L(n) asm volatile("s_waitcnt lgkmcnt(" #n ")" ::: "memory")
; #define BAR __builtin_amdgcn_s_barrier()
; #define SCHED __builtin_amdgcn_sched_barrier(0)
; #define LDA(dst, b, h)                                                                            \
;   _Pragma("unroll") for (int m = 0; m < 4; ++m) _Pragma("unroll") for (int k = 0; k < 2; ++k)                                         \
;     dst[m][k] = *reinterpret_cast<const bf16x8*>((char*)SA(b, h) + lds_byte(wr * 64 + m * 16 + fr, k * 32 + fq * 8))
; #define LDB(dst, b, h)                                                                            \
;   _Pragma("unroll") for (int n = 0; n < 2; ++n) _Pragma("unroll") for (int k = 0; k < 2; ++k)                                         \
;     dst[n][k] = *reinterpret_cast<const bf16x8*>((char*)SB(b, h) + lds_byte(wc * 32 + n * 16 + fr, k * 32 + fq * 8))
; template <int K, bool SWAP>
; __device__ __forceinline__ void gemm_kloop(const bf16* __restrict__ A, const bf16* __restrict__ Bt,
;                                            f32x4 (&acc)[2][2][4][2], bool pref = false) {
;     ...
;     STAGE(SB(0, 1), Bt, HALF, t + 2);
;     WAIT_V(6); BAR; MMA(1, 1, At, B1); BAR;
;     LDB(B0, 1, 0); SCHED; LDA(At, 1, 0); STAGE(SA(0, 1), A, HALF, t + 2);
;     WAIT_L(8); BAR; WAIT_L(0); MMA(0, 0, At, B0); BAR; SCHED;
;     LDB(B1, 1, 1); STAGE(SB(1, 0), Bt, 0, t + 3);
;     BAR; WAIT_L(0); MMA(0, 1, At, B1); BAR;
	v_readfirstlane_b32 s9, v147
	v_add_u32_e32 v164, 0x2000, v147
	v_lshl_add_u64 v[162:163], v[246:247], 0, s[48:49]
	s_mov_b32 m0, s9
	v_readfirstlane_b32 s9, v164
	global_load_lds_dwordx4 v[162:163], off
	v_lshl_add_u64 v[162:163], v[248:249], 0, s[48:49]
	s_mov_b32 m0, s9
	s_nop 0
	global_load_lds_dwordx4 v[162:163], off
	s_waitcnt vmcnt(6)
	s_barrier
	s_setprio 1
	v_mfma_f32_16x16x32_bf16 v[12:15], v[230:233], v[198:201], v[12:15]
	v_mfma_f32_16x16x32_bf16 v[8:11], v[238:241], v[198:201], v[8:11]
	v_mfma_f32_16x16x32_bf16 v[0:3], v[238:241], v[206:209], v[0:3]
	v_mfma_f32_16x16x32_bf16 v[4:7], v[230:233], v[206:209], v[4:7]
	v_mfma_f32_16x16x32_bf16 v[64:67], v[230:233], v[214:217], v[64:67]
	v_mfma_f32_16x16x32_bf16 v[68:71], v[238:241], v[214:217], v[68:71]
	v_mfma_f32_16x16x32_bf16 v[80:83], v[238:241], v[222:225], v[80:83]
	v_mfma_f32_16x16x32_bf16 v[76:79], v[230:233], v[222:225], v[76:79]
	v_mfma_f32_16x16x32_bf16 v[12:15], v[234:237], v[202:205], v[12:15]
	v_mfma_f32_16x16x32_bf16 v[8:11], v[242:245], v[202:205], v[8:11]
	v_mfma_f32_16x16x32_bf16 v[0:3], v[242:245], v[210:213], v[0:3]
	v_mfma_f32_16x16x32_bf16 v[4:7], v[234:237], v[210:213], v[4:7]
	v_mfma_f32_16x16x32_bf16 v[64:67], v[234:237], v[218:221], v[64:67]
	v_mfma_f32_16x16x32_bf16 v[68:71], v[242:245], v[218:221], v[68:71]
	v_mfma_f32_16x16x32_bf16 v[80:83], v[242:245], v[226:229], v[80:83]
	v_mfma_f32_16x16x32_bf16 v[76:79], v[234:237], v[226:229], v[76:79]
	s_setprio 0
	s_barrier
	ds_read_b128 v[162:165], v153
	ds_read_b128 v[166:169], v153 offset:1024
	ds_read_b128 v[170:173], v153 offset:2048
	ds_read_b128 v[174:177], v153 offset:3072
	v_add_u32_e32 v186, 0x4000, v146
	v_lshl_add_u64 v[230:231], v[178:179], 0, s[50:51]
	v_readfirstlane_b32 s9, v186
	v_add_u32_e32 v186, 0x6000, v146
	s_mov_b32 m0, s9
	v_readfirstlane_b32 s9, v186
	ds_read_b128 v[198:201], v151 offset:32768
	ds_read_b128 v[202:205], v151 offset:33792
	ds_read_b128 v[206:209], v150 offset:32768
	ds_read_b128 v[210:213], v150 offset:33792
	ds_read_b128 v[214:217], v149 offset:32768
	ds_read_b128 v[218:221], v149 offset:33792
	ds_read_b128 v[222:225], v148 offset:32768
	ds_read_b128 v[226:229], v148 offset:33792
	global_load_lds_dwordx4 v[230:231], off
	v_lshl_add_u64 v[230:231], v[188:189], 0, s[50:51]
	s_mov_b32 m0, s9
	s_nop 0
	global_load_lds_dwordx4 v[230:231], off
	s_waitcnt lgkmcnt(8)
	s_barrier
	s_waitcnt lgkmcnt(0)
	s_setprio 1
	s_waitcnt lgkmcnt(0)
	v_mfma_f32_16x16x32_bf16 v[124:127], v[162:165], v[198:201], v[124:127]
	v_mfma_f32_16x16x32_bf16 v[120:123], v[170:173], v[198:201], v[120:123]
	v_mfma_f32_16x16x32_bf16 v[112:115], v[170:173], v[206:209], v[112:115]
	v_mfma_f32_16x16x32_bf16 v[116:119], v[162:165], v[206:209], v[116:119]
	v_mfma_f32_16x16x32_bf16 v[108:111], v[162:165], v[214:217], v[108:111]
	v_mfma_f32_16x16x32_bf16 v[104:107], v[170:173], v[214:217], v[104:107]
	v_mfma_f32_16x16x32_bf16 v[96:99], v[170:173], v[222:225], v[96:99]
	v_mfma_f32_16x16x32_bf16 v[100:103], v[162:165], v[222:225], v[100:103]
	v_mfma_f32_16x16x32_bf16 v[124:127], v[166:169], v[202:205], v[124:127]
	v_mfma_f32_16x16x32_bf16 v[120:123], v[174:177], v[202:205], v[120:123]
	v_mfma_f32_16x16x32_bf16 v[112:115], v[174:177], v[210:213], v[112:115]
	v_mfma_f32_16x16x32_bf16 v[116:119], v[166:169], v[210:213], v[116:119]
	v_mfma_f32_16x16x32_bf16 v[108:111], v[166:169], v[218:221], v[108:111]
	v_mfma_f32_16x16x32_bf16 v[104:107], v[174:177], v[218:221], v[104:107]
	v_mfma_f32_16x16x32_bf16 v[96:99], v[174:177], v[226:229], v[96:99]
	v_mfma_f32_16x16x32_bf16 v[100:103], v[166:169], v[226:229], v[100:103]
	s_setprio 0
	s_barrier
	v_readfirstlane_b32 s9, v154
	v_add_u32_e32 v186, 0x2000, v154
	v_lshl_add_u64 v[250:251], v[246:247], 0, s[52:53]
	s_mov_b32 m0, s9
	v_readfirstlane_b32 s9, v186
	ds_read_b128 v[230:233], v152
	ds_read_b128 v[234:237], v152 offset:1024
	ds_read_b128 v[238:241], v152 offset:2048
	ds_read_b128 v[242:245], v152 offset:3072
	global_load_lds_dwordx4 v[250:251], off
	v_lshl_add_u64 v[250:251], v[248:249], 0, s[52:53]
	s_mov_b32 m0, s9
	s_nop 0
	global_load_lds_dwordx4 v[250:251], off
	s_barrier
	s_waitcnt lgkmcnt(0)
	s_setprio 1
	s_waitcnt lgkmcnt(0)
	v_mfma_f32_16x16x32_bf16 v[92:95], v[230:233], v[198:201], v[92:95]
	v_mfma_f32_16x16x32_bf16 v[88:91], v[238:241], v[198:201], v[88:91]
	v_mfma_f32_16x16x32_bf16 v[72:75], v[238:241], v[206:209], v[72:75]
	v_mfma_f32_16x16x32_bf16 v[84:87], v[230:233], v[206:209], v[84:87]
	v_mfma_f32_16x16x32_bf16 v[60:63], v[230:233], v[214:217], v[60:63]
	v_mfma_f32_16x16x32_bf16 v[56:59], v[238:241], v[214:217], v[56:59]
	v_mfma_f32_16x16x32_bf16 v[48:51], v[238:241], v[222:225], v[48:51]
	v_mfma_f32_16x16x32_bf16 v[52:55], v[230:233], v[222:225], v[52:55]
	v_mfma_f32_16x16x32_bf16 v[92:95], v[234:237], v[202:205], v[92:95]
	v_mfma_f32_16x16x32_bf16 v[88:91], v[242:245], v[202:205], v[88:91]
	v_mfma_f32_16x16x32_bf16 v[72:75], v[242:245], v[210:213], v[72:75]
	v_mfma_f32_16x16x32_bf16 v[84:87], v[234:237], v[210:213], v[84:87]
	v_mfma_f32_16x16x32_bf16 v[60:63], v[234:237], v[218:221], v[60:63]
	v_mfma_f32_16x16x32_bf16 v[56:59], v[242:245], v[218:221], v[56:59]
	v_mfma_f32_16x16x32_bf16 v[48:51], v[242:245], v[226:229], v[48:51]
	v_mfma_f32_16x16x32_bf16 v[52:55], v[234:237], v[226:229], v[52:55]
	s_setprio 0
	v_readfirstlane_b32 s9, v155
	v_lshl_add_u64 v[178:179], v[178:179], 0, s[54:55]
	s_mov_b32 m0, s9
	v_readfirstlane_b32 s9, v156
	s_barrier
; #define WAIT_V(n) asm volatile("s_waitcnt vmcnt(" #n ")" ::: "memory")
; #define WAIT_L(n) asm volatile("s_waitcnt lgkmcnt(" #n ")" ::: "memory")
; #define BAR __builtin_amdgcn_s_barrier()
; #define SCHED __builtin_amdgcn_sched_barrier(0)
; #define LDA(dst, b, h)                                                                            \
;   _Pragma("unroll") for (int m = 0; m < 4; ++m) _Pragma("unroll") for (int k = 0; k < 2; ++k)                                         \
;     dst[m][k] = *reinterpret_cast<const bf16x8*>((char*)SA(b, h) + lds_byte(wr * 64 + m * 16 + fr, k * 32 + fq * 8))
; #define LDB(dst, b, h)                                                                            \
;   _Pragma("unroll") for (int n = 0; n < 2; ++n) _Pragma("unroll") for (int k = 0; k < 2; ++k)                                         \
;     dst[n][k] = *reinterpret_cast<const bf16x8*>((char*)SB(b, h) + lds_byte(wc * 32 + n * 16 + fr, k * 32 + fq * 8))
; template <int K, bool SWAP>
; __device__ __forceinline__ void gemm_kloop(const bf16* __restrict__ A, const bf16* __restrict__ Bt,
;                                            f32x4 (&acc)[2][2][4][2], bool pref = false) {
;     ...
;     LDA(At, 1, 1); STAGE(SA(1, 0), A, 0, t + 3);
;     BAR; WAIT_L(0); MMA(1, 0, At, B0); BAR; SCHED;
;     STAGE(SB(1, 1), Bt, HALF, t + 3);
;     WAIT_V(6); BAR; MMA(1, 1, At, B1); BAR;
;   }
;   { LDB(B0, 0, 0); LDA(At, 0, 0); STAGE(SA(1, 1), A, HALF, nt - 1);
;     BAR; WAIT_L(0); MMA(0, 0, At, B0); BAR;
	ds_read_b128 v[198:201], v151 offset:49152
	ds_read_b128 v[202:205], v151 offset:50176
	ds_read_b128 v[206:209], v150 offset:49152
	ds_read_b128 v[210:213], v150 offset:50176
	ds_read_b128 v[214:217], v149 offset:49152
	ds_read_b128 v[218:221], v149 offset:50176
	ds_read_b128 v[222:225], v148 offset:49152
	ds_read_b128 v[226:229], v148 offset:50176
	global_load_lds_dwordx4 v[178:179], off
	v_lshl_add_u64 v[178:179], v[188:189], 0, s[54:55]
	s_mov_b32 m0, s9
	s_nop 0
	global_load_lds_dwordx4 v[178:179], off
	s_barrier
	s_waitcnt lgkmcnt(0)
	s_setprio 1
	s_waitcnt lgkmcnt(0)
	v_mfma_f32_16x16x32_bf16 v[44:47], v[162:165], v[198:201], v[44:47]
	v_mfma_f32_16x16x32_bf16 v[40:43], v[170:173], v[198:201], v[40:43]
	v_mfma_f32_16x16x32_bf16 v[32:35], v[170:173], v[206:209], v[32:35]
	v_mfma_f32_16x16x32_bf16 v[36:39], v[162:165], v[206:209], v[36:39]
	v_mfma_f32_16x16x32_bf16 v[28:31], v[162:165], v[214:217], v[28:31]
	v_mfma_f32_16x16x32_bf16 v[24:27], v[170:173], v[214:217], v[24:27]
	v_mfma_f32_16x16x32_bf16 v[16:19], v[170:173], v[222:225], v[16:19]
	v_mfma_f32_16x16x32_bf16 v[20:23], v[162:165], v[222:225], v[20:23]
	v_mfma_f32_16x16x32_bf16 v[44:47], v[166:169], v[202:205], v[44:47]
	v_mfma_f32_16x16x32_bf16 v[40:43], v[174:177], v[202:205], v[40:43]
	v_mfma_f32_16x16x32_bf16 v[32:35], v[174:177], v[210:213], v[32:35]
	v_mfma_f32_16x16x32_bf16 v[36:39], v[166:169], v[210:213], v[36:39]
	v_mfma_f32_16x16x32_bf16 v[28:31], v[166:169], v[218:221], v[28:31]
	v_mfma_f32_16x16x32_bf16 v[24:27], v[174:177], v[218:221], v[24:27]
	v_mfma_f32_16x16x32_bf16 v[16:19], v[174:177], v[226:229], v[16:19]
	v_mfma_f32_16x16x32_bf16 v[20:23], v[166:169], v[226:229], v[20:23]
	s_setprio 0
	s_barrier
	v_readfirstlane_b32 s9, v157
	v_add_u32_e32 v164, 0x2000, v157
	v_lshl_add_u64 v[162:163], v[246:247], 0, s[56:57]
	s_mov_b32 m0, s9
	v_readfirstlane_b32 s9, v164
	global_load_lds_dwordx4 v[162:163], off
	v_lshl_add_u64 v[162:163], v[248:249], 0, s[56:57]
	s_mov_b32 m0, s9
	s_nop 0
	global_load_lds_dwordx4 v[162:163], off
	s_waitcnt vmcnt(6)
	s_barrier
	s_setprio 1
	v_mfma_f32_16x16x32_bf16 v[12:15], v[230:233], v[198:201], v[12:15]
	v_mfma_f32_16x16x32_bf16 v[8:11], v[238:241], v[198:201], v[8:11]
	v_mfma_f32_16x16x32_bf16 v[0:3], v[238:241], v[206:209], v[0:3]
	v_mfma_f32_16x16x32_bf16 v[4:7], v[230:233], v[206:209], v[4:7]
	v_mfma_f32_16x16x32_bf16 v[64:67], v[230:233], v[214:217], v[64:67]
	v_mfma_f32_16x16x32_bf16 v[68:71], v[238:241], v[214:217], v[68:71]
	v_mfma_f32_16x16x32_bf16 v[80:83], v[238:241], v[222:225], v[80:83]
	v_mfma_f32_16x16x32_bf16 v[76:79], v[230:233], v[222:225], v[76:79]
	v_mfma_f32_16x16x32_bf16 v[12:15], v[234:237], v[202:205], v[12:15]
	v_mfma_f32_16x16x32_bf16 v[8:11], v[242:245], v[202:205], v[8:11]
	v_mfma_f32_16x16x32_bf16 v[0:3], v[242:245], v[210:213], v[0:3]
	v_mfma_f32_16x16x32_bf16 v[4:7], v[234:237], v[210:213], v[4:7]
	v_mfma_f32_16x16x32_bf16 v[64:67], v[234:237], v[218:221], v[64:67]
	v_mfma_f32_16x16x32_bf16 v[68:71], v[242:245], v[218:221], v[68:71]
	v_mfma_f32_16x16x32_bf16 v[80:83], v[242:245], v[226:229], v[80:83]
	v_mfma_f32_16x16x32_bf16 v[76:79], v[234:237], v[226:229], v[76:79]
	s_setprio 0
	s_add_i32 s8, s8, 2
	v_lshl_add_u64 v[136:137], v[136:137], 0, s[44:45]
	v_lshl_add_u64 v[138:139], v[138:139], 0, s[44:45]
	v_lshl_add_u64 v[140:141], v[140:141], 0, s[44:45]
	s_cmp_lt_u32 s8, 12
	v_lshl_add_u64 v[142:143], v[142:143], 0, s[44:45]
	s_barrier
	s_cbranch_scc1 .LBB0_514
	s_add_u32 s4, s4, 0x40780
	s_addc_u32 s5, s5, 0
	v_lshl_add_u64 v[130:131], s[4:5], 0, v[130:131]
	v_readfirstlane_b32 s8, v160
	v_lshl_add_u64 v[128:129], v[128:129], 1, v[130:131]
	s_mov_b32 m0, s8
	ds_read_b128 v[136:139], v159
	ds_read_b128 v[140:143], v159 offset:1024
	ds_read_b128 v[154:157], v159 offset:2048
	ds_read_b128 v[162:165], v159 offset:3072
	ds_read_b128 v[166:169], v151
	ds_read_b128 v[170:173], v151 offset:1024
	ds_read_b128 v[174:177], v150
	ds_read_b128 v[198:201], v150 offset:1024
	ds_read_b128 v[202:205], v149
	ds_read_b128 v[206:209], v149 offset:1024
	ds_read_b128 v[210:213], v148
	ds_read_b128 v[214:217], v148 offset:1024
	global_load_lds_dwordx4 v[128:129], off
	v_lshl_add_u64 v[128:129], s[4:5], 0, v[134:135]
	v_readfirstlane_b32 s4, v161
	v_lshl_add_u64 v[128:129], v[132:133], 1, v[128:129]
	s_mov_b32 m0, s4
	s_nop 0
	global_load_lds_dwordx4 v[128:129], off
	s_barrier
	s_waitcnt lgkmcnt(0)
	s_setprio 1
	s_waitcnt lgkmcnt(0)
	v_mfma_f32_16x16x32_bf16 v[124:127], v[136:139], v[166:169], v[124:127]
	v_mfma_f32_16x16x32_bf16 v[120:123], v[154:157], v[166:169], v[120:123]
	v_mfma_f32_16x16x32_bf16 v[112:115], v[154:157], v[174:177], v[112:115]
	v_mfma_f32_16x16x32_bf16 v[116:119], v[136:139], v[174:177], v[116:119]
	v_mfma_f32_16x16x32_bf16 v[108:111], v[136:139], v[202:205], v[108:111]
	v_mfma_f32_16x16x32_bf16 v[104:107], v[154:157], v[202:205], v[104:107]
	v_mfma_f32_16x16x32_bf16 v[96:99], v[154:157], v[210:213], v[96:99]
	v_mfma_f32_16x16x32_bf16 v[100:103], v[136:139], v[210:213], v[100:103]
	v_mfma_f32_16x16x32_bf16 v[124:127], v[140:143], v[170:173], v[124:127]
	v_mfma_f32_16x16x32_bf16 v[120:123], v[162:165], v[170:173], v[120:123]
	v_mfma_f32_16x16x32_bf16 v[112:115], v[162:165], v[198:201], v[112:115]
	v_mfma_f32_16x16x32_bf16 v[116:119], v[140:143], v[198:201], v[116:119]
	v_mfma_f32_16x16x32_bf16 v[108:111], v[140:143], v[206:209], v[108:111]
	v_mfma_f32_16x16x32_bf16 v[104:107], v[162:165], v[206:209], v[104:107]
	v_mfma_f32_16x16x32_bf16 v[96:99], v[162:165], v[214:217], v[96:99]
	v_mfma_f32_16x16x32_bf16 v[100:103], v[140:143], v[214:217], v[100:103]
	s_setprio 0
	s_barrier
; #define WAIT_V(n) asm volatile("s_waitcnt vmcnt(" #n ")" ::: "memory")
; #define WAIT_L(n) asm volatile("s_waitcnt lgkmcnt(" #n ")" ::: "memory")
; #define BAR __builtin_amdgcn_s_barrier()
; #define LDA(dst, b, h)                                                                            \
;   _Pragma("unroll") for (int m = 0; m < 4; ++m) _Pragma("unroll") for (int k = 0; k < 2; ++k)                                         \
;     dst[m][k] = *reinterpret_cast<const bf16x8*>((char*)SA(b, h) + lds_byte(wr * 64 + m * 16 + fr, k * 32 + fq * 8))
; #define LDB(dst, b, h)                                                                            \
;   _Pragma("unroll") for (int n = 0; n < 2; ++n) _Pragma("unroll") for (int k = 0; k < 2; ++k)                                         \
;     dst[n][k] = *reinterpret_cast<const bf16x8*>((char*)SB(b, h) + lds_byte(wc * 32 + n * 16 + fr, k * 32 + fq * 8))
; template <int K, bool SWAP>
; __device__ __forceinline__ void gemm_kloop(const bf16* __restrict__ A, const bf16* __restrict__ Bt,
;                                            f32x4 (&acc)[2][2][4][2], bool pref = false) {
;     ...
;     LDB(B1, 0, 1); BAR; WAIT_L(0); MMA(0, 1, At, B1); BAR;
;     LDA(At, 0, 1); WAIT_V(4); BAR; WAIT_L(0); MMA(1, 0, At, B0); MMA(1, 1, At, B1); BAR; }
;   { LDB(B0, 1, 0); LDA(At, 1, 0); WAIT_V(2); BAR; WAIT_L(0); MMA(0, 0, At, B0); BAR;
	ds_read_b128 v[128:131], v158
	ds_read_b128 v[132:135], v158 offset:1024
	ds_read_b128 v[218:221], v158 offset:2048
	ds_read_b128 v[158:161], v158 offset:3072
	s_barrier
	s_waitcnt lgkmcnt(0)
	s_setprio 1
	s_waitcnt lgkmcnt(0)
	v_mfma_f32_16x16x32_bf16 v[92:95], v[128:131], v[166:169], v[92:95]
	v_mfma_f32_16x16x32_bf16 v[88:91], v[218:221], v[166:169], v[88:91]
	v_mfma_f32_16x16x32_bf16 v[72:75], v[218:221], v[174:177], v[72:75]
	v_mfma_f32_16x16x32_bf16 v[84:87], v[128:131], v[174:177], v[84:87]
	v_mfma_f32_16x16x32_bf16 v[60:63], v[128:131], v[202:205], v[60:63]
	v_mfma_f32_16x16x32_bf16 v[56:59], v[218:221], v[202:205], v[56:59]
	v_mfma_f32_16x16x32_bf16 v[48:51], v[218:221], v[210:213], v[48:51]
	v_mfma_f32_16x16x32_bf16 v[52:55], v[128:131], v[210:213], v[52:55]
	v_mfma_f32_16x16x32_bf16 v[92:95], v[132:135], v[170:173], v[92:95]
	v_mfma_f32_16x16x32_bf16 v[88:91], v[158:161], v[170:173], v[88:91]
	v_mfma_f32_16x16x32_bf16 v[72:75], v[158:161], v[198:201], v[72:75]
	v_mfma_f32_16x16x32_bf16 v[84:87], v[132:135], v[198:201], v[84:87]
	v_mfma_f32_16x16x32_bf16 v[60:63], v[132:135], v[206:209], v[60:63]
	v_mfma_f32_16x16x32_bf16 v[56:59], v[158:161], v[206:209], v[56:59]
	v_mfma_f32_16x16x32_bf16 v[48:51], v[158:161], v[214:217], v[48:51]
	v_mfma_f32_16x16x32_bf16 v[52:55], v[132:135], v[214:217], v[52:55]
	s_setprio 0
	s_barrier
	ds_read_b128 v[166:169], v151 offset:16384
	ds_read_b128 v[170:173], v151 offset:17408
	ds_read_b128 v[174:177], v150 offset:16384
	ds_read_b128 v[198:201], v150 offset:17408
	ds_read_b128 v[202:205], v149 offset:16384
	ds_read_b128 v[206:209], v149 offset:17408
	ds_read_b128 v[210:213], v148 offset:16384
	ds_read_b128 v[214:217], v148 offset:17408
	s_waitcnt vmcnt(4)
	s_barrier
	s_waitcnt lgkmcnt(0)
	s_setprio 1
	s_waitcnt lgkmcnt(0)
	v_mfma_f32_16x16x32_bf16 v[44:47], v[136:139], v[166:169], v[44:47]
	v_mfma_f32_16x16x32_bf16 v[40:43], v[154:157], v[166:169], v[40:43]
	v_mfma_f32_16x16x32_bf16 v[32:35], v[154:157], v[174:177], v[32:35]
	v_mfma_f32_16x16x32_bf16 v[36:39], v[136:139], v[174:177], v[36:39]
	v_mfma_f32_16x16x32_bf16 v[28:31], v[136:139], v[202:205], v[28:31]
	v_mfma_f32_16x16x32_bf16 v[24:27], v[154:157], v[202:205], v[24:27]
	v_mfma_f32_16x16x32_bf16 v[16:19], v[154:157], v[210:213], v[16:19]
	v_mfma_f32_16x16x32_bf16 v[20:23], v[136:139], v[210:213], v[20:23]
	v_mfma_f32_16x16x32_bf16 v[44:47], v[140:143], v[170:173], v[44:47]
	v_mfma_f32_16x16x32_bf16 v[40:43], v[162:165], v[170:173], v[40:43]
	v_mfma_f32_16x16x32_bf16 v[32:35], v[162:165], v[198:201], v[32:35]
	v_mfma_f32_16x16x32_bf16 v[36:39], v[140:143], v[198:201], v[36:39]
	v_mfma_f32_16x16x32_bf16 v[28:31], v[140:143], v[206:209], v[28:31]
	v_mfma_f32_16x16x32_bf16 v[24:27], v[162:165], v[206:209], v[24:27]
	v_mfma_f32_16x16x32_bf16 v[16:19], v[162:165], v[214:217], v[16:19]
	v_mfma_f32_16x16x32_bf16 v[20:23], v[140:143], v[214:217], v[20:23]
	s_setprio 0
	s_setprio 1
	v_mfma_f32_16x16x32_bf16 v[64:67], v[128:131], v[202:205], v[64:67]
	v_mfma_f32_16x16x32_bf16 v[136:139], v[132:135], v[206:209], v[64:67]
	v_mfma_f32_16x16x32_bf16 v[64:67], v[218:221], v[202:205], v[68:71]
	v_mfma_f32_16x16x32_bf16 v[12:15], v[128:131], v[166:169], v[12:15]
	v_mfma_f32_16x16x32_bf16 v[8:11], v[218:221], v[166:169], v[8:11]
	v_mfma_f32_16x16x32_bf16 v[4:7], v[128:131], v[174:177], v[4:7]
	v_mfma_f32_16x16x32_bf16 v[0:3], v[218:221], v[174:177], v[0:3]
	v_mfma_f32_16x16x32_bf16 v[140:143], v[158:161], v[206:209], v[64:67]
	v_mfma_f32_16x16x32_bf16 v[64:67], v[128:131], v[210:213], v[76:79]
	v_mfma_f32_16x16x32_bf16 v[12:15], v[132:135], v[170:173], v[12:15]
	v_mfma_f32_16x16x32_bf16 v[8:11], v[158:161], v[170:173], v[8:11]
	v_mfma_f32_16x16x32_bf16 v[4:7], v[132:135], v[198:201], v[4:7]
	v_mfma_f32_16x16x32_bf16 v[0:3], v[158:161], v[198:201], v[0:3]
	v_mfma_f32_16x16x32_bf16 v[128:131], v[132:135], v[214:217], v[64:67]
	v_mfma_f32_16x16x32_bf16 v[64:67], v[218:221], v[210:213], v[80:83]
	v_mfma_f32_16x16x32_bf16 v[132:135], v[158:161], v[214:217], v[64:67]
	s_setprio 0
	s_barrier
	ds_read_b128 v[154:157], v153
	ds_read_b128 v[158:161], v153 offset:1024
	ds_read_b128 v[162:165], v153 offset:2048
	ds_read_b128 v[166:169], v153 offset:3072
	s_nop 0
	ds_read_b128 v[64:67], v151 offset:32768
	ds_read_b128 v[68:71], v151 offset:33792
	ds_read_b128 v[76:79], v150 offset:32768
	ds_read_b128 v[80:83], v150 offset:33792
	ds_read_b128 v[170:173], v149 offset:32768
	ds_read_b128 v[174:177], v149 offset:33792
	ds_read_b128 v[198:201], v148 offset:32768
	ds_read_b128 v[202:205], v148 offset:33792
	s_waitcnt vmcnt(2)
	s_barrier
; #define WAIT_V(n) asm volatile("s_waitcnt vmcnt(" #n ")" ::: "memory")
; #define WAIT_L(n) asm volatile("s_waitcnt lgkmcnt(" #n ")" ::: "memory")
; #define BAR __builtin_amdgcn_s_barrier()
; #define LDA(dst, b, h)                                                                            \
;   _Pragma("unroll") for (int m = 0; m < 4; ++m) _Pragma("unroll") for (int k = 0; k < 2; ++k)                                         \
;     dst[m][k] = *reinterpret_cast<const bf16x8*>((char*)SA(b, h) + lds_byte(wr * 64 + m * 16 + fr, k * 32 + fq * 8))
; #define LDB(dst, b, h)                                                                            \
;   _Pragma("unroll") for (int n = 0; n < 2; ++n) _Pragma("unroll") for (int k = 0; k < 2; ++k)                                         \
;     dst[n][k] = *reinterpret_cast<const bf16x8*>((char*)SB(b, h) + lds_byte(wc * 32 + n * 16 + fr, k * 32 + fq * 8))
; template <int K, bool SWAP>
; __device__ __forceinline__ void gemm_kloop(const bf16* __restrict__ A, const bf16* __restrict__ Bt,
;                                            f32x4 (&acc)[2][2][4][2], bool pref = false) {
;     ...
;   { LDB(B0, 1, 0); LDA(At, 1, 0); WAIT_V(2); BAR; WAIT_L(0); MMA(0, 0, At, B0); BAR;
;     LDB(B1, 1, 1); WAIT_V(0); BAR; WAIT_L(0); MMA(0, 1, At, B1); BAR;
;     LDA(At, 1, 1); BAR; WAIT_L(0); MMA(1, 0, At, B0); MMA(1, 1, At, B1); BAR; }
;   if (wr == 0) BAR;
	s_waitcnt lgkmcnt(0)
	s_setprio 1
	s_waitcnt lgkmcnt(0)
	v_mfma_f32_16x16x32_bf16 v[124:127], v[154:157], v[64:67], v[124:127]
	v_mfma_f32_16x16x32_bf16 v[120:123], v[162:165], v[64:67], v[120:123]
	v_mfma_f32_16x16x32_bf16 v[112:115], v[162:165], v[76:79], v[112:115]
	v_mfma_f32_16x16x32_bf16 v[116:119], v[154:157], v[76:79], v[116:119]
	v_mfma_f32_16x16x32_bf16 v[108:111], v[154:157], v[170:173], v[108:111]
	v_mfma_f32_16x16x32_bf16 v[104:107], v[162:165], v[170:173], v[104:107]
	v_mfma_f32_16x16x32_bf16 v[96:99], v[162:165], v[198:201], v[96:99]
	v_mfma_f32_16x16x32_bf16 v[100:103], v[154:157], v[198:201], v[100:103]
	v_mfma_f32_16x16x32_bf16 v[124:127], v[158:161], v[68:71], v[124:127]
	v_mfma_f32_16x16x32_bf16 v[120:123], v[166:169], v[68:71], v[120:123]
	v_mfma_f32_16x16x32_bf16 v[112:115], v[166:169], v[80:83], v[112:115]
	v_mfma_f32_16x16x32_bf16 v[116:119], v[158:161], v[80:83], v[116:119]
	v_mfma_f32_16x16x32_bf16 v[108:111], v[158:161], v[174:177], v[108:111]
	v_mfma_f32_16x16x32_bf16 v[104:107], v[166:169], v[174:177], v[104:107]
	v_mfma_f32_16x16x32_bf16 v[96:99], v[166:169], v[202:205], v[96:99]
	v_mfma_f32_16x16x32_bf16 v[100:103], v[158:161], v[202:205], v[100:103]
	s_setprio 0
	s_barrier
	ds_read_b128 v[206:209], v152
	ds_read_b128 v[210:213], v152 offset:1024
	ds_read_b128 v[214:217], v152 offset:2048
	ds_read_b128 v[218:221], v152 offset:3072
	s_waitcnt vmcnt(0)
	s_barrier
	s_waitcnt lgkmcnt(0)
	s_setprio 1
	s_waitcnt lgkmcnt(0)
	v_mfma_f32_16x16x32_bf16 v[92:95], v[206:209], v[64:67], v[92:95]
	v_mfma_f32_16x16x32_bf16 v[64:67], v[214:217], v[64:67], v[88:91]
	v_mfma_f32_16x16x32_bf16 v[88:91], v[218:221], v[68:71], v[64:67]
	v_mfma_f32_16x16x32_bf16 v[64:67], v[206:209], v[76:79], v[84:87]
	v_mfma_f32_16x16x32_bf16 v[84:87], v[210:213], v[80:83], v[64:67]
	v_mfma_f32_16x16x32_bf16 v[64:67], v[214:217], v[76:79], v[72:75]
	v_mfma_f32_16x16x32_bf16 v[60:63], v[206:209], v[170:173], v[60:63]
	v_mfma_f32_16x16x32_bf16 v[56:59], v[214:217], v[170:173], v[56:59]
	v_mfma_f32_16x16x32_bf16 v[52:55], v[206:209], v[198:201], v[52:55]
	v_mfma_f32_16x16x32_bf16 v[48:51], v[214:217], v[198:201], v[48:51]
	v_mfma_f32_16x16x32_bf16 v[92:95], v[210:213], v[68:71], v[92:95]
	v_mfma_f32_16x16x32_bf16 v[80:83], v[218:221], v[80:83], v[64:67]
	v_mfma_f32_16x16x32_bf16 v[76:79], v[210:213], v[174:177], v[60:63]
	v_mfma_f32_16x16x32_bf16 v[72:75], v[218:221], v[174:177], v[56:59]
	v_mfma_f32_16x16x32_bf16 v[68:71], v[210:213], v[202:205], v[52:55]
	v_mfma_f32_16x16x32_bf16 v[64:67], v[218:221], v[202:205], v[48:51]
	s_setprio 0
	s_barrier
	ds_read_b128 v[170:173], v151 offset:49152
	ds_read_b128 v[174:177], v151 offset:50176
	ds_read_b128 v[198:201], v150 offset:49152
	ds_read_b128 v[150:153], v150 offset:50176
	ds_read_b128 v[202:205], v149 offset:49152
	ds_read_b128 v[222:225], v149 offset:50176
	ds_read_b128 v[226:229], v148 offset:49152
	ds_read_b128 v[146:149], v148 offset:50176
	s_barrier
	s_waitcnt lgkmcnt(0)
	s_setprio 1
	s_waitcnt lgkmcnt(0)
	v_mfma_f32_16x16x32_bf16 v[44:47], v[154:157], v[170:173], v[44:47]
	v_mfma_f32_16x16x32_bf16 v[40:43], v[162:165], v[170:173], v[40:43]
	v_mfma_f32_16x16x32_bf16 v[36:39], v[154:157], v[198:201], v[36:39]
	v_mfma_f32_16x16x32_bf16 v[32:35], v[162:165], v[198:201], v[32:35]
	v_mfma_f32_16x16x32_bf16 v[28:31], v[154:157], v[202:205], v[28:31]
	v_mfma_f32_16x16x32_bf16 v[24:27], v[162:165], v[202:205], v[24:27]
	v_mfma_f32_16x16x32_bf16 v[20:23], v[154:157], v[226:229], v[20:23]
	v_mfma_f32_16x16x32_bf16 v[16:19], v[162:165], v[226:229], v[16:19]
	v_mfma_f32_16x16x32_bf16 v[60:63], v[158:161], v[174:177], v[44:47]
	v_mfma_f32_16x16x32_bf16 v[56:59], v[166:169], v[174:177], v[40:43]
	v_mfma_f32_16x16x32_bf16 v[52:55], v[158:161], v[150:153], v[36:39]
	v_mfma_f32_16x16x32_bf16 v[48:51], v[166:169], v[150:153], v[32:35]
	v_mfma_f32_16x16x32_bf16 v[44:47], v[158:161], v[222:225], v[28:31]
	v_mfma_f32_16x16x32_bf16 v[40:43], v[166:169], v[222:225], v[24:27]
	v_mfma_f32_16x16x32_bf16 v[36:39], v[158:161], v[146:149], v[20:23]
	v_mfma_f32_16x16x32_bf16 v[32:35], v[166:169], v[146:149], v[16:19]
	s_setprio 0
	s_setprio 1
	v_mfma_f32_16x16x32_bf16 v[0:3], v[214:217], v[198:201], v[0:3]
	v_mfma_f32_16x16x32_bf16 v[12:15], v[206:209], v[170:173], v[12:15]
	v_mfma_f32_16x16x32_bf16 v[16:19], v[218:221], v[150:153], v[0:3]
	v_mfma_f32_16x16x32_bf16 v[0:3], v[206:209], v[202:205], v[136:139]
	v_mfma_f32_16x16x32_bf16 v[28:31], v[210:213], v[174:177], v[12:15]
	v_mfma_f32_16x16x32_bf16 v[8:11], v[214:217], v[170:173], v[8:11]
	v_mfma_f32_16x16x32_bf16 v[12:15], v[210:213], v[222:225], v[0:3]
	v_mfma_f32_16x16x32_bf16 v[0:3], v[214:217], v[202:205], v[140:143]
	v_mfma_f32_16x16x32_bf16 v[24:27], v[218:221], v[174:177], v[8:11]
	v_mfma_f32_16x16x32_bf16 v[4:7], v[206:209], v[198:201], v[4:7]
	v_mfma_f32_16x16x32_bf16 v[8:11], v[218:221], v[222:225], v[0:3]
	v_mfma_f32_16x16x32_bf16 v[0:3], v[206:209], v[226:229], v[128:131]
	v_mfma_f32_16x16x32_bf16 v[20:23], v[210:213], v[150:153], v[4:7]
	v_mfma_f32_16x16x32_bf16 v[4:7], v[210:213], v[146:149], v[0:3]
	v_mfma_f32_16x16x32_bf16 v[0:3], v[214:217], v[226:229], v[132:135]
	v_mfma_f32_16x16x32_bf16 v[0:3], v[218:221], v[146:149], v[0:3]
	s_setprio 0
	s_movk_i32 s4, 0x100
	v_cmp_gt_u32_e32 vcc, s4, v144
	s_barrier
	s_and_saveexec_b64 s[4:5], vcc
	s_cbranch_execz .LBB0_517
	s_barrier

; #define WAIT_L(n) asm volatile("s_waitcnt lgkmcnt(" #n ")" ::: "memory")
; #define BAR __builtin_amdgcn_s_barrier()
; #define SCHED __builtin_amdgcn_sched_barrier(0)
; #define LDA(dst, b, h)                                                                            \
;   _Pragma("unroll") for (int m = 0; m < 4; ++m) _Pragma("unroll") for (int k = 0; k < 2; ++k)                                         \
;     dst[m][k] = *reinterpret_cast<const bf16x8*>((char*)SA(b, h) + lds_byte(wr * 64 + m * 16 + fr, k * 32 + fq * 8))
; #define LDB(dst, b, h)                                                                            \
;   _Pragma("unroll") for (int n = 0; n < 2; ++n) _Pragma("unroll") for (int k = 0; k < 2; ++k)                                         \
;     dst[n][k] = *reinterpret_cast<const bf16x8*>((char*)SB(b, h) + lds_byte(wc * 32 + n * 16 + fr, k * 32 + fq * 8))
; template <int K, bool SWAP>
; __device__ __forceinline__ void gemm_kloop(const bf16* __restrict__ A, const bf16* __restrict__ Bt,
;                                            f32x4 (&acc)[2][2][4][2], bool pref = false) {
;     ...
;     LDB(B0, 0, 0); SCHED; LDA(At, 0, 0); STAGE(SA(1, 1), A, HALF, t + 1);
;     WAIT_L(8); BAR; WAIT_L(0); MMA(0, 0, At, B0); BAR; SCHED;
;     LDB(B1, 0, 1); STAGE(SB(0, 0), Bt, 0, t + 2);
;     BAR; WAIT_L(0); MMA(0, 1, At, B1); BAR;
;     LDA(At, 0, 1); STAGE(SA(0, 0), A, 0, t + 2);
;     BAR; WAIT_L(0); MMA(1, 0, At, B0); BAR; SCHED;
.LBB0_527:
	ds_read_b128 v[162:165], v159
	ds_read_b128 v[166:169], v159 offset:1024
	ds_read_b128 v[170:173], v159 offset:2048
	ds_read_b128 v[174:177], v159 offset:3072
	v_add_u32_e32 v160, 0xc000, v146
	v_lshl_add_u64 v[178:179], s[58:59], 0, v[140:141]
	v_readfirstlane_b32 s9, v160
	v_lshl_add_u64 v[188:189], v[178:179], 0, s[42:43]
	s_mov_b32 m0, s9
	v_add_u32_e32 v161, 0xe000, v146
	ds_read_b128 v[198:201], v151
	ds_read_b128 v[202:205], v151 offset:1024
	ds_read_b128 v[206:209], v150
	ds_read_b128 v[210:213], v150 offset:1024
	ds_read_b128 v[214:217], v149
	ds_read_b128 v[218:221], v149 offset:1024
	ds_read_b128 v[222:225], v148
	ds_read_b128 v[226:229], v148 offset:1024
	global_load_lds_dwordx4 v[188:189], off
	v_lshl_add_u64 v[188:189], s[58:59], 0, v[142:143]
	v_readfirstlane_b32 s9, v161
	v_lshl_add_u64 v[230:231], v[188:189], 0, s[42:43]
	s_mov_b32 m0, s9
	s_nop 0
	global_load_lds_dwordx4 v[230:231], off
	s_waitcnt lgkmcnt(8)
	s_barrier
	s_waitcnt lgkmcnt(0)
	s_setprio 1
	s_waitcnt lgkmcnt(0)
	v_mfma_f32_16x16x32_bf16 v[124:127], v[162:165], v[198:201], v[124:127]
	v_mfma_f32_16x16x32_bf16 v[120:123], v[170:173], v[198:201], v[120:123]
	v_mfma_f32_16x16x32_bf16 v[112:115], v[170:173], v[206:209], v[112:115]
	v_mfma_f32_16x16x32_bf16 v[116:119], v[162:165], v[206:209], v[116:119]
	v_mfma_f32_16x16x32_bf16 v[108:111], v[162:165], v[214:217], v[108:111]
	v_mfma_f32_16x16x32_bf16 v[104:107], v[170:173], v[214:217], v[104:107]
	v_mfma_f32_16x16x32_bf16 v[96:99], v[170:173], v[222:225], v[96:99]
	v_mfma_f32_16x16x32_bf16 v[100:103], v[162:165], v[222:225], v[100:103]
	v_mfma_f32_16x16x32_bf16 v[124:127], v[166:169], v[202:205], v[124:127]
	v_mfma_f32_16x16x32_bf16 v[120:123], v[174:177], v[202:205], v[120:123]
	v_mfma_f32_16x16x32_bf16 v[112:115], v[174:177], v[210:213], v[112:115]
	v_mfma_f32_16x16x32_bf16 v[116:119], v[166:169], v[210:213], v[116:119]
	v_mfma_f32_16x16x32_bf16 v[108:111], v[166:169], v[218:221], v[108:111]
	v_mfma_f32_16x16x32_bf16 v[104:107], v[174:177], v[218:221], v[104:107]
	v_mfma_f32_16x16x32_bf16 v[96:99], v[174:177], v[226:229], v[96:99]
	v_mfma_f32_16x16x32_bf16 v[100:103], v[166:169], v[226:229], v[100:103]
	s_setprio 0
	s_barrier
	v_add_u32_e32 v186, s7, v145
	v_lshl_add_u64 v[246:247], s[58:59], 0, v[136:137]
	v_readfirstlane_b32 s9, v186
	v_lshl_add_u64 v[248:249], v[246:247], 0, s[44:45]
	s_mov_b32 m0, s9
	v_add_u32_e32 v186, 0x2000, v186
	ds_read_b128 v[230:233], v158
	ds_read_b128 v[234:237], v158 offset:1024
	ds_read_b128 v[238:241], v158 offset:2048
	ds_read_b128 v[242:245], v158 offset:3072
	global_load_lds_dwordx4 v[248:249], off
	v_lshl_add_u64 v[248:249], s[58:59], 0, v[138:139]
	v_readfirstlane_b32 s9, v186
	v_lshl_add_u64 v[250:251], v[248:249], 0, s[44:45]
	s_mov_b32 m0, s9
	s_nop 0
	global_load_lds_dwordx4 v[250:251], off
	s_barrier
	s_waitcnt lgkmcnt(0)
	s_setprio 1
	s_waitcnt lgkmcnt(0)
	v_mfma_f32_16x16x32_bf16 v[92:95], v[230:233], v[198:201], v[92:95]
	v_mfma_f32_16x16x32_bf16 v[88:91], v[238:241], v[198:201], v[88:91]
	v_mfma_f32_16x16x32_bf16 v[80:83], v[238:241], v[206:209], v[80:83]
	v_mfma_f32_16x16x32_bf16 v[84:87], v[230:233], v[206:209], v[84:87]
	v_mfma_f32_16x16x32_bf16 v[76:79], v[230:233], v[214:217], v[76:79]
	v_mfma_f32_16x16x32_bf16 v[72:75], v[238:241], v[214:217], v[72:75]
	v_mfma_f32_16x16x32_bf16 v[64:67], v[238:241], v[222:225], v[64:67]
	v_mfma_f32_16x16x32_bf16 v[68:71], v[230:233], v[222:225], v[68:71]
	v_mfma_f32_16x16x32_bf16 v[92:95], v[234:237], v[202:205], v[92:95]
	v_mfma_f32_16x16x32_bf16 v[88:91], v[242:245], v[202:205], v[88:91]
	v_mfma_f32_16x16x32_bf16 v[80:83], v[242:245], v[210:213], v[80:83]
	v_mfma_f32_16x16x32_bf16 v[84:87], v[234:237], v[210:213], v[84:87]
	v_mfma_f32_16x16x32_bf16 v[76:79], v[234:237], v[218:221], v[76:79]
	v_mfma_f32_16x16x32_bf16 v[72:75], v[242:245], v[218:221], v[72:75]
	v_mfma_f32_16x16x32_bf16 v[64:67], v[242:245], v[226:229], v[64:67]
	v_mfma_f32_16x16x32_bf16 v[68:71], v[234:237], v[226:229], v[68:71]
	s_setprio 0
	v_readfirstlane_b32 s9, v146
	v_add_u32_e32 v186, 0x2000, v146
	v_lshl_add_u64 v[250:251], v[178:179], 0, s[46:47]
	s_mov_b32 m0, s9
	v_readfirstlane_b32 s9, v186
	s_barrier
	ds_read_b128 v[198:201], v151 offset:16384
	ds_read_b128 v[202:205], v151 offset:17408
	ds_read_b128 v[206:209], v150 offset:16384
	ds_read_b128 v[210:213], v150 offset:17408
	ds_read_b128 v[214:217], v149 offset:16384
	ds_read_b128 v[218:221], v149 offset:17408
	ds_read_b128 v[222:225], v148 offset:16384
	ds_read_b128 v[226:229], v148 offset:17408
	global_load_lds_dwordx4 v[250:251], off
	v_lshl_add_u64 v[250:251], v[188:189], 0, s[46:47]
	s_mov_b32 m0, s9
	s_nop 0
	global_load_lds_dwordx4 v[250:251], off
	s_barrier
	s_waitcnt lgkmcnt(0)
	s_setprio 1
	s_waitcnt lgkmcnt(0)
	v_mfma_f32_16x16x32_bf16 v[60:63], v[162:165], v[198:201], v[60:63]
	v_mfma_f32_16x16x32_bf16 v[56:59], v[170:173], v[198:201], v[56:59]
	v_mfma_f32_16x16x32_bf16 v[48:51], v[170:173], v[206:209], v[48:51]
	v_mfma_f32_16x16x32_bf16 v[52:55], v[162:165], v[206:209], v[52:55]
	v_mfma_f32_16x16x32_bf16 v[44:47], v[162:165], v[214:217], v[44:47]
	v_mfma_f32_16x16x32_bf16 v[40:43], v[170:173], v[214:217], v[40:43]
	v_mfma_f32_16x16x32_bf16 v[32:35], v[170:173], v[222:225], v[32:35]
	v_mfma_f32_16x16x32_bf16 v[36:39], v[162:165], v[222:225], v[36:39]
	v_mfma_f32_16x16x32_bf16 v[60:63], v[166:169], v[202:205], v[60:63]
	v_mfma_f32_16x16x32_bf16 v[56:59], v[174:177], v[202:205], v[56:59]
	v_mfma_f32_16x16x32_bf16 v[48:51], v[174:177], v[210:213], v[48:51]
	v_mfma_f32_16x16x32_bf16 v[52:55], v[166:169], v[210:213], v[52:55]
	v_mfma_f32_16x16x32_bf16 v[44:47], v[166:169], v[218:221], v[44:47]
	v_mfma_f32_16x16x32_bf16 v[40:43], v[174:177], v[218:221], v[40:43]
	v_mfma_f32_16x16x32_bf16 v[32:35], v[174:177], v[226:229], v[32:35]
	v_mfma_f32_16x16x32_bf16 v[36:39], v[166:169], v[226:229], v[36:39]
	s_setprio 0
	s_barrier
; #define WAIT_V(n) asm volatile("s_waitcnt vmcnt(" #n ")" ::: "memory")
; #define WAIT_L(n) asm volatile("s_waitcnt lgkmcnt(" #n ")" ::: "memory")
; #define BAR __builtin_amdgcn_s_barrier()
; #define SCHED __builtin_amdgcn_sched_barrier(0)
; #define LDA(dst, b, h)                                                                            \
;   _Pragma("unroll") for (int m = 0; m < 4; ++m) _Pragma("unroll") for (int k = 0; k < 2; ++k)                                         \
;     dst[m][k] = *reinterpret_cast<const bf16x8*>((char*)SA(b, h) + lds_byte(wr * 64 + m * 16 + fr, k * 32 + fq * 8))
; #define LDB(dst, b, h)                                                                            \
;   _Pragma("unroll") for (int n = 0; n < 2; ++n) _Pragma("unroll") for (int k = 0; k < 2; ++k)                                         \
;     dst[n][k] = *reinterpret_cast<const bf16x8*>((char*)SB(b, h) + lds_byte(wc * 32 + n * 16 + fr, k * 32 + fq * 8))
; template <int K, bool SWAP>
; __device__ __forceinline__ void gemm_kloop(const bf16* __restrict__ A, const bf16* __restrict__ Bt,
;                                            f32x4 (&acc)[2][2][4][2], bool pref = false) {
;     ...
;     STAGE(SB(0, 1), Bt, HALF, t + 2);
;     WAIT_V(6); BAR; MMA(1, 1, At, B1); BAR;
;     LDB(B0, 1, 0); SCHED; LDA(At, 1, 0); STAGE(SA(0, 1), A, HALF, t + 2);
;     WAIT_L(8); BAR; WAIT_L(0); MMA(0, 0, At, B0); BAR; SCHED;
;     LDB(B1, 1, 1); STAGE(SB(1, 0), Bt, 0, t + 3);
;     BAR; WAIT_L(0); MMA(0, 1, At, B1); BAR;
	v_readfirstlane_b32 s9, v147
	v_add_u32_e32 v164, 0x2000, v147
	v_lshl_add_u64 v[162:163], v[246:247], 0, s[48:49]
	s_mov_b32 m0, s9
	v_readfirstlane_b32 s9, v164
	global_load_lds_dwordx4 v[162:163], off
	v_lshl_add_u64 v[162:163], v[248:249], 0, s[48:49]
	s_mov_b32 m0, s9
	s_nop 0
	global_load_lds_dwordx4 v[162:163], off
	s_waitcnt vmcnt(6)
	s_barrier
	s_setprio 1
	v_mfma_f32_16x16x32_bf16 v[28:31], v[230:233], v[198:201], v[28:31]
	v_mfma_f32_16x16x32_bf16 v[24:27], v[238:241], v[198:201], v[24:27]
	v_mfma_f32_16x16x32_bf16 v[16:19], v[238:241], v[206:209], v[16:19]
	v_mfma_f32_16x16x32_bf16 v[20:23], v[230:233], v[206:209], v[20:23]
	v_mfma_f32_16x16x32_bf16 v[12:15], v[230:233], v[214:217], v[12:15]
	v_mfma_f32_16x16x32_bf16 v[8:11], v[238:241], v[214:217], v[8:11]
	v_mfma_f32_16x16x32_bf16 v[0:3], v[238:241], v[222:225], v[0:3]
	v_mfma_f32_16x16x32_bf16 v[4:7], v[230:233], v[222:225], v[4:7]
	v_mfma_f32_16x16x32_bf16 v[28:31], v[234:237], v[202:205], v[28:31]
	v_mfma_f32_16x16x32_bf16 v[24:27], v[242:245], v[202:205], v[24:27]
	v_mfma_f32_16x16x32_bf16 v[16:19], v[242:245], v[210:213], v[16:19]
	v_mfma_f32_16x16x32_bf16 v[20:23], v[234:237], v[210:213], v[20:23]
	v_mfma_f32_16x16x32_bf16 v[12:15], v[234:237], v[218:221], v[12:15]
	v_mfma_f32_16x16x32_bf16 v[8:11], v[242:245], v[218:221], v[8:11]
	v_mfma_f32_16x16x32_bf16 v[0:3], v[242:245], v[226:229], v[0:3]
	v_mfma_f32_16x16x32_bf16 v[4:7], v[234:237], v[226:229], v[4:7]
	s_setprio 0
	s_barrier
	ds_read_b128 v[162:165], v153
	ds_read_b128 v[166:169], v153 offset:1024
	ds_read_b128 v[170:173], v153 offset:2048
	ds_read_b128 v[174:177], v153 offset:3072
	v_add_u32_e32 v186, 0x4000, v146
	v_lshl_add_u64 v[230:231], v[178:179], 0, s[50:51]
	v_readfirstlane_b32 s9, v186
	v_add_u32_e32 v186, 0x6000, v146
	s_mov_b32 m0, s9
	v_readfirstlane_b32 s9, v186
	ds_read_b128 v[198:201], v151 offset:32768
	ds_read_b128 v[202:205], v151 offset:33792
	ds_read_b128 v[206:209], v150 offset:32768
	ds_read_b128 v[210:213], v150 offset:33792
	ds_read_b128 v[214:217], v149 offset:32768
	ds_read_b128 v[218:221], v149 offset:33792
	ds_read_b128 v[222:225], v148 offset:32768
	ds_read_b128 v[226:229], v148 offset:33792
	global_load_lds_dwordx4 v[230:231], off
	v_lshl_add_u64 v[230:231], v[188:189], 0, s[50:51]
	s_mov_b32 m0, s9
	s_nop 0
	global_load_lds_dwordx4 v[230:231], off
	s_waitcnt lgkmcnt(8)
	s_barrier
	s_waitcnt lgkmcnt(0)
	s_setprio 1
	s_waitcnt lgkmcnt(0)
	v_mfma_f32_16x16x32_bf16 v[124:127], v[162:165], v[198:201], v[124:127]
	v_mfma_f32_16x16x32_bf16 v[120:123], v[170:173], v[198:201], v[120:123]
	v_mfma_f32_16x16x32_bf16 v[112:115], v[170:173], v[206:209], v[112:115]
	v_mfma_f32_16x16x32_bf16 v[116:119], v[162:165], v[206:209], v[116:119]
	v_mfma_f32_16x16x32_bf16 v[108:111], v[162:165], v[214:217], v[108:111]
	v_mfma_f32_16x16x32_bf16 v[104:107], v[170:173], v[214:217], v[104:107]
	v_mfma_f32_16x16x32_bf16 v[96:99], v[170:173], v[222:225], v[96:99]
	v_mfma_f32_16x16x32_bf16 v[100:103], v[162:165], v[222:225], v[100:103]
	v_mfma_f32_16x16x32_bf16 v[124:127], v[166:169], v[202:205], v[124:127]
	v_mfma_f32_16x16x32_bf16 v[120:123], v[174:177], v[202:205], v[120:123]
	v_mfma_f32_16x16x32_bf16 v[112:115], v[174:177], v[210:213], v[112:115]
	v_mfma_f32_16x16x32_bf16 v[116:119], v[166:169], v[210:213], v[116:119]
	v_mfma_f32_16x16x32_bf16 v[108:111], v[166:169], v[218:221], v[108:111]
	v_mfma_f32_16x16x32_bf16 v[104:107], v[174:177], v[218:221], v[104:107]
	v_mfma_f32_16x16x32_bf16 v[96:99], v[174:177], v[226:229], v[96:99]
	v_mfma_f32_16x16x32_bf16 v[100:103], v[166:169], v[226:229], v[100:103]
	s_setprio 0
	s_barrier
	v_readfirstlane_b32 s9, v154
	v_add_u32_e32 v186, 0x2000, v154
	v_lshl_add_u64 v[250:251], v[246:247], 0, s[52:53]
	s_mov_b32 m0, s9
	v_readfirstlane_b32 s9, v186
	ds_read_b128 v[230:233], v152
	ds_read_b128 v[234:237], v152 offset:1024
	ds_read_b128 v[238:241], v152 offset:2048
	ds_read_b128 v[242:245], v152 offset:3072
	global_load_lds_dwordx4 v[250:251], off
	v_lshl_add_u64 v[250:251], v[248:249], 0, s[52:53]
	s_mov_b32 m0, s9
	s_nop 0
	global_load_lds_dwordx4 v[250:251], off
	s_barrier
	s_waitcnt lgkmcnt(0)
	s_setprio 1
	s_waitcnt lgkmcnt(0)
	v_mfma_f32_16x16x32_bf16 v[92:95], v[230:233], v[198:201], v[92:95]
	v_mfma_f32_16x16x32_bf16 v[88:91], v[238:241], v[198:201], v[88:91]
	v_mfma_f32_16x16x32_bf16 v[80:83], v[238:241], v[206:209], v[80:83]
	v_mfma_f32_16x16x32_bf16 v[84:87], v[230:233], v[206:209], v[84:87]
	v_mfma_f32_16x16x32_bf16 v[76:79], v[230:233], v[214:217], v[76:79]
	v_mfma_f32_16x16x32_bf16 v[72:75], v[238:241], v[214:217], v[72:75]
	v_mfma_f32_16x16x32_bf16 v[64:67], v[238:241], v[222:225], v[64:67]
	v_mfma_f32_16x16x32_bf16 v[68:71], v[230:233], v[222:225], v[68:71]
	v_mfma_f32_16x16x32_bf16 v[92:95], v[234:237], v[202:205], v[92:95]
	v_mfma_f32_16x16x32_bf16 v[88:91], v[242:245], v[202:205], v[88:91]
	v_mfma_f32_16x16x32_bf16 v[80:83], v[242:245], v[210:213], v[80:83]
	v_mfma_f32_16x16x32_bf16 v[84:87], v[234:237], v[210:213], v[84:87]
	v_mfma_f32_16x16x32_bf16 v[76:79], v[234:237], v[218:221], v[76:79]
	v_mfma_f32_16x16x32_bf16 v[72:75], v[242:245], v[218:221], v[72:75]
	v_mfma_f32_16x16x32_bf16 v[64:67], v[242:245], v[226:229], v[64:67]
	v_mfma_f32_16x16x32_bf16 v[68:71], v[234:237], v[226:229], v[68:71]
	s_setprio 0
	v_readfirstlane_b32 s9, v155
	v_lshl_add_u64 v[178:179], v[178:179], 0, s[54:55]
	s_mov_b32 m0, s9
	v_readfirstlane_b32 s9, v156
	s_barrier
; #define WAIT_V(n) asm volatile("s_waitcnt vmcnt(" #n ")" ::: "memory")
; #define WAIT_L(n) asm volatile("s_waitcnt lgkmcnt(" #n ")" ::: "memory")
; #define BAR __builtin_amdgcn_s_barrier()
; #define SCHED __builtin_amdgcn_sched_barrier(0)
; #define LDA(dst, b, h)                                                                            \
;   _Pragma("unroll") for (int m = 0; m < 4; ++m) _Pragma("unroll") for (int k = 0; k < 2; ++k)                                         \
;     dst[m][k] = *reinterpret_cast<const bf16x8*>((char*)SA(b, h) + lds_byte(wr * 64 + m * 16 + fr, k * 32 + fq * 8))
; #define LDB(dst, b, h)                                                                            \
;   _Pragma("unroll") for (int n = 0; n < 2; ++n) _Pragma("unroll") for (int k = 0; k < 2; ++k)                                         \
;     dst[n][k] = *reinterpret_cast<const bf16x8*>((char*)SB(b, h) + lds_byte(wc * 32 + n * 16 + fr, k * 32 + fq * 8))
; template <int K, bool SWAP>
; __device__ __forceinline__ void gemm_kloop(const bf16* __restrict__ A, const bf16* __restrict__ Bt,
;                                            f32x4 (&acc)[2][2][4][2], bool pref = false) {
;     ...
;     LDA(At, 1, 1); STAGE(SA(1, 0), A, 0, t + 3);
;     BAR; WAIT_L(0); MMA(1, 0, At, B0); BAR; SCHED;
;     STAGE(SB(1, 1), Bt, HALF, t + 3);
;     WAIT_V(6); BAR; MMA(1, 1, At, B1); BAR;
;   }
;   { LDB(B0, 0, 0); LDA(At, 0, 0); STAGE(SA(1, 1), A, HALF, nt - 1);
;     BAR; WAIT_L(0); MMA(0, 0, At, B0); BAR;
	ds_read_b128 v[198:201], v151 offset:49152
	ds_read_b128 v[202:205], v151 offset:50176
	ds_read_b128 v[206:209], v150 offset:49152
	ds_read_b128 v[210:213], v150 offset:50176
	ds_read_b128 v[214:217], v149 offset:49152
	ds_read_b128 v[218:221], v149 offset:50176
	ds_read_b128 v[222:225], v148 offset:49152
	ds_read_b128 v[226:229], v148 offset:50176
	global_load_lds_dwordx4 v[178:179], off
	v_lshl_add_u64 v[178:179], v[188:189], 0, s[54:55]
	s_mov_b32 m0, s9
	s_nop 0
	global_load_lds_dwordx4 v[178:179], off
	s_barrier
	s_waitcnt lgkmcnt(0)
	s_setprio 1
	s_waitcnt lgkmcnt(0)
	v_mfma_f32_16x16x32_bf16 v[60:63], v[162:165], v[198:201], v[60:63]
	v_mfma_f32_16x16x32_bf16 v[56:59], v[170:173], v[198:201], v[56:59]
	v_mfma_f32_16x16x32_bf16 v[48:51], v[170:173], v[206:209], v[48:51]
	v_mfma_f32_16x16x32_bf16 v[52:55], v[162:165], v[206:209], v[52:55]
	v_mfma_f32_16x16x32_bf16 v[44:47], v[162:165], v[214:217], v[44:47]
	v_mfma_f32_16x16x32_bf16 v[40:43], v[170:173], v[214:217], v[40:43]
	v_mfma_f32_16x16x32_bf16 v[32:35], v[170:173], v[222:225], v[32:35]
	v_mfma_f32_16x16x32_bf16 v[36:39], v[162:165], v[222:225], v[36:39]
	v_mfma_f32_16x16x32_bf16 v[60:63], v[166:169], v[202:205], v[60:63]
	v_mfma_f32_16x16x32_bf16 v[56:59], v[174:177], v[202:205], v[56:59]
	v_mfma_f32_16x16x32_bf16 v[48:51], v[174:177], v[210:213], v[48:51]
	v_mfma_f32_16x16x32_bf16 v[52:55], v[166:169], v[210:213], v[52:55]
	v_mfma_f32_16x16x32_bf16 v[44:47], v[166:169], v[218:221], v[44:47]
	v_mfma_f32_16x16x32_bf16 v[40:43], v[174:177], v[218:221], v[40:43]
	v_mfma_f32_16x16x32_bf16 v[32:35], v[174:177], v[226:229], v[32:35]
	v_mfma_f32_16x16x32_bf16 v[36:39], v[166:169], v[226:229], v[36:39]
	s_setprio 0
	s_barrier
	v_readfirstlane_b32 s9, v157
	v_add_u32_e32 v164, 0x2000, v157
	v_lshl_add_u64 v[162:163], v[246:247], 0, s[56:57]
	s_mov_b32 m0, s9
	v_readfirstlane_b32 s9, v164
	global_load_lds_dwordx4 v[162:163], off
	v_lshl_add_u64 v[162:163], v[248:249], 0, s[56:57]
	s_mov_b32 m0, s9
	s_nop 0
	global_load_lds_dwordx4 v[162:163], off
	s_waitcnt vmcnt(6)
	s_barrier
	s_setprio 1
	v_mfma_f32_16x16x32_bf16 v[28:31], v[230:233], v[198:201], v[28:31]
	v_mfma_f32_16x16x32_bf16 v[24:27], v[238:241], v[198:201], v[24:27]
	v_mfma_f32_16x16x32_bf16 v[16:19], v[238:241], v[206:209], v[16:19]
	v_mfma_f32_16x16x32_bf16 v[20:23], v[230:233], v[206:209], v[20:23]
	v_mfma_f32_16x16x32_bf16 v[12:15], v[230:233], v[214:217], v[12:15]
	v_mfma_f32_16x16x32_bf16 v[8:11], v[238:241], v[214:217], v[8:11]
	v_mfma_f32_16x16x32_bf16 v[0:3], v[238:241], v[222:225], v[0:3]
	v_mfma_f32_16x16x32_bf16 v[4:7], v[230:233], v[222:225], v[4:7]
	v_mfma_f32_16x16x32_bf16 v[28:31], v[234:237], v[202:205], v[28:31]
	v_mfma_f32_16x16x32_bf16 v[24:27], v[242:245], v[202:205], v[24:27]
	v_mfma_f32_16x16x32_bf16 v[16:19], v[242:245], v[210:213], v[16:19]
	v_mfma_f32_16x16x32_bf16 v[20:23], v[234:237], v[210:213], v[20:23]
	v_mfma_f32_16x16x32_bf16 v[12:15], v[234:237], v[218:221], v[12:15]
	v_mfma_f32_16x16x32_bf16 v[8:11], v[242:245], v[218:221], v[8:11]
	v_mfma_f32_16x16x32_bf16 v[0:3], v[242:245], v[226:229], v[0:3]
	v_mfma_f32_16x16x32_bf16 v[4:7], v[234:237], v[226:229], v[4:7]
	s_setprio 0
	s_add_i32 s8, s8, 2
	v_lshl_add_u64 v[136:137], v[136:137], 0, s[44:45]
	v_lshl_add_u64 v[138:139], v[138:139], 0, s[44:45]
	v_lshl_add_u64 v[140:141], v[140:141], 0, s[44:45]
	s_cmp_lt_u32 s8, 12
	v_lshl_add_u64 v[142:143], v[142:143], 0, s[44:45]
	s_barrier
	s_cbranch_scc1 .LBB0_527
	s_add_u32 s0, s0, 0x40780
	s_addc_u32 s1, s1, 0
	v_lshl_add_u64 v[130:131], s[0:1], 0, v[130:131]
	v_readfirstlane_b32 s8, v160
	v_lshl_add_u64 v[128:129], v[128:129], 1, v[130:131]
	s_mov_b32 m0, s8
	ds_read_b128 v[136:139], v159
	ds_read_b128 v[140:143], v159 offset:1024
	ds_read_b128 v[154:157], v159 offset:2048
	ds_read_b128 v[162:165], v159 offset:3072
	ds_read_b128 v[166:169], v151
	ds_read_b128 v[170:173], v151 offset:1024
	ds_read_b128 v[174:177], v150
	ds_read_b128 v[198:201], v150 offset:1024
	ds_read_b128 v[202:205], v149
	ds_read_b128 v[206:209], v149 offset:1024
	ds_read_b128 v[210:213], v148
	ds_read_b128 v[214:217], v148 offset:1024
	global_load_lds_dwordx4 v[128:129], off
	v_lshl_add_u64 v[128:129], s[0:1], 0, v[134:135]
	v_readfirstlane_b32 s0, v161
	v_lshl_add_u64 v[128:129], v[132:133], 1, v[128:129]
	s_mov_b32 m0, s0
	s_nop 0
	global_load_lds_dwordx4 v[128:129], off
	s_barrier
	s_waitcnt lgkmcnt(0)
	s_setprio 1
	s_waitcnt lgkmcnt(0)
	v_mfma_f32_16x16x32_bf16 v[124:127], v[136:139], v[166:169], v[124:127]
	v_mfma_f32_16x16x32_bf16 v[120:123], v[154:157], v[166:169], v[120:123]
	v_mfma_f32_16x16x32_bf16 v[112:115], v[154:157], v[174:177], v[112:115]
	v_mfma_f32_16x16x32_bf16 v[116:119], v[136:139], v[174:177], v[116:119]
	v_mfma_f32_16x16x32_bf16 v[108:111], v[136:139], v[202:205], v[108:111]
	v_mfma_f32_16x16x32_bf16 v[104:107], v[154:157], v[202:205], v[104:107]
	v_mfma_f32_16x16x32_bf16 v[96:99], v[154:157], v[210:213], v[96:99]
	v_mfma_f32_16x16x32_bf16 v[100:103], v[136:139], v[210:213], v[100:103]
	v_mfma_f32_16x16x32_bf16 v[124:127], v[140:143], v[170:173], v[124:127]
	v_mfma_f32_16x16x32_bf16 v[120:123], v[162:165], v[170:173], v[120:123]
	v_mfma_f32_16x16x32_bf16 v[112:115], v[162:165], v[198:201], v[112:115]
	v_mfma_f32_16x16x32_bf16 v[116:119], v[140:143], v[198:201], v[116:119]
	v_mfma_f32_16x16x32_bf16 v[108:111], v[140:143], v[206:209], v[108:111]
	v_mfma_f32_16x16x32_bf16 v[104:107], v[162:165], v[206:209], v[104:107]
	v_mfma_f32_16x16x32_bf16 v[96:99], v[162:165], v[214:217], v[96:99]
	v_mfma_f32_16x16x32_bf16 v[100:103], v[140:143], v[214:217], v[100:103]
	s_setprio 0
	s_barrier
; #define WAIT_V(n) asm volatile("s_waitcnt vmcnt(" #n ")" ::: "memory")
; #define WAIT_L(n) asm volatile("s_waitcnt lgkmcnt(" #n ")" ::: "memory")
; #define BAR __builtin_amdgcn_s_barrier()
; #define LDA(dst, b, h)                                                                            \
;   _Pragma("unroll") for (int m = 0; m < 4; ++m) _Pragma("unroll") for (int k = 0; k < 2; ++k)                                         \
;     dst[m][k] = *reinterpret_cast<const bf16x8*>((char*)SA(b, h) + lds_byte(wr * 64 + m * 16 + fr, k * 32 + fq * 8))
; #define LDB(dst, b, h)                                                                            \
;   _Pragma("unroll") for (int n = 0; n < 2; ++n) _Pragma("unroll") for (int k = 0; k < 2; ++k)                                         \
;     dst[n][k] = *reinterpret_cast<const bf16x8*>((char*)SB(b, h) + lds_byte(wc * 32 + n * 16 + fr, k * 32 + fq * 8))
; template <int K, bool SWAP>
; __device__ __forceinline__ void gemm_kloop(const bf16* __restrict__ A, const bf16* __restrict__ Bt,
;                                            f32x4 (&acc)[2][2][4][2], bool pref = false) {
;     ...
;     LDB(B1, 0, 1); BAR; WAIT_L(0); MMA(0, 1, At, B1); BAR;
;     LDA(At, 0, 1); WAIT_V(4); BAR; WAIT_L(0); MMA(1, 0, At, B0); MMA(1, 1, At, B1); BAR; }
;   { LDB(B0, 1, 0); LDA(At, 1, 0); WAIT_V(2); BAR; WAIT_L(0); MMA(0, 0, At, B0); BAR;
	ds_read_b128 v[128:131], v158
	ds_read_b128 v[132:135], v158 offset:1024
	ds_read_b128 v[218:221], v158 offset:2048
	ds_read_b128 v[158:161], v158 offset:3072
	s_barrier
	s_waitcnt lgkmcnt(0)
	s_setprio 1
	s_waitcnt lgkmcnt(0)
	v_mfma_f32_16x16x32_bf16 v[92:95], v[128:131], v[166:169], v[92:95]
	v_mfma_f32_16x16x32_bf16 v[88:91], v[218:221], v[166:169], v[88:91]
	v_mfma_f32_16x16x32_bf16 v[80:83], v[218:221], v[174:177], v[80:83]
	v_mfma_f32_16x16x32_bf16 v[76:79], v[128:131], v[202:205], v[76:79]
	v_mfma_f32_16x16x32_bf16 v[92:95], v[132:135], v[170:173], v[92:95]
	v_mfma_f32_16x16x32_bf16 v[88:91], v[158:161], v[170:173], v[88:91]
	v_mfma_f32_16x16x32_bf16 v[84:87], v[128:131], v[174:177], v[84:87]
	v_mfma_f32_16x16x32_bf16 v[80:83], v[158:161], v[198:201], v[80:83]
	v_mfma_f32_16x16x32_bf16 v[76:79], v[132:135], v[206:209], v[76:79]
	v_mfma_f32_16x16x32_bf16 v[72:75], v[218:221], v[202:205], v[72:75]
	v_mfma_f32_16x16x32_bf16 v[68:71], v[128:131], v[210:213], v[68:71]
	v_mfma_f32_16x16x32_bf16 v[64:67], v[218:221], v[210:213], v[64:67]
	v_mfma_f32_16x16x32_bf16 v[166:169], v[132:135], v[198:201], v[84:87]
	v_mfma_f32_16x16x32_bf16 v[170:173], v[158:161], v[206:209], v[72:75]
	v_mfma_f32_16x16x32_bf16 v[174:177], v[132:135], v[214:217], v[68:71]
	v_mfma_f32_16x16x32_bf16 v[198:201], v[158:161], v[214:217], v[64:67]
	s_setprio 0
	s_barrier
	s_nop 1
	ds_read_b128 v[64:67], v151 offset:16384
	ds_read_b128 v[68:71], v151 offset:17408
	ds_read_b128 v[72:75], v150 offset:16384
	ds_read_b128 v[84:87], v150 offset:17408
	ds_read_b128 v[202:205], v149 offset:16384
	ds_read_b128 v[206:209], v149 offset:17408
	ds_read_b128 v[210:213], v148 offset:16384
	ds_read_b128 v[214:217], v148 offset:17408
	s_waitcnt vmcnt(4)
	s_barrier
	s_waitcnt lgkmcnt(0)
	s_setprio 1
	s_waitcnt lgkmcnt(0)
	v_mfma_f32_16x16x32_bf16 v[60:63], v[136:139], v[64:67], v[60:63]
	v_mfma_f32_16x16x32_bf16 v[52:55], v[136:139], v[72:75], v[52:55]
	v_mfma_f32_16x16x32_bf16 v[40:43], v[154:157], v[202:205], v[40:43]
	v_mfma_f32_16x16x32_bf16 v[60:63], v[140:143], v[68:71], v[60:63]
	v_mfma_f32_16x16x32_bf16 v[56:59], v[154:157], v[64:67], v[56:59]
	v_mfma_f32_16x16x32_bf16 v[52:55], v[140:143], v[84:87], v[52:55]
	v_mfma_f32_16x16x32_bf16 v[48:51], v[154:157], v[72:75], v[48:51]
	v_mfma_f32_16x16x32_bf16 v[44:47], v[136:139], v[202:205], v[44:47]
	v_mfma_f32_16x16x32_bf16 v[40:43], v[162:165], v[206:209], v[40:43]
	v_mfma_f32_16x16x32_bf16 v[36:39], v[136:139], v[210:213], v[36:39]
	v_mfma_f32_16x16x32_bf16 v[32:35], v[154:157], v[210:213], v[32:35]
	v_mfma_f32_16x16x32_bf16 v[222:225], v[162:165], v[68:71], v[56:59]
	v_mfma_f32_16x16x32_bf16 v[226:229], v[162:165], v[84:87], v[48:51]
	v_mfma_f32_16x16x32_bf16 v[230:233], v[140:143], v[206:209], v[44:47]
	v_mfma_f32_16x16x32_bf16 v[136:139], v[140:143], v[214:217], v[36:39]
	v_mfma_f32_16x16x32_bf16 v[140:143], v[162:165], v[214:217], v[32:35]
	s_setprio 0
	s_setprio 1
	v_mfma_f32_16x16x32_bf16 v[20:23], v[128:131], v[72:75], v[20:23]
	v_mfma_f32_16x16x32_bf16 v[0:3], v[218:221], v[210:213], v[0:3]
	v_mfma_f32_16x16x32_bf16 v[28:31], v[128:131], v[64:67], v[28:31]
	v_mfma_f32_16x16x32_bf16 v[24:27], v[218:221], v[64:67], v[24:27]
	v_mfma_f32_16x16x32_bf16 v[20:23], v[132:135], v[84:87], v[20:23]
	v_mfma_f32_16x16x32_bf16 v[16:19], v[218:221], v[72:75], v[16:19]
	v_mfma_f32_16x16x32_bf16 v[12:15], v[128:131], v[202:205], v[12:15]
	v_mfma_f32_16x16x32_bf16 v[8:11], v[218:221], v[202:205], v[8:11]
	v_mfma_f32_16x16x32_bf16 v[4:7], v[128:131], v[210:213], v[4:7]
	v_mfma_f32_16x16x32_bf16 v[0:3], v[158:161], v[214:217], v[0:3]
	v_mfma_f32_16x16x32_bf16 v[154:157], v[132:135], v[68:71], v[28:31]
	v_mfma_f32_16x16x32_bf16 v[162:165], v[158:161], v[68:71], v[24:27]
	v_mfma_f32_16x16x32_bf16 v[234:237], v[158:161], v[84:87], v[16:19]
	v_mfma_f32_16x16x32_bf16 v[238:241], v[132:135], v[206:209], v[12:15]
	v_mfma_f32_16x16x32_bf16 v[202:205], v[158:161], v[206:209], v[8:11]
	v_mfma_f32_16x16x32_bf16 v[128:131], v[132:135], v[214:217], v[4:7]
	s_setprio 0
	s_barrier
	s_nop 0
	ds_read_b128 v[4:7], v153
	ds_read_b128 v[8:11], v153 offset:1024
	ds_read_b128 v[12:15], v153 offset:2048
	ds_read_b128 v[16:19], v153 offset:3072
	ds_read_b128 v[24:27], v151 offset:32768
	ds_read_b128 v[28:31], v151 offset:33792
	ds_read_b128 v[32:35], v150 offset:32768
	ds_read_b128 v[36:39], v150 offset:33792
	ds_read_b128 v[44:47], v149 offset:32768
	ds_read_b128 v[132:135], v149 offset:33792
	ds_read_b128 v[158:161], v148 offset:32768
	ds_read_b128 v[206:209], v148 offset:33792
	s_waitcnt vmcnt(2)
	s_barrier
; #define WAIT_V(n) asm volatile("s_waitcnt vmcnt(" #n ")" ::: "memory")
; #define WAIT_L(n) asm volatile("s_waitcnt lgkmcnt(" #n ")" ::: "memory")
; #define BAR __builtin_amdgcn_s_barrier()
; #define LDA(dst, b, h)                                                                            \
;   _Pragma("unroll") for (int m = 0; m < 4; ++m) _Pragma("unroll") for (int k = 0; k < 2; ++k)                                         \
;     dst[m][k] = *reinterpret_cast<const bf16x8*>((char*)SA(b, h) + lds_byte(wr * 64 + m * 16 + fr, k * 32 + fq * 8))
; #define LDB(dst, b, h)                                                                            \
;   _Pragma("unroll") for (int n = 0; n < 2; ++n) _Pragma("unroll") for (int k = 0; k < 2; ++k)                                         \
;     dst[n][k] = *reinterpret_cast<const bf16x8*>((char*)SB(b, h) + lds_byte(wc * 32 + n * 16 + fr, k * 32 + fq * 8))
; template <int K, bool SWAP>
; __device__ __forceinline__ void gemm_kloop(const bf16* __restrict__ A, const bf16* __restrict__ Bt,
;                                            f32x4 (&acc)[2][2][4][2], bool pref = false) {
;     ...
;   { LDB(B0, 1, 0); LDA(At, 1, 0); WAIT_V(2); BAR; WAIT_L(0); MMA(0, 0, At, B0); BAR;
;     LDB(B1, 1, 1); WAIT_V(0); BAR; WAIT_L(0); MMA(0, 1, At, B1); BAR;
;     LDA(At, 1, 1); BAR; WAIT_L(0); MMA(1, 0, At, B0); MMA(1, 1, At, B1); BAR; }
;   if (wr == 0) BAR;
	s_waitcnt lgkmcnt(0)
	s_setprio 1
	s_waitcnt lgkmcnt(0)
	v_mfma_f32_16x16x32_bf16 v[48:51], v[4:7], v[24:27], v[124:127]
	v_mfma_f32_16x16x32_bf16 v[124:127], v[8:11], v[28:31], v[48:51]
	v_mfma_f32_16x16x32_bf16 v[48:51], v[12:15], v[24:27], v[120:123]
	v_mfma_f32_16x16x32_bf16 v[84:87], v[16:19], v[28:31], v[48:51]
	v_mfma_f32_16x16x32_bf16 v[48:51], v[4:7], v[32:35], v[116:119]
	v_mfma_f32_16x16x32_bf16 v[120:123], v[8:11], v[36:39], v[48:51]
	v_mfma_f32_16x16x32_bf16 v[48:51], v[12:15], v[32:35], v[112:115]
	v_mfma_f32_16x16x32_bf16 v[72:75], v[16:19], v[36:39], v[48:51]
	v_mfma_f32_16x16x32_bf16 v[48:51], v[4:7], v[44:47], v[108:111]
	v_mfma_f32_16x16x32_bf16 v[112:115], v[8:11], v[132:135], v[48:51]
	v_mfma_f32_16x16x32_bf16 v[48:51], v[12:15], v[44:47], v[104:107]
	v_mfma_f32_16x16x32_bf16 v[68:71], v[16:19], v[132:135], v[48:51]
	v_mfma_f32_16x16x32_bf16 v[48:51], v[4:7], v[158:161], v[100:103]
	v_mfma_f32_16x16x32_bf16 v[104:107], v[8:11], v[206:209], v[48:51]
	v_mfma_f32_16x16x32_bf16 v[48:51], v[12:15], v[158:161], v[96:99]
	v_mfma_f32_16x16x32_bf16 v[64:67], v[16:19], v[206:209], v[48:51]
	s_setprio 0
	s_barrier
	ds_read_b128 v[210:213], v152
	ds_read_b128 v[214:217], v152 offset:1024
	ds_read_b128 v[218:221], v152 offset:2048
	ds_read_b128 v[242:245], v152 offset:3072
	s_waitcnt vmcnt(0)
	s_barrier
	s_waitcnt lgkmcnt(0)
	s_setprio 1
	s_waitcnt lgkmcnt(0)
	v_mfma_f32_16x16x32_bf16 v[48:51], v[210:213], v[24:27], v[92:95]
	v_mfma_f32_16x16x32_bf16 v[24:27], v[218:221], v[24:27], v[88:91]
	v_mfma_f32_16x16x32_bf16 v[56:59], v[242:245], v[28:31], v[24:27]
	v_mfma_f32_16x16x32_bf16 v[24:27], v[210:213], v[32:35], v[166:169]
	v_mfma_f32_16x16x32_bf16 v[108:111], v[214:217], v[36:39], v[24:27]
	v_mfma_f32_16x16x32_bf16 v[24:27], v[218:221], v[32:35], v[80:83]
	v_mfma_f32_16x16x32_bf16 v[116:119], v[214:217], v[28:31], v[48:51]
	v_mfma_f32_16x16x32_bf16 v[48:51], v[242:245], v[36:39], v[24:27]
	v_mfma_f32_16x16x32_bf16 v[24:27], v[210:213], v[44:47], v[76:79]
	v_mfma_f32_16x16x32_bf16 v[100:103], v[214:217], v[132:135], v[24:27]
	v_mfma_f32_16x16x32_bf16 v[24:27], v[218:221], v[44:47], v[170:173]
	v_mfma_f32_16x16x32_bf16 v[44:47], v[242:245], v[132:135], v[24:27]
	v_mfma_f32_16x16x32_bf16 v[24:27], v[210:213], v[158:161], v[174:177]
	v_mfma_f32_16x16x32_bf16 v[96:99], v[214:217], v[206:209], v[24:27]
	v_mfma_f32_16x16x32_bf16 v[24:27], v[218:221], v[158:161], v[198:201]
	v_mfma_f32_16x16x32_bf16 v[36:39], v[242:245], v[206:209], v[24:27]
	s_setprio 0
	s_barrier
	ds_read_b128 v[132:135], v151 offset:49152
	ds_read_b128 v[158:161], v151 offset:50176
	ds_read_b128 v[166:169], v150 offset:49152
	ds_read_b128 v[150:153], v150 offset:50176
	ds_read_b128 v[170:173], v149 offset:49152
	ds_read_b128 v[174:177], v149 offset:50176
	ds_read_b128 v[198:201], v148 offset:49152
	ds_read_b128 v[146:149], v148 offset:50176
	s_barrier
	s_waitcnt lgkmcnt(0)
	s_setprio 1
	s_waitcnt lgkmcnt(0)
	v_mfma_f32_16x16x32_bf16 v[24:27], v[4:7], v[132:135], v[60:63]
	v_mfma_f32_16x16x32_bf16 v[92:95], v[8:11], v[158:161], v[24:27]
	v_mfma_f32_16x16x32_bf16 v[24:27], v[12:15], v[132:135], v[222:225]
	v_mfma_f32_16x16x32_bf16 v[32:35], v[16:19], v[158:161], v[24:27]
	v_mfma_f32_16x16x32_bf16 v[24:27], v[4:7], v[166:169], v[52:55]
	v_mfma_f32_16x16x32_bf16 v[88:91], v[8:11], v[150:153], v[24:27]
	v_mfma_f32_16x16x32_bf16 v[24:27], v[12:15], v[166:169], v[226:229]
	v_mfma_f32_16x16x32_bf16 v[28:31], v[16:19], v[150:153], v[24:27]
	v_mfma_f32_16x16x32_bf16 v[24:27], v[4:7], v[170:173], v[230:233]
	v_mfma_f32_16x16x32_bf16 v[4:7], v[4:7], v[198:201], v[136:139]
	v_mfma_f32_16x16x32_bf16 v[76:79], v[8:11], v[174:177], v[24:27]
	v_mfma_f32_16x16x32_bf16 v[24:27], v[12:15], v[170:173], v[40:43]
	v_mfma_f32_16x16x32_bf16 v[52:55], v[8:11], v[146:149], v[4:7]
	v_mfma_f32_16x16x32_bf16 v[4:7], v[12:15], v[198:201], v[140:143]
	v_mfma_f32_16x16x32_bf16 v[24:27], v[16:19], v[174:177], v[24:27]
	v_mfma_f32_16x16x32_bf16 v[16:19], v[16:19], v[146:149], v[4:7]
	s_setprio 0
	s_setprio 1
	v_mfma_f32_16x16x32_bf16 v[4:7], v[210:213], v[132:135], v[154:157]
	v_mfma_f32_16x16x32_bf16 v[80:83], v[214:217], v[158:161], v[4:7]
	v_mfma_f32_16x16x32_bf16 v[4:7], v[218:221], v[132:135], v[162:165]
	v_mfma_f32_16x16x32_bf16 v[12:15], v[242:245], v[158:161], v[4:7]
	v_mfma_f32_16x16x32_bf16 v[4:7], v[210:213], v[166:169], v[20:23]
	v_mfma_f32_16x16x32_bf16 v[60:63], v[214:217], v[150:153], v[4:7]
	v_mfma_f32_16x16x32_bf16 v[4:7], v[218:221], v[166:169], v[234:237]
	v_mfma_f32_16x16x32_bf16 v[8:11], v[242:245], v[150:153], v[4:7]
	v_mfma_f32_16x16x32_bf16 v[4:7], v[210:213], v[170:173], v[238:241]
	v_mfma_f32_16x16x32_bf16 v[40:43], v[214:217], v[174:177], v[4:7]
	v_mfma_f32_16x16x32_bf16 v[4:7], v[218:221], v[170:173], v[202:205]
	v_mfma_f32_16x16x32_bf16 v[20:23], v[210:213], v[198:201], v[128:131]
	v_mfma_f32_16x16x32_bf16 v[0:3], v[218:221], v[198:201], v[0:3]
	v_mfma_f32_16x16x32_bf16 v[4:7], v[242:245], v[174:177], v[4:7]
	v_mfma_f32_16x16x32_bf16 v[20:23], v[214:217], v[146:149], v[20:23]
	v_mfma_f32_16x16x32_bf16 v[0:3], v[242:245], v[146:149], v[0:3]
	s_setprio 0
	s_movk_i32 s0, 0x100
	v_cmp_gt_u32_e32 vcc, s0, v144
	s_barrier
	s_and_saveexec_b64 s[0:1], vcc
	s_cbranch_execz .LBB0_530
	s_barrier

; #define WAIT_L(n) asm volatile("s_waitcnt lgkmcnt(" #n ")" ::: "memory")
; #define BAR __builtin_amdgcn_s_barrier()
; #define SCHED __builtin_amdgcn_sched_barrier(0)
; #define LDA(dst, b, h)                                                                            \
;   _Pragma("unroll") for (int m = 0; m < 4; ++m) _Pragma("unroll") for (int k = 0; k < 2; ++k)                                         \
;     dst[m][k] = *reinterpret_cast<const bf16x8*>((char*)SA(b, h) + lds_byte(wr * 64 + m * 16 + fr, k * 32 + fq * 8))
; #define LDB(dst, b, h)                                                                            \
;   _Pragma("unroll") for (int n = 0; n < 2; ++n) _Pragma("unroll") for (int k = 0; k < 2; ++k)                                         \
;     dst[n][k] = *reinterpret_cast<const bf16x8*>((char*)SB(b, h) + lds_byte(wc * 32 + n * 16 + fr, k * 32 + fq * 8))
; template <int K, bool SWAP>
; __device__ __forceinline__ void gemm_kloop(const bf16* __restrict__ A, const bf16* __restrict__ Bt,
;                                            f32x4 (&acc)[2][2][4][2], bool pref = false) {
;     ...
;     LDB(B0, 0, 0); SCHED; LDA(At, 0, 0); STAGE(SA(1, 1), A, HALF, t + 1);
;     WAIT_L(8); BAR; WAIT_L(0); MMA(0, 0, At, B0); BAR; SCHED;
;     LDB(B1, 0, 1); STAGE(SB(0, 0), Bt, 0, t + 2);
;     BAR; WAIT_L(0); MMA(0, 1, At, B1); BAR;
;     LDA(At, 0, 1); STAGE(SA(0, 0), A, 0, t + 2);
;     BAR; WAIT_L(0); MMA(1, 0, At, B0); BAR; SCHED;
.LBB0_542:
	ds_read_b128 v[162:165], v159
	ds_read_b128 v[166:169], v159 offset:1024
	ds_read_b128 v[170:173], v159 offset:2048
	ds_read_b128 v[174:177], v159 offset:3072
	v_add_u32_e32 v160, 0xc000, v146
	v_lshl_add_u64 v[178:179], s[58:59], 0, v[140:141]
	v_readfirstlane_b32 s5, v160
	v_lshl_add_u64 v[188:189], v[178:179], 0, s[42:43]
	s_mov_b32 m0, s5
	v_add_u32_e32 v161, 0xe000, v146
	ds_read_b128 v[198:201], v151
	ds_read_b128 v[202:205], v151 offset:1024
	ds_read_b128 v[206:209], v150
	ds_read_b128 v[210:213], v150 offset:1024
	ds_read_b128 v[214:217], v149
	ds_read_b128 v[218:221], v149 offset:1024
	ds_read_b128 v[222:225], v148
	ds_read_b128 v[226:229], v148 offset:1024
	global_load_lds_dwordx4 v[188:189], off
	v_lshl_add_u64 v[188:189], s[58:59], 0, v[142:143]
	v_readfirstlane_b32 s5, v161
	v_lshl_add_u64 v[230:231], v[188:189], 0, s[42:43]
	s_mov_b32 m0, s5
	s_nop 0
	global_load_lds_dwordx4 v[230:231], off
	s_waitcnt lgkmcnt(8)
	s_barrier
	s_waitcnt lgkmcnt(0)
	s_setprio 1
	s_waitcnt lgkmcnt(0)
	v_mfma_f32_16x16x32_bf16 v[124:127], v[162:165], v[198:201], v[124:127]
	v_mfma_f32_16x16x32_bf16 v[120:123], v[170:173], v[198:201], v[120:123]
	v_mfma_f32_16x16x32_bf16 v[112:115], v[170:173], v[206:209], v[112:115]
	v_mfma_f32_16x16x32_bf16 v[116:119], v[162:165], v[206:209], v[116:119]
	v_mfma_f32_16x16x32_bf16 v[108:111], v[162:165], v[214:217], v[108:111]
	v_mfma_f32_16x16x32_bf16 v[104:107], v[170:173], v[214:217], v[104:107]
	v_mfma_f32_16x16x32_bf16 v[96:99], v[170:173], v[222:225], v[96:99]
	v_mfma_f32_16x16x32_bf16 v[100:103], v[162:165], v[222:225], v[100:103]
	v_mfma_f32_16x16x32_bf16 v[124:127], v[166:169], v[202:205], v[124:127]
	v_mfma_f32_16x16x32_bf16 v[120:123], v[174:177], v[202:205], v[120:123]
	v_mfma_f32_16x16x32_bf16 v[112:115], v[174:177], v[210:213], v[112:115]
	v_mfma_f32_16x16x32_bf16 v[116:119], v[166:169], v[210:213], v[116:119]
	v_mfma_f32_16x16x32_bf16 v[108:111], v[166:169], v[218:221], v[108:111]
	v_mfma_f32_16x16x32_bf16 v[104:107], v[174:177], v[218:221], v[104:107]
	v_mfma_f32_16x16x32_bf16 v[96:99], v[174:177], v[226:229], v[96:99]
	v_mfma_f32_16x16x32_bf16 v[100:103], v[166:169], v[226:229], v[100:103]
	s_setprio 0
	s_barrier
	v_add_u32_e32 v186, s8, v145
	v_lshl_add_u64 v[246:247], s[58:59], 0, v[136:137]
	v_readfirstlane_b32 s5, v186
	v_lshl_add_u64 v[248:249], v[246:247], 0, s[44:45]
	s_mov_b32 m0, s5
	v_add_u32_e32 v186, 0x2000, v186
	ds_read_b128 v[230:233], v158
	ds_read_b128 v[234:237], v158 offset:1024
	ds_read_b128 v[238:241], v158 offset:2048
	ds_read_b128 v[242:245], v158 offset:3072
	global_load_lds_dwordx4 v[248:249], off
	v_lshl_add_u64 v[248:249], s[58:59], 0, v[138:139]
	v_readfirstlane_b32 s5, v186
	v_lshl_add_u64 v[250:251], v[248:249], 0, s[44:45]
	s_mov_b32 m0, s5
	s_nop 0
	global_load_lds_dwordx4 v[250:251], off
	s_barrier
	s_waitcnt lgkmcnt(0)
	s_setprio 1
	s_waitcnt lgkmcnt(0)
	v_mfma_f32_16x16x32_bf16 v[92:95], v[230:233], v[198:201], v[92:95]
	v_mfma_f32_16x16x32_bf16 v[88:91], v[238:241], v[198:201], v[88:91]
	v_mfma_f32_16x16x32_bf16 v[80:83], v[238:241], v[206:209], v[80:83]
	v_mfma_f32_16x16x32_bf16 v[84:87], v[230:233], v[206:209], v[84:87]
	v_mfma_f32_16x16x32_bf16 v[76:79], v[230:233], v[214:217], v[76:79]
	v_mfma_f32_16x16x32_bf16 v[72:75], v[238:241], v[214:217], v[72:75]
	v_mfma_f32_16x16x32_bf16 v[64:67], v[238:241], v[222:225], v[64:67]
	v_mfma_f32_16x16x32_bf16 v[68:71], v[230:233], v[222:225], v[68:71]
	v_mfma_f32_16x16x32_bf16 v[92:95], v[234:237], v[202:205], v[92:95]
	v_mfma_f32_16x16x32_bf16 v[88:91], v[242:245], v[202:205], v[88:91]
	v_mfma_f32_16x16x32_bf16 v[80:83], v[242:245], v[210:213], v[80:83]
	v_mfma_f32_16x16x32_bf16 v[84:87], v[234:237], v[210:213], v[84:87]
	v_mfma_f32_16x16x32_bf16 v[76:79], v[234:237], v[218:221], v[76:79]
	v_mfma_f32_16x16x32_bf16 v[72:75], v[242:245], v[218:221], v[72:75]
	v_mfma_f32_16x16x32_bf16 v[64:67], v[242:245], v[226:229], v[64:67]
	v_mfma_f32_16x16x32_bf16 v[68:71], v[234:237], v[226:229], v[68:71]
	s_setprio 0
	v_readfirstlane_b32 s5, v146
	v_add_u32_e32 v186, 0x2000, v146
	v_lshl_add_u64 v[250:251], v[178:179], 0, s[46:47]
	s_mov_b32 m0, s5
	v_readfirstlane_b32 s5, v186
	s_barrier
	ds_read_b128 v[198:201], v151 offset:16384
	ds_read_b128 v[202:205], v151 offset:17408
	ds_read_b128 v[206:209], v150 offset:16384
	ds_read_b128 v[210:213], v150 offset:17408
	ds_read_b128 v[214:217], v149 offset:16384
	ds_read_b128 v[218:221], v149 offset:17408
	ds_read_b128 v[222:225], v148 offset:16384
	ds_read_b128 v[226:229], v148 offset:17408
	global_load_lds_dwordx4 v[250:251], off
	v_lshl_add_u64 v[250:251], v[188:189], 0, s[46:47]
	s_mov_b32 m0, s5
	s_nop 0
	global_load_lds_dwordx4 v[250:251], off
	s_barrier
	s_waitcnt lgkmcnt(0)
	s_setprio 1
	s_waitcnt lgkmcnt(0)
	v_mfma_f32_16x16x32_bf16 v[60:63], v[162:165], v[198:201], v[60:63]
	v_mfma_f32_16x16x32_bf16 v[56:59], v[170:173], v[198:201], v[56:59]
	v_mfma_f32_16x16x32_bf16 v[48:51], v[170:173], v[206:209], v[48:51]
	v_mfma_f32_16x16x32_bf16 v[52:55], v[162:165], v[206:209], v[52:55]
	v_mfma_f32_16x16x32_bf16 v[44:47], v[162:165], v[214:217], v[44:47]
	v_mfma_f32_16x16x32_bf16 v[40:43], v[170:173], v[214:217], v[40:43]
	v_mfma_f32_16x16x32_bf16 v[32:35], v[170:173], v[222:225], v[32:35]
	v_mfma_f32_16x16x32_bf16 v[36:39], v[162:165], v[222:225], v[36:39]
	v_mfma_f32_16x16x32_bf16 v[60:63], v[166:169], v[202:205], v[60:63]
	v_mfma_f32_16x16x32_bf16 v[56:59], v[174:177], v[202:205], v[56:59]
	v_mfma_f32_16x16x32_bf16 v[48:51], v[174:177], v[210:213], v[48:51]
	v_mfma_f32_16x16x32_bf16 v[52:55], v[166:169], v[210:213], v[52:55]
	v_mfma_f32_16x16x32_bf16 v[44:47], v[166:169], v[218:221], v[44:47]
	v_mfma_f32_16x16x32_bf16 v[40:43], v[174:177], v[218:221], v[40:43]
	v_mfma_f32_16x16x32_bf16 v[32:35], v[174:177], v[226:229], v[32:35]
	v_mfma_f32_16x16x32_bf16 v[36:39], v[166:169], v[226:229], v[36:39]
	s_setprio 0
	s_barrier
; #define WAIT_V(n) asm volatile("s_waitcnt vmcnt(" #n ")" ::: "memory")
; #define WAIT_L(n) asm volatile("s_waitcnt lgkmcnt(" #n ")" ::: "memory")
; #define BAR __builtin_amdgcn_s_barrier()
; #define SCHED __builtin_amdgcn_sched_barrier(0)
; #define LDA(dst, b, h)                                                                            \
;   _Pragma("unroll") for (int m = 0; m < 4; ++m) _Pragma("unroll") for (int k = 0; k < 2; ++k)                                         \
;     dst[m][k] = *reinterpret_cast<const bf16x8*>((char*)SA(b, h) + lds_byte(wr * 64 + m * 16 + fr, k * 32 + fq * 8))
; #define LDB(dst, b, h)                                                                            \
;   _Pragma("unroll") for (int n = 0; n < 2; ++n) _Pragma("unroll") for (int k = 0; k < 2; ++k)                                         \
;     dst[n][k] = *reinterpret_cast<const bf16x8*>((char*)SB(b, h) + lds_byte(wc * 32 + n * 16 + fr, k * 32 + fq * 8))
; template <int K, bool SWAP>
; __device__ __forceinline__ void gemm_kloop(const bf16* __restrict__ A, const bf16* __restrict__ Bt,
;                                            f32x4 (&acc)[2][2][4][2], bool pref = false) {
;     ...
;     STAGE(SB(0, 1), Bt, HALF, t + 2);
;     WAIT_V(6); BAR; MMA(1, 1, At, B1); BAR;
;     LDB(B0, 1, 0); SCHED; LDA(At, 1, 0); STAGE(SA(0, 1), A, HALF, t + 2);
;     WAIT_L(8); BAR; WAIT_L(0); MMA(0, 0, At, B0); BAR; SCHED;
;     LDB(B1, 1, 1); STAGE(SB(1, 0), Bt, 0, t + 3);
;     BAR; WAIT_L(0); MMA(0, 1, At, B1); BAR;
	v_readfirstlane_b32 s5, v147
	v_add_u32_e32 v164, 0x2000, v147
	v_lshl_add_u64 v[162:163], v[246:247], 0, s[48:49]
	s_mov_b32 m0, s5
	v_readfirstlane_b32 s5, v164
	global_load_lds_dwordx4 v[162:163], off
	v_lshl_add_u64 v[162:163], v[248:249], 0, s[48:49]
	s_mov_b32 m0, s5
	s_nop 0
	global_load_lds_dwordx4 v[162:163], off
	s_waitcnt vmcnt(6)
	s_barrier
	s_setprio 1
	v_mfma_f32_16x16x32_bf16 v[28:31], v[230:233], v[198:201], v[28:31]
	v_mfma_f32_16x16x32_bf16 v[24:27], v[238:241], v[198:201], v[24:27]
	v_mfma_f32_16x16x32_bf16 v[16:19], v[238:241], v[206:209], v[16:19]
	v_mfma_f32_16x16x32_bf16 v[20:23], v[230:233], v[206:209], v[20:23]
	v_mfma_f32_16x16x32_bf16 v[12:15], v[230:233], v[214:217], v[12:15]
	v_mfma_f32_16x16x32_bf16 v[8:11], v[238:241], v[214:217], v[8:11]
	v_mfma_f32_16x16x32_bf16 v[0:3], v[238:241], v[222:225], v[0:3]
	v_mfma_f32_16x16x32_bf16 v[4:7], v[230:233], v[222:225], v[4:7]
	v_mfma_f32_16x16x32_bf16 v[28:31], v[234:237], v[202:205], v[28:31]
	v_mfma_f32_16x16x32_bf16 v[24:27], v[242:245], v[202:205], v[24:27]
	v_mfma_f32_16x16x32_bf16 v[16:19], v[242:245], v[210:213], v[16:19]
	v_mfma_f32_16x16x32_bf16 v[20:23], v[234:237], v[210:213], v[20:23]
	v_mfma_f32_16x16x32_bf16 v[12:15], v[234:237], v[218:221], v[12:15]
	v_mfma_f32_16x16x32_bf16 v[8:11], v[242:245], v[218:221], v[8:11]
	v_mfma_f32_16x16x32_bf16 v[0:3], v[242:245], v[226:229], v[0:3]
	v_mfma_f32_16x16x32_bf16 v[4:7], v[234:237], v[226:229], v[4:7]
	s_setprio 0
	s_barrier
	ds_read_b128 v[162:165], v153
	ds_read_b128 v[166:169], v153 offset:1024
	ds_read_b128 v[170:173], v153 offset:2048
	ds_read_b128 v[174:177], v153 offset:3072
	v_add_u32_e32 v186, 0x4000, v146
	v_lshl_add_u64 v[230:231], v[178:179], 0, s[50:51]
	v_readfirstlane_b32 s5, v186
	v_add_u32_e32 v186, 0x6000, v146
	s_mov_b32 m0, s5
	v_readfirstlane_b32 s5, v186
	ds_read_b128 v[198:201], v151 offset:32768
	ds_read_b128 v[202:205], v151 offset:33792
	ds_read_b128 v[206:209], v150 offset:32768
	ds_read_b128 v[210:213], v150 offset:33792
	ds_read_b128 v[214:217], v149 offset:32768
	ds_read_b128 v[218:221], v149 offset:33792
	ds_read_b128 v[222:225], v148 offset:32768
	ds_read_b128 v[226:229], v148 offset:33792
	global_load_lds_dwordx4 v[230:231], off
	v_lshl_add_u64 v[230:231], v[188:189], 0, s[50:51]
	s_mov_b32 m0, s5
	s_nop 0
	global_load_lds_dwordx4 v[230:231], off
	s_waitcnt lgkmcnt(8)
	s_barrier
	s_waitcnt lgkmcnt(0)
	s_setprio 1
	s_waitcnt lgkmcnt(0)
	v_mfma_f32_16x16x32_bf16 v[124:127], v[162:165], v[198:201], v[124:127]
	v_mfma_f32_16x16x32_bf16 v[120:123], v[170:173], v[198:201], v[120:123]
	v_mfma_f32_16x16x32_bf16 v[112:115], v[170:173], v[206:209], v[112:115]
	v_mfma_f32_16x16x32_bf16 v[116:119], v[162:165], v[206:209], v[116:119]
	v_mfma_f32_16x16x32_bf16 v[108:111], v[162:165], v[214:217], v[108:111]
	v_mfma_f32_16x16x32_bf16 v[104:107], v[170:173], v[214:217], v[104:107]
	v_mfma_f32_16x16x32_bf16 v[96:99], v[170:173], v[222:225], v[96:99]
	v_mfma_f32_16x16x32_bf16 v[100:103], v[162:165], v[222:225], v[100:103]
	v_mfma_f32_16x16x32_bf16 v[124:127], v[166:169], v[202:205], v[124:127]
	v_mfma_f32_16x16x32_bf16 v[120:123], v[174:177], v[202:205], v[120:123]
	v_mfma_f32_16x16x32_bf16 v[112:115], v[174:177], v[210:213], v[112:115]
	v_mfma_f32_16x16x32_bf16 v[116:119], v[166:169], v[210:213], v[116:119]
	v_mfma_f32_16x16x32_bf16 v[108:111], v[166:169], v[218:221], v[108:111]
	v_mfma_f32_16x16x32_bf16 v[104:107], v[174:177], v[218:221], v[104:107]
	v_mfma_f32_16x16x32_bf16 v[96:99], v[174:177], v[226:229], v[96:99]
	v_mfma_f32_16x16x32_bf16 v[100:103], v[166:169], v[226:229], v[100:103]
	s_setprio 0
	s_barrier
	v_readfirstlane_b32 s5, v154
	v_add_u32_e32 v186, 0x2000, v154
	v_lshl_add_u64 v[250:251], v[246:247], 0, s[52:53]
	s_mov_b32 m0, s5
	v_readfirstlane_b32 s5, v186
	ds_read_b128 v[230:233], v152
	ds_read_b128 v[234:237], v152 offset:1024
	ds_read_b128 v[238:241], v152 offset:2048
	ds_read_b128 v[242:245], v152 offset:3072
	global_load_lds_dwordx4 v[250:251], off
	v_lshl_add_u64 v[250:251], v[248:249], 0, s[52:53]
	s_mov_b32 m0, s5
	s_nop 0
	global_load_lds_dwordx4 v[250:251], off
	s_barrier
	s_waitcnt lgkmcnt(0)
	s_setprio 1
	s_waitcnt lgkmcnt(0)
	v_mfma_f32_16x16x32_bf16 v[92:95], v[230:233], v[198:201], v[92:95]
	v_mfma_f32_16x16x32_bf16 v[88:91], v[238:241], v[198:201], v[88:91]
	v_mfma_f32_16x16x32_bf16 v[80:83], v[238:241], v[206:209], v[80:83]
	v_mfma_f32_16x16x32_bf16 v[84:87], v[230:233], v[206:209], v[84:87]
	v_mfma_f32_16x16x32_bf16 v[76:79], v[230:233], v[214:217], v[76:79]
	v_mfma_f32_16x16x32_bf16 v[72:75], v[238:241], v[214:217], v[72:75]
	v_mfma_f32_16x16x32_bf16 v[64:67], v[238:241], v[222:225], v[64:67]
	v_mfma_f32_16x16x32_bf16 v[68:71], v[230:233], v[222:225], v[68:71]
	v_mfma_f32_16x16x32_bf16 v[92:95], v[234:237], v[202:205], v[92:95]
	v_mfma_f32_16x16x32_bf16 v[88:91], v[242:245], v[202:205], v[88:91]
	v_mfma_f32_16x16x32_bf16 v[80:83], v[242:245], v[210:213], v[80:83]
	v_mfma_f32_16x16x32_bf16 v[84:87], v[234:237], v[210:213], v[84:87]
	v_mfma_f32_16x16x32_bf16 v[76:79], v[234:237], v[218:221], v[76:79]
	v_mfma_f32_16x16x32_bf16 v[72:75], v[242:245], v[218:221], v[72:75]
	v_mfma_f32_16x16x32_bf16 v[64:67], v[242:245], v[226:229], v[64:67]
	v_mfma_f32_16x16x32_bf16 v[68:71], v[234:237], v[226:229], v[68:71]
	s_setprio 0
	v_readfirstlane_b32 s5, v155
	v_lshl_add_u64 v[178:179], v[178:179], 0, s[54:55]
	s_mov_b32 m0, s5
	v_readfirstlane_b32 s5, v156
	s_barrier
; #define WAIT_V(n) asm volatile("s_waitcnt vmcnt(" #n ")" ::: "memory")
; #define WAIT_L(n) asm volatile("s_waitcnt lgkmcnt(" #n ")" ::: "memory")
; #define BAR __builtin_amdgcn_s_barrier()
; #define SCHED __builtin_amdgcn_sched_barrier(0)
; #define LDA(dst, b, h)                                                                            \
;   _Pragma("unroll") for (int m = 0; m < 4; ++m) _Pragma("unroll") for (int k = 0; k < 2; ++k)                                         \
;     dst[m][k] = *reinterpret_cast<const bf16x8*>((char*)SA(b, h) + lds_byte(wr * 64 + m * 16 + fr, k * 32 + fq * 8))
; #define LDB(dst, b, h)                                                                            \
;   _Pragma("unroll") for (int n = 0; n < 2; ++n) _Pragma("unroll") for (int k = 0; k < 2; ++k)                                         \
;     dst[n][k] = *reinterpret_cast<const bf16x8*>((char*)SB(b, h) + lds_byte(wc * 32 + n * 16 + fr, k * 32 + fq * 8))
; template <int K, bool SWAP>
; __device__ __forceinline__ void gemm_kloop(const bf16* __restrict__ A, const bf16* __restrict__ Bt,
;                                            f32x4 (&acc)[2][2][4][2], bool pref = false) {
;     ...
;     LDA(At, 1, 1); STAGE(SA(1, 0), A, 0, t + 3);
;     BAR; WAIT_L(0); MMA(1, 0, At, B0); BAR; SCHED;
;     STAGE(SB(1, 1), Bt, HALF, t + 3);
;     WAIT_V(6); BAR; MMA(1, 1, At, B1); BAR;
;   }
;   { LDB(B0, 0, 0); LDA(At, 0, 0); STAGE(SA(1, 1), A, HALF, nt - 1);
;     BAR; WAIT_L(0); MMA(0, 0, At, B0); BAR;
;     LDB(B1, 0, 1); BAR; WAIT_L(0); MMA(0, 1, At, B1); BAR;
;     LDA(At, 0, 1); WAIT_V(4); BAR; WAIT_L(0); MMA(1, 0, At, B0); MMA(1, 1, At, B1); BAR; }
	ds_read_b128 v[198:201], v151 offset:49152
	ds_read_b128 v[202:205], v151 offset:50176
	ds_read_b128 v[206:209], v150 offset:49152
	ds_read_b128 v[210:213], v150 offset:50176
	ds_read_b128 v[214:217], v149 offset:49152
	ds_read_b128 v[218:221], v149 offset:50176
	ds_read_b128 v[222:225], v148 offset:49152
	ds_read_b128 v[226:229], v148 offset:50176
	global_load_lds_dwordx4 v[178:179], off
	v_lshl_add_u64 v[178:179], v[188:189], 0, s[54:55]
	s_mov_b32 m0, s5
	s_nop 0
	global_load_lds_dwordx4 v[178:179], off
	s_barrier
	s_waitcnt lgkmcnt(0)
	s_setprio 1
	s_waitcnt lgkmcnt(0)
	v_mfma_f32_16x16x32_bf16 v[60:63], v[162:165], v[198:201], v[60:63]
	v_mfma_f32_16x16x32_bf16 v[56:59], v[170:173], v[198:201], v[56:59]
	v_mfma_f32_16x16x32_bf16 v[48:51], v[170:173], v[206:209], v[48:51]
	v_mfma_f32_16x16x32_bf16 v[52:55], v[162:165], v[206:209], v[52:55]
	v_mfma_f32_16x16x32_bf16 v[44:47], v[162:165], v[214:217], v[44:47]
	v_mfma_f32_16x16x32_bf16 v[40:43], v[170:173], v[214:217], v[40:43]
	v_mfma_f32_16x16x32_bf16 v[32:35], v[170:173], v[222:225], v[32:35]
	v_mfma_f32_16x16x32_bf16 v[36:39], v[162:165], v[222:225], v[36:39]
	v_mfma_f32_16x16x32_bf16 v[60:63], v[166:169], v[202:205], v[60:63]
	v_mfma_f32_16x16x32_bf16 v[56:59], v[174:177], v[202:205], v[56:59]
	v_mfma_f32_16x16x32_bf16 v[48:51], v[174:177], v[210:213], v[48:51]
	v_mfma_f32_16x16x32_bf16 v[52:55], v[166:169], v[210:213], v[52:55]
	v_mfma_f32_16x16x32_bf16 v[44:47], v[166:169], v[218:221], v[44:47]
	v_mfma_f32_16x16x32_bf16 v[40:43], v[174:177], v[218:221], v[40:43]
	v_mfma_f32_16x16x32_bf16 v[32:35], v[174:177], v[226:229], v[32:35]
	v_mfma_f32_16x16x32_bf16 v[36:39], v[166:169], v[226:229], v[36:39]
	s_setprio 0
	s_barrier
	v_readfirstlane_b32 s5, v157
	v_add_u32_e32 v164, 0x2000, v157
	v_lshl_add_u64 v[162:163], v[246:247], 0, s[56:57]
	s_mov_b32 m0, s5
	v_readfirstlane_b32 s5, v164
	global_load_lds_dwordx4 v[162:163], off
	v_lshl_add_u64 v[162:163], v[248:249], 0, s[56:57]
	s_mov_b32 m0, s5
	s_nop 0
	global_load_lds_dwordx4 v[162:163], off
	s_waitcnt vmcnt(6)
	s_barrier
	s_setprio 1
	v_mfma_f32_16x16x32_bf16 v[28:31], v[230:233], v[198:201], v[28:31]
	v_mfma_f32_16x16x32_bf16 v[24:27], v[238:241], v[198:201], v[24:27]
	v_mfma_f32_16x16x32_bf16 v[16:19], v[238:241], v[206:209], v[16:19]
	v_mfma_f32_16x16x32_bf16 v[20:23], v[230:233], v[206:209], v[20:23]
	v_mfma_f32_16x16x32_bf16 v[12:15], v[230:233], v[214:217], v[12:15]
	v_mfma_f32_16x16x32_bf16 v[8:11], v[238:241], v[214:217], v[8:11]
	v_mfma_f32_16x16x32_bf16 v[0:3], v[238:241], v[222:225], v[0:3]
	v_mfma_f32_16x16x32_bf16 v[4:7], v[230:233], v[222:225], v[4:7]
	v_mfma_f32_16x16x32_bf16 v[28:31], v[234:237], v[202:205], v[28:31]
	v_mfma_f32_16x16x32_bf16 v[24:27], v[242:245], v[202:205], v[24:27]
	v_mfma_f32_16x16x32_bf16 v[16:19], v[242:245], v[210:213], v[16:19]
	v_mfma_f32_16x16x32_bf16 v[20:23], v[234:237], v[210:213], v[20:23]
	v_mfma_f32_16x16x32_bf16 v[12:15], v[234:237], v[218:221], v[12:15]
	v_mfma_f32_16x16x32_bf16 v[8:11], v[242:245], v[218:221], v[8:11]
	v_mfma_f32_16x16x32_bf16 v[0:3], v[242:245], v[226:229], v[0:3]
	v_mfma_f32_16x16x32_bf16 v[4:7], v[234:237], v[226:229], v[4:7]
	s_setprio 0
	s_add_i32 s4, s4, 2
	v_lshl_add_u64 v[136:137], v[136:137], 0, s[44:45]
	v_lshl_add_u64 v[138:139], v[138:139], 0, s[44:45]
	v_lshl_add_u64 v[140:141], v[140:141], 0, s[44:45]
	s_cmp_lt_u32 s4, 12
	v_lshl_add_u64 v[142:143], v[142:143], 0, s[44:45]
	s_barrier
	s_cbranch_scc1 .LBB0_542
	s_add_u32 s0, s0, 0x40780
	s_addc_u32 s1, s1, 0
	v_lshl_add_u64 v[130:131], s[0:1], 0, v[130:131]
	v_readfirstlane_b32 s4, v160
	v_lshl_add_u64 v[128:129], v[128:129], 1, v[130:131]
	s_mov_b32 m0, s4
	ds_read_b128 v[136:139], v159
	ds_read_b128 v[140:143], v159 offset:1024
	ds_read_b128 v[154:157], v159 offset:2048
	ds_read_b128 v[162:165], v159 offset:3072
	ds_read_b128 v[166:169], v151
	ds_read_b128 v[170:173], v151 offset:1024
	ds_read_b128 v[174:177], v150
	ds_read_b128 v[198:201], v150 offset:1024
	ds_read_b128 v[202:205], v149
	ds_read_b128 v[206:209], v149 offset:1024
	ds_read_b128 v[210:213], v148
	ds_read_b128 v[214:217], v148 offset:1024
	global_load_lds_dwordx4 v[128:129], off
	v_lshl_add_u64 v[128:129], s[0:1], 0, v[134:135]
	v_readfirstlane_b32 s0, v161
	v_lshl_add_u64 v[128:129], v[132:133], 1, v[128:129]
	s_mov_b32 m0, s0
	s_nop 0
	global_load_lds_dwordx4 v[128:129], off
	s_barrier
	s_waitcnt lgkmcnt(0)
	s_setprio 1
	s_waitcnt lgkmcnt(0)
	v_mfma_f32_16x16x32_bf16 v[124:127], v[136:139], v[166:169], v[124:127]
	v_mfma_f32_16x16x32_bf16 v[120:123], v[154:157], v[166:169], v[120:123]
	v_mfma_f32_16x16x32_bf16 v[112:115], v[154:157], v[174:177], v[112:115]
	v_mfma_f32_16x16x32_bf16 v[116:119], v[136:139], v[174:177], v[116:119]
	v_mfma_f32_16x16x32_bf16 v[108:111], v[136:139], v[202:205], v[108:111]
	v_mfma_f32_16x16x32_bf16 v[104:107], v[154:157], v[202:205], v[104:107]
	v_mfma_f32_16x16x32_bf16 v[96:99], v[154:157], v[210:213], v[96:99]
	v_mfma_f32_16x16x32_bf16 v[100:103], v[136:139], v[210:213], v[100:103]
	v_mfma_f32_16x16x32_bf16 v[124:127], v[140:143], v[170:173], v[124:127]
	v_mfma_f32_16x16x32_bf16 v[120:123], v[162:165], v[170:173], v[120:123]
	v_mfma_f32_16x16x32_bf16 v[112:115], v[162:165], v[198:201], v[112:115]
	v_mfma_f32_16x16x32_bf16 v[116:119], v[140:143], v[198:201], v[116:119]
	v_mfma_f32_16x16x32_bf16 v[108:111], v[140:143], v[206:209], v[108:111]
	v_mfma_f32_16x16x32_bf16 v[104:107], v[162:165], v[206:209], v[104:107]
	v_mfma_f32_16x16x32_bf16 v[96:99], v[162:165], v[214:217], v[96:99]
	v_mfma_f32_16x16x32_bf16 v[100:103], v[140:143], v[214:217], v[100:103]
	s_setprio 0
	s_barrier
; #define WAIT_V(n) asm volatile("s_waitcnt vmcnt(" #n ")" ::: "memory")
; #define WAIT_L(n) asm volatile("s_waitcnt lgkmcnt(" #n ")" ::: "memory")
; #define BAR __builtin_amdgcn_s_barrier()
; #define LDA(dst, b, h)                                                                            \
;   _Pragma("unroll") for (int m = 0; m < 4; ++m) _Pragma("unroll") for (int k = 0; k < 2; ++k)                                         \
;     dst[m][k] = *reinterpret_cast<const bf16x8*>((char*)SA(b, h) + lds_byte(wr * 64 + m * 16 + fr, k * 32 + fq * 8))
; #define LDB(dst, b, h)                                                                            \
;   _Pragma("unroll") for (int n = 0; n < 2; ++n) _Pragma("unroll") for (int k = 0; k < 2; ++k)                                         \
;     dst[n][k] = *reinterpret_cast<const bf16x8*>((char*)SB(b, h) + lds_byte(wc * 32 + n * 16 + fr, k * 32 + fq * 8))
; template <int K, bool SWAP>
; __device__ __forceinline__ void gemm_kloop(const bf16* __restrict__ A, const bf16* __restrict__ Bt,
;                                            f32x4 (&acc)[2][2][4][2], bool pref = false) {
;     ...
;     LDB(B1, 0, 1); BAR; WAIT_L(0); MMA(0, 1, At, B1); BAR;
;     LDA(At, 0, 1); WAIT_V(4); BAR; WAIT_L(0); MMA(1, 0, At, B0); MMA(1, 1, At, B1); BAR; }
;   { LDB(B0, 1, 0); LDA(At, 1, 0); WAIT_V(2); BAR; WAIT_L(0); MMA(0, 0, At, B0); BAR;
	ds_read_b128 v[128:131], v158
	ds_read_b128 v[132:135], v158 offset:1024
	ds_read_b128 v[218:221], v158 offset:2048
	ds_read_b128 v[158:161], v158 offset:3072
	s_barrier
	s_waitcnt lgkmcnt(0)
	s_setprio 1
	s_waitcnt lgkmcnt(0)
	v_mfma_f32_16x16x32_bf16 v[92:95], v[128:131], v[166:169], v[92:95]
	v_mfma_f32_16x16x32_bf16 v[88:91], v[218:221], v[166:169], v[88:91]
	v_mfma_f32_16x16x32_bf16 v[76:79], v[128:131], v[202:205], v[76:79]
	v_mfma_f32_16x16x32_bf16 v[72:75], v[218:221], v[202:205], v[72:75]
	v_mfma_f32_16x16x32_bf16 v[68:71], v[128:131], v[210:213], v[68:71]
	v_mfma_f32_16x16x32_bf16 v[64:67], v[218:221], v[210:213], v[64:67]
	v_mfma_f32_16x16x32_bf16 v[92:95], v[132:135], v[170:173], v[92:95]
	v_mfma_f32_16x16x32_bf16 v[88:91], v[158:161], v[170:173], v[88:91]
	v_mfma_f32_16x16x32_bf16 v[84:87], v[128:131], v[174:177], v[84:87]
	v_mfma_f32_16x16x32_bf16 v[80:83], v[218:221], v[174:177], v[80:83]
	v_mfma_f32_16x16x32_bf16 v[76:79], v[132:135], v[206:209], v[76:79]
	v_mfma_f32_16x16x32_bf16 v[72:75], v[158:161], v[206:209], v[72:75]
	v_mfma_f32_16x16x32_bf16 v[68:71], v[132:135], v[214:217], v[68:71]
	v_mfma_f32_16x16x32_bf16 v[64:67], v[158:161], v[214:217], v[64:67]
	v_mfma_f32_16x16x32_bf16 v[84:87], v[132:135], v[198:201], v[84:87]
	v_mfma_f32_16x16x32_bf16 v[80:83], v[158:161], v[198:201], v[80:83]
	s_setprio 0
	s_barrier
	ds_read_b128 v[166:169], v151 offset:16384
	ds_read_b128 v[170:173], v151 offset:17408
	ds_read_b128 v[174:177], v150 offset:16384
	ds_read_b128 v[198:201], v150 offset:17408
	ds_read_b128 v[202:205], v149 offset:16384
	ds_read_b128 v[206:209], v149 offset:17408
	ds_read_b128 v[210:213], v148 offset:16384
	ds_read_b128 v[214:217], v148 offset:17408
	s_waitcnt vmcnt(4)
	s_barrier
	s_waitcnt lgkmcnt(0)
	s_setprio 1
	s_waitcnt lgkmcnt(0)
	v_mfma_f32_16x16x32_bf16 v[60:63], v[136:139], v[166:169], v[60:63]
	v_mfma_f32_16x16x32_bf16 v[56:59], v[154:157], v[166:169], v[56:59]
	v_mfma_f32_16x16x32_bf16 v[52:55], v[136:139], v[174:177], v[52:55]
	v_mfma_f32_16x16x32_bf16 v[48:51], v[154:157], v[174:177], v[48:51]
	v_mfma_f32_16x16x32_bf16 v[44:47], v[136:139], v[202:205], v[44:47]
	v_mfma_f32_16x16x32_bf16 v[36:39], v[136:139], v[210:213], v[36:39]
	v_mfma_f32_16x16x32_bf16 v[60:63], v[140:143], v[170:173], v[60:63]
	v_mfma_f32_16x16x32_bf16 v[56:59], v[162:165], v[170:173], v[56:59]
	v_mfma_f32_16x16x32_bf16 v[52:55], v[140:143], v[198:201], v[52:55]
	v_mfma_f32_16x16x32_bf16 v[48:51], v[162:165], v[198:201], v[48:51]
	v_mfma_f32_16x16x32_bf16 v[44:47], v[140:143], v[206:209], v[44:47]
	v_mfma_f32_16x16x32_bf16 v[40:43], v[154:157], v[202:205], v[40:43]
	v_mfma_f32_16x16x32_bf16 v[36:39], v[140:143], v[214:217], v[36:39]
	v_mfma_f32_16x16x32_bf16 v[32:35], v[154:157], v[210:213], v[32:35]
	v_mfma_f32_16x16x32_bf16 v[40:43], v[162:165], v[206:209], v[40:43]
	v_mfma_f32_16x16x32_bf16 v[32:35], v[162:165], v[214:217], v[32:35]
	s_setprio 0
	s_setprio 1
	v_mfma_f32_16x16x32_bf16 v[28:31], v[128:131], v[166:169], v[28:31]
	v_mfma_f32_16x16x32_bf16 v[24:27], v[218:221], v[166:169], v[24:27]
	v_mfma_f32_16x16x32_bf16 v[16:19], v[218:221], v[174:177], v[16:19]
	v_mfma_f32_16x16x32_bf16 v[20:23], v[128:131], v[174:177], v[20:23]
	v_mfma_f32_16x16x32_bf16 v[12:15], v[128:131], v[202:205], v[12:15]
	v_mfma_f32_16x16x32_bf16 v[8:11], v[218:221], v[202:205], v[8:11]
	v_mfma_f32_16x16x32_bf16 v[0:3], v[218:221], v[210:213], v[0:3]
	v_mfma_f32_16x16x32_bf16 v[4:7], v[128:131], v[210:213], v[4:7]
	v_mfma_f32_16x16x32_bf16 v[28:31], v[132:135], v[170:173], v[28:31]
	v_mfma_f32_16x16x32_bf16 v[24:27], v[158:161], v[170:173], v[24:27]
	v_mfma_f32_16x16x32_bf16 v[16:19], v[158:161], v[198:201], v[16:19]
	v_mfma_f32_16x16x32_bf16 v[20:23], v[132:135], v[198:201], v[20:23]
	v_mfma_f32_16x16x32_bf16 v[12:15], v[132:135], v[206:209], v[12:15]
	v_mfma_f32_16x16x32_bf16 v[8:11], v[158:161], v[206:209], v[8:11]
	v_mfma_f32_16x16x32_bf16 v[0:3], v[158:161], v[214:217], v[0:3]
	v_mfma_f32_16x16x32_bf16 v[4:7], v[132:135], v[214:217], v[4:7]
	s_setprio 0
	s_barrier
	ds_read_b128 v[154:157], v153
	ds_read_b128 v[158:161], v153 offset:1024
	ds_read_b128 v[162:165], v153 offset:2048
	ds_read_b128 v[166:169], v153 offset:3072
	ds_read_b128 v[170:173], v151 offset:32768
	ds_read_b128 v[174:177], v151 offset:33792
	ds_read_b128 v[198:201], v150 offset:32768
	ds_read_b128 v[202:205], v150 offset:33792
	ds_read_b128 v[206:209], v149 offset:32768
	ds_read_b128 v[210:213], v149 offset:33792
	ds_read_b128 v[214:217], v148 offset:32768
	ds_read_b128 v[218:221], v148 offset:33792
	s_waitcnt vmcnt(2)
	s_barrier
; #define WAIT_V(n) asm volatile("s_waitcnt vmcnt(" #n ")" ::: "memory")
; #define WAIT_L(n) asm volatile("s_waitcnt lgkmcnt(" #n ")" ::: "memory")
; #define BAR __builtin_amdgcn_s_barrier()
; #define LDA(dst, b, h)                                                                            \
;   _Pragma("unroll") for (int m = 0; m < 4; ++m) _Pragma("unroll") for (int k = 0; k < 2; ++k)                                         \
;     dst[m][k] = *reinterpret_cast<const bf16x8*>((char*)SA(b, h) + lds_byte(wr * 64 + m * 16 + fr, k * 32 + fq * 8))
; #define LDB(dst, b, h)                                                                            \
;   _Pragma("unroll") for (int n = 0; n < 2; ++n) _Pragma("unroll") for (int k = 0; k < 2; ++k)                                         \
;     dst[n][k] = *reinterpret_cast<const bf16x8*>((char*)SB(b, h) + lds_byte(wc * 32 + n * 16 + fr, k * 32 + fq * 8))
; template <int K, bool SWAP>
; __device__ __forceinline__ void gemm_kloop(const bf16* __restrict__ A, const bf16* __restrict__ Bt,
;                                            f32x4 (&acc)[2][2][4][2], bool pref = false) {
;     ...
;   { LDB(B0, 1, 0); LDA(At, 1, 0); WAIT_V(2); BAR; WAIT_L(0); MMA(0, 0, At, B0); BAR;
;     LDB(B1, 1, 1); WAIT_V(0); BAR; WAIT_L(0); MMA(0, 1, At, B1); BAR;
;     LDA(At, 1, 1); BAR; WAIT_L(0); MMA(1, 0, At, B0); MMA(1, 1, At, B1); BAR; }
;   if (wr == 0) BAR;
	s_waitcnt lgkmcnt(0)
	s_setprio 1
	s_waitcnt lgkmcnt(0)
	v_mfma_f32_16x16x32_bf16 v[124:127], v[154:157], v[170:173], v[124:127]
	v_mfma_f32_16x16x32_bf16 v[120:123], v[162:165], v[170:173], v[120:123]
	v_mfma_f32_16x16x32_bf16 v[116:119], v[154:157], v[198:201], v[116:119]
	v_mfma_f32_16x16x32_bf16 v[112:115], v[162:165], v[198:201], v[112:115]
	v_mfma_f32_16x16x32_bf16 v[108:111], v[154:157], v[206:209], v[108:111]
	v_mfma_f32_16x16x32_bf16 v[104:107], v[162:165], v[206:209], v[104:107]
	v_mfma_f32_16x16x32_bf16 v[100:103], v[154:157], v[214:217], v[100:103]
	v_mfma_f32_16x16x32_bf16 v[96:99], v[162:165], v[214:217], v[96:99]
	v_mfma_f32_16x16x32_bf16 v[140:143], v[158:161], v[174:177], v[124:127]
	v_mfma_f32_16x16x32_bf16 v[136:139], v[166:169], v[174:177], v[120:123]
	v_mfma_f32_16x16x32_bf16 v[132:135], v[158:161], v[202:205], v[116:119]
	v_mfma_f32_16x16x32_bf16 v[128:131], v[166:169], v[202:205], v[112:115]
	v_mfma_f32_16x16x32_bf16 v[124:127], v[158:161], v[210:213], v[108:111]
	v_mfma_f32_16x16x32_bf16 v[120:123], v[166:169], v[210:213], v[104:107]
	v_mfma_f32_16x16x32_bf16 v[116:119], v[158:161], v[218:221], v[100:103]
	v_mfma_f32_16x16x32_bf16 v[112:115], v[166:169], v[218:221], v[96:99]
	s_setprio 0
	s_barrier
	ds_read_b128 v[222:225], v152
	ds_read_b128 v[226:229], v152 offset:1024
	ds_read_b128 v[230:233], v152 offset:2048
	ds_read_b128 v[234:237], v152 offset:3072
	s_waitcnt vmcnt(0)
	s_barrier
	s_waitcnt lgkmcnt(0)
	s_setprio 1
	s_waitcnt lgkmcnt(0)
	v_mfma_f32_16x16x32_bf16 v[92:95], v[222:225], v[170:173], v[92:95]
	v_mfma_f32_16x16x32_bf16 v[88:91], v[230:233], v[170:173], v[88:91]
	v_mfma_f32_16x16x32_bf16 v[84:87], v[222:225], v[198:201], v[84:87]
	v_mfma_f32_16x16x32_bf16 v[80:83], v[230:233], v[198:201], v[80:83]
	v_mfma_f32_16x16x32_bf16 v[76:79], v[222:225], v[206:209], v[76:79]
	v_mfma_f32_16x16x32_bf16 v[72:75], v[230:233], v[206:209], v[72:75]
	v_mfma_f32_16x16x32_bf16 v[68:71], v[222:225], v[214:217], v[68:71]
	v_mfma_f32_16x16x32_bf16 v[64:67], v[230:233], v[214:217], v[64:67]
	v_mfma_f32_16x16x32_bf16 v[108:111], v[226:229], v[174:177], v[92:95]
	v_mfma_f32_16x16x32_bf16 v[104:107], v[234:237], v[174:177], v[88:91]
	v_mfma_f32_16x16x32_bf16 v[100:103], v[226:229], v[202:205], v[84:87]
	v_mfma_f32_16x16x32_bf16 v[96:99], v[234:237], v[202:205], v[80:83]
	v_mfma_f32_16x16x32_bf16 v[92:95], v[226:229], v[210:213], v[76:79]
	v_mfma_f32_16x16x32_bf16 v[88:91], v[234:237], v[210:213], v[72:75]
	v_mfma_f32_16x16x32_bf16 v[76:79], v[226:229], v[218:221], v[68:71]
	v_mfma_f32_16x16x32_bf16 v[72:75], v[234:237], v[218:221], v[64:67]
	s_setprio 0
	s_barrier
	ds_read_b128 v[80:83], v151 offset:49152
	ds_read_b128 v[84:87], v151 offset:50176
	ds_read_b128 v[170:173], v150 offset:49152
	ds_read_b128 v[150:153], v150 offset:50176
	ds_read_b128 v[174:177], v149 offset:49152
	ds_read_b128 v[198:201], v149 offset:50176
	ds_read_b128 v[202:205], v148 offset:49152
	ds_read_b128 v[146:149], v148 offset:50176
	s_barrier
	s_waitcnt lgkmcnt(0)
	s_setprio 1
	s_waitcnt lgkmcnt(0)
	v_mfma_f32_16x16x32_bf16 v[60:63], v[154:157], v[80:83], v[60:63]
	v_mfma_f32_16x16x32_bf16 v[56:59], v[162:165], v[80:83], v[56:59]
	v_mfma_f32_16x16x32_bf16 v[52:55], v[154:157], v[170:173], v[52:55]
	v_mfma_f32_16x16x32_bf16 v[48:51], v[162:165], v[170:173], v[48:51]
	v_mfma_f32_16x16x32_bf16 v[44:47], v[154:157], v[174:177], v[44:47]
	v_mfma_f32_16x16x32_bf16 v[40:43], v[162:165], v[174:177], v[40:43]
	v_mfma_f32_16x16x32_bf16 v[36:39], v[154:157], v[202:205], v[36:39]
	v_mfma_f32_16x16x32_bf16 v[32:35], v[162:165], v[202:205], v[32:35]
	v_mfma_f32_16x16x32_bf16 v[68:71], v[158:161], v[84:87], v[60:63]
	v_mfma_f32_16x16x32_bf16 v[64:67], v[166:169], v[84:87], v[56:59]
	v_mfma_f32_16x16x32_bf16 v[60:63], v[158:161], v[150:153], v[52:55]
	v_mfma_f32_16x16x32_bf16 v[56:59], v[166:169], v[150:153], v[48:51]
	v_mfma_f32_16x16x32_bf16 v[52:55], v[158:161], v[198:201], v[44:47]
	v_mfma_f32_16x16x32_bf16 v[48:51], v[166:169], v[198:201], v[40:43]
	v_mfma_f32_16x16x32_bf16 v[44:47], v[158:161], v[146:149], v[36:39]
	v_mfma_f32_16x16x32_bf16 v[36:39], v[166:169], v[146:149], v[32:35]
	s_setprio 0
	s_setprio 1
	v_mfma_f32_16x16x32_bf16 v[28:31], v[222:225], v[80:83], v[28:31]
	v_mfma_f32_16x16x32_bf16 v[24:27], v[230:233], v[80:83], v[24:27]
	v_mfma_f32_16x16x32_bf16 v[16:19], v[230:233], v[170:173], v[16:19]
	v_mfma_f32_16x16x32_bf16 v[20:23], v[222:225], v[170:173], v[20:23]
	v_mfma_f32_16x16x32_bf16 v[12:15], v[222:225], v[174:177], v[12:15]
	v_mfma_f32_16x16x32_bf16 v[8:11], v[230:233], v[174:177], v[8:11]
	v_mfma_f32_16x16x32_bf16 v[0:3], v[230:233], v[202:205], v[0:3]
	v_mfma_f32_16x16x32_bf16 v[4:7], v[222:225], v[202:205], v[4:7]
	v_mfma_f32_16x16x32_bf16 v[28:31], v[226:229], v[84:87], v[28:31]
	v_mfma_f32_16x16x32_bf16 v[24:27], v[234:237], v[84:87], v[24:27]
	v_mfma_f32_16x16x32_bf16 v[16:19], v[234:237], v[150:153], v[16:19]
	v_mfma_f32_16x16x32_bf16 v[20:23], v[226:229], v[150:153], v[20:23]
	v_mfma_f32_16x16x32_bf16 v[12:15], v[226:229], v[198:201], v[12:15]
	v_mfma_f32_16x16x32_bf16 v[8:11], v[234:237], v[198:201], v[8:11]
	v_mfma_f32_16x16x32_bf16 v[0:3], v[234:237], v[146:149], v[0:3]
	v_mfma_f32_16x16x32_bf16 v[4:7], v[226:229], v[146:149], v[4:7]
	s_setprio 0
	s_movk_i32 s0, 0x100
	v_cmp_gt_u32_e32 vcc, s0, v144
	s_barrier
	s_and_saveexec_b64 s[0:1], vcc
	s_cbranch_execz .LBB0_545
	s_barrier

; #define WAIT_L(n) asm volatile("s_waitcnt lgkmcnt(" #n ")" ::: "memory")
; #define BAR __builtin_amdgcn_s_barrier()
; #define SCHED __builtin_amdgcn_sched_barrier(0)
; #define LDA(dst, b, h)                                                                            \
;   _Pragma("unroll") for (int m = 0; m < 4; ++m) _Pragma("unroll") for (int k = 0; k < 2; ++k)                                         \
;     dst[m][k] = *reinterpret_cast<const bf16x8*>((char*)SA(b, h) + lds_byte(wr * 64 + m * 16 + fr, k * 32 + fq * 8))
; #define LDB(dst, b, h)                                                                            \
;   _Pragma("unroll") for (int n = 0; n < 2; ++n) _Pragma("unroll") for (int k = 0; k < 2; ++k)                                         \
;     dst[n][k] = *reinterpret_cast<const bf16x8*>((char*)SB(b, h) + lds_byte(wc * 32 + n * 16 + fr, k * 32 + fq * 8))
; template <int K, bool SWAP>
; __device__ __forceinline__ void gemm_kloop(const bf16* __restrict__ A, const bf16* __restrict__ Bt,
;                                            f32x4 (&acc)[2][2][4][2], bool pref = false) {
;     ...
;     LDB(B0, 0, 0); SCHED; LDA(At, 0, 0); STAGE(SA(1, 1), A, HALF, t + 1);
;     WAIT_L(8); BAR; WAIT_L(0); MMA(0, 0, At, B0); BAR; SCHED;
;     LDB(B1, 0, 1); STAGE(SB(0, 0), Bt, 0, t + 2);
;     BAR; WAIT_L(0); MMA(0, 1, At, B1); BAR;
;     LDA(At, 0, 1); STAGE(SA(0, 0), A, 0, t + 2);
;     BAR; WAIT_L(0); MMA(1, 0, At, B0); BAR; SCHED;
.LBB0_590:
	ds_read_b128 v[162:165], v159
	ds_read_b128 v[166:169], v159 offset:1024
	ds_read_b128 v[170:173], v159 offset:2048
	ds_read_b128 v[174:177], v159 offset:3072
	v_add_u32_e32 v160, 0xc000, v146
	v_lshl_add_u64 v[178:179], s[6:7], 0, v[140:141]
	v_readfirstlane_b32 s14, v160
	v_lshl_add_u64 v[188:189], v[178:179], 0, s[22:23]
	s_mov_b32 m0, s14
	v_add_u32_e32 v161, 0xe000, v146
	ds_read_b128 v[198:201], v151
	ds_read_b128 v[202:205], v151 offset:1024
	ds_read_b128 v[206:209], v150
	ds_read_b128 v[210:213], v150 offset:1024
	ds_read_b128 v[214:217], v149
	ds_read_b128 v[218:221], v149 offset:1024
	ds_read_b128 v[222:225], v148
	ds_read_b128 v[226:229], v148 offset:1024
	global_load_lds_dwordx4 v[188:189], off
	v_lshl_add_u64 v[188:189], s[6:7], 0, v[142:143]
	v_readfirstlane_b32 s14, v161
	v_lshl_add_u64 v[230:231], v[188:189], 0, s[22:23]
	s_mov_b32 m0, s14
	s_nop 0
	global_load_lds_dwordx4 v[230:231], off
	s_waitcnt lgkmcnt(8)
	s_barrier
	s_waitcnt lgkmcnt(0)
	s_setprio 1
	s_waitcnt lgkmcnt(0)
	v_mfma_f32_16x16x32_bf16 v[124:127], v[162:165], v[198:201], v[124:127]
	v_mfma_f32_16x16x32_bf16 v[120:123], v[170:173], v[198:201], v[120:123]
	v_mfma_f32_16x16x32_bf16 v[112:115], v[170:173], v[206:209], v[112:115]
	v_mfma_f32_16x16x32_bf16 v[116:119], v[162:165], v[206:209], v[116:119]
	v_mfma_f32_16x16x32_bf16 v[108:111], v[162:165], v[214:217], v[108:111]
	v_mfma_f32_16x16x32_bf16 v[104:107], v[170:173], v[214:217], v[104:107]
	v_mfma_f32_16x16x32_bf16 v[96:99], v[170:173], v[222:225], v[96:99]
	v_mfma_f32_16x16x32_bf16 v[100:103], v[162:165], v[222:225], v[100:103]
	v_mfma_f32_16x16x32_bf16 v[124:127], v[166:169], v[202:205], v[124:127]
	v_mfma_f32_16x16x32_bf16 v[120:123], v[174:177], v[202:205], v[120:123]
	v_mfma_f32_16x16x32_bf16 v[112:115], v[174:177], v[210:213], v[112:115]
	v_mfma_f32_16x16x32_bf16 v[116:119], v[166:169], v[210:213], v[116:119]
	v_mfma_f32_16x16x32_bf16 v[108:111], v[166:169], v[218:221], v[108:111]
	v_mfma_f32_16x16x32_bf16 v[104:107], v[174:177], v[218:221], v[104:107]
	v_mfma_f32_16x16x32_bf16 v[96:99], v[174:177], v[226:229], v[96:99]
	v_mfma_f32_16x16x32_bf16 v[100:103], v[166:169], v[226:229], v[100:103]
	s_setprio 0
	s_barrier
	v_add_u32_e32 v186, s1, v145
	v_lshl_add_u64 v[246:247], s[6:7], 0, v[136:137]
	v_readfirstlane_b32 s14, v186
	v_lshl_add_u64 v[248:249], v[246:247], 0, s[40:41]
	s_mov_b32 m0, s14
	v_add_u32_e32 v186, 0x2000, v186
	ds_read_b128 v[230:233], v156
	ds_read_b128 v[234:237], v156 offset:1024
	ds_read_b128 v[238:241], v156 offset:2048
	ds_read_b128 v[242:245], v156 offset:3072
	global_load_lds_dwordx4 v[248:249], off
	v_lshl_add_u64 v[248:249], s[6:7], 0, v[138:139]
	v_readfirstlane_b32 s14, v186
	v_lshl_add_u64 v[250:251], v[248:249], 0, s[40:41]
	s_mov_b32 m0, s14
	s_nop 0
	global_load_lds_dwordx4 v[250:251], off
	s_barrier
	s_waitcnt lgkmcnt(0)
	s_setprio 1
	s_waitcnt lgkmcnt(0)
	v_mfma_f32_16x16x32_bf16 v[92:95], v[230:233], v[198:201], v[92:95]
	v_mfma_f32_16x16x32_bf16 v[88:91], v[238:241], v[198:201], v[88:91]
	v_mfma_f32_16x16x32_bf16 v[80:83], v[238:241], v[206:209], v[80:83]
	v_mfma_f32_16x16x32_bf16 v[84:87], v[230:233], v[206:209], v[84:87]
	v_mfma_f32_16x16x32_bf16 v[76:79], v[230:233], v[214:217], v[76:79]
	v_mfma_f32_16x16x32_bf16 v[72:75], v[238:241], v[214:217], v[72:75]
	v_mfma_f32_16x16x32_bf16 v[64:67], v[238:241], v[222:225], v[64:67]
	v_mfma_f32_16x16x32_bf16 v[68:71], v[230:233], v[222:225], v[68:71]
	v_mfma_f32_16x16x32_bf16 v[92:95], v[234:237], v[202:205], v[92:95]
	v_mfma_f32_16x16x32_bf16 v[88:91], v[242:245], v[202:205], v[88:91]
	v_mfma_f32_16x16x32_bf16 v[80:83], v[242:245], v[210:213], v[80:83]
	v_mfma_f32_16x16x32_bf16 v[84:87], v[234:237], v[210:213], v[84:87]
	v_mfma_f32_16x16x32_bf16 v[76:79], v[234:237], v[218:221], v[76:79]
	v_mfma_f32_16x16x32_bf16 v[72:75], v[242:245], v[218:221], v[72:75]
	v_mfma_f32_16x16x32_bf16 v[64:67], v[242:245], v[226:229], v[64:67]
	v_mfma_f32_16x16x32_bf16 v[68:71], v[234:237], v[226:229], v[68:71]
	s_setprio 0
	v_readfirstlane_b32 s14, v146
	v_add_u32_e32 v186, 0x2000, v146
	v_lshl_add_u64 v[250:251], v[178:179], 0, s[58:59]
	s_mov_b32 m0, s14
	v_readfirstlane_b32 s14, v186
	s_barrier
	ds_read_b128 v[198:201], v151 offset:16384
	ds_read_b128 v[202:205], v151 offset:17408
	ds_read_b128 v[206:209], v150 offset:16384
	ds_read_b128 v[210:213], v150 offset:17408
	ds_read_b128 v[214:217], v149 offset:16384
	ds_read_b128 v[218:221], v149 offset:17408
	ds_read_b128 v[222:225], v148 offset:16384
	ds_read_b128 v[226:229], v148 offset:17408
	global_load_lds_dwordx4 v[250:251], off
	v_lshl_add_u64 v[250:251], v[188:189], 0, s[58:59]
	s_mov_b32 m0, s14
	s_nop 0
	global_load_lds_dwordx4 v[250:251], off
	s_barrier
	s_waitcnt lgkmcnt(0)
	s_setprio 1
	s_waitcnt lgkmcnt(0)
	v_mfma_f32_16x16x32_bf16 v[60:63], v[162:165], v[198:201], v[60:63]
	v_mfma_f32_16x16x32_bf16 v[56:59], v[170:173], v[198:201], v[56:59]
	v_mfma_f32_16x16x32_bf16 v[48:51], v[170:173], v[206:209], v[48:51]
	v_mfma_f32_16x16x32_bf16 v[52:55], v[162:165], v[206:209], v[52:55]
	v_mfma_f32_16x16x32_bf16 v[44:47], v[162:165], v[214:217], v[44:47]
	v_mfma_f32_16x16x32_bf16 v[40:43], v[170:173], v[214:217], v[40:43]
	v_mfma_f32_16x16x32_bf16 v[32:35], v[170:173], v[222:225], v[32:35]
	v_mfma_f32_16x16x32_bf16 v[36:39], v[162:165], v[222:225], v[36:39]
	v_mfma_f32_16x16x32_bf16 v[60:63], v[166:169], v[202:205], v[60:63]
	v_mfma_f32_16x16x32_bf16 v[56:59], v[174:177], v[202:205], v[56:59]
	v_mfma_f32_16x16x32_bf16 v[48:51], v[174:177], v[210:213], v[48:51]
	v_mfma_f32_16x16x32_bf16 v[52:55], v[166:169], v[210:213], v[52:55]
	v_mfma_f32_16x16x32_bf16 v[44:47], v[166:169], v[218:221], v[44:47]
	v_mfma_f32_16x16x32_bf16 v[40:43], v[174:177], v[218:221], v[40:43]
	v_mfma_f32_16x16x32_bf16 v[32:35], v[174:177], v[226:229], v[32:35]
	v_mfma_f32_16x16x32_bf16 v[36:39], v[166:169], v[226:229], v[36:39]
	s_setprio 0
	s_barrier
; #define WAIT_V(n) asm volatile("s_waitcnt vmcnt(" #n ")" ::: "memory")
; #define WAIT_L(n) asm volatile("s_waitcnt lgkmcnt(" #n ")" ::: "memory")
; #define BAR __builtin_amdgcn_s_barrier()
; #define SCHED __builtin_amdgcn_sched_barrier(0)
; #define LDA(dst, b, h)                                                                            \
;   _Pragma("unroll") for (int m = 0; m < 4; ++m) _Pragma("unroll") for (int k = 0; k < 2; ++k)                                         \
;     dst[m][k] = *reinterpret_cast<const bf16x8*>((char*)SA(b, h) + lds_byte(wr * 64 + m * 16 + fr, k * 32 + fq * 8))
; #define LDB(dst, b, h)                                                                            \
;   _Pragma("unroll") for (int n = 0; n < 2; ++n) _Pragma("unroll") for (int k = 0; k < 2; ++k)                                         \
;     dst[n][k] = *reinterpret_cast<const bf16x8*>((char*)SB(b, h) + lds_byte(wc * 32 + n * 16 + fr, k * 32 + fq * 8))
; template <int K, bool SWAP>
; __device__ __forceinline__ void gemm_kloop(const bf16* __restrict__ A, const bf16* __restrict__ Bt,
;                                            f32x4 (&acc)[2][2][4][2], bool pref = false) {
;     ...
;     STAGE(SB(0, 1), Bt, HALF, t + 2);
;     WAIT_V(6); BAR; MMA(1, 1, At, B1); BAR;
;     LDB(B0, 1, 0); SCHED; LDA(At, 1, 0); STAGE(SA(0, 1), A, HALF, t + 2);
;     WAIT_L(8); BAR; WAIT_L(0); MMA(0, 0, At, B0); BAR; SCHED;
;     LDB(B1, 1, 1); STAGE(SB(1, 0), Bt, 0, t + 3);
;     BAR; WAIT_L(0); MMA(0, 1, At, B1); BAR;
;     LDA(At, 1, 1); STAGE(SA(1, 0), A, 0, t + 3);
	v_readfirstlane_b32 s14, v147
	v_add_u32_e32 v164, 0x2000, v147
	v_lshl_add_u64 v[162:163], v[246:247], 0, s[60:61]
	s_mov_b32 m0, s14
	v_readfirstlane_b32 s14, v164
	global_load_lds_dwordx4 v[162:163], off
	v_lshl_add_u64 v[162:163], v[248:249], 0, s[60:61]
	s_mov_b32 m0, s14
	s_nop 0
	global_load_lds_dwordx4 v[162:163], off
	s_waitcnt vmcnt(6)
	s_barrier
	s_setprio 1
	v_mfma_f32_16x16x32_bf16 v[28:31], v[230:233], v[198:201], v[28:31]
	v_mfma_f32_16x16x32_bf16 v[24:27], v[238:241], v[198:201], v[24:27]
	v_mfma_f32_16x16x32_bf16 v[16:19], v[238:241], v[206:209], v[16:19]
	v_mfma_f32_16x16x32_bf16 v[20:23], v[230:233], v[206:209], v[20:23]
	v_mfma_f32_16x16x32_bf16 v[12:15], v[230:233], v[214:217], v[12:15]
	v_mfma_f32_16x16x32_bf16 v[8:11], v[238:241], v[214:217], v[8:11]
	v_mfma_f32_16x16x32_bf16 v[0:3], v[238:241], v[222:225], v[0:3]
	v_mfma_f32_16x16x32_bf16 v[4:7], v[230:233], v[222:225], v[4:7]
	v_mfma_f32_16x16x32_bf16 v[28:31], v[234:237], v[202:205], v[28:31]
	v_mfma_f32_16x16x32_bf16 v[24:27], v[242:245], v[202:205], v[24:27]
	v_mfma_f32_16x16x32_bf16 v[16:19], v[242:245], v[210:213], v[16:19]
	v_mfma_f32_16x16x32_bf16 v[20:23], v[234:237], v[210:213], v[20:23]
	v_mfma_f32_16x16x32_bf16 v[12:15], v[234:237], v[218:221], v[12:15]
	v_mfma_f32_16x16x32_bf16 v[8:11], v[242:245], v[218:221], v[8:11]
	v_mfma_f32_16x16x32_bf16 v[0:3], v[242:245], v[226:229], v[0:3]
	v_mfma_f32_16x16x32_bf16 v[4:7], v[234:237], v[226:229], v[4:7]
	s_setprio 0
	s_barrier
	ds_read_b128 v[162:165], v153
	ds_read_b128 v[166:169], v153 offset:1024
	ds_read_b128 v[170:173], v153 offset:2048
	ds_read_b128 v[174:177], v153 offset:3072
	v_add_u32_e32 v186, 0x4000, v146
	v_lshl_add_u64 v[230:231], v[178:179], 0, s[72:73]
	v_readfirstlane_b32 s14, v186
	v_add_u32_e32 v186, 0x6000, v146
	s_mov_b32 m0, s14
	v_readfirstlane_b32 s14, v186
	ds_read_b128 v[198:201], v151 offset:32768
	ds_read_b128 v[202:205], v151 offset:33792
	ds_read_b128 v[206:209], v150 offset:32768
	ds_read_b128 v[210:213], v150 offset:33792
	ds_read_b128 v[214:217], v149 offset:32768
	ds_read_b128 v[218:221], v149 offset:33792
	ds_read_b128 v[222:225], v148 offset:32768
	ds_read_b128 v[226:229], v148 offset:33792
	global_load_lds_dwordx4 v[230:231], off
	v_lshl_add_u64 v[230:231], v[188:189], 0, s[72:73]
	s_mov_b32 m0, s14
	s_nop 0
	global_load_lds_dwordx4 v[230:231], off
	s_waitcnt lgkmcnt(8)
	s_barrier
	s_waitcnt lgkmcnt(0)
	s_setprio 1
	s_waitcnt lgkmcnt(0)
	v_mfma_f32_16x16x32_bf16 v[124:127], v[162:165], v[198:201], v[124:127]
	v_mfma_f32_16x16x32_bf16 v[120:123], v[170:173], v[198:201], v[120:123]
	v_mfma_f32_16x16x32_bf16 v[112:115], v[170:173], v[206:209], v[112:115]
	v_mfma_f32_16x16x32_bf16 v[116:119], v[162:165], v[206:209], v[116:119]
	v_mfma_f32_16x16x32_bf16 v[108:111], v[162:165], v[214:217], v[108:111]
	v_mfma_f32_16x16x32_bf16 v[104:107], v[170:173], v[214:217], v[104:107]
	v_mfma_f32_16x16x32_bf16 v[96:99], v[170:173], v[222:225], v[96:99]
	v_mfma_f32_16x16x32_bf16 v[100:103], v[162:165], v[222:225], v[100:103]
	v_mfma_f32_16x16x32_bf16 v[124:127], v[166:169], v[202:205], v[124:127]
	v_mfma_f32_16x16x32_bf16 v[120:123], v[174:177], v[202:205], v[120:123]
	v_mfma_f32_16x16x32_bf16 v[112:115], v[174:177], v[210:213], v[112:115]
	v_mfma_f32_16x16x32_bf16 v[116:119], v[166:169], v[210:213], v[116:119]
	v_mfma_f32_16x16x32_bf16 v[108:111], v[166:169], v[218:221], v[108:111]
	v_mfma_f32_16x16x32_bf16 v[104:107], v[174:177], v[218:221], v[104:107]
	v_mfma_f32_16x16x32_bf16 v[96:99], v[174:177], v[226:229], v[96:99]
	v_mfma_f32_16x16x32_bf16 v[100:103], v[166:169], v[226:229], v[100:103]
	s_setprio 0
	s_barrier
	v_readfirstlane_b32 s14, v154
	v_add_u32_e32 v186, 0x2000, v154
	v_lshl_add_u64 v[250:251], v[246:247], 0, vcc
	s_mov_b32 m0, s14
	v_readfirstlane_b32 s14, v186
	ds_read_b128 v[230:233], v152
	ds_read_b128 v[234:237], v152 offset:1024
	ds_read_b128 v[238:241], v152 offset:2048
	ds_read_b128 v[242:245], v152 offset:3072
	global_load_lds_dwordx4 v[250:251], off
	v_lshl_add_u64 v[250:251], v[248:249], 0, vcc
	s_mov_b32 m0, s14
	s_nop 0
	global_load_lds_dwordx4 v[250:251], off
	s_barrier
	s_waitcnt lgkmcnt(0)
	s_setprio 1
	s_waitcnt lgkmcnt(0)
	v_mfma_f32_16x16x32_bf16 v[92:95], v[230:233], v[198:201], v[92:95]
	v_mfma_f32_16x16x32_bf16 v[88:91], v[238:241], v[198:201], v[88:91]
	v_mfma_f32_16x16x32_bf16 v[80:83], v[238:241], v[206:209], v[80:83]
	v_mfma_f32_16x16x32_bf16 v[84:87], v[230:233], v[206:209], v[84:87]
	v_mfma_f32_16x16x32_bf16 v[76:79], v[230:233], v[214:217], v[76:79]
	v_mfma_f32_16x16x32_bf16 v[72:75], v[238:241], v[214:217], v[72:75]
	v_mfma_f32_16x16x32_bf16 v[64:67], v[238:241], v[222:225], v[64:67]
	v_mfma_f32_16x16x32_bf16 v[68:71], v[230:233], v[222:225], v[68:71]
	v_mfma_f32_16x16x32_bf16 v[92:95], v[234:237], v[202:205], v[92:95]
	v_mfma_f32_16x16x32_bf16 v[88:91], v[242:245], v[202:205], v[88:91]
	v_mfma_f32_16x16x32_bf16 v[80:83], v[242:245], v[210:213], v[80:83]
	v_mfma_f32_16x16x32_bf16 v[84:87], v[234:237], v[210:213], v[84:87]
	v_mfma_f32_16x16x32_bf16 v[76:79], v[234:237], v[218:221], v[76:79]
	v_mfma_f32_16x16x32_bf16 v[72:75], v[242:245], v[218:221], v[72:75]
	v_mfma_f32_16x16x32_bf16 v[64:67], v[242:245], v[226:229], v[64:67]
	v_mfma_f32_16x16x32_bf16 v[68:71], v[234:237], v[226:229], v[68:71]
	s_setprio 0
	v_readfirstlane_b32 s14, v155
	v_lshl_add_u64 v[178:179], v[178:179], 0, s[64:65]
	s_mov_b32 m0, s14
	v_readfirstlane_b32 s14, v157
	s_barrier
; #define WAIT_V(n) asm volatile("s_waitcnt vmcnt(" #n ")" ::: "memory")
; #define WAIT_L(n) asm volatile("s_waitcnt lgkmcnt(" #n ")" ::: "memory")
; #define BAR __builtin_amdgcn_s_barrier()
; #define SCHED __builtin_amdgcn_sched_barrier(0)
; #define LDA(dst, b, h)                                                                            \
;   _Pragma("unroll") for (int m = 0; m < 4; ++m) _Pragma("unroll") for (int k = 0; k < 2; ++k)                                         \
;     dst[m][k] = *reinterpret_cast<const bf16x8*>((char*)SA(b, h) + lds_byte(wr * 64 + m * 16 + fr, k * 32 + fq * 8))
; #define LDB(dst, b, h)                                                                            \
;   _Pragma("unroll") for (int n = 0; n < 2; ++n) _Pragma("unroll") for (int k = 0; k < 2; ++k)                                         \
;     dst[n][k] = *reinterpret_cast<const bf16x8*>((char*)SB(b, h) + lds_byte(wc * 32 + n * 16 + fr, k * 32 + fq * 8))
; template <int K, bool SWAP>
; __device__ __forceinline__ void gemm_kloop(const bf16* __restrict__ A, const bf16* __restrict__ Bt,
;                                            f32x4 (&acc)[2][2][4][2], bool pref = false) {
;     ...
;     LDA(At, 1, 1); STAGE(SA(1, 0), A, 0, t + 3);
;     BAR; WAIT_L(0); MMA(1, 0, At, B0); BAR; SCHED;
;     STAGE(SB(1, 1), Bt, HALF, t + 3);
;     WAIT_V(6); BAR; MMA(1, 1, At, B1); BAR;
;   }
;   { LDB(B0, 0, 0); LDA(At, 0, 0); STAGE(SA(1, 1), A, HALF, nt - 1);
;     BAR; WAIT_L(0); MMA(0, 0, At, B0); BAR;
;     LDB(B1, 0, 1); BAR; WAIT_L(0); MMA(0, 1, At, B1); BAR;
;     LDA(At, 0, 1); WAIT_V(4); BAR; WAIT_L(0); MMA(1, 0, At, B0); MMA(1, 1, At, B1); BAR; }
	ds_read_b128 v[198:201], v151 offset:49152
	ds_read_b128 v[202:205], v151 offset:50176
	ds_read_b128 v[206:209], v150 offset:49152
	ds_read_b128 v[210:213], v150 offset:50176
	ds_read_b128 v[214:217], v149 offset:49152
	ds_read_b128 v[218:221], v149 offset:50176
	ds_read_b128 v[222:225], v148 offset:49152
	ds_read_b128 v[226:229], v148 offset:50176
	global_load_lds_dwordx4 v[178:179], off
	v_lshl_add_u64 v[178:179], v[188:189], 0, s[64:65]
	s_mov_b32 m0, s14
	s_nop 0
	global_load_lds_dwordx4 v[178:179], off
	s_barrier
	s_waitcnt lgkmcnt(0)
	s_setprio 1
	s_waitcnt lgkmcnt(0)
	v_mfma_f32_16x16x32_bf16 v[60:63], v[162:165], v[198:201], v[60:63]
	v_mfma_f32_16x16x32_bf16 v[56:59], v[170:173], v[198:201], v[56:59]
	v_mfma_f32_16x16x32_bf16 v[48:51], v[170:173], v[206:209], v[48:51]
	v_mfma_f32_16x16x32_bf16 v[52:55], v[162:165], v[206:209], v[52:55]
	v_mfma_f32_16x16x32_bf16 v[44:47], v[162:165], v[214:217], v[44:47]
	v_mfma_f32_16x16x32_bf16 v[40:43], v[170:173], v[214:217], v[40:43]
	v_mfma_f32_16x16x32_bf16 v[32:35], v[170:173], v[222:225], v[32:35]
	v_mfma_f32_16x16x32_bf16 v[36:39], v[162:165], v[222:225], v[36:39]
	v_mfma_f32_16x16x32_bf16 v[60:63], v[166:169], v[202:205], v[60:63]
	v_mfma_f32_16x16x32_bf16 v[56:59], v[174:177], v[202:205], v[56:59]
	v_mfma_f32_16x16x32_bf16 v[48:51], v[174:177], v[210:213], v[48:51]
	v_mfma_f32_16x16x32_bf16 v[52:55], v[166:169], v[210:213], v[52:55]
	v_mfma_f32_16x16x32_bf16 v[44:47], v[166:169], v[218:221], v[44:47]
	v_mfma_f32_16x16x32_bf16 v[40:43], v[174:177], v[218:221], v[40:43]
	v_mfma_f32_16x16x32_bf16 v[32:35], v[174:177], v[226:229], v[32:35]
	v_mfma_f32_16x16x32_bf16 v[36:39], v[166:169], v[226:229], v[36:39]
	s_setprio 0
	s_barrier
	v_readfirstlane_b32 s14, v158
	v_add_u32_e32 v164, 0x2000, v158
	v_lshl_add_u64 v[162:163], v[246:247], 0, s[70:71]
	s_mov_b32 m0, s14
	v_readfirstlane_b32 s14, v164
	global_load_lds_dwordx4 v[162:163], off
	v_lshl_add_u64 v[162:163], v[248:249], 0, s[70:71]
	s_mov_b32 m0, s14
	s_nop 0
	global_load_lds_dwordx4 v[162:163], off
	s_waitcnt vmcnt(6)
	s_barrier
	s_setprio 1
	v_mfma_f32_16x16x32_bf16 v[28:31], v[230:233], v[198:201], v[28:31]
	v_mfma_f32_16x16x32_bf16 v[24:27], v[238:241], v[198:201], v[24:27]
	v_mfma_f32_16x16x32_bf16 v[16:19], v[238:241], v[206:209], v[16:19]
	v_mfma_f32_16x16x32_bf16 v[20:23], v[230:233], v[206:209], v[20:23]
	v_mfma_f32_16x16x32_bf16 v[12:15], v[230:233], v[214:217], v[12:15]
	v_mfma_f32_16x16x32_bf16 v[8:11], v[238:241], v[214:217], v[8:11]
	v_mfma_f32_16x16x32_bf16 v[0:3], v[238:241], v[222:225], v[0:3]
	v_mfma_f32_16x16x32_bf16 v[4:7], v[230:233], v[222:225], v[4:7]
	v_mfma_f32_16x16x32_bf16 v[28:31], v[234:237], v[202:205], v[28:31]
	v_mfma_f32_16x16x32_bf16 v[24:27], v[242:245], v[202:205], v[24:27]
	v_mfma_f32_16x16x32_bf16 v[16:19], v[242:245], v[210:213], v[16:19]
	v_mfma_f32_16x16x32_bf16 v[20:23], v[234:237], v[210:213], v[20:23]
	v_mfma_f32_16x16x32_bf16 v[12:15], v[234:237], v[218:221], v[12:15]
	v_mfma_f32_16x16x32_bf16 v[8:11], v[242:245], v[218:221], v[8:11]
	v_mfma_f32_16x16x32_bf16 v[0:3], v[242:245], v[226:229], v[0:3]
	v_mfma_f32_16x16x32_bf16 v[4:7], v[234:237], v[226:229], v[4:7]
	s_setprio 0
	s_add_i32 s5, s5, 2
	v_lshl_add_u64 v[136:137], v[136:137], 0, s[44:45]
	v_lshl_add_u64 v[138:139], v[138:139], 0, s[44:45]
	v_lshl_add_u64 v[140:141], v[140:141], 0, s[44:45]
	s_cmp_lt_u32 s5, 60
	v_lshl_add_u64 v[142:143], v[142:143], 0, s[44:45]
	s_barrier
	s_cbranch_scc1 .LBB0_590
	s_add_u32 s12, s12, 0x101f80
	s_addc_u32 s13, s13, 0
	v_lshl_add_u64 v[130:131], s[12:13], 0, v[130:131]
	v_readfirstlane_b32 s5, v160
	v_lshl_add_u64 v[128:129], v[128:129], 1, v[130:131]
	s_mov_b32 m0, s5
	ds_read_b128 v[136:139], v159
	ds_read_b128 v[140:143], v159 offset:1024
	ds_read_b128 v[162:165], v159 offset:2048
	ds_read_b128 v[166:169], v159 offset:3072
	ds_read_b128 v[170:173], v151
	ds_read_b128 v[174:177], v151 offset:1024
	ds_read_b128 v[198:201], v150
	ds_read_b128 v[202:205], v150 offset:1024
	ds_read_b128 v[206:209], v149
	ds_read_b128 v[210:213], v149 offset:1024
	ds_read_b128 v[214:217], v148
	ds_read_b128 v[218:221], v148 offset:1024
	global_load_lds_dwordx4 v[128:129], off
	v_lshl_add_u64 v[128:129], s[12:13], 0, v[134:135]
	v_readfirstlane_b32 s5, v161
	v_lshl_add_u64 v[128:129], v[132:133], 1, v[128:129]
	s_mov_b32 m0, s5
	s_nop 0
	global_load_lds_dwordx4 v[128:129], off
	s_barrier
	s_waitcnt lgkmcnt(0)
	s_setprio 1
	s_waitcnt lgkmcnt(0)
	v_mfma_f32_16x16x32_bf16 v[124:127], v[136:139], v[170:173], v[124:127]
	v_mfma_f32_16x16x32_bf16 v[120:123], v[162:165], v[170:173], v[120:123]
	v_mfma_f32_16x16x32_bf16 v[112:115], v[162:165], v[198:201], v[112:115]
	v_mfma_f32_16x16x32_bf16 v[116:119], v[136:139], v[198:201], v[116:119]
	v_mfma_f32_16x16x32_bf16 v[108:111], v[136:139], v[206:209], v[108:111]
	v_mfma_f32_16x16x32_bf16 v[104:107], v[162:165], v[206:209], v[104:107]
	v_mfma_f32_16x16x32_bf16 v[96:99], v[162:165], v[214:217], v[96:99]
	v_mfma_f32_16x16x32_bf16 v[100:103], v[136:139], v[214:217], v[100:103]
	v_mfma_f32_16x16x32_bf16 v[124:127], v[140:143], v[174:177], v[124:127]
	v_mfma_f32_16x16x32_bf16 v[120:123], v[166:169], v[174:177], v[120:123]
	v_mfma_f32_16x16x32_bf16 v[112:115], v[166:169], v[202:205], v[112:115]
	v_mfma_f32_16x16x32_bf16 v[116:119], v[140:143], v[202:205], v[116:119]
	v_mfma_f32_16x16x32_bf16 v[108:111], v[140:143], v[210:213], v[108:111]
	v_mfma_f32_16x16x32_bf16 v[104:107], v[166:169], v[210:213], v[104:107]
	v_mfma_f32_16x16x32_bf16 v[96:99], v[166:169], v[218:221], v[96:99]
	v_mfma_f32_16x16x32_bf16 v[100:103], v[140:143], v[218:221], v[100:103]
	s_setprio 0
	s_barrier
; #define WAIT_V(n) asm volatile("s_waitcnt vmcnt(" #n ")" ::: "memory")
; #define WAIT_L(n) asm volatile("s_waitcnt lgkmcnt(" #n ")" ::: "memory")
; #define BAR __builtin_amdgcn_s_barrier()
; #define LDA(dst, b, h)                                                                            \
;   _Pragma("unroll") for (int m = 0; m < 4; ++m) _Pragma("unroll") for (int k = 0; k < 2; ++k)                                         \
;     dst[m][k] = *reinterpret_cast<const bf16x8*>((char*)SA(b, h) + lds_byte(wr * 64 + m * 16 + fr, k * 32 + fq * 8))
; #define LDB(dst, b, h)                                                                            \
;   _Pragma("unroll") for (int n = 0; n < 2; ++n) _Pragma("unroll") for (int k = 0; k < 2; ++k)                                         \
;     dst[n][k] = *reinterpret_cast<const bf16x8*>((char*)SB(b, h) + lds_byte(wc * 32 + n * 16 + fr, k * 32 + fq * 8))
; template <int K, bool SWAP>
; __device__ __forceinline__ void gemm_kloop(const bf16* __restrict__ A, const bf16* __restrict__ Bt,
;                                            f32x4 (&acc)[2][2][4][2], bool pref = false) {
;     ...
;     LDB(B1, 0, 1); BAR; WAIT_L(0); MMA(0, 1, At, B1); BAR;
;     LDA(At, 0, 1); WAIT_V(4); BAR; WAIT_L(0); MMA(1, 0, At, B0); MMA(1, 1, At, B1); BAR; }
;   { LDB(B0, 1, 0); LDA(At, 1, 0); WAIT_V(2); BAR; WAIT_L(0); MMA(0, 0, At, B0); BAR;
	ds_read_b128 v[128:131], v156
	ds_read_b128 v[132:135], v156 offset:1024
	ds_read_b128 v[158:161], v156 offset:2048
	ds_read_b128 v[154:157], v156 offset:3072
	s_barrier
	s_waitcnt lgkmcnt(0)
	s_setprio 1
	s_waitcnt lgkmcnt(0)
	v_mfma_f32_16x16x32_bf16 v[92:95], v[128:131], v[170:173], v[92:95]
	v_mfma_f32_16x16x32_bf16 v[88:91], v[158:161], v[170:173], v[88:91]
	v_mfma_f32_16x16x32_bf16 v[80:83], v[158:161], v[198:201], v[80:83]
	v_mfma_f32_16x16x32_bf16 v[84:87], v[128:131], v[198:201], v[84:87]
	v_mfma_f32_16x16x32_bf16 v[76:79], v[128:131], v[206:209], v[76:79]
	v_mfma_f32_16x16x32_bf16 v[72:75], v[158:161], v[206:209], v[72:75]
	v_mfma_f32_16x16x32_bf16 v[64:67], v[158:161], v[214:217], v[64:67]
	v_mfma_f32_16x16x32_bf16 v[68:71], v[128:131], v[214:217], v[68:71]
	v_mfma_f32_16x16x32_bf16 v[92:95], v[132:135], v[174:177], v[92:95]
	v_mfma_f32_16x16x32_bf16 v[88:91], v[154:157], v[174:177], v[88:91]
	v_mfma_f32_16x16x32_bf16 v[80:83], v[154:157], v[202:205], v[80:83]
	v_mfma_f32_16x16x32_bf16 v[84:87], v[132:135], v[202:205], v[84:87]
	v_mfma_f32_16x16x32_bf16 v[76:79], v[132:135], v[210:213], v[76:79]
	v_mfma_f32_16x16x32_bf16 v[72:75], v[154:157], v[210:213], v[72:75]
	v_mfma_f32_16x16x32_bf16 v[64:67], v[154:157], v[218:221], v[64:67]
	v_mfma_f32_16x16x32_bf16 v[68:71], v[132:135], v[218:221], v[68:71]
	s_setprio 0
	s_barrier
	ds_read_b128 v[170:173], v151 offset:16384
	ds_read_b128 v[174:177], v151 offset:17408
	ds_read_b128 v[198:201], v150 offset:16384
	ds_read_b128 v[202:205], v150 offset:17408
	ds_read_b128 v[206:209], v149 offset:16384
	ds_read_b128 v[210:213], v149 offset:17408
	ds_read_b128 v[214:217], v148 offset:16384
	ds_read_b128 v[218:221], v148 offset:17408
	s_waitcnt vmcnt(4)
	s_barrier
	s_waitcnt lgkmcnt(0)
	s_setprio 1
	s_waitcnt lgkmcnt(0)
	v_mfma_f32_16x16x32_bf16 v[60:63], v[136:139], v[170:173], v[60:63]
	v_mfma_f32_16x16x32_bf16 v[56:59], v[162:165], v[170:173], v[56:59]
	v_mfma_f32_16x16x32_bf16 v[48:51], v[162:165], v[198:201], v[48:51]
	v_mfma_f32_16x16x32_bf16 v[52:55], v[136:139], v[198:201], v[52:55]
	v_mfma_f32_16x16x32_bf16 v[44:47], v[136:139], v[206:209], v[44:47]
	v_mfma_f32_16x16x32_bf16 v[40:43], v[162:165], v[206:209], v[40:43]
	v_mfma_f32_16x16x32_bf16 v[32:35], v[162:165], v[214:217], v[32:35]
	v_mfma_f32_16x16x32_bf16 v[36:39], v[136:139], v[214:217], v[36:39]
	v_mfma_f32_16x16x32_bf16 v[60:63], v[140:143], v[174:177], v[60:63]
	v_mfma_f32_16x16x32_bf16 v[56:59], v[166:169], v[174:177], v[56:59]
	v_mfma_f32_16x16x32_bf16 v[48:51], v[166:169], v[202:205], v[48:51]
	v_mfma_f32_16x16x32_bf16 v[52:55], v[140:143], v[202:205], v[52:55]
	v_mfma_f32_16x16x32_bf16 v[44:47], v[140:143], v[210:213], v[44:47]
	v_mfma_f32_16x16x32_bf16 v[40:43], v[166:169], v[210:213], v[40:43]
	v_mfma_f32_16x16x32_bf16 v[32:35], v[166:169], v[218:221], v[32:35]
	v_mfma_f32_16x16x32_bf16 v[36:39], v[140:143], v[218:221], v[36:39]
	s_setprio 0
	s_setprio 1
	v_mfma_f32_16x16x32_bf16 v[28:31], v[128:131], v[170:173], v[28:31]
	v_mfma_f32_16x16x32_bf16 v[24:27], v[158:161], v[170:173], v[24:27]
	v_mfma_f32_16x16x32_bf16 v[16:19], v[158:161], v[198:201], v[16:19]
	v_mfma_f32_16x16x32_bf16 v[20:23], v[128:131], v[198:201], v[20:23]
	v_mfma_f32_16x16x32_bf16 v[12:15], v[128:131], v[206:209], v[12:15]
	v_mfma_f32_16x16x32_bf16 v[8:11], v[158:161], v[206:209], v[8:11]
	v_mfma_f32_16x16x32_bf16 v[0:3], v[158:161], v[214:217], v[0:3]
	v_mfma_f32_16x16x32_bf16 v[4:7], v[128:131], v[214:217], v[4:7]
	v_mfma_f32_16x16x32_bf16 v[28:31], v[132:135], v[174:177], v[28:31]
	v_mfma_f32_16x16x32_bf16 v[24:27], v[154:157], v[174:177], v[24:27]
	v_mfma_f32_16x16x32_bf16 v[16:19], v[154:157], v[202:205], v[16:19]
	v_mfma_f32_16x16x32_bf16 v[20:23], v[132:135], v[202:205], v[20:23]
	v_mfma_f32_16x16x32_bf16 v[12:15], v[132:135], v[210:213], v[12:15]
	v_mfma_f32_16x16x32_bf16 v[8:11], v[154:157], v[210:213], v[8:11]
	v_mfma_f32_16x16x32_bf16 v[0:3], v[154:157], v[218:221], v[0:3]
	v_mfma_f32_16x16x32_bf16 v[4:7], v[132:135], v[218:221], v[4:7]
	s_setprio 0
	s_barrier
	ds_read_b128 v[128:131], v153
	ds_read_b128 v[132:135], v153 offset:1024
	ds_read_b128 v[136:139], v153 offset:2048
	ds_read_b128 v[140:143], v153 offset:3072
	ds_read_b128 v[154:157], v151 offset:32768
	ds_read_b128 v[158:161], v151 offset:33792
	ds_read_b128 v[162:165], v150 offset:32768
	ds_read_b128 v[166:169], v150 offset:33792
	ds_read_b128 v[170:173], v149 offset:32768
	ds_read_b128 v[174:177], v149 offset:33792
	ds_read_b128 v[198:201], v148 offset:32768
	ds_read_b128 v[202:205], v148 offset:33792
	s_waitcnt vmcnt(2)
	s_barrier
; #define WAIT_V(n) asm volatile("s_waitcnt vmcnt(" #n ")" ::: "memory")
; #define WAIT_L(n) asm volatile("s_waitcnt lgkmcnt(" #n ")" ::: "memory")
; #define BAR __builtin_amdgcn_s_barrier()
; #define LDA(dst, b, h)                                                                            \
;   _Pragma("unroll") for (int m = 0; m < 4; ++m) _Pragma("unroll") for (int k = 0; k < 2; ++k)                                         \
;     dst[m][k] = *reinterpret_cast<const bf16x8*>((char*)SA(b, h) + lds_byte(wr * 64 + m * 16 + fr, k * 32 + fq * 8))
; #define LDB(dst, b, h)                                                                            \
;   _Pragma("unroll") for (int n = 0; n < 2; ++n) _Pragma("unroll") for (int k = 0; k < 2; ++k)                                         \
;     dst[n][k] = *reinterpret_cast<const bf16x8*>((char*)SB(b, h) + lds_byte(wc * 32 + n * 16 + fr, k * 32 + fq * 8))
; template <int K, bool SWAP>
; __device__ __forceinline__ void gemm_kloop(const bf16* __restrict__ A, const bf16* __restrict__ Bt,
;                                            f32x4 (&acc)[2][2][4][2], bool pref = false) {
;     ...
;   { LDB(B0, 1, 0); LDA(At, 1, 0); WAIT_V(2); BAR; WAIT_L(0); MMA(0, 0, At, B0); BAR;
;     LDB(B1, 1, 1); WAIT_V(0); BAR; WAIT_L(0); MMA(0, 1, At, B1); BAR;
;     LDA(At, 1, 1); BAR; WAIT_L(0); MMA(1, 0, At, B0); MMA(1, 1, At, B1); BAR; }
;   if (wr == 0) BAR;
	s_waitcnt lgkmcnt(0)
	s_setprio 1
	s_waitcnt lgkmcnt(0)
	v_mfma_f32_16x16x32_bf16 v[124:127], v[128:131], v[154:157], v[124:127]
	v_mfma_f32_16x16x32_bf16 v[120:123], v[136:139], v[154:157], v[120:123]
	v_mfma_f32_16x16x32_bf16 v[112:115], v[136:139], v[162:165], v[112:115]
	v_mfma_f32_16x16x32_bf16 v[116:119], v[128:131], v[162:165], v[116:119]
	v_mfma_f32_16x16x32_bf16 v[108:111], v[128:131], v[170:173], v[108:111]
	v_mfma_f32_16x16x32_bf16 v[104:107], v[136:139], v[170:173], v[104:107]
	v_mfma_f32_16x16x32_bf16 v[96:99], v[136:139], v[198:201], v[96:99]
	v_mfma_f32_16x16x32_bf16 v[100:103], v[128:131], v[198:201], v[100:103]
	v_mfma_f32_16x16x32_bf16 v[124:127], v[132:135], v[158:161], v[124:127]
	v_mfma_f32_16x16x32_bf16 v[120:123], v[140:143], v[158:161], v[120:123]
	v_mfma_f32_16x16x32_bf16 v[112:115], v[140:143], v[166:169], v[112:115]
	v_mfma_f32_16x16x32_bf16 v[116:119], v[132:135], v[166:169], v[116:119]
	v_mfma_f32_16x16x32_bf16 v[108:111], v[132:135], v[174:177], v[108:111]
	v_mfma_f32_16x16x32_bf16 v[104:107], v[140:143], v[174:177], v[104:107]
	v_mfma_f32_16x16x32_bf16 v[96:99], v[140:143], v[202:205], v[96:99]
	v_mfma_f32_16x16x32_bf16 v[100:103], v[132:135], v[202:205], v[100:103]
	s_setprio 0
	s_barrier
	ds_read_b128 v[206:209], v152
	ds_read_b128 v[210:213], v152 offset:1024
	ds_read_b128 v[214:217], v152 offset:2048
	ds_read_b128 v[218:221], v152 offset:3072
	s_waitcnt vmcnt(0)
	s_barrier
	s_waitcnt lgkmcnt(0)
	s_setprio 1
	s_waitcnt lgkmcnt(0)
	v_mfma_f32_16x16x32_bf16 v[92:95], v[206:209], v[154:157], v[92:95]
	v_mfma_f32_16x16x32_bf16 v[88:91], v[214:217], v[154:157], v[88:91]
	v_mfma_f32_16x16x32_bf16 v[80:83], v[214:217], v[162:165], v[80:83]
	v_mfma_f32_16x16x32_bf16 v[84:87], v[206:209], v[162:165], v[84:87]
	v_mfma_f32_16x16x32_bf16 v[76:79], v[206:209], v[170:173], v[76:79]
	v_mfma_f32_16x16x32_bf16 v[72:75], v[214:217], v[170:173], v[72:75]
	v_mfma_f32_16x16x32_bf16 v[64:67], v[214:217], v[198:201], v[64:67]
	v_mfma_f32_16x16x32_bf16 v[68:71], v[206:209], v[198:201], v[68:71]
	v_mfma_f32_16x16x32_bf16 v[92:95], v[210:213], v[158:161], v[92:95]
	v_mfma_f32_16x16x32_bf16 v[88:91], v[218:221], v[158:161], v[88:91]
	v_mfma_f32_16x16x32_bf16 v[80:83], v[218:221], v[166:169], v[80:83]
	v_mfma_f32_16x16x32_bf16 v[84:87], v[210:213], v[166:169], v[84:87]
	v_mfma_f32_16x16x32_bf16 v[76:79], v[210:213], v[174:177], v[76:79]
	v_mfma_f32_16x16x32_bf16 v[72:75], v[218:221], v[174:177], v[72:75]
	v_mfma_f32_16x16x32_bf16 v[64:67], v[218:221], v[202:205], v[64:67]
	v_mfma_f32_16x16x32_bf16 v[68:71], v[210:213], v[202:205], v[68:71]
	s_setprio 0
	s_barrier
	ds_read_b128 v[152:155], v151 offset:49152
	ds_read_b128 v[156:159], v151 offset:50176
	ds_read_b128 v[160:163], v150 offset:49152
	ds_read_b128 v[164:167], v150 offset:50176
	ds_read_b128 v[168:171], v149 offset:49152
	ds_read_b128 v[172:175], v149 offset:50176
	ds_read_b128 v[176:179], v148 offset:49152
	ds_read_b128 v[146:149], v148 offset:50176
	s_barrier
	s_waitcnt lgkmcnt(0)
	s_setprio 1
	s_waitcnt lgkmcnt(0)
	v_mfma_f32_16x16x32_bf16 v[60:63], v[128:131], v[152:155], v[60:63]
	v_mfma_f32_16x16x32_bf16 v[56:59], v[136:139], v[152:155], v[56:59]
	v_mfma_f32_16x16x32_bf16 v[48:51], v[136:139], v[160:163], v[48:51]
	v_mfma_f32_16x16x32_bf16 v[52:55], v[128:131], v[160:163], v[52:55]
	v_mfma_f32_16x16x32_bf16 v[44:47], v[128:131], v[168:171], v[44:47]
	v_mfma_f32_16x16x32_bf16 v[40:43], v[136:139], v[168:171], v[40:43]
	v_mfma_f32_16x16x32_bf16 v[32:35], v[136:139], v[176:179], v[32:35]
	v_mfma_f32_16x16x32_bf16 v[36:39], v[128:131], v[176:179], v[36:39]
	v_mfma_f32_16x16x32_bf16 v[60:63], v[132:135], v[156:159], v[60:63]
	v_mfma_f32_16x16x32_bf16 v[56:59], v[140:143], v[156:159], v[56:59]
	v_mfma_f32_16x16x32_bf16 v[48:51], v[140:143], v[164:167], v[48:51]
	v_mfma_f32_16x16x32_bf16 v[52:55], v[132:135], v[164:167], v[52:55]
	v_mfma_f32_16x16x32_bf16 v[44:47], v[132:135], v[172:175], v[44:47]
	v_mfma_f32_16x16x32_bf16 v[40:43], v[140:143], v[172:175], v[40:43]
	v_mfma_f32_16x16x32_bf16 v[32:35], v[140:143], v[146:149], v[32:35]
	v_mfma_f32_16x16x32_bf16 v[36:39], v[132:135], v[146:149], v[36:39]
	s_setprio 0
	s_setprio 1
	v_mfma_f32_16x16x32_bf16 v[28:31], v[206:209], v[152:155], v[28:31]
	v_mfma_f32_16x16x32_bf16 v[24:27], v[214:217], v[152:155], v[24:27]
	v_mfma_f32_16x16x32_bf16 v[16:19], v[214:217], v[160:163], v[16:19]
	v_mfma_f32_16x16x32_bf16 v[20:23], v[206:209], v[160:163], v[20:23]
	v_mfma_f32_16x16x32_bf16 v[12:15], v[206:209], v[168:171], v[12:15]
	v_mfma_f32_16x16x32_bf16 v[8:11], v[214:217], v[168:171], v[8:11]
	v_mfma_f32_16x16x32_bf16 v[0:3], v[214:217], v[176:179], v[0:3]
	v_mfma_f32_16x16x32_bf16 v[4:7], v[206:209], v[176:179], v[4:7]
	v_mfma_f32_16x16x32_bf16 v[28:31], v[210:213], v[156:159], v[28:31]
	v_mfma_f32_16x16x32_bf16 v[24:27], v[218:221], v[156:159], v[24:27]
	v_mfma_f32_16x16x32_bf16 v[16:19], v[218:221], v[164:167], v[16:19]
	v_mfma_f32_16x16x32_bf16 v[20:23], v[210:213], v[164:167], v[20:23]
	v_mfma_f32_16x16x32_bf16 v[12:15], v[210:213], v[172:175], v[12:15]
	v_mfma_f32_16x16x32_bf16 v[8:11], v[218:221], v[172:175], v[8:11]
	v_mfma_f32_16x16x32_bf16 v[0:3], v[218:221], v[146:149], v[0:3]
	v_mfma_f32_16x16x32_bf16 v[4:7], v[210:213], v[146:149], v[4:7]
	s_setprio 0
	s_movk_i32 s5, 0x100
	v_cmp_gt_u32_e32 vcc, s5, v144
	s_barrier
	s_and_saveexec_b64 s[12:13], vcc
	s_cbranch_execz .LBB0_593
	s_barrier

; #define WAIT_V(n) asm volatile("s_waitcnt vmcnt(" #n ")" ::: "memory")
; #define WAIT_L(n) asm volatile("s_waitcnt lgkmcnt(" #n ")" ::: "memory")
; #define BAR __builtin_amdgcn_s_barrier()
; #define SCHED __builtin_amdgcn_sched_barrier(0)
; #define LDA(dst, b, h)                                                                            \
;   _Pragma("unroll") for (int m = 0; m < 4; ++m) _Pragma("unroll") for (int k = 0; k < 2; ++k)                                         \
;     dst[m][k] = *reinterpret_cast<const bf16x8*>((char*)SA(b, h) + lds_byte(wr * 64 + m * 16 + fr, k * 32 + fq * 8))
; #define LDB(dst, b, h)                                                                            \
;   _Pragma("unroll") for (int n = 0; n < 2; ++n) _Pragma("unroll") for (int k = 0; k < 2; ++k)                                         \
;     dst[n][k] = *reinterpret_cast<const bf16x8*>((char*)SB(b, h) + lds_byte(wc * 32 + n * 16 + fr, k * 32 + fq * 8))
; template <int K, bool SWAP>
; __device__ __forceinline__ void gemm_kloop(const bf16* __restrict__ A, const bf16* __restrict__ Bt,
;                                            f32x4 (&acc)[2][2][4][2], bool pref = false) {
;     ...
;   if (wr == 1) BAR;
;   WAIT_V(4); BAR;
;   STAGE(SB(1, 0), Bt, 0, 1); STAGE(SA(1, 0), A, 0, 1); STAGE(SB(1, 1), Bt, HALF, 1);
;   WAIT_V(6); BAR;
;   for (int t = 0; t < nt - 2; t += 2) {
;     LDB(B0, 0, 0); SCHED; LDA(At, 0, 0); STAGE(SA(1, 1), A, HALF, t + 1);
;     WAIT_L(8); BAR; WAIT_L(0); MMA(0, 0, At, B0); BAR; SCHED;
.LBB0_671:
	s_or_b64 exec, exec, s[0:1]
	v_add_u32_e32 v0, v15, v0
	v_and_b32_e32 v0, 0xfffffc00, v0
	v_sub_u32_e32 v0, v15, v0
	v_lshrrev_b32_e32 v2, 4, v0
	v_bitop3_b32 v2, v2, v0, 32 bitop3:0x6c
	v_ashrrev_i32_e32 v3, 31, v2
	v_add_u32_e32 v1, v128, v1
	v_lshrrev_b32_e32 v3, 26, v3
	v_ashrrev_i32_e32 v1, 6, v1
	v_add_u32_e32 v3, v2, v3
	v_lshlrev_b32_e32 v0, 3, v1
	v_ashrrev_i32_e32 v4, 6, v3
	v_and_b32_e32 v3, 0xc0, v3
	v_and_b32_e32 v0, -16, v0
	v_lshlrev_b32_e32 v1, 5, v1
	v_sub_u32_e32 v2, v2, v3
	v_add_u32_e32 v0, v4, v0
	v_and_b32_e32 v1, 32, v1
	v_ashrrev_i16_sdwa v2, v193, sext(v2) dst_sel:DWORD dst_unused:UNUSED_PAD src0_sel:DWORD src1_sel:BYTE_0
	v_add_u32_sdwa v2, v1, sext(v2) dst_sel:DWORD dst_unused:UNUSED_PAD src0_sel:DWORD src1_sel:WORD_0
	v_ashrrev_i32_e32 v1, 31, v0
	v_lshlrev_b64 v[0:1], 9, v[0:1]
	v_ashrrev_i32_e32 v3, 31, v2
	v_readlane_b32 s68, v254, 33
	v_lshl_add_u64 v[4:5], s[58:59], 0, v[0:1]
	v_lshlrev_b64 v[2:3], 1, v[2:3]
	v_add_u32_e32 v6, s68, v15
	v_lshl_add_u64 v[8:9], v[4:5], 0, v[2:3]
	s_mov_b64 s[0:1], 0x80
	v_readfirstlane_b32 s63, v6
	v_lshl_add_u64 v[4:5], v[8:9], 0, s[0:1]
	s_mov_b32 m0, s63
	s_waitcnt vmcnt(4)
	s_barrier
	global_load_lds_dwordx4 v[4:5], off
	v_ashrrev_i32_e32 v4, 31, v13
	v_lshrrev_b32_e32 v4, 22, v4
	v_add_u32_e32 v4, v13, v4
	v_ashrrev_i32_e32 v5, 10, v4
	v_mul_i32_i24_e32 v4, 0x400, v5
	v_sub_u32_e32 v4, v13, v4
	v_lshrrev_b32_e32 v6, 4, v4
	v_bitop3_b32 v6, v6, v4, 32 bitop3:0x6c
	v_ashrrev_i32_e32 v7, 31, v6
	v_lshrrev_b32_e32 v7, 26, v7
	v_add_u32_e32 v7, v6, v7
	v_lshlrev_b32_e32 v4, 3, v5
	v_ashrrev_i32_e32 v10, 6, v7
	v_and_b32_e32 v7, 0xc0, v7
	v_and_b32_e32 v4, -16, v4
	v_lshlrev_b32_e32 v5, 5, v5
	v_sub_u32_e32 v6, v6, v7
	v_add_u32_e32 v4, v10, v4
	v_and_b32_e32 v5, 32, v5
	v_ashrrev_i16_sdwa v6, v193, sext(v6) dst_sel:DWORD dst_unused:UNUSED_PAD src0_sel:DWORD src1_sel:BYTE_0
	v_add_u32_sdwa v6, v5, sext(v6) dst_sel:DWORD dst_unused:UNUSED_PAD src0_sel:DWORD src1_sel:WORD_0
	v_ashrrev_i32_e32 v5, 31, v4
	v_lshlrev_b64 v[4:5], 9, v[4:5]
	v_ashrrev_i32_e32 v7, 31, v6
	v_lshl_add_u64 v[10:11], s[58:59], 0, v[4:5]
	v_lshlrev_b64 v[6:7], 1, v[6:7]
	v_lshl_add_u64 v[10:11], v[10:11], 0, v[6:7]
	v_add_u32_e32 v17, s68, v13
	v_lshl_add_u64 v[18:19], v[10:11], 0, s[0:1]
	v_readfirstlane_b32 s67, v17
	v_readlane_b32 s0, v254, 50
	s_mov_b32 m0, s67
	v_readlane_b32 s1, v254, 51
	v_add_u32_e32 v17, 0x8000, v12
	global_load_lds_dwordx4 v[18:19], off
	v_lshl_add_u64 v[18:19], s[0:1], 0, v[0:1]
	v_readfirstlane_b32 s65, v17
	v_lshl_add_u64 v[18:19], v[18:19], 0, v[2:3]
	s_mov_b32 m0, s65
	v_add_u32_e32 v17, 0xa000, v12
	global_load_lds_dwordx4 v[18:19], off
	v_lshl_add_u64 v[18:19], s[0:1], 0, v[4:5]
	v_readfirstlane_b32 s61, v17
	s_add_u32 s0, s58, 0x10080
	v_readlane_b32 s69, v254, 34
	v_lshl_add_u64 v[18:19], v[18:19], 0, v[6:7]
	s_mov_b32 m0, s61
	s_addc_u32 s1, s59, 0
	v_add_u32_e32 v17, s69, v15
	global_load_lds_dwordx4 v[18:19], off
	v_lshl_add_u64 v[18:19], s[0:1], 0, v[0:1]
	v_readfirstlane_b32 s41, v17
	v_lshl_add_u64 v[18:19], v[18:19], 0, v[2:3]
	s_mov_b32 m0, s41
	v_add_u32_e32 v17, s69, v13
	global_load_lds_dwordx4 v[18:19], off
	v_lshl_add_u64 v[18:19], s[0:1], 0, v[4:5]
	v_readfirstlane_b32 s23, v17
	v_lshl_add_u64 v[18:19], v[18:19], 0, v[6:7]
	s_mov_b32 m0, s23
	v_and_b32_e32 v17, 15, v128
	global_load_lds_dwordx4 v[18:19], off
	v_lshlrev_b32_e32 v18, 2, v128
	v_and_b32_e32 v42, 48, v128
	v_lshlrev_b32_e32 v17, 6, v17
	v_and_b32_e32 v43, 32, v18
	v_bitop3_b32 v126, v17, v43, v42 bitop3:0x36
	v_lshlrev_b32_e32 v17, 6, v128
	s_add_i32 s40, 0, 0x10000
	v_and_b32_e32 v127, 0x3000, v17
	v_add3_u32 v129, s40, v126, v127
	s_waitcnt vmcnt(6)
	s_barrier
	ds_read_b128 v[18:21], v129
	ds_read_b128 v[22:25], v129 offset:1024
	ds_read_b128 v[26:29], v129 offset:2048
	ds_read_b128 v[30:33], v129 offset:3072
	s_add_u32 s0, s58, 0x10180
	s_addc_u32 s1, s59, 0
	v_and_b32_e32 v17, 0x3c0, v17
	v_lshlrev_b32_e32 v16, 13, v16
	v_bitop3_b32 v17, v17, v43, v42 bitop3:0x36
	s_mov_b64 s[70:71], s[72:73]
	v_add_u32_e32 v66, 0xc000, v12
	v_add3_u32 v178, 0, v126, v16
	v_add3_u32 v179, 0, v17, v16
	v_lshl_add_u64 v[16:17], s[70:71], 0, v[0:1]
	v_readfirstlane_b32 s66, v66
	v_lshl_add_u64 v[16:17], v[16:17], 0, v[2:3]
	s_mov_b32 m0, s66
	v_add_u32_e32 v66, 0xe000, v12
	ds_read_b128 v[34:37], v178
	ds_read_b128 v[38:41], v178 offset:1024
	ds_read_b128 v[42:45], v179 offset:2048
	ds_read_b128 v[46:49], v179 offset:3072
	ds_read_b128 v[50:53], v179 offset:4096
	ds_read_b128 v[54:57], v179 offset:5120
	ds_read_b128 v[58:61], v179 offset:6144
	ds_read_b128 v[62:65], v179 offset:7168
	global_load_lds_dwordx4 v[16:17], off
	v_lshl_add_u64 v[16:17], s[70:71], 0, v[4:5]
	v_readfirstlane_b32 s64, v66
	v_lshl_add_u64 v[16:17], v[16:17], 0, v[6:7]
	s_mov_b32 m0, s64
	s_add_u32 s58, s58, 0x10100
	global_load_lds_dwordx4 v[16:17], off
	s_waitcnt lgkmcnt(8)
	s_barrier
	s_waitcnt lgkmcnt(0)
	s_addc_u32 s59, s59, 0
	s_setprio 1
	s_waitcnt lgkmcnt(0)
	v_mfma_f32_16x16x32_bf16 v[66:69], v[18:21], v[34:37], 0
	v_mfma_f32_16x16x32_bf16 v[70:73], v[26:29], v[34:37], 0
	v_mfma_f32_16x16x32_bf16 v[74:77], v[18:21], v[42:45], 0
	v_mfma_f32_16x16x32_bf16 v[78:81], v[26:29], v[42:45], 0
	v_mfma_f32_16x16x32_bf16 v[82:85], v[18:21], v[50:53], 0
	v_mfma_f32_16x16x32_bf16 v[86:89], v[26:29], v[50:53], 0
	v_mfma_f32_16x16x32_bf16 v[90:93], v[18:21], v[58:61], 0
	v_mfma_f32_16x16x32_bf16 v[94:97], v[26:29], v[58:61], 0
	v_mfma_f32_16x16x32_bf16 v[66:69], v[22:25], v[38:41], v[66:69]
	v_mfma_f32_16x16x32_bf16 v[70:73], v[30:33], v[38:41], v[70:73]
	v_mfma_f32_16x16x32_bf16 v[74:77], v[22:25], v[46:49], v[74:77]
	v_mfma_f32_16x16x32_bf16 v[78:81], v[30:33], v[46:49], v[78:81]
	v_mfma_f32_16x16x32_bf16 v[82:85], v[22:25], v[54:57], v[82:85]
	v_mfma_f32_16x16x32_bf16 v[86:89], v[30:33], v[54:57], v[86:89]
	v_mfma_f32_16x16x32_bf16 v[90:93], v[22:25], v[62:65], v[90:93]
	v_mfma_f32_16x16x32_bf16 v[94:97], v[30:33], v[62:65], v[94:97]
	s_setprio 0
	s_barrier
; #define WAIT_V(n) asm volatile("s_waitcnt vmcnt(" #n ")" ::: "memory")
; #define WAIT_L(n) asm volatile("s_waitcnt lgkmcnt(" #n ")" ::: "memory")
; #define BAR __builtin_amdgcn_s_barrier()
; #define SCHED __builtin_amdgcn_sched_barrier(0)
; #define LDA(dst, b, h)                                                                            \
;   _Pragma("unroll") for (int m = 0; m < 4; ++m) _Pragma("unroll") for (int k = 0; k < 2; ++k)                                         \
;     dst[m][k] = *reinterpret_cast<const bf16x8*>((char*)SA(b, h) + lds_byte(wr * 64 + m * 16 + fr, k * 32 + fq * 8))
; #define LDB(dst, b, h)                                                                            \
;   _Pragma("unroll") for (int n = 0; n < 2; ++n) _Pragma("unroll") for (int k = 0; k < 2; ++k)                                         \
;     dst[n][k] = *reinterpret_cast<const bf16x8*>((char*)SB(b, h) + lds_byte(wc * 32 + n * 16 + fr, k * 32 + fq * 8))
; template <int K, bool SWAP>
; __device__ __forceinline__ void gemm_kloop(const bf16* __restrict__ A, const bf16* __restrict__ Bt,
;                                            f32x4 (&acc)[2][2][4][2], bool pref = false) {
;     ...
;     WAIT_L(8); BAR; WAIT_L(0); MMA(0, 0, At, B0); BAR; SCHED;
;     LDB(B1, 0, 1); STAGE(SB(0, 0), Bt, 0, t + 2);
;     BAR; WAIT_L(0); MMA(0, 1, At, B1); BAR;
;     LDA(At, 0, 1); STAGE(SA(0, 0), A, 0, t + 2);
;     BAR; WAIT_L(0); MMA(1, 0, At, B0); BAR; SCHED;
;     STAGE(SB(0, 1), Bt, HALF, t + 2);
;     WAIT_V(6); BAR; MMA(1, 1, At, B1); BAR;
;     LDB(B0, 1, 0); SCHED; LDA(At, 1, 0); STAGE(SA(0, 1), A, HALF, t + 2);
	v_add_u32_e32 v15, s40, v15
	v_add3_u32 v186, s33, v126, v127
	v_readfirstlane_b32 s70, v15
	v_add_u32_e32 v15, s40, v13
	v_lshl_add_u64 v[16:17], v[8:9], 0, s[44:45]
	s_mov_b32 m0, s70
	v_readfirstlane_b32 s70, v15
	ds_read_b128 v[98:101], v186
	ds_read_b128 v[102:105], v186 offset:1024
	ds_read_b128 v[106:109], v186 offset:2048
	ds_read_b128 v[110:113], v186 offset:3072
	global_load_lds_dwordx4 v[16:17], off
	v_lshl_add_u64 v[16:17], v[10:11], 0, s[44:45]
	s_mov_b32 m0, s70
	s_nop 0
	global_load_lds_dwordx4 v[16:17], off
	s_barrier
	s_waitcnt lgkmcnt(0)
	s_setprio 1
	s_waitcnt lgkmcnt(0)
	v_mfma_f32_16x16x32_bf16 v[114:117], v[98:101], v[34:37], 0
	v_mfma_f32_16x16x32_bf16 v[34:37], v[106:109], v[34:37], 0
	v_mfma_f32_16x16x32_bf16 v[114:117], v[102:105], v[38:41], v[114:117]
	v_mfma_f32_16x16x32_bf16 v[34:37], v[110:113], v[38:41], v[34:37]
	v_mfma_f32_16x16x32_bf16 v[38:41], v[98:101], v[42:45], 0
	v_mfma_f32_16x16x32_bf16 v[42:45], v[106:109], v[42:45], 0
	v_mfma_f32_16x16x32_bf16 v[38:41], v[102:105], v[46:49], v[38:41]
	v_mfma_f32_16x16x32_bf16 v[42:45], v[110:113], v[46:49], v[42:45]
	v_mfma_f32_16x16x32_bf16 v[46:49], v[98:101], v[50:53], 0
	v_mfma_f32_16x16x32_bf16 v[50:53], v[106:109], v[50:53], 0
	v_mfma_f32_16x16x32_bf16 v[46:49], v[102:105], v[54:57], v[46:49]
	v_mfma_f32_16x16x32_bf16 v[50:53], v[110:113], v[54:57], v[50:53]
	v_mfma_f32_16x16x32_bf16 v[54:57], v[98:101], v[58:61], 0
	v_mfma_f32_16x16x32_bf16 v[58:61], v[106:109], v[58:61], 0
	v_mfma_f32_16x16x32_bf16 v[54:57], v[102:105], v[62:65], v[54:57]
	v_mfma_f32_16x16x32_bf16 v[58:61], v[110:113], v[62:65], v[58:61]
	s_setprio 0
	v_lshl_add_u64 v[16:17], s[4:5], 0, v[0:1]
	v_readfirstlane_b32 s70, v12
	v_lshl_add_u64 v[16:17], v[16:17], 0, v[2:3]
	s_mov_b32 m0, s70
	v_add_u32_e32 v15, 0x2000, v12
	s_barrier
	ds_read_b128 v[62:65], v178 offset:16384
	ds_read_b128 v[118:121], v178 offset:17408
	ds_read_b128 v[122:125], v179 offset:18432
	ds_read_b128 v[130:133], v179 offset:19456
	ds_read_b128 v[134:137], v179 offset:20480
	ds_read_b128 v[138:141], v179 offset:21504
	ds_read_b128 v[142:145], v179 offset:22528
	ds_read_b128 v[146:149], v179 offset:23552
	global_load_lds_dwordx4 v[16:17], off
	v_lshl_add_u64 v[16:17], s[4:5], 0, v[4:5]
	v_readfirstlane_b32 s70, v15
	v_lshl_add_u64 v[16:17], v[16:17], 0, v[6:7]
	s_mov_b32 m0, s70
	s_nop 0
	global_load_lds_dwordx4 v[16:17], off
	s_barrier
	s_waitcnt lgkmcnt(0)
	s_setprio 1
	s_waitcnt lgkmcnt(0)
	v_mfma_f32_16x16x32_bf16 v[150:153], v[18:21], v[62:65], 0
	v_mfma_f32_16x16x32_bf16 v[158:161], v[18:21], v[122:125], 0
	v_mfma_f32_16x16x32_bf16 v[166:169], v[18:21], v[134:137], 0
	v_mfma_f32_16x16x32_bf16 v[16:19], v[18:21], v[142:145], 0
	v_mfma_f32_16x16x32_bf16 v[150:153], v[22:25], v[118:121], v[150:153]
	v_mfma_f32_16x16x32_bf16 v[158:161], v[22:25], v[130:133], v[158:161]
	v_mfma_f32_16x16x32_bf16 v[166:169], v[22:25], v[138:141], v[166:169]
	v_mfma_f32_16x16x32_bf16 v[16:19], v[22:25], v[146:149], v[16:19]
	v_mfma_f32_16x16x32_bf16 v[20:23], v[26:29], v[142:145], 0
	v_mfma_f32_16x16x32_bf16 v[154:157], v[26:29], v[62:65], 0
	v_mfma_f32_16x16x32_bf16 v[162:165], v[26:29], v[122:125], 0
	v_mfma_f32_16x16x32_bf16 v[170:173], v[26:29], v[134:137], 0
	v_mfma_f32_16x16x32_bf16 v[20:23], v[30:33], v[146:149], v[20:23]
	v_mfma_f32_16x16x32_bf16 v[154:157], v[30:33], v[118:121], v[154:157]
	v_mfma_f32_16x16x32_bf16 v[162:165], v[30:33], v[130:133], v[162:165]
	v_mfma_f32_16x16x32_bf16 v[170:173], v[30:33], v[138:141], v[170:173]
	s_setprio 0
	s_barrier
	v_lshl_add_u64 v[24:25], s[58:59], 0, v[0:1]
	v_readfirstlane_b32 s70, v14
	v_add_u32_e32 v13, s33, v13
	v_lshl_add_u64 v[24:25], v[24:25], 0, v[2:3]
	s_mov_b32 m0, s70
	v_lshl_add_u64 v[14:15], s[58:59], 0, v[4:5]
	v_readfirstlane_b32 s58, v13
	global_load_lds_dwordx4 v[24:25], off
	v_lshl_add_u64 v[14:15], v[14:15], 0, v[6:7]
	s_mov_b32 m0, s58
	s_nop 0
	global_load_lds_dwordx4 v[14:15], off
	s_waitcnt vmcnt(6)
	s_barrier
	s_setprio 1
	v_mfma_f32_16x16x32_bf16 v[24:27], v[98:101], v[62:65], 0
	v_mfma_f32_16x16x32_bf16 v[28:31], v[106:109], v[62:65], 0
	v_mfma_f32_16x16x32_bf16 v[24:27], v[102:105], v[118:121], v[24:27]
	v_mfma_f32_16x16x32_bf16 v[28:31], v[110:113], v[118:121], v[28:31]
	v_mfma_f32_16x16x32_bf16 v[62:65], v[98:101], v[122:125], 0
	v_mfma_f32_16x16x32_bf16 v[118:121], v[106:109], v[122:125], 0
	v_mfma_f32_16x16x32_bf16 v[122:125], v[98:101], v[134:137], 0
	v_mfma_f32_16x16x32_bf16 v[98:101], v[98:101], v[142:145], 0
	v_mfma_f32_16x16x32_bf16 v[62:65], v[102:105], v[130:133], v[62:65]
	v_mfma_f32_16x16x32_bf16 v[122:125], v[102:105], v[138:141], v[122:125]
	v_mfma_f32_16x16x32_bf16 v[98:101], v[102:105], v[146:149], v[98:101]
	v_mfma_f32_16x16x32_bf16 v[102:105], v[106:109], v[142:145], 0
	v_mfma_f32_16x16x32_bf16 v[118:121], v[110:113], v[130:133], v[118:121]
	v_mfma_f32_16x16x32_bf16 v[130:133], v[106:109], v[134:137], 0
	v_mfma_f32_16x16x32_bf16 v[102:105], v[110:113], v[146:149], v[102:105]
	v_mfma_f32_16x16x32_bf16 v[130:133], v[110:113], v[138:141], v[130:133]
	s_setprio 0
	v_add3_u32 v188, s68, v126, v127
	s_barrier
	ds_read_b128 v[106:109], v188
	ds_read_b128 v[110:113], v188 offset:1024
	ds_read_b128 v[134:137], v188 offset:2048
	ds_read_b128 v[138:141], v188 offset:3072
	v_add_u32_e32 v13, 0x4000, v12
	v_lshl_add_u64 v[14:15], s[8:9], 0, v[0:1]
	v_readfirstlane_b32 s58, v13
	v_lshl_add_u64 v[14:15], v[14:15], 0, v[2:3]
	s_mov_b32 m0, s58
	v_add_u32_e32 v12, 0x6000, v12
	ds_read_b128 v[142:145], v178 offset:32768
	ds_read_b128 v[146:149], v178 offset:33792
	ds_read_b128 v[174:177], v179 offset:34816
	ds_read_b128 v[198:201], v179 offset:35840
	ds_read_b128 v[202:205], v179 offset:36864
	ds_read_b128 v[206:209], v179 offset:37888
	ds_read_b128 v[210:213], v179 offset:38912
	ds_read_b128 v[214:217], v179 offset:39936
	global_load_lds_dwordx4 v[14:15], off
	v_lshl_add_u64 v[14:15], s[8:9], 0, v[4:5]
	v_readfirstlane_b32 s58, v12
	v_lshl_add_u64 v[14:15], v[14:15], 0, v[6:7]
	s_mov_b32 m0, s58
	s_nop 0
	global_load_lds_dwordx4 v[14:15], off
	s_waitcnt lgkmcnt(8)
	s_barrier
; #define WAIT_L(n) asm volatile("s_waitcnt lgkmcnt(" #n ")" ::: "memory")
; #define BAR __builtin_amdgcn_s_barrier()
; #define SCHED __builtin_amdgcn_sched_barrier(0)
; #define LDA(dst, b, h)                                                                            \
;   _Pragma("unroll") for (int m = 0; m < 4; ++m) _Pragma("unroll") for (int k = 0; k < 2; ++k)                                         \
;     dst[m][k] = *reinterpret_cast<const bf16x8*>((char*)SA(b, h) + lds_byte(wr * 64 + m * 16 + fr, k * 32 + fq * 8))
; #define LDB(dst, b, h)                                                                            \
;   _Pragma("unroll") for (int n = 0; n < 2; ++n) _Pragma("unroll") for (int k = 0; k < 2; ++k)                                         \
;     dst[n][k] = *reinterpret_cast<const bf16x8*>((char*)SB(b, h) + lds_byte(wc * 32 + n * 16 + fr, k * 32 + fq * 8))
; template <int K, bool SWAP>
; __device__ __forceinline__ void gemm_kloop(const bf16* __restrict__ A, const bf16* __restrict__ Bt,
;                                            f32x4 (&acc)[2][2][4][2], bool pref = false) {
;     ...
;     WAIT_L(8); BAR; WAIT_L(0); MMA(0, 0, At, B0); BAR; SCHED;
;     LDB(B1, 1, 1); STAGE(SB(1, 0), Bt, 0, t + 3);
;     BAR; WAIT_L(0); MMA(0, 1, At, B1); BAR;
;     LDA(At, 1, 1); STAGE(SA(1, 0), A, 0, t + 3);
;     BAR; WAIT_L(0); MMA(1, 0, At, B0); BAR; SCHED;
;     STAGE(SB(1, 1), Bt, HALF, t + 3);
	s_waitcnt lgkmcnt(0)
	s_setprio 1
	s_waitcnt lgkmcnt(0)
	v_mfma_f32_16x16x32_bf16 v[12:15], v[106:109], v[142:145], v[66:69]
	v_mfma_f32_16x16x32_bf16 v[66:69], v[134:137], v[142:145], v[70:73]
	v_mfma_f32_16x16x32_bf16 v[70:73], v[106:109], v[174:177], v[74:77]
	v_mfma_f32_16x16x32_bf16 v[74:77], v[134:137], v[174:177], v[78:81]
	v_mfma_f32_16x16x32_bf16 v[78:81], v[106:109], v[202:205], v[82:85]
	v_mfma_f32_16x16x32_bf16 v[82:85], v[134:137], v[202:205], v[86:89]
	v_mfma_f32_16x16x32_bf16 v[86:89], v[106:109], v[210:213], v[90:93]
	v_mfma_f32_16x16x32_bf16 v[90:93], v[134:137], v[210:213], v[94:97]
	v_mfma_f32_16x16x32_bf16 v[12:15], v[110:113], v[146:149], v[12:15]
	v_mfma_f32_16x16x32_bf16 v[66:69], v[138:141], v[146:149], v[66:69]
	v_mfma_f32_16x16x32_bf16 v[70:73], v[110:113], v[198:201], v[70:73]
	v_mfma_f32_16x16x32_bf16 v[74:77], v[138:141], v[198:201], v[74:77]
	v_mfma_f32_16x16x32_bf16 v[78:81], v[110:113], v[206:209], v[78:81]
	v_mfma_f32_16x16x32_bf16 v[82:85], v[138:141], v[206:209], v[82:85]
	v_mfma_f32_16x16x32_bf16 v[86:89], v[110:113], v[214:217], v[86:89]
	v_mfma_f32_16x16x32_bf16 v[90:93], v[138:141], v[214:217], v[90:93]
	s_setprio 0
	s_barrier
	s_mov_b32 m0, s63
	v_add3_u32 v189, s69, v126, v127
	v_lshl_add_u64 v[8:9], v[8:9], 0, s[52:53]
	ds_read_b128 v[94:97], v189
	ds_read_b128 v[218:221], v189 offset:1024
	ds_read_b128 v[222:225], v189 offset:2048
	ds_read_b128 v[226:229], v189 offset:3072
	global_load_lds_dwordx4 v[8:9], off
	v_lshl_add_u64 v[8:9], v[10:11], 0, s[52:53]
	s_mov_b32 m0, s67
	s_nop 0
	global_load_lds_dwordx4 v[8:9], off
	s_barrier
	s_waitcnt lgkmcnt(0)
	s_setprio 1
	s_waitcnt lgkmcnt(0)
	v_mfma_f32_16x16x32_bf16 v[8:11], v[94:97], v[142:145], v[114:117]
	v_mfma_f32_16x16x32_bf16 v[32:35], v[222:225], v[142:145], v[34:37]
	v_mfma_f32_16x16x32_bf16 v[36:39], v[94:97], v[174:177], v[38:41]
	v_mfma_f32_16x16x32_bf16 v[40:43], v[222:225], v[174:177], v[42:45]
	v_mfma_f32_16x16x32_bf16 v[44:47], v[94:97], v[202:205], v[46:49]
	v_mfma_f32_16x16x32_bf16 v[48:51], v[222:225], v[202:205], v[50:53]
	v_mfma_f32_16x16x32_bf16 v[52:55], v[94:97], v[210:213], v[54:57]
	v_mfma_f32_16x16x32_bf16 v[56:59], v[222:225], v[210:213], v[58:61]
	v_mfma_f32_16x16x32_bf16 v[8:11], v[218:221], v[146:149], v[8:11]
	v_mfma_f32_16x16x32_bf16 v[32:35], v[226:229], v[146:149], v[32:35]
	v_mfma_f32_16x16x32_bf16 v[36:39], v[218:221], v[198:201], v[36:39]
	v_mfma_f32_16x16x32_bf16 v[40:43], v[226:229], v[198:201], v[40:43]
	v_mfma_f32_16x16x32_bf16 v[44:47], v[218:221], v[206:209], v[44:47]
	v_mfma_f32_16x16x32_bf16 v[48:51], v[226:229], v[206:209], v[48:51]
	v_mfma_f32_16x16x32_bf16 v[52:55], v[218:221], v[214:217], v[52:55]
	v_mfma_f32_16x16x32_bf16 v[56:59], v[226:229], v[214:217], v[56:59]
	s_setprio 0
	v_lshl_add_u64 v[60:61], s[14:15], 0, v[0:1]
	s_mov_b32 m0, s65
	v_lshl_add_u64 v[60:61], v[60:61], 0, v[2:3]
	s_barrier
	ds_read_b128 v[114:117], v178 offset:49152
	ds_read_b128 v[142:145], v178 offset:50176
	ds_read_b128 v[146:149], v179 offset:51200
	ds_read_b128 v[174:177], v179 offset:52224
	ds_read_b128 v[198:201], v179 offset:53248
	ds_read_b128 v[202:205], v179 offset:54272
	ds_read_b128 v[206:209], v179 offset:55296
	ds_read_b128 v[210:213], v179 offset:56320
	global_load_lds_dwordx4 v[60:61], off
	v_lshl_add_u64 v[60:61], s[14:15], 0, v[4:5]
	v_lshl_add_u64 v[60:61], v[60:61], 0, v[6:7]
	s_mov_b32 m0, s61
	s_nop 0
	global_load_lds_dwordx4 v[60:61], off
	s_barrier
	s_waitcnt lgkmcnt(0)
	s_setprio 1
	s_waitcnt lgkmcnt(0)
	v_mfma_f32_16x16x32_bf16 v[16:19], v[106:109], v[206:209], v[16:19]
	v_mfma_f32_16x16x32_bf16 v[20:23], v[134:137], v[206:209], v[20:23]
	v_mfma_f32_16x16x32_bf16 v[154:157], v[134:137], v[114:117], v[154:157]
	v_mfma_f32_16x16x32_bf16 v[150:153], v[106:109], v[114:117], v[150:153]
	v_mfma_f32_16x16x32_bf16 v[158:161], v[106:109], v[146:149], v[158:161]
	v_mfma_f32_16x16x32_bf16 v[162:165], v[134:137], v[146:149], v[162:165]
	v_mfma_f32_16x16x32_bf16 v[170:173], v[134:137], v[198:201], v[170:173]
	v_mfma_f32_16x16x32_bf16 v[166:169], v[106:109], v[198:201], v[166:169]
	v_mfma_f32_16x16x32_bf16 v[16:19], v[110:113], v[210:213], v[16:19]
	v_mfma_f32_16x16x32_bf16 v[20:23], v[138:141], v[210:213], v[20:23]
	v_mfma_f32_16x16x32_bf16 v[154:157], v[138:141], v[142:145], v[154:157]
	v_mfma_f32_16x16x32_bf16 v[150:153], v[110:113], v[142:145], v[150:153]
	v_mfma_f32_16x16x32_bf16 v[158:161], v[110:113], v[174:177], v[158:161]
	v_mfma_f32_16x16x32_bf16 v[162:165], v[138:141], v[174:177], v[162:165]
	v_mfma_f32_16x16x32_bf16 v[170:173], v[138:141], v[202:205], v[170:173]
	v_mfma_f32_16x16x32_bf16 v[166:169], v[110:113], v[202:205], v[166:169]
	s_setprio 0
	s_barrier
	v_lshl_add_u64 v[60:61], s[0:1], 0, v[0:1]
	s_mov_b32 m0, s41
	v_lshl_add_u64 v[60:61], v[60:61], 0, v[2:3]
	global_load_lds_dwordx4 v[60:61], off
	v_lshl_add_u64 v[60:61], s[0:1], 0, v[4:5]
	v_lshl_add_u64 v[60:61], v[60:61], 0, v[6:7]
	s_mov_b32 m0, s23
	s_nop 0
	global_load_lds_dwordx4 v[60:61], off
	s_waitcnt vmcnt(6)
	s_barrier
; #define WAIT_V(n) asm volatile("s_waitcnt vmcnt(" #n ")" ::: "memory")
; #define WAIT_L(n) asm volatile("s_waitcnt lgkmcnt(" #n ")" ::: "memory")
; #define BAR __builtin_amdgcn_s_barrier()
; #define LDA(dst, b, h)                                                                            \
;   _Pragma("unroll") for (int m = 0; m < 4; ++m) _Pragma("unroll") for (int k = 0; k < 2; ++k)                                         \
;     dst[m][k] = *reinterpret_cast<const bf16x8*>((char*)SA(b, h) + lds_byte(wr * 64 + m * 16 + fr, k * 32 + fq * 8))
; #define LDB(dst, b, h)                                                                            \
;   _Pragma("unroll") for (int n = 0; n < 2; ++n) _Pragma("unroll") for (int k = 0; k < 2; ++k)                                         \
;     dst[n][k] = *reinterpret_cast<const bf16x8*>((char*)SB(b, h) + lds_byte(wc * 32 + n * 16 + fr, k * 32 + fq * 8))
; template <int K, bool SWAP>
; __device__ __forceinline__ void gemm_kloop(const bf16* __restrict__ A, const bf16* __restrict__ Bt,
;                                            f32x4 (&acc)[2][2][4][2], bool pref = false) {
;     ...
;     WAIT_V(6); BAR; MMA(1, 1, At, B1); BAR;
;   }
;   { LDB(B0, 0, 0); LDA(At, 0, 0); STAGE(SA(1, 1), A, HALF, nt - 1);
;     BAR; WAIT_L(0); MMA(0, 0, At, B0); BAR;
;     LDB(B1, 0, 1); BAR; WAIT_L(0); MMA(0, 1, At, B1); BAR;
;     LDA(At, 0, 1); WAIT_V(4); BAR; WAIT_L(0); MMA(1, 0, At, B0); MMA(1, 1, At, B1); BAR; }
	s_setprio 1
	v_mfma_f32_16x16x32_bf16 v[24:27], v[94:97], v[114:117], v[24:27]
	v_mfma_f32_16x16x32_bf16 v[28:31], v[222:225], v[114:117], v[28:31]
	v_mfma_f32_16x16x32_bf16 v[60:63], v[94:97], v[146:149], v[62:65]
	v_mfma_f32_16x16x32_bf16 v[106:109], v[222:225], v[146:149], v[118:121]
	v_mfma_f32_16x16x32_bf16 v[110:113], v[94:97], v[198:201], v[122:125]
	v_mfma_f32_16x16x32_bf16 v[114:117], v[222:225], v[198:201], v[130:133]
	v_mfma_f32_16x16x32_bf16 v[94:97], v[94:97], v[206:209], v[98:101]
	v_mfma_f32_16x16x32_bf16 v[98:101], v[222:225], v[206:209], v[102:105]
	v_mfma_f32_16x16x32_bf16 v[24:27], v[218:221], v[142:145], v[24:27]
	v_mfma_f32_16x16x32_bf16 v[28:31], v[226:229], v[142:145], v[28:31]
	v_mfma_f32_16x16x32_bf16 v[60:63], v[218:221], v[174:177], v[60:63]
	v_mfma_f32_16x16x32_bf16 v[106:109], v[226:229], v[174:177], v[106:109]
	v_mfma_f32_16x16x32_bf16 v[110:113], v[218:221], v[202:205], v[110:113]
	v_mfma_f32_16x16x32_bf16 v[114:117], v[226:229], v[202:205], v[114:117]
	v_mfma_f32_16x16x32_bf16 v[94:97], v[218:221], v[210:213], v[94:97]
	v_mfma_f32_16x16x32_bf16 v[98:101], v[226:229], v[210:213], v[98:101]
	s_setprio 0
	v_lshl_add_u64 v[0:1], s[6:7], 0, v[0:1]
	s_mov_b32 m0, s66
	v_lshl_add_u64 v[0:1], v[0:1], 0, v[2:3]
	s_barrier
	ds_read_b128 v[102:105], v129
	ds_read_b128 v[118:121], v129 offset:1024
	ds_read_b128 v[122:125], v129 offset:2048
	ds_read_b128 v[130:133], v129 offset:3072
	ds_read_b128 v[134:137], v178
	ds_read_b128 v[138:141], v178 offset:1024
	ds_read_b128 v[142:145], v179 offset:2048
	ds_read_b128 v[146:149], v179 offset:3072
	ds_read_b128 v[174:177], v179 offset:4096
	ds_read_b128 v[198:201], v179 offset:5120
	ds_read_b128 v[202:205], v179 offset:6144
	ds_read_b128 v[206:209], v179 offset:7168
	global_load_lds_dwordx4 v[0:1], off
	v_lshl_add_u64 v[0:1], s[6:7], 0, v[4:5]
	v_lshl_add_u64 v[0:1], v[0:1], 0, v[6:7]
	s_mov_b32 m0, s64
	s_nop 0
	global_load_lds_dwordx4 v[0:1], off
	s_barrier
	s_waitcnt lgkmcnt(0)
	s_setprio 1
	s_waitcnt lgkmcnt(0)
	v_mfma_f32_16x16x32_bf16 v[0:3], v[102:105], v[134:137], v[12:15]
	v_mfma_f32_16x16x32_bf16 v[4:7], v[122:125], v[134:137], v[66:69]
	v_mfma_f32_16x16x32_bf16 v[12:15], v[102:105], v[142:145], v[70:73]
	v_mfma_f32_16x16x32_bf16 v[64:67], v[122:125], v[142:145], v[74:77]
	v_mfma_f32_16x16x32_bf16 v[68:71], v[102:105], v[174:177], v[78:81]
	v_mfma_f32_16x16x32_bf16 v[72:75], v[122:125], v[174:177], v[82:85]
	v_mfma_f32_16x16x32_bf16 v[76:79], v[102:105], v[202:205], v[86:89]
	v_mfma_f32_16x16x32_bf16 v[80:83], v[122:125], v[202:205], v[90:93]
	v_mfma_f32_16x16x32_bf16 v[0:3], v[118:121], v[138:141], v[0:3]
	v_mfma_f32_16x16x32_bf16 v[4:7], v[130:133], v[138:141], v[4:7]
	v_mfma_f32_16x16x32_bf16 v[12:15], v[118:121], v[146:149], v[12:15]
	v_mfma_f32_16x16x32_bf16 v[64:67], v[130:133], v[146:149], v[64:67]
	v_mfma_f32_16x16x32_bf16 v[68:71], v[118:121], v[198:201], v[68:71]
	v_mfma_f32_16x16x32_bf16 v[72:75], v[130:133], v[198:201], v[72:75]
	v_mfma_f32_16x16x32_bf16 v[76:79], v[118:121], v[206:209], v[76:79]
	v_mfma_f32_16x16x32_bf16 v[84:87], v[130:133], v[206:209], v[80:83]
	s_setprio 0
	s_barrier
	s_nop 0
	ds_read_b128 v[80:83], v186
	ds_read_b128 v[88:91], v186 offset:1024
	ds_read_b128 v[210:213], v186 offset:2048
	ds_read_b128 v[214:217], v186 offset:3072
	s_barrier
	s_waitcnt lgkmcnt(0)
	s_setprio 1
	s_waitcnt lgkmcnt(0)
	v_mfma_f32_16x16x32_bf16 v[40:43], v[210:213], v[142:145], v[40:43]
	v_mfma_f32_16x16x32_bf16 v[8:11], v[80:83], v[134:137], v[8:11]
	v_mfma_f32_16x16x32_bf16 v[32:35], v[210:213], v[134:137], v[32:35]
	v_mfma_f32_16x16x32_bf16 v[134:137], v[214:217], v[146:149], v[40:43]
	v_mfma_f32_16x16x32_bf16 v[40:43], v[80:83], v[174:177], v[44:47]
	v_mfma_f32_16x16x32_bf16 v[44:47], v[88:91], v[198:201], v[40:43]
	v_mfma_f32_16x16x32_bf16 v[40:43], v[210:213], v[174:177], v[48:51]
	v_mfma_f32_16x16x32_bf16 v[8:11], v[88:91], v[138:141], v[8:11]
	v_mfma_f32_16x16x32_bf16 v[32:35], v[214:217], v[138:141], v[32:35]
	v_mfma_f32_16x16x32_bf16 v[36:39], v[80:83], v[142:145], v[36:39]
	v_mfma_f32_16x16x32_bf16 v[138:141], v[214:217], v[198:201], v[40:43]
	v_mfma_f32_16x16x32_bf16 v[40:43], v[80:83], v[202:205], v[52:55]
	v_mfma_f32_16x16x32_bf16 v[36:39], v[88:91], v[146:149], v[36:39]
	v_mfma_f32_16x16x32_bf16 v[52:55], v[88:91], v[206:209], v[40:43]
	v_mfma_f32_16x16x32_bf16 v[40:43], v[210:213], v[202:205], v[56:59]
	v_mfma_f32_16x16x32_bf16 v[142:145], v[214:217], v[206:209], v[40:43]
	s_setprio 0
	s_barrier
	s_nop 4
	ds_read_b128 v[40:43], v178 offset:16384
	ds_read_b128 v[48:51], v178 offset:17408
	ds_read_b128 v[56:59], v179 offset:18432
	ds_read_b128 v[146:149], v179 offset:19456
	ds_read_b128 v[174:177], v179 offset:20480
	ds_read_b128 v[198:201], v179 offset:21504
	ds_read_b128 v[202:205], v179 offset:22528
	ds_read_b128 v[206:209], v179 offset:23552
	s_waitcnt vmcnt(4)
	s_barrier
; #define WAIT_V(n) asm volatile("s_waitcnt vmcnt(" #n ")" ::: "memory")
; #define WAIT_L(n) asm volatile("s_waitcnt lgkmcnt(" #n ")" ::: "memory")
; #define BAR __builtin_amdgcn_s_barrier()
; #define LDA(dst, b, h)                                                                            \
;   _Pragma("unroll") for (int m = 0; m < 4; ++m) _Pragma("unroll") for (int k = 0; k < 2; ++k)                                         \
;     dst[m][k] = *reinterpret_cast<const bf16x8*>((char*)SA(b, h) + lds_byte(wr * 64 + m * 16 + fr, k * 32 + fq * 8))
; #define LDB(dst, b, h)                                                                            \
;   _Pragma("unroll") for (int n = 0; n < 2; ++n) _Pragma("unroll") for (int k = 0; k < 2; ++k)                                         \
;     dst[n][k] = *reinterpret_cast<const bf16x8*>((char*)SB(b, h) + lds_byte(wc * 32 + n * 16 + fr, k * 32 + fq * 8))
; template <int K, bool SWAP>
; __device__ __forceinline__ void gemm_kloop(const bf16* __restrict__ A, const bf16* __restrict__ Bt,
;                                            f32x4 (&acc)[2][2][4][2], bool pref = false) {
;     ...
;     LDA(At, 0, 1); WAIT_V(4); BAR; WAIT_L(0); MMA(1, 0, At, B0); MMA(1, 1, At, B1); BAR; }
;   { LDB(B0, 1, 0); LDA(At, 1, 0); WAIT_V(2); BAR; WAIT_L(0); MMA(0, 0, At, B0); BAR;
	s_waitcnt lgkmcnt(0)
	s_setprio 1
	s_waitcnt lgkmcnt(0)
	v_mfma_f32_16x16x32_bf16 v[16:19], v[102:105], v[202:205], v[16:19]
	v_mfma_f32_16x16x32_bf16 v[218:221], v[118:121], v[206:209], v[16:19]
	v_mfma_f32_16x16x32_bf16 v[16:19], v[122:125], v[202:205], v[20:23]
	v_mfma_f32_16x16x32_bf16 v[150:153], v[102:105], v[40:43], v[150:153]
	v_mfma_f32_16x16x32_bf16 v[154:157], v[122:125], v[40:43], v[154:157]
	v_mfma_f32_16x16x32_bf16 v[158:161], v[102:105], v[56:59], v[158:161]
	v_mfma_f32_16x16x32_bf16 v[162:165], v[122:125], v[56:59], v[162:165]
	v_mfma_f32_16x16x32_bf16 v[166:169], v[102:105], v[174:177], v[166:169]
	v_mfma_f32_16x16x32_bf16 v[170:173], v[122:125], v[174:177], v[170:173]
	v_mfma_f32_16x16x32_bf16 v[20:23], v[130:133], v[206:209], v[16:19]
	v_mfma_f32_16x16x32_bf16 v[150:153], v[118:121], v[48:51], v[150:153]
	v_mfma_f32_16x16x32_bf16 v[154:157], v[130:133], v[48:51], v[154:157]
	v_mfma_f32_16x16x32_bf16 v[158:161], v[118:121], v[146:149], v[158:161]
	v_mfma_f32_16x16x32_bf16 v[162:165], v[130:133], v[146:149], v[162:165]
	v_mfma_f32_16x16x32_bf16 v[166:169], v[118:121], v[198:201], v[166:169]
	v_mfma_f32_16x16x32_bf16 v[170:173], v[130:133], v[198:201], v[170:173]
	s_setprio 0
	s_setprio 1
	v_mfma_f32_16x16x32_bf16 v[16:19], v[80:83], v[40:43], v[24:27]
	v_mfma_f32_16x16x32_bf16 v[130:133], v[88:91], v[48:51], v[16:19]
	v_mfma_f32_16x16x32_bf16 v[16:19], v[210:213], v[40:43], v[28:31]
	v_mfma_f32_16x16x32_bf16 v[28:31], v[214:217], v[48:51], v[16:19]
	v_mfma_f32_16x16x32_bf16 v[16:19], v[80:83], v[56:59], v[60:63]
	v_mfma_f32_16x16x32_bf16 v[222:225], v[88:91], v[146:149], v[16:19]
	v_mfma_f32_16x16x32_bf16 v[16:19], v[210:213], v[56:59], v[106:109]
	v_mfma_f32_16x16x32_bf16 v[146:149], v[214:217], v[146:149], v[16:19]
	v_mfma_f32_16x16x32_bf16 v[16:19], v[80:83], v[174:177], v[110:113]
	v_mfma_f32_16x16x32_bf16 v[226:229], v[88:91], v[198:201], v[16:19]
	v_mfma_f32_16x16x32_bf16 v[16:19], v[210:213], v[174:177], v[114:117]
	v_mfma_f32_16x16x32_bf16 v[174:177], v[214:217], v[198:201], v[16:19]
	v_mfma_f32_16x16x32_bf16 v[16:19], v[80:83], v[202:205], v[94:97]
	v_mfma_f32_16x16x32_bf16 v[198:201], v[88:91], v[206:209], v[16:19]
	v_mfma_f32_16x16x32_bf16 v[16:19], v[210:213], v[202:205], v[98:101]
	v_mfma_f32_16x16x32_bf16 v[202:205], v[214:217], v[206:209], v[16:19]
	s_setprio 0
	s_barrier
	ds_read_b128 v[60:63], v188
	ds_read_b128 v[206:209], v188 offset:1024
	ds_read_b128 v[210:213], v188 offset:2048
	ds_read_b128 v[214:217], v188 offset:3072
	s_nop 0
	ds_read_b128 v[16:19], v178 offset:32768
	ds_read_b128 v[24:27], v178 offset:33792
	ds_read_b128 v[92:95], v179 offset:34816
	ds_read_b128 v[100:103], v179 offset:35840
	ds_read_b128 v[108:111], v179 offset:36864
	ds_read_b128 v[116:119], v179 offset:37888
	ds_read_b128 v[124:127], v179 offset:38912
	ds_read_b128 v[230:233], v179 offset:39936
	s_waitcnt vmcnt(2)
	s_barrier
	s_waitcnt lgkmcnt(0)
	s_setprio 1
	s_waitcnt lgkmcnt(0)
	v_mfma_f32_16x16x32_bf16 v[0:3], v[60:63], v[16:19], v[0:3]
	v_mfma_f32_16x16x32_bf16 v[120:123], v[206:209], v[24:27], v[0:3]
	v_mfma_f32_16x16x32_bf16 v[0:3], v[210:213], v[16:19], v[4:7]
	v_mfma_f32_16x16x32_bf16 v[112:115], v[214:217], v[24:27], v[0:3]
	v_mfma_f32_16x16x32_bf16 v[0:3], v[60:63], v[92:95], v[12:15]
	v_mfma_f32_16x16x32_bf16 v[104:107], v[206:209], v[100:103], v[0:3]
	v_mfma_f32_16x16x32_bf16 v[0:3], v[210:213], v[92:95], v[64:67]
	v_mfma_f32_16x16x32_bf16 v[96:99], v[214:217], v[100:103], v[0:3]
	v_mfma_f32_16x16x32_bf16 v[0:3], v[60:63], v[108:111], v[68:71]
	v_mfma_f32_16x16x32_bf16 v[88:91], v[206:209], v[116:119], v[0:3]
	v_mfma_f32_16x16x32_bf16 v[0:3], v[210:213], v[108:111], v[72:75]
	v_mfma_f32_16x16x32_bf16 v[80:83], v[214:217], v[116:119], v[0:3]
	v_mfma_f32_16x16x32_bf16 v[0:3], v[60:63], v[124:127], v[76:79]
	v_mfma_f32_16x16x32_bf16 v[72:75], v[206:209], v[230:233], v[0:3]
	v_mfma_f32_16x16x32_bf16 v[0:3], v[210:213], v[124:127], v[84:87]
	v_mfma_f32_16x16x32_bf16 v[64:67], v[214:217], v[230:233], v[0:3]
	s_setprio 0
	s_barrier
; #define WAIT_V(n) asm volatile("s_waitcnt vmcnt(" #n ")" ::: "memory")
; #define WAIT_L(n) asm volatile("s_waitcnt lgkmcnt(" #n ")" ::: "memory")
; #define BAR __builtin_amdgcn_s_barrier()
; #define LDA(dst, b, h)                                                                            \
;   _Pragma("unroll") for (int m = 0; m < 4; ++m) _Pragma("unroll") for (int k = 0; k < 2; ++k)                                         \
;     dst[m][k] = *reinterpret_cast<const bf16x8*>((char*)SA(b, h) + lds_byte(wr * 64 + m * 16 + fr, k * 32 + fq * 8))
; #define LDB(dst, b, h)                                                                            \
;   _Pragma("unroll") for (int n = 0; n < 2; ++n) _Pragma("unroll") for (int k = 0; k < 2; ++k)                                         \
;     dst[n][k] = *reinterpret_cast<const bf16x8*>((char*)SB(b, h) + lds_byte(wc * 32 + n * 16 + fr, k * 32 + fq * 8))
; template <int K, bool SWAP>
; __device__ __forceinline__ void gemm_kloop(const bf16* __restrict__ A, const bf16* __restrict__ Bt,
;                                            f32x4 (&acc)[2][2][4][2], bool pref = false) {
;     ...
;     LDB(B1, 1, 1); WAIT_V(0); BAR; WAIT_L(0); MMA(0, 1, At, B1); BAR;
;     LDA(At, 1, 1); BAR; WAIT_L(0); MMA(1, 0, At, B0); MMA(1, 1, At, B1); BAR; }
;   if (wr == 0) BAR;
	ds_read_b128 v[4:7], v189
	ds_read_b128 v[12:15], v189 offset:1024
	ds_read_b128 v[234:237], v189 offset:2048
	ds_read_b128 v[238:241], v189 offset:3072
	s_waitcnt vmcnt(0)
	s_barrier
	s_waitcnt lgkmcnt(0)
	s_setprio 1
	s_waitcnt lgkmcnt(0)
	v_mfma_f32_16x16x32_bf16 v[0:3], v[4:7], v[16:19], v[8:11]
	v_mfma_f32_16x16x32_bf16 v[56:59], v[12:15], v[24:27], v[0:3]
	v_mfma_f32_16x16x32_bf16 v[0:3], v[234:237], v[16:19], v[32:35]
	v_mfma_f32_16x16x32_bf16 v[48:51], v[238:241], v[24:27], v[0:3]
	v_mfma_f32_16x16x32_bf16 v[0:3], v[4:7], v[92:95], v[36:39]
	v_mfma_f32_16x16x32_bf16 v[40:43], v[12:15], v[100:103], v[0:3]
	v_mfma_f32_16x16x32_bf16 v[0:3], v[234:237], v[92:95], v[134:137]
	v_mfma_f32_16x16x32_bf16 v[32:35], v[238:241], v[100:103], v[0:3]
	v_mfma_f32_16x16x32_bf16 v[0:3], v[4:7], v[108:111], v[44:47]
	v_mfma_f32_16x16x32_bf16 v[24:27], v[12:15], v[116:119], v[0:3]
	v_mfma_f32_16x16x32_bf16 v[0:3], v[234:237], v[108:111], v[138:141]
	v_mfma_f32_16x16x32_bf16 v[16:19], v[238:241], v[116:119], v[0:3]
	v_mfma_f32_16x16x32_bf16 v[0:3], v[4:7], v[124:127], v[52:55]
	v_mfma_f32_16x16x32_bf16 v[8:11], v[12:15], v[230:233], v[0:3]
	v_mfma_f32_16x16x32_bf16 v[0:3], v[234:237], v[124:127], v[142:145]
	v_mfma_f32_16x16x32_bf16 v[0:3], v[238:241], v[230:233], v[0:3]
	s_setprio 0
	s_barrier
	ds_read_b128 v[36:39], v178 offset:49152
	ds_read_b128 v[44:47], v178 offset:50176
	ds_read_b128 v[134:137], v179 offset:51200
	ds_read_b128 v[138:141], v179 offset:52224
	ds_read_b128 v[142:145], v179 offset:53248
	ds_read_b128 v[230:233], v179 offset:54272
	ds_read_b128 v[242:245], v179 offset:55296
	ds_read_b128 v[246:249], v179 offset:56320
	s_barrier
	s_waitcnt lgkmcnt(0)
	s_setprio 1
	s_waitcnt lgkmcnt(0)
	v_mfma_f32_16x16x32_bf16 v[52:55], v[60:63], v[36:39], v[150:153]
	v_mfma_f32_16x16x32_bf16 v[124:127], v[206:209], v[44:47], v[52:55]
	v_mfma_f32_16x16x32_bf16 v[52:55], v[210:213], v[36:39], v[154:157]
	v_mfma_f32_16x16x32_bf16 v[116:119], v[214:217], v[44:47], v[52:55]
	v_mfma_f32_16x16x32_bf16 v[52:55], v[60:63], v[134:137], v[158:161]
	v_mfma_f32_16x16x32_bf16 v[108:111], v[206:209], v[138:141], v[52:55]
	v_mfma_f32_16x16x32_bf16 v[52:55], v[210:213], v[134:137], v[162:165]
	v_mfma_f32_16x16x32_bf16 v[100:103], v[214:217], v[138:141], v[52:55]
	v_mfma_f32_16x16x32_bf16 v[52:55], v[60:63], v[142:145], v[166:169]
	v_mfma_f32_16x16x32_bf16 v[92:95], v[206:209], v[230:233], v[52:55]
	v_mfma_f32_16x16x32_bf16 v[52:55], v[210:213], v[142:145], v[170:173]
	v_mfma_f32_16x16x32_bf16 v[84:87], v[214:217], v[230:233], v[52:55]
	v_mfma_f32_16x16x32_bf16 v[52:55], v[60:63], v[242:245], v[218:221]
	v_mfma_f32_16x16x32_bf16 v[20:23], v[210:213], v[242:245], v[20:23]
	v_mfma_f32_16x16x32_bf16 v[76:79], v[206:209], v[246:249], v[52:55]
	v_mfma_f32_16x16x32_bf16 v[68:71], v[214:217], v[246:249], v[20:23]
	s_setprio 0
	s_setprio 1
	v_mfma_f32_16x16x32_bf16 v[20:23], v[4:7], v[36:39], v[130:133]
	v_mfma_f32_16x16x32_bf16 v[60:63], v[12:15], v[44:47], v[20:23]
	v_mfma_f32_16x16x32_bf16 v[20:23], v[234:237], v[36:39], v[28:31]
	v_mfma_f32_16x16x32_bf16 v[52:55], v[238:241], v[44:47], v[20:23]
	v_mfma_f32_16x16x32_bf16 v[20:23], v[4:7], v[134:137], v[222:225]
	v_mfma_f32_16x16x32_bf16 v[44:47], v[12:15], v[138:141], v[20:23]
	v_mfma_f32_16x16x32_bf16 v[20:23], v[234:237], v[134:137], v[146:149]
	v_mfma_f32_16x16x32_bf16 v[36:39], v[238:241], v[138:141], v[20:23]
	v_mfma_f32_16x16x32_bf16 v[20:23], v[4:7], v[142:145], v[226:229]
	v_mfma_f32_16x16x32_bf16 v[4:7], v[4:7], v[242:245], v[198:201]
	v_mfma_f32_16x16x32_bf16 v[28:31], v[12:15], v[230:233], v[20:23]
	v_mfma_f32_16x16x32_bf16 v[20:23], v[234:237], v[142:145], v[174:177]
	v_mfma_f32_16x16x32_bf16 v[12:15], v[12:15], v[246:249], v[4:7]
	v_mfma_f32_16x16x32_bf16 v[4:7], v[234:237], v[242:245], v[202:205]
	v_mfma_f32_16x16x32_bf16 v[20:23], v[238:241], v[230:233], v[20:23]
	v_mfma_f32_16x16x32_bf16 v[4:7], v[238:241], v[246:249], v[4:7]
	s_setprio 0
	s_movk_i32 s0, 0x100
	v_cmp_gt_u32_e32 vcc, s0, v128
	s_barrier
	s_and_saveexec_b64 s[0:1], vcc
	s_cbranch_execz .LBB0_673
	s_barrier

; #define WAIT_L(n) asm volatile("s_waitcnt lgkmcnt(" #n ")" ::: "memory")
; #define BAR __builtin_amdgcn_s_barrier()
; #define SCHED __builtin_amdgcn_sched_barrier(0)
; #define LDA(dst, b, h)                                                                            \
;   _Pragma("unroll") for (int m = 0; m < 4; ++m) _Pragma("unroll") for (int k = 0; k < 2; ++k)                                         \
;     dst[m][k] = *reinterpret_cast<const bf16x8*>((char*)SA(b, h) + lds_byte(wr * 64 + m * 16 + fr, k * 32 + fq * 8))
; #define LDB(dst, b, h)                                                                            \
;   _Pragma("unroll") for (int n = 0; n < 2; ++n) _Pragma("unroll") for (int k = 0; k < 2; ++k)                                         \
;     dst[n][k] = *reinterpret_cast<const bf16x8*>((char*)SB(b, h) + lds_byte(wc * 32 + n * 16 + fr, k * 32 + fq * 8))
; template <int K, bool SWAP>
; __device__ __forceinline__ void gemm_kloop(const bf16* __restrict__ A, const bf16* __restrict__ Bt,
;                                            f32x4 (&acc)[2][2][4][2], bool pref = false) {
;     ...
;     LDB(B0, 0, 0); SCHED; LDA(At, 0, 0); STAGE(SA(1, 1), A, HALF, t + 1);
;     WAIT_L(8); BAR; WAIT_L(0); MMA(0, 0, At, B0); BAR; SCHED;
;     LDB(B1, 0, 1); STAGE(SB(0, 0), Bt, 0, t + 2);
;     BAR; WAIT_L(0); MMA(0, 1, At, B1); BAR;
;     LDA(At, 0, 1); STAGE(SA(0, 0), A, 0, t + 2);
;     BAR; WAIT_L(0); MMA(1, 0, At, B0); BAR; SCHED;
.LBB0_791:
	ds_read_b128 v[162:165], v159
	ds_read_b128 v[166:169], v159 offset:1024
	ds_read_b128 v[170:173], v159 offset:2048
	ds_read_b128 v[174:177], v159 offset:3072
	v_add_u32_e32 v160, 0xc000, v145
	v_lshl_add_u64 v[178:179], s[6:7], 0, v[140:141]
	v_readfirstlane_b32 s13, v160
	v_lshl_add_u64 v[188:189], v[178:179], 0, s[74:75]
	s_mov_b32 m0, s13
	v_add_u32_e32 v161, 0xe000, v145
	ds_read_b128 v[198:201], v156
	ds_read_b128 v[202:205], v156 offset:1024
	ds_read_b128 v[206:209], v151
	ds_read_b128 v[210:213], v151 offset:1024
	ds_read_b128 v[214:217], v150
	ds_read_b128 v[218:221], v150 offset:1024
	ds_read_b128 v[222:225], v149
	ds_read_b128 v[226:229], v149 offset:1024
	global_load_lds_dwordx4 v[188:189], off
	v_lshl_add_u64 v[188:189], s[6:7], 0, v[142:143]
	v_readfirstlane_b32 s13, v161
	v_lshl_add_u64 v[230:231], v[188:189], 0, s[74:75]
	s_mov_b32 m0, s13
	s_nop 0
	global_load_lds_dwordx4 v[230:231], off
	s_waitcnt lgkmcnt(8)
	s_barrier
	s_waitcnt lgkmcnt(0)
	s_setprio 1
	s_waitcnt lgkmcnt(0)
	v_mfma_f32_16x16x32_bf16 v[124:127], v[162:165], v[198:201], v[124:127]
	v_mfma_f32_16x16x32_bf16 v[120:123], v[170:173], v[198:201], v[120:123]
	v_mfma_f32_16x16x32_bf16 v[112:115], v[170:173], v[206:209], v[112:115]
	v_mfma_f32_16x16x32_bf16 v[116:119], v[162:165], v[206:209], v[116:119]
	v_mfma_f32_16x16x32_bf16 v[108:111], v[162:165], v[214:217], v[108:111]
	v_mfma_f32_16x16x32_bf16 v[104:107], v[170:173], v[214:217], v[104:107]
	v_mfma_f32_16x16x32_bf16 v[96:99], v[170:173], v[222:225], v[96:99]
	v_mfma_f32_16x16x32_bf16 v[100:103], v[162:165], v[222:225], v[100:103]
	v_mfma_f32_16x16x32_bf16 v[124:127], v[166:169], v[202:205], v[124:127]
	v_mfma_f32_16x16x32_bf16 v[120:123], v[174:177], v[202:205], v[120:123]
	v_mfma_f32_16x16x32_bf16 v[112:115], v[174:177], v[210:213], v[112:115]
	v_mfma_f32_16x16x32_bf16 v[116:119], v[166:169], v[210:213], v[116:119]
	v_mfma_f32_16x16x32_bf16 v[108:111], v[166:169], v[218:221], v[108:111]
	v_mfma_f32_16x16x32_bf16 v[104:107], v[174:177], v[218:221], v[104:107]
	v_mfma_f32_16x16x32_bf16 v[96:99], v[174:177], v[226:229], v[96:99]
	v_mfma_f32_16x16x32_bf16 v[100:103], v[166:169], v[226:229], v[100:103]
	s_setprio 0
	s_barrier
	v_add_u32_e32 v186, s9, v144
	v_lshl_add_u64 v[246:247], s[6:7], 0, v[136:137]
	v_readfirstlane_b32 s13, v186
	v_lshl_add_u64 v[248:249], v[246:247], 0, s[76:77]
	s_mov_b32 m0, s13
	v_add_u32_e32 v186, 0x2000, v186
	ds_read_b128 v[230:233], v158
	ds_read_b128 v[234:237], v158 offset:1024
	ds_read_b128 v[238:241], v158 offset:2048
	ds_read_b128 v[242:245], v158 offset:3072
	global_load_lds_dwordx4 v[248:249], off
	v_lshl_add_u64 v[248:249], s[6:7], 0, v[138:139]
	v_readfirstlane_b32 s13, v186
	v_lshl_add_u64 v[250:251], v[248:249], 0, s[76:77]
	s_mov_b32 m0, s13
	s_nop 0
	global_load_lds_dwordx4 v[250:251], off
	s_barrier
	s_waitcnt lgkmcnt(0)
	s_setprio 1
	s_waitcnt lgkmcnt(0)
	v_mfma_f32_16x16x32_bf16 v[92:95], v[230:233], v[198:201], v[92:95]
	v_mfma_f32_16x16x32_bf16 v[88:91], v[238:241], v[198:201], v[88:91]
	v_mfma_f32_16x16x32_bf16 v[80:83], v[238:241], v[206:209], v[80:83]
	v_mfma_f32_16x16x32_bf16 v[84:87], v[230:233], v[206:209], v[84:87]
	v_mfma_f32_16x16x32_bf16 v[76:79], v[230:233], v[214:217], v[76:79]
	v_mfma_f32_16x16x32_bf16 v[72:75], v[238:241], v[214:217], v[72:75]
	v_mfma_f32_16x16x32_bf16 v[64:67], v[238:241], v[222:225], v[64:67]
	v_mfma_f32_16x16x32_bf16 v[68:71], v[230:233], v[222:225], v[68:71]
	v_mfma_f32_16x16x32_bf16 v[92:95], v[234:237], v[202:205], v[92:95]
	v_mfma_f32_16x16x32_bf16 v[88:91], v[242:245], v[202:205], v[88:91]
	v_mfma_f32_16x16x32_bf16 v[80:83], v[242:245], v[210:213], v[80:83]
	v_mfma_f32_16x16x32_bf16 v[84:87], v[234:237], v[210:213], v[84:87]
	v_mfma_f32_16x16x32_bf16 v[76:79], v[234:237], v[218:221], v[76:79]
	v_mfma_f32_16x16x32_bf16 v[72:75], v[242:245], v[218:221], v[72:75]
	v_mfma_f32_16x16x32_bf16 v[64:67], v[242:245], v[226:229], v[64:67]
	v_mfma_f32_16x16x32_bf16 v[68:71], v[234:237], v[226:229], v[68:71]
	s_setprio 0
	v_readfirstlane_b32 s13, v145
	v_add_u32_e32 v186, 0x2000, v145
	v_lshl_add_u64 v[250:251], v[178:179], 0, s[46:47]
	s_mov_b32 m0, s13
	v_readfirstlane_b32 s13, v186
	s_barrier
	ds_read_b128 v[198:201], v156 offset:16384
	ds_read_b128 v[202:205], v156 offset:17408
	ds_read_b128 v[206:209], v151 offset:16384
	ds_read_b128 v[210:213], v151 offset:17408
	ds_read_b128 v[214:217], v150 offset:16384
	ds_read_b128 v[218:221], v150 offset:17408
	ds_read_b128 v[222:225], v149 offset:16384
	ds_read_b128 v[226:229], v149 offset:17408
	global_load_lds_dwordx4 v[250:251], off
	v_lshl_add_u64 v[250:251], v[188:189], 0, s[46:47]
	s_mov_b32 m0, s13
	s_nop 0
	global_load_lds_dwordx4 v[250:251], off
	s_barrier
	s_waitcnt lgkmcnt(0)
	s_setprio 1
	s_waitcnt lgkmcnt(0)
	v_mfma_f32_16x16x32_bf16 v[60:63], v[162:165], v[198:201], v[60:63]
	v_mfma_f32_16x16x32_bf16 v[56:59], v[170:173], v[198:201], v[56:59]
	v_mfma_f32_16x16x32_bf16 v[48:51], v[170:173], v[206:209], v[48:51]
	v_mfma_f32_16x16x32_bf16 v[52:55], v[162:165], v[206:209], v[52:55]
	v_mfma_f32_16x16x32_bf16 v[44:47], v[162:165], v[214:217], v[44:47]
	v_mfma_f32_16x16x32_bf16 v[40:43], v[170:173], v[214:217], v[40:43]
	v_mfma_f32_16x16x32_bf16 v[32:35], v[170:173], v[222:225], v[32:35]
	v_mfma_f32_16x16x32_bf16 v[36:39], v[162:165], v[222:225], v[36:39]
	v_mfma_f32_16x16x32_bf16 v[60:63], v[166:169], v[202:205], v[60:63]
	v_mfma_f32_16x16x32_bf16 v[56:59], v[174:177], v[202:205], v[56:59]
	v_mfma_f32_16x16x32_bf16 v[48:51], v[174:177], v[210:213], v[48:51]
	v_mfma_f32_16x16x32_bf16 v[52:55], v[166:169], v[210:213], v[52:55]
	v_mfma_f32_16x16x32_bf16 v[44:47], v[166:169], v[218:221], v[44:47]
	v_mfma_f32_16x16x32_bf16 v[40:43], v[174:177], v[218:221], v[40:43]
	v_mfma_f32_16x16x32_bf16 v[32:35], v[174:177], v[226:229], v[32:35]
	v_mfma_f32_16x16x32_bf16 v[36:39], v[166:169], v[226:229], v[36:39]
	s_setprio 0
	s_barrier
; #define WAIT_V(n) asm volatile("s_waitcnt vmcnt(" #n ")" ::: "memory")
; #define WAIT_L(n) asm volatile("s_waitcnt lgkmcnt(" #n ")" ::: "memory")
; #define BAR __builtin_amdgcn_s_barrier()
; #define SCHED __builtin_amdgcn_sched_barrier(0)
; #define LDA(dst, b, h)                                                                            \
;   _Pragma("unroll") for (int m = 0; m < 4; ++m) _Pragma("unroll") for (int k = 0; k < 2; ++k)                                         \
;     dst[m][k] = *reinterpret_cast<const bf16x8*>((char*)SA(b, h) + lds_byte(wr * 64 + m * 16 + fr, k * 32 + fq * 8))
; #define LDB(dst, b, h)                                                                            \
;   _Pragma("unroll") for (int n = 0; n < 2; ++n) _Pragma("unroll") for (int k = 0; k < 2; ++k)                                         \
;     dst[n][k] = *reinterpret_cast<const bf16x8*>((char*)SB(b, h) + lds_byte(wc * 32 + n * 16 + fr, k * 32 + fq * 8))
; template <int K, bool SWAP>
; __device__ __forceinline__ void gemm_kloop(const bf16* __restrict__ A, const bf16* __restrict__ Bt,
;                                            f32x4 (&acc)[2][2][4][2], bool pref = false) {
;     ...
;     STAGE(SB(0, 1), Bt, HALF, t + 2);
;     WAIT_V(6); BAR; MMA(1, 1, At, B1); BAR;
;     LDB(B0, 1, 0); SCHED; LDA(At, 1, 0); STAGE(SA(0, 1), A, HALF, t + 2);
;     WAIT_L(8); BAR; WAIT_L(0); MMA(0, 0, At, B0); BAR; SCHED;
;     LDB(B1, 1, 1); STAGE(SB(1, 0), Bt, 0, t + 3);
;     BAR; WAIT_L(0); MMA(0, 1, At, B1); BAR;
;     LDA(At, 1, 1); STAGE(SA(1, 0), A, 0, t + 3);
	v_readfirstlane_b32 s13, v146
	v_add_u32_e32 v164, 0x2000, v146
	v_lshl_add_u64 v[162:163], v[246:247], 0, s[78:79]
	s_mov_b32 m0, s13
	v_readfirstlane_b32 s13, v164
	global_load_lds_dwordx4 v[162:163], off
	v_lshl_add_u64 v[162:163], v[248:249], 0, s[78:79]
	s_mov_b32 m0, s13
	s_nop 0
	global_load_lds_dwordx4 v[162:163], off
	s_waitcnt vmcnt(6)
	s_barrier
	s_setprio 1
	v_mfma_f32_16x16x32_bf16 v[28:31], v[230:233], v[198:201], v[28:31]
	v_mfma_f32_16x16x32_bf16 v[24:27], v[238:241], v[198:201], v[24:27]
	v_mfma_f32_16x16x32_bf16 v[16:19], v[238:241], v[206:209], v[16:19]
	v_mfma_f32_16x16x32_bf16 v[20:23], v[230:233], v[206:209], v[20:23]
	v_mfma_f32_16x16x32_bf16 v[12:15], v[230:233], v[214:217], v[12:15]
	v_mfma_f32_16x16x32_bf16 v[8:11], v[238:241], v[214:217], v[8:11]
	v_mfma_f32_16x16x32_bf16 v[0:3], v[238:241], v[222:225], v[0:3]
	v_mfma_f32_16x16x32_bf16 v[4:7], v[230:233], v[222:225], v[4:7]
	v_mfma_f32_16x16x32_bf16 v[28:31], v[234:237], v[202:205], v[28:31]
	v_mfma_f32_16x16x32_bf16 v[24:27], v[242:245], v[202:205], v[24:27]
	v_mfma_f32_16x16x32_bf16 v[16:19], v[242:245], v[210:213], v[16:19]
	v_mfma_f32_16x16x32_bf16 v[20:23], v[234:237], v[210:213], v[20:23]
	v_mfma_f32_16x16x32_bf16 v[12:15], v[234:237], v[218:221], v[12:15]
	v_mfma_f32_16x16x32_bf16 v[8:11], v[242:245], v[218:221], v[8:11]
	v_mfma_f32_16x16x32_bf16 v[0:3], v[242:245], v[226:229], v[0:3]
	v_mfma_f32_16x16x32_bf16 v[4:7], v[234:237], v[226:229], v[4:7]
	s_setprio 0
	s_barrier
	ds_read_b128 v[162:165], v147
	ds_read_b128 v[166:169], v147 offset:1024
	ds_read_b128 v[170:173], v147 offset:2048
	ds_read_b128 v[174:177], v147 offset:3072
	v_add_u32_e32 v186, 0x4000, v145
	v_lshl_add_u64 v[230:231], v[178:179], 0, s[80:81]
	v_readfirstlane_b32 s13, v186
	v_add_u32_e32 v186, 0x6000, v145
	s_mov_b32 m0, s13
	v_readfirstlane_b32 s13, v186
	ds_read_b128 v[198:201], v156 offset:32768
	ds_read_b128 v[202:205], v156 offset:33792
	ds_read_b128 v[206:209], v151 offset:32768
	ds_read_b128 v[210:213], v151 offset:33792
	ds_read_b128 v[214:217], v150 offset:32768
	ds_read_b128 v[218:221], v150 offset:33792
	ds_read_b128 v[222:225], v149 offset:32768
	ds_read_b128 v[226:229], v149 offset:33792
	global_load_lds_dwordx4 v[230:231], off
	v_lshl_add_u64 v[230:231], v[188:189], 0, s[80:81]
	s_mov_b32 m0, s13
	s_nop 0
	global_load_lds_dwordx4 v[230:231], off
	s_waitcnt lgkmcnt(8)
	s_barrier
	s_waitcnt lgkmcnt(0)
	s_setprio 1
	s_waitcnt lgkmcnt(0)
	v_mfma_f32_16x16x32_bf16 v[124:127], v[162:165], v[198:201], v[124:127]
	v_mfma_f32_16x16x32_bf16 v[120:123], v[170:173], v[198:201], v[120:123]
	v_mfma_f32_16x16x32_bf16 v[112:115], v[170:173], v[206:209], v[112:115]
	v_mfma_f32_16x16x32_bf16 v[116:119], v[162:165], v[206:209], v[116:119]
	v_mfma_f32_16x16x32_bf16 v[108:111], v[162:165], v[214:217], v[108:111]
	v_mfma_f32_16x16x32_bf16 v[104:107], v[170:173], v[214:217], v[104:107]
	v_mfma_f32_16x16x32_bf16 v[96:99], v[170:173], v[222:225], v[96:99]
	v_mfma_f32_16x16x32_bf16 v[100:103], v[162:165], v[222:225], v[100:103]
	v_mfma_f32_16x16x32_bf16 v[124:127], v[166:169], v[202:205], v[124:127]
	v_mfma_f32_16x16x32_bf16 v[120:123], v[174:177], v[202:205], v[120:123]
	v_mfma_f32_16x16x32_bf16 v[112:115], v[174:177], v[210:213], v[112:115]
	v_mfma_f32_16x16x32_bf16 v[116:119], v[166:169], v[210:213], v[116:119]
	v_mfma_f32_16x16x32_bf16 v[108:111], v[166:169], v[218:221], v[108:111]
	v_mfma_f32_16x16x32_bf16 v[104:107], v[174:177], v[218:221], v[104:107]
	v_mfma_f32_16x16x32_bf16 v[96:99], v[174:177], v[226:229], v[96:99]
	v_mfma_f32_16x16x32_bf16 v[100:103], v[166:169], v[226:229], v[100:103]
	s_setprio 0
	s_barrier
	v_readfirstlane_b32 s13, v152
	v_add_u32_e32 v186, 0x2000, v152
	v_lshl_add_u64 v[250:251], v[246:247], 0, s[82:83]
	s_mov_b32 m0, s13
	v_readfirstlane_b32 s13, v186
	ds_read_b128 v[230:233], v157
	ds_read_b128 v[234:237], v157 offset:1024
	ds_read_b128 v[238:241], v157 offset:2048
	ds_read_b128 v[242:245], v157 offset:3072
	global_load_lds_dwordx4 v[250:251], off
	v_lshl_add_u64 v[250:251], v[248:249], 0, s[82:83]
	s_mov_b32 m0, s13
	s_nop 0
	global_load_lds_dwordx4 v[250:251], off
	s_barrier
	s_waitcnt lgkmcnt(0)
	s_setprio 1
	s_waitcnt lgkmcnt(0)
	v_mfma_f32_16x16x32_bf16 v[92:95], v[230:233], v[198:201], v[92:95]
	v_mfma_f32_16x16x32_bf16 v[88:91], v[238:241], v[198:201], v[88:91]
	v_mfma_f32_16x16x32_bf16 v[80:83], v[238:241], v[206:209], v[80:83]
	v_mfma_f32_16x16x32_bf16 v[84:87], v[230:233], v[206:209], v[84:87]
	v_mfma_f32_16x16x32_bf16 v[76:79], v[230:233], v[214:217], v[76:79]
	v_mfma_f32_16x16x32_bf16 v[72:75], v[238:241], v[214:217], v[72:75]
	v_mfma_f32_16x16x32_bf16 v[64:67], v[238:241], v[222:225], v[64:67]
	v_mfma_f32_16x16x32_bf16 v[68:71], v[230:233], v[222:225], v[68:71]
	v_mfma_f32_16x16x32_bf16 v[92:95], v[234:237], v[202:205], v[92:95]
	v_mfma_f32_16x16x32_bf16 v[88:91], v[242:245], v[202:205], v[88:91]
	v_mfma_f32_16x16x32_bf16 v[80:83], v[242:245], v[210:213], v[80:83]
	v_mfma_f32_16x16x32_bf16 v[84:87], v[234:237], v[210:213], v[84:87]
	v_mfma_f32_16x16x32_bf16 v[76:79], v[234:237], v[218:221], v[76:79]
	v_mfma_f32_16x16x32_bf16 v[72:75], v[242:245], v[218:221], v[72:75]
	v_mfma_f32_16x16x32_bf16 v[64:67], v[242:245], v[226:229], v[64:67]
	v_mfma_f32_16x16x32_bf16 v[68:71], v[234:237], v[226:229], v[68:71]
	s_setprio 0
	v_readfirstlane_b32 s13, v153
	v_lshl_add_u64 v[178:179], v[178:179], 0, s[54:55]
	s_mov_b32 m0, s13
	v_readfirstlane_b32 s13, v154
	s_barrier
; #define WAIT_V(n) asm volatile("s_waitcnt vmcnt(" #n ")" ::: "memory")
; #define WAIT_L(n) asm volatile("s_waitcnt lgkmcnt(" #n ")" ::: "memory")
; #define BAR __builtin_amdgcn_s_barrier()
; #define SCHED __builtin_amdgcn_sched_barrier(0)
; #define LDA(dst, b, h)                                                                            \
;   _Pragma("unroll") for (int m = 0; m < 4; ++m) _Pragma("unroll") for (int k = 0; k < 2; ++k)                                         \
;     dst[m][k] = *reinterpret_cast<const bf16x8*>((char*)SA(b, h) + lds_byte(wr * 64 + m * 16 + fr, k * 32 + fq * 8))
; #define LDB(dst, b, h)                                                                            \
;   _Pragma("unroll") for (int n = 0; n < 2; ++n) _Pragma("unroll") for (int k = 0; k < 2; ++k)                                         \
;     dst[n][k] = *reinterpret_cast<const bf16x8*>((char*)SB(b, h) + lds_byte(wc * 32 + n * 16 + fr, k * 32 + fq * 8))
; template <int K, bool SWAP>
; __device__ __forceinline__ void gemm_kloop(const bf16* __restrict__ A, const bf16* __restrict__ Bt,
;                                            f32x4 (&acc)[2][2][4][2], bool pref = false) {
;     ...
;     LDA(At, 1, 1); STAGE(SA(1, 0), A, 0, t + 3);
;     BAR; WAIT_L(0); MMA(1, 0, At, B0); BAR; SCHED;
;     STAGE(SB(1, 1), Bt, HALF, t + 3);
;     WAIT_V(6); BAR; MMA(1, 1, At, B1); BAR;
;   }
;   { LDB(B0, 0, 0); LDA(At, 0, 0); STAGE(SA(1, 1), A, HALF, nt - 1);
;     BAR; WAIT_L(0); MMA(0, 0, At, B0); BAR;
;     LDB(B1, 0, 1); BAR; WAIT_L(0); MMA(0, 1, At, B1); BAR;
;     LDA(At, 0, 1); WAIT_V(4); BAR; WAIT_L(0); MMA(1, 0, At, B0); MMA(1, 1, At, B1); BAR; }
	ds_read_b128 v[198:201], v156 offset:49152
	ds_read_b128 v[202:205], v156 offset:50176
	ds_read_b128 v[206:209], v151 offset:49152
	ds_read_b128 v[210:213], v151 offset:50176
	ds_read_b128 v[214:217], v150 offset:49152
	ds_read_b128 v[218:221], v150 offset:50176
	ds_read_b128 v[222:225], v149 offset:49152
	ds_read_b128 v[226:229], v149 offset:50176
	global_load_lds_dwordx4 v[178:179], off
	v_lshl_add_u64 v[178:179], v[188:189], 0, s[54:55]
	s_mov_b32 m0, s13
	s_nop 0
	global_load_lds_dwordx4 v[178:179], off
	s_barrier
	s_waitcnt lgkmcnt(0)
	s_setprio 1
	s_waitcnt lgkmcnt(0)
	v_mfma_f32_16x16x32_bf16 v[60:63], v[162:165], v[198:201], v[60:63]
	v_mfma_f32_16x16x32_bf16 v[56:59], v[170:173], v[198:201], v[56:59]
	v_mfma_f32_16x16x32_bf16 v[48:51], v[170:173], v[206:209], v[48:51]
	v_mfma_f32_16x16x32_bf16 v[52:55], v[162:165], v[206:209], v[52:55]
	v_mfma_f32_16x16x32_bf16 v[44:47], v[162:165], v[214:217], v[44:47]
	v_mfma_f32_16x16x32_bf16 v[40:43], v[170:173], v[214:217], v[40:43]
	v_mfma_f32_16x16x32_bf16 v[32:35], v[170:173], v[222:225], v[32:35]
	v_mfma_f32_16x16x32_bf16 v[36:39], v[162:165], v[222:225], v[36:39]
	v_mfma_f32_16x16x32_bf16 v[60:63], v[166:169], v[202:205], v[60:63]
	v_mfma_f32_16x16x32_bf16 v[56:59], v[174:177], v[202:205], v[56:59]
	v_mfma_f32_16x16x32_bf16 v[48:51], v[174:177], v[210:213], v[48:51]
	v_mfma_f32_16x16x32_bf16 v[52:55], v[166:169], v[210:213], v[52:55]
	v_mfma_f32_16x16x32_bf16 v[44:47], v[166:169], v[218:221], v[44:47]
	v_mfma_f32_16x16x32_bf16 v[40:43], v[174:177], v[218:221], v[40:43]
	v_mfma_f32_16x16x32_bf16 v[32:35], v[174:177], v[226:229], v[32:35]
	v_mfma_f32_16x16x32_bf16 v[36:39], v[166:169], v[226:229], v[36:39]
	s_setprio 0
	s_barrier
	v_readfirstlane_b32 s13, v155
	v_add_u32_e32 v164, 0x2000, v155
	v_lshl_add_u64 v[162:163], v[246:247], 0, s[84:85]
	s_mov_b32 m0, s13
	v_readfirstlane_b32 s13, v164
	global_load_lds_dwordx4 v[162:163], off
	v_lshl_add_u64 v[162:163], v[248:249], 0, s[84:85]
	s_mov_b32 m0, s13
	s_nop 0
	global_load_lds_dwordx4 v[162:163], off
	s_waitcnt vmcnt(6)
	s_barrier
	s_setprio 1
	v_mfma_f32_16x16x32_bf16 v[28:31], v[230:233], v[198:201], v[28:31]
	v_mfma_f32_16x16x32_bf16 v[24:27], v[238:241], v[198:201], v[24:27]
	v_mfma_f32_16x16x32_bf16 v[16:19], v[238:241], v[206:209], v[16:19]
	v_mfma_f32_16x16x32_bf16 v[20:23], v[230:233], v[206:209], v[20:23]
	v_mfma_f32_16x16x32_bf16 v[12:15], v[230:233], v[214:217], v[12:15]
	v_mfma_f32_16x16x32_bf16 v[8:11], v[238:241], v[214:217], v[8:11]
	v_mfma_f32_16x16x32_bf16 v[0:3], v[238:241], v[222:225], v[0:3]
	v_mfma_f32_16x16x32_bf16 v[4:7], v[230:233], v[222:225], v[4:7]
	v_mfma_f32_16x16x32_bf16 v[28:31], v[234:237], v[202:205], v[28:31]
	v_mfma_f32_16x16x32_bf16 v[24:27], v[242:245], v[202:205], v[24:27]
	v_mfma_f32_16x16x32_bf16 v[16:19], v[242:245], v[210:213], v[16:19]
	v_mfma_f32_16x16x32_bf16 v[20:23], v[234:237], v[210:213], v[20:23]
	v_mfma_f32_16x16x32_bf16 v[12:15], v[234:237], v[218:221], v[12:15]
	v_mfma_f32_16x16x32_bf16 v[8:11], v[242:245], v[218:221], v[8:11]
	v_mfma_f32_16x16x32_bf16 v[0:3], v[242:245], v[226:229], v[0:3]
	v_mfma_f32_16x16x32_bf16 v[4:7], v[234:237], v[226:229], v[4:7]
	s_setprio 0
	s_add_i32 s12, s12, 2
	v_lshl_add_u64 v[136:137], v[136:137], 0, s[44:45]
	v_lshl_add_u64 v[138:139], v[138:139], 0, s[44:45]
	v_lshl_add_u64 v[140:141], v[140:141], 0, s[44:45]
	s_cmp_lt_u32 s12, 4
	v_lshl_add_u64 v[142:143], v[142:143], 0, s[44:45]
	s_barrier
	s_cbranch_scc1 .LBB0_791
	s_add_u32 s0, s0, 0x20380
	s_addc_u32 s1, s1, 0
	v_lshl_add_u64 v[130:131], s[0:1], 0, v[130:131]
	v_readfirstlane_b32 s12, v160
	v_lshl_add_u64 v[128:129], v[128:129], 1, v[130:131]
	s_mov_b32 m0, s12
	ds_read_b128 v[136:139], v159
	ds_read_b128 v[140:143], v159 offset:1024
	ds_read_b128 v[152:155], v159 offset:2048
	ds_read_b128 v[162:165], v159 offset:3072
	ds_read_b128 v[166:169], v156
	ds_read_b128 v[170:173], v156 offset:1024
	ds_read_b128 v[174:177], v151
	ds_read_b128 v[198:201], v151 offset:1024
	ds_read_b128 v[202:205], v150
	ds_read_b128 v[206:209], v150 offset:1024
	ds_read_b128 v[210:213], v149
	ds_read_b128 v[214:217], v149 offset:1024
	global_load_lds_dwordx4 v[128:129], off
	v_lshl_add_u64 v[128:129], s[0:1], 0, v[134:135]
	v_readfirstlane_b32 s0, v161
	v_lshl_add_u64 v[128:129], v[132:133], 1, v[128:129]
	s_mov_b32 m0, s0
	s_nop 0
	global_load_lds_dwordx4 v[128:129], off
	s_barrier
	s_waitcnt lgkmcnt(0)
	s_setprio 1
	s_waitcnt lgkmcnt(0)
	v_mfma_f32_16x16x32_bf16 v[124:127], v[136:139], v[166:169], v[124:127]
	v_mfma_f32_16x16x32_bf16 v[120:123], v[152:155], v[166:169], v[120:123]
	v_mfma_f32_16x16x32_bf16 v[112:115], v[152:155], v[174:177], v[112:115]
	v_mfma_f32_16x16x32_bf16 v[108:111], v[136:139], v[202:205], v[108:111]
	v_mfma_f32_16x16x32_bf16 v[100:103], v[136:139], v[210:213], v[100:103]
	v_mfma_f32_16x16x32_bf16 v[96:99], v[152:155], v[210:213], v[96:99]
	v_mfma_f32_16x16x32_bf16 v[124:127], v[140:143], v[170:173], v[124:127]
	v_mfma_f32_16x16x32_bf16 v[120:123], v[162:165], v[170:173], v[120:123]
	v_mfma_f32_16x16x32_bf16 v[116:119], v[136:139], v[174:177], v[116:119]
	v_mfma_f32_16x16x32_bf16 v[112:115], v[162:165], v[198:201], v[112:115]
	v_mfma_f32_16x16x32_bf16 v[108:111], v[140:143], v[206:209], v[108:111]
	v_mfma_f32_16x16x32_bf16 v[104:107], v[152:155], v[202:205], v[104:107]
	v_mfma_f32_16x16x32_bf16 v[100:103], v[140:143], v[214:217], v[100:103]
	v_mfma_f32_16x16x32_bf16 v[96:99], v[162:165], v[214:217], v[96:99]
	v_mfma_f32_16x16x32_bf16 v[116:119], v[140:143], v[198:201], v[116:119]
	v_mfma_f32_16x16x32_bf16 v[104:107], v[162:165], v[206:209], v[104:107]
	s_setprio 0
	s_barrier
; #define WAIT_V(n) asm volatile("s_waitcnt vmcnt(" #n ")" ::: "memory")
; #define WAIT_L(n) asm volatile("s_waitcnt lgkmcnt(" #n ")" ::: "memory")
; #define BAR __builtin_amdgcn_s_barrier()
; #define LDA(dst, b, h)                                                                            \
;   _Pragma("unroll") for (int m = 0; m < 4; ++m) _Pragma("unroll") for (int k = 0; k < 2; ++k)                                         \
;     dst[m][k] = *reinterpret_cast<const bf16x8*>((char*)SA(b, h) + lds_byte(wr * 64 + m * 16 + fr, k * 32 + fq * 8))
; #define LDB(dst, b, h)                                                                            \
;   _Pragma("unroll") for (int n = 0; n < 2; ++n) _Pragma("unroll") for (int k = 0; k < 2; ++k)                                         \
;     dst[n][k] = *reinterpret_cast<const bf16x8*>((char*)SB(b, h) + lds_byte(wc * 32 + n * 16 + fr, k * 32 + fq * 8))
; template <int K, bool SWAP>
; __device__ __forceinline__ void gemm_kloop(const bf16* __restrict__ A, const bf16* __restrict__ Bt,
;                                            f32x4 (&acc)[2][2][4][2], bool pref = false) {
;     ...
;     LDB(B1, 0, 1); BAR; WAIT_L(0); MMA(0, 1, At, B1); BAR;
;     LDA(At, 0, 1); WAIT_V(4); BAR; WAIT_L(0); MMA(1, 0, At, B0); MMA(1, 1, At, B1); BAR; }
;   { LDB(B0, 1, 0); LDA(At, 1, 0); WAIT_V(2); BAR; WAIT_L(0); MMA(0, 0, At, B0); BAR;
	ds_read_b128 v[128:131], v158
	ds_read_b128 v[132:135], v158 offset:1024
	ds_read_b128 v[218:221], v158 offset:2048
	ds_read_b128 v[158:161], v158 offset:3072
	s_barrier
	s_waitcnt lgkmcnt(0)
	s_setprio 1
	s_waitcnt lgkmcnt(0)
	v_mfma_f32_16x16x32_bf16 v[88:91], v[218:221], v[166:169], v[88:91]
	v_mfma_f32_16x16x32_bf16 v[84:87], v[128:131], v[174:177], v[84:87]
	v_mfma_f32_16x16x32_bf16 v[76:79], v[128:131], v[202:205], v[76:79]
	v_mfma_f32_16x16x32_bf16 v[72:75], v[218:221], v[202:205], v[72:75]
	v_mfma_f32_16x16x32_bf16 v[68:71], v[128:131], v[210:213], v[68:71]
	v_mfma_f32_16x16x32_bf16 v[64:67], v[218:221], v[210:213], v[64:67]
	v_mfma_f32_16x16x32_bf16 v[92:95], v[128:131], v[166:169], v[92:95]
	v_mfma_f32_16x16x32_bf16 v[88:91], v[158:161], v[170:173], v[88:91]
	v_mfma_f32_16x16x32_bf16 v[84:87], v[132:135], v[198:201], v[84:87]
	v_mfma_f32_16x16x32_bf16 v[80:83], v[218:221], v[174:177], v[80:83]
	v_mfma_f32_16x16x32_bf16 v[76:79], v[132:135], v[206:209], v[76:79]
	v_mfma_f32_16x16x32_bf16 v[72:75], v[158:161], v[206:209], v[72:75]
	v_mfma_f32_16x16x32_bf16 v[68:71], v[132:135], v[214:217], v[68:71]
	v_mfma_f32_16x16x32_bf16 v[64:67], v[158:161], v[214:217], v[64:67]
	v_mfma_f32_16x16x32_bf16 v[92:95], v[132:135], v[170:173], v[92:95]
	v_mfma_f32_16x16x32_bf16 v[80:83], v[158:161], v[198:201], v[80:83]
	s_setprio 0
	s_barrier
	ds_read_b128 v[166:169], v156 offset:16384
	ds_read_b128 v[170:173], v156 offset:17408
	ds_read_b128 v[174:177], v151 offset:16384
	ds_read_b128 v[198:201], v151 offset:17408
	ds_read_b128 v[202:205], v150 offset:16384
	ds_read_b128 v[206:209], v150 offset:17408
	ds_read_b128 v[210:213], v149 offset:16384
	ds_read_b128 v[214:217], v149 offset:17408
	s_waitcnt vmcnt(4)
	s_barrier
	s_waitcnt lgkmcnt(0)
	s_setprio 1
	s_waitcnt lgkmcnt(0)
	v_mfma_f32_16x16x32_bf16 v[60:63], v[136:139], v[166:169], v[60:63]
	v_mfma_f32_16x16x32_bf16 v[56:59], v[152:155], v[166:169], v[56:59]
	v_mfma_f32_16x16x32_bf16 v[48:51], v[152:155], v[174:177], v[48:51]
	v_mfma_f32_16x16x32_bf16 v[52:55], v[136:139], v[174:177], v[52:55]
	v_mfma_f32_16x16x32_bf16 v[44:47], v[136:139], v[202:205], v[44:47]
	v_mfma_f32_16x16x32_bf16 v[40:43], v[152:155], v[202:205], v[40:43]
	v_mfma_f32_16x16x32_bf16 v[32:35], v[152:155], v[210:213], v[32:35]
	v_mfma_f32_16x16x32_bf16 v[36:39], v[136:139], v[210:213], v[36:39]
	v_mfma_f32_16x16x32_bf16 v[60:63], v[140:143], v[170:173], v[60:63]
	v_mfma_f32_16x16x32_bf16 v[56:59], v[162:165], v[170:173], v[56:59]
	v_mfma_f32_16x16x32_bf16 v[48:51], v[162:165], v[198:201], v[48:51]
	v_mfma_f32_16x16x32_bf16 v[52:55], v[140:143], v[198:201], v[52:55]
	v_mfma_f32_16x16x32_bf16 v[44:47], v[140:143], v[206:209], v[44:47]
	v_mfma_f32_16x16x32_bf16 v[40:43], v[162:165], v[206:209], v[40:43]
	v_mfma_f32_16x16x32_bf16 v[32:35], v[162:165], v[214:217], v[32:35]
	v_mfma_f32_16x16x32_bf16 v[36:39], v[140:143], v[214:217], v[36:39]
	s_setprio 0
	s_setprio 1
	v_mfma_f32_16x16x32_bf16 v[28:31], v[128:131], v[166:169], v[28:31]
	v_mfma_f32_16x16x32_bf16 v[24:27], v[218:221], v[166:169], v[24:27]
	v_mfma_f32_16x16x32_bf16 v[16:19], v[218:221], v[174:177], v[16:19]
	v_mfma_f32_16x16x32_bf16 v[20:23], v[128:131], v[174:177], v[20:23]
	v_mfma_f32_16x16x32_bf16 v[12:15], v[128:131], v[202:205], v[12:15]
	v_mfma_f32_16x16x32_bf16 v[8:11], v[218:221], v[202:205], v[8:11]
	v_mfma_f32_16x16x32_bf16 v[0:3], v[218:221], v[210:213], v[0:3]
	v_mfma_f32_16x16x32_bf16 v[4:7], v[128:131], v[210:213], v[4:7]
	v_mfma_f32_16x16x32_bf16 v[28:31], v[132:135], v[170:173], v[28:31]
	v_mfma_f32_16x16x32_bf16 v[24:27], v[158:161], v[170:173], v[24:27]
	v_mfma_f32_16x16x32_bf16 v[16:19], v[158:161], v[198:201], v[16:19]
	v_mfma_f32_16x16x32_bf16 v[20:23], v[132:135], v[198:201], v[20:23]
	v_mfma_f32_16x16x32_bf16 v[12:15], v[132:135], v[206:209], v[12:15]
	v_mfma_f32_16x16x32_bf16 v[8:11], v[158:161], v[206:209], v[8:11]
	v_mfma_f32_16x16x32_bf16 v[0:3], v[158:161], v[214:217], v[0:3]
	v_mfma_f32_16x16x32_bf16 v[4:7], v[132:135], v[214:217], v[4:7]
	s_setprio 0
	s_barrier
	ds_read_b128 v[128:131], v147
	ds_read_b128 v[140:143], v147 offset:1024
	ds_read_b128 v[158:161], v147 offset:2048
	ds_read_b128 v[162:165], v147 offset:3072
	ds_read_b128 v[166:169], v156 offset:32768
	ds_read_b128 v[170:173], v156 offset:33792
	ds_read_b128 v[174:177], v151 offset:32768
	ds_read_b128 v[198:201], v151 offset:33792
	ds_read_b128 v[202:205], v150 offset:32768
	ds_read_b128 v[206:209], v150 offset:33792
	ds_read_b128 v[210:213], v149 offset:32768
	ds_read_b128 v[214:217], v149 offset:33792
	s_waitcnt vmcnt(2)
	s_barrier
; #define WAIT_V(n) asm volatile("s_waitcnt vmcnt(" #n ")" ::: "memory")
; #define WAIT_L(n) asm volatile("s_waitcnt lgkmcnt(" #n ")" ::: "memory")
; #define BAR __builtin_amdgcn_s_barrier()
; #define LDA(dst, b, h)                                                                            \
;   _Pragma("unroll") for (int m = 0; m < 4; ++m) _Pragma("unroll") for (int k = 0; k < 2; ++k)                                         \
;     dst[m][k] = *reinterpret_cast<const bf16x8*>((char*)SA(b, h) + lds_byte(wr * 64 + m * 16 + fr, k * 32 + fq * 8))
; #define LDB(dst, b, h)                                                                            \
;   _Pragma("unroll") for (int n = 0; n < 2; ++n) _Pragma("unroll") for (int k = 0; k < 2; ++k)                                         \
;     dst[n][k] = *reinterpret_cast<const bf16x8*>((char*)SB(b, h) + lds_byte(wc * 32 + n * 16 + fr, k * 32 + fq * 8))
; template <int K, bool SWAP>
; __device__ __forceinline__ void gemm_kloop(const bf16* __restrict__ A, const bf16* __restrict__ Bt,
;                                            f32x4 (&acc)[2][2][4][2], bool pref = false) {
;     ...
;   { LDB(B0, 1, 0); LDA(At, 1, 0); WAIT_V(2); BAR; WAIT_L(0); MMA(0, 0, At, B0); BAR;
;     LDB(B1, 1, 1); WAIT_V(0); BAR; WAIT_L(0); MMA(0, 1, At, B1); BAR;
;     LDA(At, 1, 1); BAR; WAIT_L(0); MMA(1, 0, At, B0); MMA(1, 1, At, B1); BAR; }
;   if (wr == 0) BAR;
	s_waitcnt lgkmcnt(0)
	s_setprio 1
	s_waitcnt lgkmcnt(0)
	v_mfma_f32_16x16x32_bf16 v[124:127], v[128:131], v[166:169], v[124:127]
	v_mfma_f32_16x16x32_bf16 v[120:123], v[158:161], v[166:169], v[120:123]
	v_mfma_f32_16x16x32_bf16 v[116:119], v[128:131], v[174:177], v[116:119]
	v_mfma_f32_16x16x32_bf16 v[112:115], v[158:161], v[174:177], v[112:115]
	v_mfma_f32_16x16x32_bf16 v[108:111], v[128:131], v[202:205], v[108:111]
	v_mfma_f32_16x16x32_bf16 v[104:107], v[158:161], v[202:205], v[104:107]
	v_mfma_f32_16x16x32_bf16 v[100:103], v[128:131], v[210:213], v[100:103]
	v_mfma_f32_16x16x32_bf16 v[96:99], v[158:161], v[210:213], v[96:99]
	v_mfma_f32_16x16x32_bf16 v[152:155], v[140:143], v[170:173], v[124:127]
	v_mfma_f32_16x16x32_bf16 v[144:147], v[162:165], v[170:173], v[120:123]
	v_mfma_f32_16x16x32_bf16 v[136:139], v[140:143], v[198:201], v[116:119]
	v_mfma_f32_16x16x32_bf16 v[132:135], v[162:165], v[198:201], v[112:115]
	v_mfma_f32_16x16x32_bf16 v[124:127], v[140:143], v[206:209], v[108:111]
	v_mfma_f32_16x16x32_bf16 v[120:123], v[162:165], v[206:209], v[104:107]
	v_mfma_f32_16x16x32_bf16 v[112:115], v[140:143], v[214:217], v[100:103]
	v_mfma_f32_16x16x32_bf16 v[108:111], v[162:165], v[214:217], v[96:99]
	s_setprio 0
	s_barrier
	ds_read_b128 v[104:107], v157
	ds_read_b128 v[116:119], v157 offset:1024
	ds_read_b128 v[218:221], v157 offset:2048
	ds_read_b128 v[222:225], v157 offset:3072
	s_waitcnt vmcnt(0)
	s_barrier
	s_waitcnt lgkmcnt(0)
	s_setprio 1
	s_waitcnt lgkmcnt(0)
	v_mfma_f32_16x16x32_bf16 v[92:95], v[104:107], v[166:169], v[92:95]
	v_mfma_f32_16x16x32_bf16 v[88:91], v[218:221], v[166:169], v[88:91]
	v_mfma_f32_16x16x32_bf16 v[84:87], v[104:107], v[174:177], v[84:87]
	v_mfma_f32_16x16x32_bf16 v[80:83], v[218:221], v[174:177], v[80:83]
	v_mfma_f32_16x16x32_bf16 v[76:79], v[104:107], v[202:205], v[76:79]
	v_mfma_f32_16x16x32_bf16 v[72:75], v[218:221], v[202:205], v[72:75]
	v_mfma_f32_16x16x32_bf16 v[68:71], v[104:107], v[210:213], v[68:71]
	v_mfma_f32_16x16x32_bf16 v[64:67], v[218:221], v[210:213], v[64:67]
	v_mfma_f32_16x16x32_bf16 v[100:103], v[116:119], v[170:173], v[92:95]
	v_mfma_f32_16x16x32_bf16 v[96:99], v[222:225], v[170:173], v[88:91]
	v_mfma_f32_16x16x32_bf16 v[88:91], v[116:119], v[198:201], v[84:87]
	v_mfma_f32_16x16x32_bf16 v[84:87], v[222:225], v[198:201], v[80:83]
	v_mfma_f32_16x16x32_bf16 v[76:79], v[116:119], v[206:209], v[76:79]
	v_mfma_f32_16x16x32_bf16 v[72:75], v[222:225], v[206:209], v[72:75]
	v_mfma_f32_16x16x32_bf16 v[68:71], v[116:119], v[214:217], v[68:71]
	v_mfma_f32_16x16x32_bf16 v[64:67], v[222:225], v[214:217], v[64:67]
	s_setprio 0
	s_barrier
	ds_read_b128 v[80:83], v156 offset:49152
	ds_read_b128 v[92:95], v156 offset:50176
	ds_read_b128 v[166:169], v151 offset:49152
	ds_read_b128 v[170:173], v151 offset:50176
	ds_read_b128 v[174:177], v150 offset:49152
	ds_read_b128 v[198:201], v150 offset:50176
	ds_read_b128 v[202:205], v149 offset:49152
	ds_read_b128 v[206:209], v149 offset:50176
	s_barrier
	s_waitcnt lgkmcnt(0)
	s_setprio 1
	s_waitcnt lgkmcnt(0)
	v_mfma_f32_16x16x32_bf16 v[60:63], v[128:131], v[80:83], v[60:63]
	v_mfma_f32_16x16x32_bf16 v[56:59], v[158:161], v[80:83], v[56:59]
	v_mfma_f32_16x16x32_bf16 v[48:51], v[158:161], v[166:169], v[48:51]
	v_mfma_f32_16x16x32_bf16 v[52:55], v[128:131], v[166:169], v[52:55]
	v_mfma_f32_16x16x32_bf16 v[44:47], v[128:131], v[174:177], v[44:47]
	v_mfma_f32_16x16x32_bf16 v[40:43], v[158:161], v[174:177], v[40:43]
	v_mfma_f32_16x16x32_bf16 v[32:35], v[158:161], v[202:205], v[32:35]
	v_mfma_f32_16x16x32_bf16 v[36:39], v[128:131], v[202:205], v[36:39]
	v_mfma_f32_16x16x32_bf16 v[60:63], v[140:143], v[92:95], v[60:63]
	v_mfma_f32_16x16x32_bf16 v[56:59], v[162:165], v[92:95], v[56:59]
	v_mfma_f32_16x16x32_bf16 v[48:51], v[162:165], v[170:173], v[48:51]
	v_mfma_f32_16x16x32_bf16 v[52:55], v[140:143], v[170:173], v[52:55]
	v_mfma_f32_16x16x32_bf16 v[44:47], v[140:143], v[198:201], v[44:47]
	v_mfma_f32_16x16x32_bf16 v[40:43], v[162:165], v[198:201], v[40:43]
	v_mfma_f32_16x16x32_bf16 v[32:35], v[162:165], v[206:209], v[32:35]
	v_mfma_f32_16x16x32_bf16 v[36:39], v[140:143], v[206:209], v[36:39]
	s_setprio 0
	s_setprio 1
	v_mfma_f32_16x16x32_bf16 v[28:31], v[104:107], v[80:83], v[28:31]
	v_mfma_f32_16x16x32_bf16 v[24:27], v[218:221], v[80:83], v[24:27]
	v_mfma_f32_16x16x32_bf16 v[16:19], v[218:221], v[166:169], v[16:19]
	v_mfma_f32_16x16x32_bf16 v[20:23], v[104:107], v[166:169], v[20:23]
	v_mfma_f32_16x16x32_bf16 v[12:15], v[104:107], v[174:177], v[12:15]
	v_mfma_f32_16x16x32_bf16 v[8:11], v[218:221], v[174:177], v[8:11]
	v_mfma_f32_16x16x32_bf16 v[0:3], v[218:221], v[202:205], v[0:3]
	v_mfma_f32_16x16x32_bf16 v[4:7], v[104:107], v[202:205], v[4:7]
	v_mfma_f32_16x16x32_bf16 v[28:31], v[116:119], v[92:95], v[28:31]
	v_mfma_f32_16x16x32_bf16 v[24:27], v[222:225], v[92:95], v[24:27]
	v_mfma_f32_16x16x32_bf16 v[16:19], v[222:225], v[170:173], v[16:19]
	v_mfma_f32_16x16x32_bf16 v[20:23], v[116:119], v[170:173], v[20:23]
	v_mfma_f32_16x16x32_bf16 v[12:15], v[116:119], v[198:201], v[12:15]
	v_mfma_f32_16x16x32_bf16 v[8:11], v[222:225], v[198:201], v[8:11]
	v_mfma_f32_16x16x32_bf16 v[0:3], v[222:225], v[206:209], v[0:3]
	v_mfma_f32_16x16x32_bf16 v[4:7], v[116:119], v[206:209], v[4:7]
	s_setprio 0
	s_movk_i32 s0, 0x100
	v_cmp_gt_u32_e32 vcc, s0, v148
	s_barrier
	s_and_saveexec_b64 s[0:1], vcc
	s_cbranch_execz .LBB0_794
	s_barrier

; #define WAIT_L(n) asm volatile("s_waitcnt lgkmcnt(" #n ")" ::: "memory")
; #define BAR __builtin_amdgcn_s_barrier()
; #define SCHED __builtin_amdgcn_sched_barrier(0)
; #define LDA(dst, b, h)                                                                            \
;   _Pragma("unroll") for (int m = 0; m < 4; ++m) _Pragma("unroll") for (int k = 0; k < 2; ++k)                                         \
;     dst[m][k] = *reinterpret_cast<const bf16x8*>((char*)SA(b, h) + lds_byte(wr * 64 + m * 16 + fr, k * 32 + fq * 8))
; #define LDB(dst, b, h)                                                                            \
;   _Pragma("unroll") for (int n = 0; n < 2; ++n) _Pragma("unroll") for (int k = 0; k < 2; ++k)                                         \
;     dst[n][k] = *reinterpret_cast<const bf16x8*>((char*)SB(b, h) + lds_byte(wc * 32 + n * 16 + fr, k * 32 + fq * 8))
; template <int K, bool SWAP>
; __device__ __forceinline__ void gemm_kloop(const bf16* __restrict__ A, const bf16* __restrict__ Bt,
;                                            f32x4 (&acc)[2][2][4][2], bool pref = false) {
;     ...
;     LDB(B0, 0, 0); SCHED; LDA(At, 0, 0); STAGE(SA(1, 1), A, HALF, t + 1);
;     WAIT_L(8); BAR; WAIT_L(0); MMA(0, 0, At, B0); BAR; SCHED;
;     LDB(B1, 0, 1); STAGE(SB(0, 0), Bt, 0, t + 2);
;     BAR; WAIT_L(0); MMA(0, 1, At, B1); BAR;
;     LDA(At, 0, 1); STAGE(SA(0, 0), A, 0, t + 2);
;     BAR; WAIT_L(0); MMA(1, 0, At, B0); BAR; SCHED;
.LBB0_797:
	ds_read_b128 v[162:165], v158
	ds_read_b128 v[166:169], v158 offset:1024
	ds_read_b128 v[170:173], v158 offset:2048
	ds_read_b128 v[174:177], v158 offset:3072
	v_add_u32_e32 v159, 0xc000, v153
	v_lshl_add_u64 v[178:179], s[6:7], 0, v[140:141]
	v_readfirstlane_b32 s5, v159
	v_lshl_add_u64 v[160:161], v[178:179], 0, s[86:87]
	s_mov_b32 m0, s5
	ds_read_b128 v[198:201], v148
	ds_read_b128 v[202:205], v148 offset:1024
	ds_read_b128 v[206:209], v147
	ds_read_b128 v[210:213], v147 offset:1024
	ds_read_b128 v[214:217], v146
	ds_read_b128 v[218:221], v146 offset:1024
	ds_read_b128 v[222:225], v145
	ds_read_b128 v[226:229], v145 offset:1024
	global_load_lds_dwordx4 v[160:161], off
	v_add_u32_e32 v160, 0xe000, v153
	v_lshl_add_u64 v[188:189], s[6:7], 0, v[142:143]
	v_readfirstlane_b32 s5, v160
	v_lshl_add_u64 v[230:231], v[188:189], 0, s[86:87]
	s_mov_b32 m0, s5
	s_nop 0
	global_load_lds_dwordx4 v[230:231], off
	s_waitcnt lgkmcnt(8)
	s_barrier
	s_waitcnt lgkmcnt(0)
	s_setprio 1
	s_waitcnt lgkmcnt(0)
	v_mfma_f32_16x16x32_bf16 v[124:127], v[162:165], v[198:201], v[124:127]
	v_mfma_f32_16x16x32_bf16 v[120:123], v[170:173], v[198:201], v[120:123]
	v_mfma_f32_16x16x32_bf16 v[112:115], v[170:173], v[206:209], v[112:115]
	v_mfma_f32_16x16x32_bf16 v[116:119], v[162:165], v[206:209], v[116:119]
	v_mfma_f32_16x16x32_bf16 v[108:111], v[162:165], v[214:217], v[108:111]
	v_mfma_f32_16x16x32_bf16 v[104:107], v[170:173], v[214:217], v[104:107]
	v_mfma_f32_16x16x32_bf16 v[96:99], v[170:173], v[222:225], v[96:99]
	v_mfma_f32_16x16x32_bf16 v[100:103], v[162:165], v[222:225], v[100:103]
	v_mfma_f32_16x16x32_bf16 v[124:127], v[166:169], v[202:205], v[124:127]
	v_mfma_f32_16x16x32_bf16 v[120:123], v[174:177], v[202:205], v[120:123]
	v_mfma_f32_16x16x32_bf16 v[112:115], v[174:177], v[210:213], v[112:115]
	v_mfma_f32_16x16x32_bf16 v[116:119], v[166:169], v[210:213], v[116:119]
	v_mfma_f32_16x16x32_bf16 v[108:111], v[166:169], v[218:221], v[108:111]
	v_mfma_f32_16x16x32_bf16 v[104:107], v[174:177], v[218:221], v[104:107]
	v_mfma_f32_16x16x32_bf16 v[96:99], v[174:177], v[226:229], v[96:99]
	v_mfma_f32_16x16x32_bf16 v[100:103], v[166:169], v[226:229], v[100:103]
	s_setprio 0
	s_barrier
	v_add_u32_e32 v161, s9, v150
	v_lshl_add_u64 v[246:247], s[6:7], 0, v[136:137]
	v_readfirstlane_b32 s5, v161
	v_lshl_add_u64 v[248:249], v[246:247], 0, s[88:89]
	s_mov_b32 m0, s5
	v_add_u32_e32 v161, 0x2000, v161
	ds_read_b128 v[230:233], v157
	ds_read_b128 v[234:237], v157 offset:1024
	ds_read_b128 v[238:241], v157 offset:2048
	ds_read_b128 v[242:245], v157 offset:3072
	global_load_lds_dwordx4 v[248:249], off
	v_lshl_add_u64 v[248:249], s[6:7], 0, v[138:139]
	v_readfirstlane_b32 s5, v161
	v_lshl_add_u64 v[250:251], v[248:249], 0, s[88:89]
	s_mov_b32 m0, s5
	s_nop 0
	global_load_lds_dwordx4 v[250:251], off
	s_barrier
	s_waitcnt lgkmcnt(0)
	s_setprio 1
	s_waitcnt lgkmcnt(0)
	v_mfma_f32_16x16x32_bf16 v[92:95], v[230:233], v[198:201], v[92:95]
	v_mfma_f32_16x16x32_bf16 v[88:91], v[238:241], v[198:201], v[88:91]
	v_mfma_f32_16x16x32_bf16 v[80:83], v[238:241], v[206:209], v[80:83]
	v_mfma_f32_16x16x32_bf16 v[84:87], v[230:233], v[206:209], v[84:87]
	v_mfma_f32_16x16x32_bf16 v[76:79], v[230:233], v[214:217], v[76:79]
	v_mfma_f32_16x16x32_bf16 v[72:75], v[238:241], v[214:217], v[72:75]
	v_mfma_f32_16x16x32_bf16 v[64:67], v[238:241], v[222:225], v[64:67]
	v_mfma_f32_16x16x32_bf16 v[68:71], v[230:233], v[222:225], v[68:71]
	v_mfma_f32_16x16x32_bf16 v[92:95], v[234:237], v[202:205], v[92:95]
	v_mfma_f32_16x16x32_bf16 v[88:91], v[242:245], v[202:205], v[88:91]
	v_mfma_f32_16x16x32_bf16 v[80:83], v[242:245], v[210:213], v[80:83]
	v_mfma_f32_16x16x32_bf16 v[84:87], v[234:237], v[210:213], v[84:87]
	v_mfma_f32_16x16x32_bf16 v[76:79], v[234:237], v[218:221], v[76:79]
	v_mfma_f32_16x16x32_bf16 v[72:75], v[242:245], v[218:221], v[72:75]
	v_mfma_f32_16x16x32_bf16 v[64:67], v[242:245], v[226:229], v[64:67]
	v_mfma_f32_16x16x32_bf16 v[68:71], v[234:237], v[226:229], v[68:71]
	s_setprio 0
	v_readfirstlane_b32 s5, v153
	v_add_u32_e32 v161, 0x2000, v153
	v_lshl_add_u64 v[250:251], v[178:179], 0, s[90:91]
	s_mov_b32 m0, s5
	v_readfirstlane_b32 s5, v161
	s_barrier
	ds_read_b128 v[198:201], v148 offset:16384
	ds_read_b128 v[202:205], v148 offset:17408
	ds_read_b128 v[206:209], v147 offset:16384
	ds_read_b128 v[210:213], v147 offset:17408
	ds_read_b128 v[214:217], v146 offset:16384
	ds_read_b128 v[218:221], v146 offset:17408
	ds_read_b128 v[222:225], v145 offset:16384
	ds_read_b128 v[226:229], v145 offset:17408
	global_load_lds_dwordx4 v[250:251], off
	v_lshl_add_u64 v[250:251], v[188:189], 0, s[90:91]
	s_mov_b32 m0, s5
	s_nop 0
	global_load_lds_dwordx4 v[250:251], off
	s_barrier
	s_waitcnt lgkmcnt(0)
	s_setprio 1
	s_waitcnt lgkmcnt(0)
	v_mfma_f32_16x16x32_bf16 v[60:63], v[162:165], v[198:201], v[60:63]
	v_mfma_f32_16x16x32_bf16 v[56:59], v[170:173], v[198:201], v[56:59]
	v_mfma_f32_16x16x32_bf16 v[48:51], v[170:173], v[206:209], v[48:51]
	v_mfma_f32_16x16x32_bf16 v[52:55], v[162:165], v[206:209], v[52:55]
	v_mfma_f32_16x16x32_bf16 v[44:47], v[162:165], v[214:217], v[44:47]
	v_mfma_f32_16x16x32_bf16 v[40:43], v[170:173], v[214:217], v[40:43]
	v_mfma_f32_16x16x32_bf16 v[32:35], v[170:173], v[222:225], v[32:35]
	v_mfma_f32_16x16x32_bf16 v[36:39], v[162:165], v[222:225], v[36:39]
	v_mfma_f32_16x16x32_bf16 v[60:63], v[166:169], v[202:205], v[60:63]
	v_mfma_f32_16x16x32_bf16 v[56:59], v[174:177], v[202:205], v[56:59]
	v_mfma_f32_16x16x32_bf16 v[48:51], v[174:177], v[210:213], v[48:51]
	v_mfma_f32_16x16x32_bf16 v[52:55], v[166:169], v[210:213], v[52:55]
	v_mfma_f32_16x16x32_bf16 v[44:47], v[166:169], v[218:221], v[44:47]
	v_mfma_f32_16x16x32_bf16 v[40:43], v[174:177], v[218:221], v[40:43]
	v_mfma_f32_16x16x32_bf16 v[32:35], v[174:177], v[226:229], v[32:35]
	v_mfma_f32_16x16x32_bf16 v[36:39], v[166:169], v[226:229], v[36:39]
	s_setprio 0
	s_barrier
; #define WAIT_V(n) asm volatile("s_waitcnt vmcnt(" #n ")" ::: "memory")
; #define WAIT_L(n) asm volatile("s_waitcnt lgkmcnt(" #n ")" ::: "memory")
; #define BAR __builtin_amdgcn_s_barrier()
; #define SCHED __builtin_amdgcn_sched_barrier(0)
; #define LDA(dst, b, h)                                                                            \
;   _Pragma("unroll") for (int m = 0; m < 4; ++m) _Pragma("unroll") for (int k = 0; k < 2; ++k)                                         \
;     dst[m][k] = *reinterpret_cast<const bf16x8*>((char*)SA(b, h) + lds_byte(wr * 64 + m * 16 + fr, k * 32 + fq * 8))
; #define LDB(dst, b, h)                                                                            \
;   _Pragma("unroll") for (int n = 0; n < 2; ++n) _Pragma("unroll") for (int k = 0; k < 2; ++k)                                         \
;     dst[n][k] = *reinterpret_cast<const bf16x8*>((char*)SB(b, h) + lds_byte(wc * 32 + n * 16 + fr, k * 32 + fq * 8))
; template <int K, bool SWAP>
; __device__ __forceinline__ void gemm_kloop(const bf16* __restrict__ A, const bf16* __restrict__ Bt,
;                                            f32x4 (&acc)[2][2][4][2], bool pref = false) {
;     ...
;     STAGE(SB(0, 1), Bt, HALF, t + 2);
;     WAIT_V(6); BAR; MMA(1, 1, At, B1); BAR;
;     LDB(B0, 1, 0); SCHED; LDA(At, 1, 0); STAGE(SA(0, 1), A, HALF, t + 2);
;     WAIT_L(8); BAR; WAIT_L(0); MMA(0, 0, At, B0); BAR; SCHED;
;     LDB(B1, 1, 1); STAGE(SB(1, 0), Bt, 0, t + 3);
;     BAR; WAIT_L(0); MMA(0, 1, At, B1); BAR;
;     LDA(At, 1, 1); STAGE(SA(1, 0), A, 0, t + 3);
	v_add_u32_e32 v161, s33, v150
	v_lshl_add_u64 v[162:163], v[246:247], 0, s[92:93]
	v_readfirstlane_b32 s5, v161
	v_add_u32_e32 v161, 0x2000, v161
	s_mov_b32 m0, s5
	v_readfirstlane_b32 s5, v161
	global_load_lds_dwordx4 v[162:163], off
	v_lshl_add_u64 v[162:163], v[248:249], 0, s[92:93]
	s_mov_b32 m0, s5
	s_nop 0
	global_load_lds_dwordx4 v[162:163], off
	s_waitcnt vmcnt(6)
	s_barrier
	s_setprio 1
	v_mfma_f32_16x16x32_bf16 v[28:31], v[230:233], v[198:201], v[28:31]
	v_mfma_f32_16x16x32_bf16 v[24:27], v[238:241], v[198:201], v[24:27]
	v_mfma_f32_16x16x32_bf16 v[16:19], v[238:241], v[206:209], v[16:19]
	v_mfma_f32_16x16x32_bf16 v[20:23], v[230:233], v[206:209], v[20:23]
	v_mfma_f32_16x16x32_bf16 v[12:15], v[230:233], v[214:217], v[12:15]
	v_mfma_f32_16x16x32_bf16 v[8:11], v[238:241], v[214:217], v[8:11]
	v_mfma_f32_16x16x32_bf16 v[0:3], v[238:241], v[222:225], v[0:3]
	v_mfma_f32_16x16x32_bf16 v[4:7], v[230:233], v[222:225], v[4:7]
	v_mfma_f32_16x16x32_bf16 v[28:31], v[234:237], v[202:205], v[28:31]
	v_mfma_f32_16x16x32_bf16 v[24:27], v[242:245], v[202:205], v[24:27]
	v_mfma_f32_16x16x32_bf16 v[16:19], v[242:245], v[210:213], v[16:19]
	v_mfma_f32_16x16x32_bf16 v[20:23], v[234:237], v[210:213], v[20:23]
	v_mfma_f32_16x16x32_bf16 v[12:15], v[234:237], v[218:221], v[12:15]
	v_mfma_f32_16x16x32_bf16 v[8:11], v[242:245], v[218:221], v[8:11]
	v_mfma_f32_16x16x32_bf16 v[0:3], v[242:245], v[226:229], v[0:3]
	v_mfma_f32_16x16x32_bf16 v[4:7], v[234:237], v[226:229], v[4:7]
	s_setprio 0
	s_barrier
	ds_read_b128 v[162:165], v151
	ds_read_b128 v[166:169], v151 offset:1024
	ds_read_b128 v[170:173], v151 offset:2048
	ds_read_b128 v[174:177], v151 offset:3072
	v_add_u32_e32 v161, 0x4000, v153
	v_lshl_add_u64 v[230:231], v[178:179], 0, s[94:95]
	v_readfirstlane_b32 s5, v161
	v_add_u32_e32 v161, 0x6000, v153
	s_mov_b32 m0, s5
	v_readfirstlane_b32 s5, v161
	ds_read_b128 v[198:201], v148 offset:32768
	ds_read_b128 v[202:205], v148 offset:33792
	ds_read_b128 v[206:209], v147 offset:32768
	ds_read_b128 v[210:213], v147 offset:33792
	ds_read_b128 v[214:217], v146 offset:32768
	ds_read_b128 v[218:221], v146 offset:33792
	ds_read_b128 v[222:225], v145 offset:32768
	ds_read_b128 v[226:229], v145 offset:33792
	global_load_lds_dwordx4 v[230:231], off
	v_lshl_add_u64 v[230:231], v[188:189], 0, s[94:95]
	s_mov_b32 m0, s5
	s_nop 0
	global_load_lds_dwordx4 v[230:231], off
	s_waitcnt lgkmcnt(8)
	s_barrier
	s_waitcnt lgkmcnt(0)
	s_setprio 1
	s_waitcnt lgkmcnt(0)
	v_mfma_f32_16x16x32_bf16 v[124:127], v[162:165], v[198:201], v[124:127]
	v_mfma_f32_16x16x32_bf16 v[120:123], v[170:173], v[198:201], v[120:123]
	v_mfma_f32_16x16x32_bf16 v[112:115], v[170:173], v[206:209], v[112:115]
	v_mfma_f32_16x16x32_bf16 v[116:119], v[162:165], v[206:209], v[116:119]
	v_mfma_f32_16x16x32_bf16 v[108:111], v[162:165], v[214:217], v[108:111]
	v_mfma_f32_16x16x32_bf16 v[104:107], v[170:173], v[214:217], v[104:107]
	v_mfma_f32_16x16x32_bf16 v[96:99], v[170:173], v[222:225], v[96:99]
	v_mfma_f32_16x16x32_bf16 v[100:103], v[162:165], v[222:225], v[100:103]
	v_mfma_f32_16x16x32_bf16 v[124:127], v[166:169], v[202:205], v[124:127]
	v_mfma_f32_16x16x32_bf16 v[120:123], v[174:177], v[202:205], v[120:123]
	v_mfma_f32_16x16x32_bf16 v[112:115], v[174:177], v[210:213], v[112:115]
	v_mfma_f32_16x16x32_bf16 v[116:119], v[166:169], v[210:213], v[116:119]
	v_mfma_f32_16x16x32_bf16 v[108:111], v[166:169], v[218:221], v[108:111]
	v_mfma_f32_16x16x32_bf16 v[104:107], v[174:177], v[218:221], v[104:107]
	v_mfma_f32_16x16x32_bf16 v[96:99], v[174:177], v[226:229], v[96:99]
	v_mfma_f32_16x16x32_bf16 v[100:103], v[166:169], v[226:229], v[100:103]
	s_setprio 0
	s_barrier
	v_readfirstlane_b32 s5, v152
	v_add_u32_e32 v161, 0x2000, v152
	v_lshl_add_u64 v[250:251], v[246:247], 0, s[96:97]
	s_mov_b32 m0, s5
	v_readfirstlane_b32 s5, v161
	ds_read_b128 v[230:233], v149
	ds_read_b128 v[234:237], v149 offset:1024
	ds_read_b128 v[238:241], v149 offset:2048
	ds_read_b128 v[242:245], v149 offset:3072
	global_load_lds_dwordx4 v[250:251], off
	v_lshl_add_u64 v[250:251], v[248:249], 0, s[96:97]
	s_mov_b32 m0, s5
	s_nop 0
	global_load_lds_dwordx4 v[250:251], off
	s_barrier
	s_waitcnt lgkmcnt(0)
	s_setprio 1
	s_waitcnt lgkmcnt(0)
	v_mfma_f32_16x16x32_bf16 v[92:95], v[230:233], v[198:201], v[92:95]
	v_mfma_f32_16x16x32_bf16 v[88:91], v[238:241], v[198:201], v[88:91]
	v_mfma_f32_16x16x32_bf16 v[80:83], v[238:241], v[206:209], v[80:83]
	v_mfma_f32_16x16x32_bf16 v[84:87], v[230:233], v[206:209], v[84:87]
	v_mfma_f32_16x16x32_bf16 v[76:79], v[230:233], v[214:217], v[76:79]
	v_mfma_f32_16x16x32_bf16 v[72:75], v[238:241], v[214:217], v[72:75]
	v_mfma_f32_16x16x32_bf16 v[64:67], v[238:241], v[222:225], v[64:67]
	v_mfma_f32_16x16x32_bf16 v[68:71], v[230:233], v[222:225], v[68:71]
	v_mfma_f32_16x16x32_bf16 v[92:95], v[234:237], v[202:205], v[92:95]
	v_mfma_f32_16x16x32_bf16 v[88:91], v[242:245], v[202:205], v[88:91]
	v_mfma_f32_16x16x32_bf16 v[80:83], v[242:245], v[210:213], v[80:83]
	v_mfma_f32_16x16x32_bf16 v[84:87], v[234:237], v[210:213], v[84:87]
	v_mfma_f32_16x16x32_bf16 v[76:79], v[234:237], v[218:221], v[76:79]
	v_mfma_f32_16x16x32_bf16 v[72:75], v[242:245], v[218:221], v[72:75]
	v_mfma_f32_16x16x32_bf16 v[64:67], v[242:245], v[226:229], v[64:67]
	v_mfma_f32_16x16x32_bf16 v[68:71], v[234:237], v[226:229], v[68:71]
	s_setprio 0
	v_readfirstlane_b32 s5, v154
	v_lshl_add_u64 v[178:179], v[178:179], 0, s[34:35]
	s_mov_b32 m0, s5
	v_readfirstlane_b32 s5, v155
	s_barrier
; #define WAIT_V(n) asm volatile("s_waitcnt vmcnt(" #n ")" ::: "memory")
; #define WAIT_L(n) asm volatile("s_waitcnt lgkmcnt(" #n ")" ::: "memory")
; #define BAR __builtin_amdgcn_s_barrier()
; #define SCHED __builtin_amdgcn_sched_barrier(0)
; #define LDA(dst, b, h)                                                                            \
;   _Pragma("unroll") for (int m = 0; m < 4; ++m) _Pragma("unroll") for (int k = 0; k < 2; ++k)                                         \
;     dst[m][k] = *reinterpret_cast<const bf16x8*>((char*)SA(b, h) + lds_byte(wr * 64 + m * 16 + fr, k * 32 + fq * 8))
; #define LDB(dst, b, h)                                                                            \
;   _Pragma("unroll") for (int n = 0; n < 2; ++n) _Pragma("unroll") for (int k = 0; k < 2; ++k)                                         \
;     dst[n][k] = *reinterpret_cast<const bf16x8*>((char*)SB(b, h) + lds_byte(wc * 32 + n * 16 + fr, k * 32 + fq * 8))
; template <int K, bool SWAP>
; __device__ __forceinline__ void gemm_kloop(const bf16* __restrict__ A, const bf16* __restrict__ Bt,
;                                            f32x4 (&acc)[2][2][4][2], bool pref = false) {
;     ...
;     LDA(At, 1, 1); STAGE(SA(1, 0), A, 0, t + 3);
;     BAR; WAIT_L(0); MMA(1, 0, At, B0); BAR; SCHED;
;     STAGE(SB(1, 1), Bt, HALF, t + 3);
;     WAIT_V(6); BAR; MMA(1, 1, At, B1); BAR;
;   }
;   { LDB(B0, 0, 0); LDA(At, 0, 0); STAGE(SA(1, 1), A, HALF, nt - 1);
;     BAR; WAIT_L(0); MMA(0, 0, At, B0); BAR;
	ds_read_b128 v[198:201], v148 offset:49152
	ds_read_b128 v[202:205], v148 offset:50176
	ds_read_b128 v[206:209], v147 offset:49152
	ds_read_b128 v[210:213], v147 offset:50176
	ds_read_b128 v[214:217], v146 offset:49152
	ds_read_b128 v[218:221], v146 offset:50176
	ds_read_b128 v[222:225], v145 offset:49152
	ds_read_b128 v[226:229], v145 offset:50176
	global_load_lds_dwordx4 v[178:179], off
	v_lshl_add_u64 v[178:179], v[188:189], 0, s[34:35]
	s_mov_b32 m0, s5
	s_nop 0
	global_load_lds_dwordx4 v[178:179], off
	s_barrier
	s_waitcnt lgkmcnt(0)
	s_setprio 1
	s_waitcnt lgkmcnt(0)
	v_mfma_f32_16x16x32_bf16 v[60:63], v[162:165], v[198:201], v[60:63]
	v_mfma_f32_16x16x32_bf16 v[56:59], v[170:173], v[198:201], v[56:59]
	v_mfma_f32_16x16x32_bf16 v[48:51], v[170:173], v[206:209], v[48:51]
	v_mfma_f32_16x16x32_bf16 v[52:55], v[162:165], v[206:209], v[52:55]
	v_mfma_f32_16x16x32_bf16 v[44:47], v[162:165], v[214:217], v[44:47]
	v_mfma_f32_16x16x32_bf16 v[40:43], v[170:173], v[214:217], v[40:43]
	v_mfma_f32_16x16x32_bf16 v[32:35], v[170:173], v[222:225], v[32:35]
	v_mfma_f32_16x16x32_bf16 v[36:39], v[162:165], v[222:225], v[36:39]
	v_mfma_f32_16x16x32_bf16 v[60:63], v[166:169], v[202:205], v[60:63]
	v_mfma_f32_16x16x32_bf16 v[56:59], v[174:177], v[202:205], v[56:59]
	v_mfma_f32_16x16x32_bf16 v[48:51], v[174:177], v[210:213], v[48:51]
	v_mfma_f32_16x16x32_bf16 v[52:55], v[166:169], v[210:213], v[52:55]
	v_mfma_f32_16x16x32_bf16 v[44:47], v[166:169], v[218:221], v[44:47]
	v_mfma_f32_16x16x32_bf16 v[40:43], v[174:177], v[218:221], v[40:43]
	v_mfma_f32_16x16x32_bf16 v[32:35], v[174:177], v[226:229], v[32:35]
	v_mfma_f32_16x16x32_bf16 v[36:39], v[166:169], v[226:229], v[36:39]
	s_setprio 0
	s_barrier
	v_readfirstlane_b32 s5, v156
	v_add_u32_e32 v161, 0x2000, v156
	v_lshl_add_u64 v[162:163], v[246:247], 0, s[36:37]
	s_mov_b32 m0, s5
	v_readfirstlane_b32 s5, v161
	global_load_lds_dwordx4 v[162:163], off
	v_lshl_add_u64 v[162:163], v[248:249], 0, s[36:37]
	s_mov_b32 m0, s5
	s_nop 0
	global_load_lds_dwordx4 v[162:163], off
	s_waitcnt vmcnt(6)
	s_barrier
	s_setprio 1
	v_mfma_f32_16x16x32_bf16 v[28:31], v[230:233], v[198:201], v[28:31]
	v_mfma_f32_16x16x32_bf16 v[24:27], v[238:241], v[198:201], v[24:27]
	v_mfma_f32_16x16x32_bf16 v[16:19], v[238:241], v[206:209], v[16:19]
	v_mfma_f32_16x16x32_bf16 v[20:23], v[230:233], v[206:209], v[20:23]
	v_mfma_f32_16x16x32_bf16 v[12:15], v[230:233], v[214:217], v[12:15]
	v_mfma_f32_16x16x32_bf16 v[8:11], v[238:241], v[214:217], v[8:11]
	v_mfma_f32_16x16x32_bf16 v[0:3], v[238:241], v[222:225], v[0:3]
	v_mfma_f32_16x16x32_bf16 v[4:7], v[230:233], v[222:225], v[4:7]
	v_mfma_f32_16x16x32_bf16 v[28:31], v[234:237], v[202:205], v[28:31]
	v_mfma_f32_16x16x32_bf16 v[24:27], v[242:245], v[202:205], v[24:27]
	v_mfma_f32_16x16x32_bf16 v[16:19], v[242:245], v[210:213], v[16:19]
	v_mfma_f32_16x16x32_bf16 v[20:23], v[234:237], v[210:213], v[20:23]
	v_mfma_f32_16x16x32_bf16 v[12:15], v[234:237], v[218:221], v[12:15]
	v_mfma_f32_16x16x32_bf16 v[8:11], v[242:245], v[218:221], v[8:11]
	v_mfma_f32_16x16x32_bf16 v[0:3], v[242:245], v[226:229], v[0:3]
	v_mfma_f32_16x16x32_bf16 v[4:7], v[234:237], v[226:229], v[4:7]
	s_setprio 0
	s_add_i32 s1, s1, 2
	v_lshl_add_u64 v[136:137], v[136:137], 0, s[44:45]
	v_lshl_add_u64 v[138:139], v[138:139], 0, s[44:45]
	v_lshl_add_u64 v[140:141], v[140:141], 0, s[44:45]
	s_cmp_lt_u32 s1, 12
	v_lshl_add_u64 v[142:143], v[142:143], 0, s[44:45]
	s_barrier
	s_cbranch_scc1 .LBB0_797
	s_add_u32 s14, s14, 0x40780
	s_addc_u32 s15, s15, 0
	v_lshl_add_u64 v[130:131], s[14:15], 0, v[130:131]
	v_readfirstlane_b32 s1, v159
	v_lshl_add_u64 v[128:129], v[128:129], 1, v[130:131]
	s_mov_b32 m0, s1
	ds_read_b128 v[136:139], v158
	ds_read_b128 v[140:143], v158 offset:1024
	ds_read_b128 v[152:155], v158 offset:2048
	ds_read_b128 v[162:165], v158 offset:3072
	ds_read_b128 v[166:169], v148
	ds_read_b128 v[170:173], v148 offset:1024
	ds_read_b128 v[174:177], v147
	ds_read_b128 v[198:201], v147 offset:1024
	ds_read_b128 v[202:205], v146
	ds_read_b128 v[206:209], v146 offset:1024
	ds_read_b128 v[210:213], v145
	ds_read_b128 v[214:217], v145 offset:1024
	global_load_lds_dwordx4 v[128:129], off
	v_lshl_add_u64 v[128:129], s[14:15], 0, v[134:135]
	v_readfirstlane_b32 s1, v160
	v_lshl_add_u64 v[128:129], v[132:133], 1, v[128:129]
	s_mov_b32 m0, s1
	s_nop 0
	global_load_lds_dwordx4 v[128:129], off
	s_barrier
	s_waitcnt lgkmcnt(0)
	s_setprio 1
	s_waitcnt lgkmcnt(0)
	v_mfma_f32_16x16x32_bf16 v[116:119], v[136:139], v[174:177], v[116:119]
	v_mfma_f32_16x16x32_bf16 v[112:115], v[152:155], v[174:177], v[112:115]
	v_mfma_f32_16x16x32_bf16 v[104:107], v[152:155], v[202:205], v[104:107]
	v_mfma_f32_16x16x32_bf16 v[108:111], v[136:139], v[202:205], v[108:111]
	v_mfma_f32_16x16x32_bf16 v[100:103], v[136:139], v[210:213], v[100:103]
	v_mfma_f32_16x16x32_bf16 v[96:99], v[152:155], v[210:213], v[96:99]
	v_mfma_f32_16x16x32_bf16 v[120:123], v[152:155], v[166:169], v[120:123]
	v_mfma_f32_16x16x32_bf16 v[124:127], v[136:139], v[166:169], v[124:127]
	v_mfma_f32_16x16x32_bf16 v[116:119], v[140:143], v[198:201], v[116:119]
	v_mfma_f32_16x16x32_bf16 v[112:115], v[162:165], v[198:201], v[112:115]
	v_mfma_f32_16x16x32_bf16 v[104:107], v[162:165], v[206:209], v[104:107]
	v_mfma_f32_16x16x32_bf16 v[108:111], v[140:143], v[206:209], v[108:111]
	v_mfma_f32_16x16x32_bf16 v[100:103], v[140:143], v[214:217], v[100:103]
	v_mfma_f32_16x16x32_bf16 v[96:99], v[162:165], v[214:217], v[96:99]
	v_mfma_f32_16x16x32_bf16 v[120:123], v[162:165], v[170:173], v[120:123]
	v_mfma_f32_16x16x32_bf16 v[124:127], v[140:143], v[170:173], v[124:127]
	s_setprio 0
	s_barrier
; #define WAIT_V(n) asm volatile("s_waitcnt vmcnt(" #n ")" ::: "memory")
; #define WAIT_L(n) asm volatile("s_waitcnt lgkmcnt(" #n ")" ::: "memory")
; #define BAR __builtin_amdgcn_s_barrier()
; #define LDA(dst, b, h)                                                                            \
;   _Pragma("unroll") for (int m = 0; m < 4; ++m) _Pragma("unroll") for (int k = 0; k < 2; ++k)                                         \
;     dst[m][k] = *reinterpret_cast<const bf16x8*>((char*)SA(b, h) + lds_byte(wr * 64 + m * 16 + fr, k * 32 + fq * 8))
; #define LDB(dst, b, h)                                                                            \
;   _Pragma("unroll") for (int n = 0; n < 2; ++n) _Pragma("unroll") for (int k = 0; k < 2; ++k)                                         \
;     dst[n][k] = *reinterpret_cast<const bf16x8*>((char*)SB(b, h) + lds_byte(wc * 32 + n * 16 + fr, k * 32 + fq * 8))
; template <int K, bool SWAP>
; __device__ __forceinline__ void gemm_kloop(const bf16* __restrict__ A, const bf16* __restrict__ Bt,
;                                            f32x4 (&acc)[2][2][4][2], bool pref = false) {
;     ...
;     BAR; WAIT_L(0); MMA(0, 0, At, B0); BAR;
;     LDB(B1, 0, 1); BAR; WAIT_L(0); MMA(0, 1, At, B1); BAR;
;     LDA(At, 0, 1); WAIT_V(4); BAR; WAIT_L(0); MMA(1, 0, At, B0); MMA(1, 1, At, B1); BAR; }
;   { LDB(B0, 1, 0); LDA(At, 1, 0); WAIT_V(2); BAR; WAIT_L(0); MMA(0, 0, At, B0); BAR;
	ds_read_b128 v[128:131], v157
	ds_read_b128 v[132:135], v157 offset:1024
	ds_read_b128 v[158:161], v157 offset:2048
	ds_read_b128 v[218:221], v157 offset:3072
	s_barrier
	s_waitcnt lgkmcnt(0)
	s_setprio 1
	s_waitcnt lgkmcnt(0)
	v_mfma_f32_16x16x32_bf16 v[92:95], v[128:131], v[166:169], v[92:95]
	v_mfma_f32_16x16x32_bf16 v[88:91], v[158:161], v[166:169], v[88:91]
	v_mfma_f32_16x16x32_bf16 v[80:83], v[158:161], v[174:177], v[80:83]
	v_mfma_f32_16x16x32_bf16 v[84:87], v[128:131], v[174:177], v[84:87]
	v_mfma_f32_16x16x32_bf16 v[76:79], v[128:131], v[202:205], v[76:79]
	v_mfma_f32_16x16x32_bf16 v[72:75], v[158:161], v[202:205], v[72:75]
	v_mfma_f32_16x16x32_bf16 v[64:67], v[158:161], v[210:213], v[64:67]
	v_mfma_f32_16x16x32_bf16 v[68:71], v[128:131], v[210:213], v[68:71]
	v_mfma_f32_16x16x32_bf16 v[92:95], v[132:135], v[170:173], v[92:95]
	v_mfma_f32_16x16x32_bf16 v[88:91], v[218:221], v[170:173], v[88:91]
	v_mfma_f32_16x16x32_bf16 v[80:83], v[218:221], v[198:201], v[80:83]
	v_mfma_f32_16x16x32_bf16 v[84:87], v[132:135], v[198:201], v[84:87]
	v_mfma_f32_16x16x32_bf16 v[76:79], v[132:135], v[206:209], v[76:79]
	v_mfma_f32_16x16x32_bf16 v[72:75], v[218:221], v[206:209], v[72:75]
	v_mfma_f32_16x16x32_bf16 v[64:67], v[218:221], v[214:217], v[64:67]
	v_mfma_f32_16x16x32_bf16 v[68:71], v[132:135], v[214:217], v[68:71]
	s_setprio 0
	s_barrier
	ds_read_b128 v[166:169], v148 offset:16384
	ds_read_b128 v[170:173], v148 offset:17408
	ds_read_b128 v[174:177], v147 offset:16384
	ds_read_b128 v[198:201], v147 offset:17408
	ds_read_b128 v[202:205], v146 offset:16384
	ds_read_b128 v[206:209], v146 offset:17408
	ds_read_b128 v[210:213], v145 offset:16384
	ds_read_b128 v[214:217], v145 offset:17408
	s_waitcnt vmcnt(4)
	s_barrier
	s_waitcnt lgkmcnt(0)
	s_setprio 1
	s_waitcnt lgkmcnt(0)
	v_mfma_f32_16x16x32_bf16 v[60:63], v[136:139], v[166:169], v[60:63]
	v_mfma_f32_16x16x32_bf16 v[56:59], v[152:155], v[166:169], v[56:59]
	v_mfma_f32_16x16x32_bf16 v[48:51], v[152:155], v[174:177], v[48:51]
	v_mfma_f32_16x16x32_bf16 v[52:55], v[136:139], v[174:177], v[52:55]
	v_mfma_f32_16x16x32_bf16 v[44:47], v[136:139], v[202:205], v[44:47]
	v_mfma_f32_16x16x32_bf16 v[40:43], v[152:155], v[202:205], v[40:43]
	v_mfma_f32_16x16x32_bf16 v[32:35], v[152:155], v[210:213], v[32:35]
	v_mfma_f32_16x16x32_bf16 v[36:39], v[136:139], v[210:213], v[36:39]
	v_mfma_f32_16x16x32_bf16 v[60:63], v[140:143], v[170:173], v[60:63]
	v_mfma_f32_16x16x32_bf16 v[56:59], v[162:165], v[170:173], v[56:59]
	v_mfma_f32_16x16x32_bf16 v[48:51], v[162:165], v[198:201], v[48:51]
	v_mfma_f32_16x16x32_bf16 v[52:55], v[140:143], v[198:201], v[52:55]
	v_mfma_f32_16x16x32_bf16 v[44:47], v[140:143], v[206:209], v[44:47]
	v_mfma_f32_16x16x32_bf16 v[40:43], v[162:165], v[206:209], v[40:43]
	v_mfma_f32_16x16x32_bf16 v[32:35], v[162:165], v[214:217], v[32:35]
	v_mfma_f32_16x16x32_bf16 v[36:39], v[140:143], v[214:217], v[36:39]
	s_setprio 0
	s_setprio 1
	v_mfma_f32_16x16x32_bf16 v[28:31], v[128:131], v[166:169], v[28:31]
	v_mfma_f32_16x16x32_bf16 v[24:27], v[158:161], v[166:169], v[24:27]
	v_mfma_f32_16x16x32_bf16 v[16:19], v[158:161], v[174:177], v[16:19]
	v_mfma_f32_16x16x32_bf16 v[20:23], v[128:131], v[174:177], v[20:23]
	v_mfma_f32_16x16x32_bf16 v[12:15], v[128:131], v[202:205], v[12:15]
	v_mfma_f32_16x16x32_bf16 v[8:11], v[158:161], v[202:205], v[8:11]
	v_mfma_f32_16x16x32_bf16 v[0:3], v[158:161], v[210:213], v[0:3]
	v_mfma_f32_16x16x32_bf16 v[4:7], v[128:131], v[210:213], v[4:7]
	v_mfma_f32_16x16x32_bf16 v[28:31], v[132:135], v[170:173], v[28:31]
	v_mfma_f32_16x16x32_bf16 v[24:27], v[218:221], v[170:173], v[24:27]
	v_mfma_f32_16x16x32_bf16 v[16:19], v[218:221], v[198:201], v[16:19]
	v_mfma_f32_16x16x32_bf16 v[20:23], v[132:135], v[198:201], v[20:23]
	v_mfma_f32_16x16x32_bf16 v[12:15], v[132:135], v[206:209], v[12:15]
	v_mfma_f32_16x16x32_bf16 v[8:11], v[218:221], v[206:209], v[8:11]
	v_mfma_f32_16x16x32_bf16 v[0:3], v[218:221], v[214:217], v[0:3]
	v_mfma_f32_16x16x32_bf16 v[4:7], v[132:135], v[214:217], v[4:7]
	s_setprio 0
	s_barrier
	ds_read_b128 v[136:139], v151
	ds_read_b128 v[140:143], v151 offset:1024
	ds_read_b128 v[152:155], v151 offset:2048
	ds_read_b128 v[156:159], v151 offset:3072
	ds_read_b128 v[160:163], v148 offset:32768
	ds_read_b128 v[164:167], v148 offset:33792
	ds_read_b128 v[168:171], v147 offset:32768
	ds_read_b128 v[172:175], v147 offset:33792
	ds_read_b128 v[176:179], v146 offset:32768
	ds_read_b128 v[198:201], v146 offset:33792
	ds_read_b128 v[202:205], v145 offset:32768
	ds_read_b128 v[206:209], v145 offset:33792
	s_waitcnt vmcnt(2)
	s_barrier
; #define WAIT_V(n) asm volatile("s_waitcnt vmcnt(" #n ")" ::: "memory")
; #define WAIT_L(n) asm volatile("s_waitcnt lgkmcnt(" #n ")" ::: "memory")
; #define BAR __builtin_amdgcn_s_barrier()
; #define LDA(dst, b, h)                                                                            \
;   _Pragma("unroll") for (int m = 0; m < 4; ++m) _Pragma("unroll") for (int k = 0; k < 2; ++k)                                         \
;     dst[m][k] = *reinterpret_cast<const bf16x8*>((char*)SA(b, h) + lds_byte(wr * 64 + m * 16 + fr, k * 32 + fq * 8))
; #define LDB(dst, b, h)                                                                            \
;   _Pragma("unroll") for (int n = 0; n < 2; ++n) _Pragma("unroll") for (int k = 0; k < 2; ++k)                                         \
;     dst[n][k] = *reinterpret_cast<const bf16x8*>((char*)SB(b, h) + lds_byte(wc * 32 + n * 16 + fr, k * 32 + fq * 8))
; template <int K, bool SWAP>
; __device__ __forceinline__ void gemm_kloop(const bf16* __restrict__ A, const bf16* __restrict__ Bt,
;                                            f32x4 (&acc)[2][2][4][2], bool pref = false) {
;     ...
;   { LDB(B0, 1, 0); LDA(At, 1, 0); WAIT_V(2); BAR; WAIT_L(0); MMA(0, 0, At, B0); BAR;
;     LDB(B1, 1, 1); WAIT_V(0); BAR; WAIT_L(0); MMA(0, 1, At, B1); BAR;
;     LDA(At, 1, 1); BAR; WAIT_L(0); MMA(1, 0, At, B0); MMA(1, 1, At, B1); BAR; }
;   if (wr == 0) BAR;
	s_waitcnt lgkmcnt(0)
	s_setprio 1
	s_waitcnt lgkmcnt(0)
	v_mfma_f32_16x16x32_bf16 v[124:127], v[136:139], v[160:163], v[124:127]
	v_mfma_f32_16x16x32_bf16 v[120:123], v[152:155], v[160:163], v[120:123]
	v_mfma_f32_16x16x32_bf16 v[116:119], v[136:139], v[168:171], v[116:119]
	v_mfma_f32_16x16x32_bf16 v[112:115], v[152:155], v[168:171], v[112:115]
	v_mfma_f32_16x16x32_bf16 v[108:111], v[136:139], v[176:179], v[108:111]
	v_mfma_f32_16x16x32_bf16 v[104:107], v[152:155], v[176:179], v[104:107]
	v_mfma_f32_16x16x32_bf16 v[100:103], v[136:139], v[202:205], v[100:103]
	v_mfma_f32_16x16x32_bf16 v[96:99], v[152:155], v[202:205], v[96:99]
	v_mfma_f32_16x16x32_bf16 v[132:135], v[140:143], v[164:167], v[124:127]
	v_mfma_f32_16x16x32_bf16 v[128:131], v[156:159], v[164:167], v[120:123]
	v_mfma_f32_16x16x32_bf16 v[116:119], v[140:143], v[172:175], v[116:119]
	v_mfma_f32_16x16x32_bf16 v[112:115], v[156:159], v[172:175], v[112:115]
	v_mfma_f32_16x16x32_bf16 v[108:111], v[140:143], v[198:201], v[108:111]
	v_mfma_f32_16x16x32_bf16 v[104:107], v[156:159], v[198:201], v[104:107]
	v_mfma_f32_16x16x32_bf16 v[100:103], v[140:143], v[206:209], v[100:103]
	v_mfma_f32_16x16x32_bf16 v[96:99], v[156:159], v[206:209], v[96:99]
	s_setprio 0
	s_barrier
	ds_read_b128 v[120:123], v149
	ds_read_b128 v[124:127], v149 offset:1024
	ds_read_b128 v[210:213], v149 offset:2048
	ds_read_b128 v[214:217], v149 offset:3072
	s_waitcnt vmcnt(0)
	s_barrier
	s_waitcnt lgkmcnt(0)
	s_setprio 1
	s_waitcnt lgkmcnt(0)
	v_mfma_f32_16x16x32_bf16 v[92:95], v[120:123], v[160:163], v[92:95]
	v_mfma_f32_16x16x32_bf16 v[88:91], v[210:213], v[160:163], v[88:91]
	v_mfma_f32_16x16x32_bf16 v[80:83], v[210:213], v[168:171], v[80:83]
	v_mfma_f32_16x16x32_bf16 v[84:87], v[120:123], v[168:171], v[84:87]
	v_mfma_f32_16x16x32_bf16 v[76:79], v[120:123], v[176:179], v[76:79]
	v_mfma_f32_16x16x32_bf16 v[72:75], v[210:213], v[176:179], v[72:75]
	v_mfma_f32_16x16x32_bf16 v[64:67], v[210:213], v[202:205], v[64:67]
	v_mfma_f32_16x16x32_bf16 v[68:71], v[120:123], v[202:205], v[68:71]
	v_mfma_f32_16x16x32_bf16 v[92:95], v[124:127], v[164:167], v[92:95]
	v_mfma_f32_16x16x32_bf16 v[88:91], v[214:217], v[164:167], v[88:91]
	v_mfma_f32_16x16x32_bf16 v[80:83], v[214:217], v[172:175], v[80:83]
	v_mfma_f32_16x16x32_bf16 v[84:87], v[124:127], v[172:175], v[84:87]
	v_mfma_f32_16x16x32_bf16 v[76:79], v[124:127], v[198:201], v[76:79]
	v_mfma_f32_16x16x32_bf16 v[72:75], v[214:217], v[198:201], v[72:75]
	v_mfma_f32_16x16x32_bf16 v[64:67], v[214:217], v[206:209], v[64:67]
	v_mfma_f32_16x16x32_bf16 v[68:71], v[124:127], v[206:209], v[68:71]
	s_setprio 0
	s_barrier
	ds_read_b128 v[160:163], v148 offset:49152
	ds_read_b128 v[148:151], v148 offset:50176
	ds_read_b128 v[164:167], v147 offset:49152
	ds_read_b128 v[168:171], v147 offset:50176
	ds_read_b128 v[172:175], v146 offset:49152
	ds_read_b128 v[176:179], v146 offset:50176
	ds_read_b128 v[198:201], v145 offset:49152
	ds_read_b128 v[202:205], v145 offset:50176
	s_barrier
	s_waitcnt lgkmcnt(0)
	s_setprio 1
	s_waitcnt lgkmcnt(0)
	v_mfma_f32_16x16x32_bf16 v[60:63], v[136:139], v[160:163], v[60:63]
	v_mfma_f32_16x16x32_bf16 v[56:59], v[152:155], v[160:163], v[56:59]
	v_mfma_f32_16x16x32_bf16 v[48:51], v[152:155], v[164:167], v[48:51]
	v_mfma_f32_16x16x32_bf16 v[52:55], v[136:139], v[164:167], v[52:55]
	v_mfma_f32_16x16x32_bf16 v[44:47], v[136:139], v[172:175], v[44:47]
	v_mfma_f32_16x16x32_bf16 v[40:43], v[152:155], v[172:175], v[40:43]
	v_mfma_f32_16x16x32_bf16 v[32:35], v[152:155], v[198:201], v[32:35]
	v_mfma_f32_16x16x32_bf16 v[36:39], v[136:139], v[198:201], v[36:39]
	v_mfma_f32_16x16x32_bf16 v[60:63], v[140:143], v[148:151], v[60:63]
	v_mfma_f32_16x16x32_bf16 v[56:59], v[156:159], v[148:151], v[56:59]
	v_mfma_f32_16x16x32_bf16 v[48:51], v[156:159], v[168:171], v[48:51]
	v_mfma_f32_16x16x32_bf16 v[52:55], v[140:143], v[168:171], v[52:55]
	v_mfma_f32_16x16x32_bf16 v[44:47], v[140:143], v[176:179], v[44:47]
	v_mfma_f32_16x16x32_bf16 v[40:43], v[156:159], v[176:179], v[40:43]
	v_mfma_f32_16x16x32_bf16 v[32:35], v[156:159], v[202:205], v[32:35]
	v_mfma_f32_16x16x32_bf16 v[36:39], v[140:143], v[202:205], v[36:39]
	s_setprio 0
	s_setprio 1
	v_mfma_f32_16x16x32_bf16 v[28:31], v[120:123], v[160:163], v[28:31]
	v_mfma_f32_16x16x32_bf16 v[24:27], v[210:213], v[160:163], v[24:27]
	v_mfma_f32_16x16x32_bf16 v[16:19], v[210:213], v[164:167], v[16:19]
	v_mfma_f32_16x16x32_bf16 v[20:23], v[120:123], v[164:167], v[20:23]
	v_mfma_f32_16x16x32_bf16 v[12:15], v[120:123], v[172:175], v[12:15]
	v_mfma_f32_16x16x32_bf16 v[8:11], v[210:213], v[172:175], v[8:11]
	v_mfma_f32_16x16x32_bf16 v[0:3], v[210:213], v[198:201], v[0:3]
	v_mfma_f32_16x16x32_bf16 v[4:7], v[120:123], v[198:201], v[4:7]
	v_mfma_f32_16x16x32_bf16 v[28:31], v[124:127], v[148:151], v[28:31]
	v_mfma_f32_16x16x32_bf16 v[24:27], v[214:217], v[148:151], v[24:27]
	v_mfma_f32_16x16x32_bf16 v[16:19], v[214:217], v[168:171], v[16:19]
	v_mfma_f32_16x16x32_bf16 v[20:23], v[124:127], v[168:171], v[20:23]
	v_mfma_f32_16x16x32_bf16 v[12:15], v[124:127], v[176:179], v[12:15]
	v_mfma_f32_16x16x32_bf16 v[8:11], v[214:217], v[176:179], v[8:11]
	v_mfma_f32_16x16x32_bf16 v[0:3], v[214:217], v[202:205], v[0:3]
	v_mfma_f32_16x16x32_bf16 v[4:7], v[124:127], v[202:205], v[4:7]
	s_setprio 0
	s_movk_i32 s1, 0x100
	v_cmp_gt_u32_e32 vcc, s1, v144
	s_barrier
	s_and_saveexec_b64 s[14:15], vcc
	s_mov_b32 s62, s68
	s_mov_b32 s63, s69
	s_cbranch_execz .LBB0_800
	s_barrier

; #define WAIT_V(n) asm volatile("s_waitcnt vmcnt(" #n ")" ::: "memory")
; #define WAIT_L(n) asm volatile("s_waitcnt lgkmcnt(" #n ")" ::: "memory")
; #define BAR __builtin_amdgcn_s_barrier()
; #define SCHED __builtin_amdgcn_sched_barrier(0)
; #define LDA(dst, b, h)                                                                            \
;   _Pragma("unroll") for (int m = 0; m < 4; ++m) _Pragma("unroll") for (int k = 0; k < 2; ++k)                                         \
;     dst[m][k] = *reinterpret_cast<const bf16x8*>((char*)SA(b, h) + lds_byte(wr * 64 + m * 16 + fr, k * 32 + fq * 8))
; #define LDB(dst, b, h)                                                                            \
;   _Pragma("unroll") for (int n = 0; n < 2; ++n) _Pragma("unroll") for (int k = 0; k < 2; ++k)                                         \
;     dst[n][k] = *reinterpret_cast<const bf16x8*>((char*)SB(b, h) + lds_byte(wc * 32 + n * 16 + fr, k * 32 + fq * 8))
; template <int K, bool SWAP>
; __device__ __forceinline__ void gemm_kloop(const bf16* __restrict__ A, const bf16* __restrict__ Bt,
;                                            f32x4 (&acc)[2][2][4][2], bool pref = false) {
;     ...
;     LDB(B0, 0, 0); SCHED; LDA(At, 0, 0); STAGE(SA(1, 1), A, HALF, t + 1);
;     WAIT_L(8); BAR; WAIT_L(0); MMA(0, 0, At, B0); BAR; SCHED;
;     LDB(B1, 0, 1); STAGE(SB(0, 0), Bt, 0, t + 2);
;     BAR; WAIT_L(0); MMA(0, 1, At, B1); BAR;
;     LDA(At, 0, 1); STAGE(SA(0, 0), A, 0, t + 2);
;     BAR; WAIT_L(0); MMA(1, 0, At, B0); BAR; SCHED;
;     STAGE(SB(0, 1), Bt, HALF, t + 2);
;     WAIT_V(6); BAR; MMA(1, 1, At, B1); BAR;
.LBB0_844:
	ds_read_b128 v[162:165], v159
	ds_read_b128 v[166:169], v159 offset:1024
	ds_read_b128 v[170:173], v159 offset:2048
	ds_read_b128 v[174:177], v159 offset:3072
	v_add_u32_e32 v160, 0xc000, v146
	v_lshl_add_u64 v[178:179], s[6:7], 0, v[140:141]
	v_readfirstlane_b32 s14, v160
	v_lshl_add_u64 v[188:189], v[178:179], 0, s[38:39]
	s_mov_b32 m0, s14
	v_add_u32_e32 v161, 0xe000, v146
	ds_read_b128 v[198:201], v151
	ds_read_b128 v[202:205], v151 offset:1024
	ds_read_b128 v[206:209], v150
	ds_read_b128 v[210:213], v150 offset:1024
	ds_read_b128 v[214:217], v149
	ds_read_b128 v[218:221], v149 offset:1024
	ds_read_b128 v[222:225], v148
	ds_read_b128 v[226:229], v148 offset:1024
	global_load_lds_dwordx4 v[188:189], off
	v_lshl_add_u64 v[188:189], s[6:7], 0, v[142:143]
	v_readfirstlane_b32 s14, v161
	v_lshl_add_u64 v[230:231], v[188:189], 0, s[38:39]
	s_mov_b32 m0, s14
	s_nop 0
	global_load_lds_dwordx4 v[230:231], off
	s_waitcnt lgkmcnt(8)
	s_barrier
	s_waitcnt lgkmcnt(0)
	s_setprio 1
	s_waitcnt lgkmcnt(0)
	v_mfma_f32_16x16x32_bf16 v[124:127], v[162:165], v[198:201], v[124:127]
	v_mfma_f32_16x16x32_bf16 v[120:123], v[170:173], v[198:201], v[120:123]
	v_mfma_f32_16x16x32_bf16 v[112:115], v[170:173], v[206:209], v[112:115]
	v_mfma_f32_16x16x32_bf16 v[116:119], v[162:165], v[206:209], v[116:119]
	v_mfma_f32_16x16x32_bf16 v[108:111], v[162:165], v[214:217], v[108:111]
	v_mfma_f32_16x16x32_bf16 v[104:107], v[170:173], v[214:217], v[104:107]
	v_mfma_f32_16x16x32_bf16 v[96:99], v[170:173], v[222:225], v[96:99]
	v_mfma_f32_16x16x32_bf16 v[100:103], v[162:165], v[222:225], v[100:103]
	v_mfma_f32_16x16x32_bf16 v[124:127], v[166:169], v[202:205], v[124:127]
	v_mfma_f32_16x16x32_bf16 v[120:123], v[174:177], v[202:205], v[120:123]
	v_mfma_f32_16x16x32_bf16 v[112:115], v[174:177], v[210:213], v[112:115]
	v_mfma_f32_16x16x32_bf16 v[116:119], v[166:169], v[210:213], v[116:119]
	v_mfma_f32_16x16x32_bf16 v[108:111], v[166:169], v[218:221], v[108:111]
	v_mfma_f32_16x16x32_bf16 v[104:107], v[174:177], v[218:221], v[104:107]
	v_mfma_f32_16x16x32_bf16 v[96:99], v[174:177], v[226:229], v[96:99]
	v_mfma_f32_16x16x32_bf16 v[100:103], v[166:169], v[226:229], v[100:103]
	s_setprio 0
	s_barrier
	v_add_u32_e32 v186, s9, v145
	v_lshl_add_u64 v[246:247], s[6:7], 0, v[136:137]
	v_readfirstlane_b32 s14, v186
	v_lshl_add_u64 v[248:249], v[246:247], 0, s[18:19]
	s_mov_b32 m0, s14
	v_add_u32_e32 v186, 0x2000, v186
	ds_read_b128 v[230:233], v158
	ds_read_b128 v[234:237], v158 offset:1024
	ds_read_b128 v[238:241], v158 offset:2048
	ds_read_b128 v[242:245], v158 offset:3072
	global_load_lds_dwordx4 v[248:249], off
	v_lshl_add_u64 v[248:249], s[6:7], 0, v[138:139]
	v_readfirstlane_b32 s14, v186
	v_lshl_add_u64 v[250:251], v[248:249], 0, s[18:19]
	s_mov_b32 m0, s14
	s_nop 0
	global_load_lds_dwordx4 v[250:251], off
	s_barrier
	s_waitcnt lgkmcnt(0)
	s_setprio 1
	s_waitcnt lgkmcnt(0)
	v_mfma_f32_16x16x32_bf16 v[92:95], v[230:233], v[198:201], v[92:95]
	v_mfma_f32_16x16x32_bf16 v[88:91], v[238:241], v[198:201], v[88:91]
	v_mfma_f32_16x16x32_bf16 v[80:83], v[238:241], v[206:209], v[80:83]
	v_mfma_f32_16x16x32_bf16 v[84:87], v[230:233], v[206:209], v[84:87]
	v_mfma_f32_16x16x32_bf16 v[76:79], v[230:233], v[214:217], v[76:79]
	v_mfma_f32_16x16x32_bf16 v[72:75], v[238:241], v[214:217], v[72:75]
	v_mfma_f32_16x16x32_bf16 v[64:67], v[238:241], v[222:225], v[64:67]
	v_mfma_f32_16x16x32_bf16 v[68:71], v[230:233], v[222:225], v[68:71]
	v_mfma_f32_16x16x32_bf16 v[92:95], v[234:237], v[202:205], v[92:95]
	v_mfma_f32_16x16x32_bf16 v[88:91], v[242:245], v[202:205], v[88:91]
	v_mfma_f32_16x16x32_bf16 v[80:83], v[242:245], v[210:213], v[80:83]
	v_mfma_f32_16x16x32_bf16 v[84:87], v[234:237], v[210:213], v[84:87]
	v_mfma_f32_16x16x32_bf16 v[76:79], v[234:237], v[218:221], v[76:79]
	v_mfma_f32_16x16x32_bf16 v[72:75], v[242:245], v[218:221], v[72:75]
	v_mfma_f32_16x16x32_bf16 v[64:67], v[242:245], v[226:229], v[64:67]
	v_mfma_f32_16x16x32_bf16 v[68:71], v[234:237], v[226:229], v[68:71]
	s_setprio 0
	v_readfirstlane_b32 s14, v146
	v_add_u32_e32 v186, 0x2000, v146
	v_lshl_add_u64 v[250:251], v[178:179], 0, s[26:27]
	s_mov_b32 m0, s14
	v_readfirstlane_b32 s14, v186
	s_barrier
	ds_read_b128 v[198:201], v151 offset:16384
	ds_read_b128 v[202:205], v151 offset:17408
	ds_read_b128 v[206:209], v150 offset:16384
	ds_read_b128 v[210:213], v150 offset:17408
	ds_read_b128 v[214:217], v149 offset:16384
	ds_read_b128 v[218:221], v149 offset:17408
	ds_read_b128 v[222:225], v148 offset:16384
	ds_read_b128 v[226:229], v148 offset:17408
	global_load_lds_dwordx4 v[250:251], off
	v_lshl_add_u64 v[250:251], v[188:189], 0, s[26:27]
	s_mov_b32 m0, s14
	s_nop 0
	global_load_lds_dwordx4 v[250:251], off
	s_barrier
	s_waitcnt lgkmcnt(0)
	s_setprio 1
	s_waitcnt lgkmcnt(0)
	v_mfma_f32_16x16x32_bf16 v[60:63], v[162:165], v[198:201], v[60:63]
	v_mfma_f32_16x16x32_bf16 v[56:59], v[170:173], v[198:201], v[56:59]
	v_mfma_f32_16x16x32_bf16 v[48:51], v[170:173], v[206:209], v[48:51]
	v_mfma_f32_16x16x32_bf16 v[52:55], v[162:165], v[206:209], v[52:55]
	v_mfma_f32_16x16x32_bf16 v[44:47], v[162:165], v[214:217], v[44:47]
	v_mfma_f32_16x16x32_bf16 v[40:43], v[170:173], v[214:217], v[40:43]
	v_mfma_f32_16x16x32_bf16 v[32:35], v[170:173], v[222:225], v[32:35]
	v_mfma_f32_16x16x32_bf16 v[36:39], v[162:165], v[222:225], v[36:39]
	v_mfma_f32_16x16x32_bf16 v[60:63], v[166:169], v[202:205], v[60:63]
	v_mfma_f32_16x16x32_bf16 v[56:59], v[174:177], v[202:205], v[56:59]
	v_mfma_f32_16x16x32_bf16 v[48:51], v[174:177], v[210:213], v[48:51]
	v_mfma_f32_16x16x32_bf16 v[52:55], v[166:169], v[210:213], v[52:55]
	v_mfma_f32_16x16x32_bf16 v[44:47], v[166:169], v[218:221], v[44:47]
	v_mfma_f32_16x16x32_bf16 v[40:43], v[174:177], v[218:221], v[40:43]
	v_mfma_f32_16x16x32_bf16 v[32:35], v[174:177], v[226:229], v[32:35]
	v_mfma_f32_16x16x32_bf16 v[36:39], v[166:169], v[226:229], v[36:39]
	s_setprio 0
	s_barrier
; #define WAIT_V(n) asm volatile("s_waitcnt vmcnt(" #n ")" ::: "memory")
; #define WAIT_L(n) asm volatile("s_waitcnt lgkmcnt(" #n ")" ::: "memory")
; #define BAR __builtin_amdgcn_s_barrier()
; #define SCHED __builtin_amdgcn_sched_barrier(0)
; #define LDA(dst, b, h)                                                                            \
;   _Pragma("unroll") for (int m = 0; m < 4; ++m) _Pragma("unroll") for (int k = 0; k < 2; ++k)                                         \
;     dst[m][k] = *reinterpret_cast<const bf16x8*>((char*)SA(b, h) + lds_byte(wr * 64 + m * 16 + fr, k * 32 + fq * 8))
; #define LDB(dst, b, h)                                                                            \
;   _Pragma("unroll") for (int n = 0; n < 2; ++n) _Pragma("unroll") for (int k = 0; k < 2; ++k)                                         \
;     dst[n][k] = *reinterpret_cast<const bf16x8*>((char*)SB(b, h) + lds_byte(wc * 32 + n * 16 + fr, k * 32 + fq * 8))
; template <int K, bool SWAP>
; __device__ __forceinline__ void gemm_kloop(const bf16* __restrict__ A, const bf16* __restrict__ Bt,
;                                            f32x4 (&acc)[2][2][4][2], bool pref = false) {
;     ...
;     STAGE(SB(0, 1), Bt, HALF, t + 2);
;     WAIT_V(6); BAR; MMA(1, 1, At, B1); BAR;
;     LDB(B0, 1, 0); SCHED; LDA(At, 1, 0); STAGE(SA(0, 1), A, HALF, t + 2);
;     WAIT_L(8); BAR; WAIT_L(0); MMA(0, 0, At, B0); BAR; SCHED;
;     LDB(B1, 1, 1); STAGE(SB(1, 0), Bt, 0, t + 3);
;     BAR; WAIT_L(0); MMA(0, 1, At, B1); BAR;
;     LDA(At, 1, 1); STAGE(SA(1, 0), A, 0, t + 3);
	v_readfirstlane_b32 s14, v147
	v_add_u32_e32 v164, 0x2000, v147
	v_lshl_add_u64 v[162:163], v[246:247], 0, s[30:31]
	s_mov_b32 m0, s14
	v_readfirstlane_b32 s14, v164
	global_load_lds_dwordx4 v[162:163], off
	v_lshl_add_u64 v[162:163], v[248:249], 0, s[30:31]
	s_mov_b32 m0, s14
	s_nop 0
	global_load_lds_dwordx4 v[162:163], off
	s_waitcnt vmcnt(6)
	s_barrier
	s_setprio 1
	v_mfma_f32_16x16x32_bf16 v[28:31], v[230:233], v[198:201], v[28:31]
	v_mfma_f32_16x16x32_bf16 v[24:27], v[238:241], v[198:201], v[24:27]
	v_mfma_f32_16x16x32_bf16 v[16:19], v[238:241], v[206:209], v[16:19]
	v_mfma_f32_16x16x32_bf16 v[20:23], v[230:233], v[206:209], v[20:23]
	v_mfma_f32_16x16x32_bf16 v[12:15], v[230:233], v[214:217], v[12:15]
	v_mfma_f32_16x16x32_bf16 v[8:11], v[238:241], v[214:217], v[8:11]
	v_mfma_f32_16x16x32_bf16 v[0:3], v[238:241], v[222:225], v[0:3]
	v_mfma_f32_16x16x32_bf16 v[4:7], v[230:233], v[222:225], v[4:7]
	v_mfma_f32_16x16x32_bf16 v[28:31], v[234:237], v[202:205], v[28:31]
	v_mfma_f32_16x16x32_bf16 v[24:27], v[242:245], v[202:205], v[24:27]
	v_mfma_f32_16x16x32_bf16 v[16:19], v[242:245], v[210:213], v[16:19]
	v_mfma_f32_16x16x32_bf16 v[20:23], v[234:237], v[210:213], v[20:23]
	v_mfma_f32_16x16x32_bf16 v[12:15], v[234:237], v[218:221], v[12:15]
	v_mfma_f32_16x16x32_bf16 v[8:11], v[242:245], v[218:221], v[8:11]
	v_mfma_f32_16x16x32_bf16 v[0:3], v[242:245], v[226:229], v[0:3]
	v_mfma_f32_16x16x32_bf16 v[4:7], v[234:237], v[226:229], v[4:7]
	s_setprio 0
	s_barrier
	ds_read_b128 v[162:165], v153
	ds_read_b128 v[166:169], v153 offset:1024
	ds_read_b128 v[170:173], v153 offset:2048
	ds_read_b128 v[174:177], v153 offset:3072
	v_add_u32_e32 v186, 0x4000, v146
	v_lshl_add_u64 v[230:231], v[178:179], 0, s[16:17]
	v_readfirstlane_b32 s14, v186
	v_add_u32_e32 v186, 0x6000, v146
	s_mov_b32 m0, s14
	v_readfirstlane_b32 s14, v186
	ds_read_b128 v[198:201], v151 offset:32768
	ds_read_b128 v[202:205], v151 offset:33792
	ds_read_b128 v[206:209], v150 offset:32768
	ds_read_b128 v[210:213], v150 offset:33792
	ds_read_b128 v[214:217], v149 offset:32768
	ds_read_b128 v[218:221], v149 offset:33792
	ds_read_b128 v[222:225], v148 offset:32768
	ds_read_b128 v[226:229], v148 offset:33792
	global_load_lds_dwordx4 v[230:231], off
	v_lshl_add_u64 v[230:231], v[188:189], 0, s[16:17]
	s_mov_b32 m0, s14
	s_nop 0
	global_load_lds_dwordx4 v[230:231], off
	s_waitcnt lgkmcnt(8)
	s_barrier
	s_waitcnt lgkmcnt(0)
	s_setprio 1
	s_waitcnt lgkmcnt(0)
	v_mfma_f32_16x16x32_bf16 v[124:127], v[162:165], v[198:201], v[124:127]
	v_mfma_f32_16x16x32_bf16 v[120:123], v[170:173], v[198:201], v[120:123]
	v_mfma_f32_16x16x32_bf16 v[112:115], v[170:173], v[206:209], v[112:115]
	v_mfma_f32_16x16x32_bf16 v[116:119], v[162:165], v[206:209], v[116:119]
	v_mfma_f32_16x16x32_bf16 v[108:111], v[162:165], v[214:217], v[108:111]
	v_mfma_f32_16x16x32_bf16 v[104:107], v[170:173], v[214:217], v[104:107]
	v_mfma_f32_16x16x32_bf16 v[96:99], v[170:173], v[222:225], v[96:99]
	v_mfma_f32_16x16x32_bf16 v[100:103], v[162:165], v[222:225], v[100:103]
	v_mfma_f32_16x16x32_bf16 v[124:127], v[166:169], v[202:205], v[124:127]
	v_mfma_f32_16x16x32_bf16 v[120:123], v[174:177], v[202:205], v[120:123]
	v_mfma_f32_16x16x32_bf16 v[112:115], v[174:177], v[210:213], v[112:115]
	v_mfma_f32_16x16x32_bf16 v[116:119], v[166:169], v[210:213], v[116:119]
	v_mfma_f32_16x16x32_bf16 v[108:111], v[166:169], v[218:221], v[108:111]
	v_mfma_f32_16x16x32_bf16 v[104:107], v[174:177], v[218:221], v[104:107]
	v_mfma_f32_16x16x32_bf16 v[96:99], v[174:177], v[226:229], v[96:99]
	v_mfma_f32_16x16x32_bf16 v[100:103], v[166:169], v[226:229], v[100:103]
	s_setprio 0
	s_barrier
	v_readfirstlane_b32 s14, v154
	v_add_u32_e32 v186, 0x2000, v154
	v_lshl_add_u64 v[250:251], v[246:247], 0, s[28:29]
	s_mov_b32 m0, s14
	v_readfirstlane_b32 s14, v186
	ds_read_b128 v[230:233], v152
	ds_read_b128 v[234:237], v152 offset:1024
	ds_read_b128 v[238:241], v152 offset:2048
	ds_read_b128 v[242:245], v152 offset:3072
	global_load_lds_dwordx4 v[250:251], off
	v_lshl_add_u64 v[250:251], v[248:249], 0, s[28:29]
	s_mov_b32 m0, s14
	s_nop 0
	global_load_lds_dwordx4 v[250:251], off
	s_barrier
	s_waitcnt lgkmcnt(0)
	s_setprio 1
	s_waitcnt lgkmcnt(0)
	v_mfma_f32_16x16x32_bf16 v[92:95], v[230:233], v[198:201], v[92:95]
	v_mfma_f32_16x16x32_bf16 v[88:91], v[238:241], v[198:201], v[88:91]
	v_mfma_f32_16x16x32_bf16 v[80:83], v[238:241], v[206:209], v[80:83]
	v_mfma_f32_16x16x32_bf16 v[84:87], v[230:233], v[206:209], v[84:87]
	v_mfma_f32_16x16x32_bf16 v[76:79], v[230:233], v[214:217], v[76:79]
	v_mfma_f32_16x16x32_bf16 v[72:75], v[238:241], v[214:217], v[72:75]
	v_mfma_f32_16x16x32_bf16 v[64:67], v[238:241], v[222:225], v[64:67]
	v_mfma_f32_16x16x32_bf16 v[68:71], v[230:233], v[222:225], v[68:71]
	v_mfma_f32_16x16x32_bf16 v[92:95], v[234:237], v[202:205], v[92:95]
	v_mfma_f32_16x16x32_bf16 v[88:91], v[242:245], v[202:205], v[88:91]
	v_mfma_f32_16x16x32_bf16 v[80:83], v[242:245], v[210:213], v[80:83]
	v_mfma_f32_16x16x32_bf16 v[84:87], v[234:237], v[210:213], v[84:87]
	v_mfma_f32_16x16x32_bf16 v[76:79], v[234:237], v[218:221], v[76:79]
	v_mfma_f32_16x16x32_bf16 v[72:75], v[242:245], v[218:221], v[72:75]
	v_mfma_f32_16x16x32_bf16 v[64:67], v[242:245], v[226:229], v[64:67]
	v_mfma_f32_16x16x32_bf16 v[68:71], v[234:237], v[226:229], v[68:71]
	s_setprio 0
	v_readfirstlane_b32 s14, v155
	v_lshl_add_u64 v[178:179], v[178:179], 0, s[24:25]
	s_mov_b32 m0, s14
	v_readfirstlane_b32 s14, v156
	s_barrier
; #define WAIT_V(n) asm volatile("s_waitcnt vmcnt(" #n ")" ::: "memory")
; #define WAIT_L(n) asm volatile("s_waitcnt lgkmcnt(" #n ")" ::: "memory")
; #define BAR __builtin_amdgcn_s_barrier()
; #define SCHED __builtin_amdgcn_sched_barrier(0)
; #define LDA(dst, b, h)                                                                            \
;   _Pragma("unroll") for (int m = 0; m < 4; ++m) _Pragma("unroll") for (int k = 0; k < 2; ++k)                                         \
;     dst[m][k] = *reinterpret_cast<const bf16x8*>((char*)SA(b, h) + lds_byte(wr * 64 + m * 16 + fr, k * 32 + fq * 8))
; #define LDB(dst, b, h)                                                                            \
;   _Pragma("unroll") for (int n = 0; n < 2; ++n) _Pragma("unroll") for (int k = 0; k < 2; ++k)                                         \
;     dst[n][k] = *reinterpret_cast<const bf16x8*>((char*)SB(b, h) + lds_byte(wc * 32 + n * 16 + fr, k * 32 + fq * 8))
; template <int K, bool SWAP>
; __device__ __forceinline__ void gemm_kloop(const bf16* __restrict__ A, const bf16* __restrict__ Bt,
;                                            f32x4 (&acc)[2][2][4][2], bool pref = false) {
;     ...
;     LDA(At, 1, 1); STAGE(SA(1, 0), A, 0, t + 3);
;     BAR; WAIT_L(0); MMA(1, 0, At, B0); BAR; SCHED;
;     STAGE(SB(1, 1), Bt, HALF, t + 3);
;     WAIT_V(6); BAR; MMA(1, 1, At, B1); BAR;
;   }
;   { LDB(B0, 0, 0); LDA(At, 0, 0); STAGE(SA(1, 1), A, HALF, nt - 1);
;     BAR; WAIT_L(0); MMA(0, 0, At, B0); BAR;
	ds_read_b128 v[198:201], v151 offset:49152
	ds_read_b128 v[202:205], v151 offset:50176
	ds_read_b128 v[206:209], v150 offset:49152
	ds_read_b128 v[210:213], v150 offset:50176
	ds_read_b128 v[214:217], v149 offset:49152
	ds_read_b128 v[218:221], v149 offset:50176
	ds_read_b128 v[222:225], v148 offset:49152
	ds_read_b128 v[226:229], v148 offset:50176
	global_load_lds_dwordx4 v[178:179], off
	v_lshl_add_u64 v[178:179], v[188:189], 0, s[24:25]
	s_mov_b32 m0, s14
	s_nop 0
	global_load_lds_dwordx4 v[178:179], off
	s_barrier
	s_waitcnt lgkmcnt(0)
	s_setprio 1
	s_waitcnt lgkmcnt(0)
	v_mfma_f32_16x16x32_bf16 v[60:63], v[162:165], v[198:201], v[60:63]
	v_mfma_f32_16x16x32_bf16 v[56:59], v[170:173], v[198:201], v[56:59]
	v_mfma_f32_16x16x32_bf16 v[48:51], v[170:173], v[206:209], v[48:51]
	v_mfma_f32_16x16x32_bf16 v[52:55], v[162:165], v[206:209], v[52:55]
	v_mfma_f32_16x16x32_bf16 v[44:47], v[162:165], v[214:217], v[44:47]
	v_mfma_f32_16x16x32_bf16 v[40:43], v[170:173], v[214:217], v[40:43]
	v_mfma_f32_16x16x32_bf16 v[32:35], v[170:173], v[222:225], v[32:35]
	v_mfma_f32_16x16x32_bf16 v[36:39], v[162:165], v[222:225], v[36:39]
	v_mfma_f32_16x16x32_bf16 v[60:63], v[166:169], v[202:205], v[60:63]
	v_mfma_f32_16x16x32_bf16 v[56:59], v[174:177], v[202:205], v[56:59]
	v_mfma_f32_16x16x32_bf16 v[48:51], v[174:177], v[210:213], v[48:51]
	v_mfma_f32_16x16x32_bf16 v[52:55], v[166:169], v[210:213], v[52:55]
	v_mfma_f32_16x16x32_bf16 v[44:47], v[166:169], v[218:221], v[44:47]
	v_mfma_f32_16x16x32_bf16 v[40:43], v[174:177], v[218:221], v[40:43]
	v_mfma_f32_16x16x32_bf16 v[32:35], v[174:177], v[226:229], v[32:35]
	v_mfma_f32_16x16x32_bf16 v[36:39], v[166:169], v[226:229], v[36:39]
	s_setprio 0
	s_barrier
	v_readfirstlane_b32 s14, v157
	v_add_u32_e32 v164, 0x2000, v157
	v_lshl_add_u64 v[162:163], v[246:247], 0, s[2:3]
	s_mov_b32 m0, s14
	v_readfirstlane_b32 s14, v164
	global_load_lds_dwordx4 v[162:163], off
	v_lshl_add_u64 v[162:163], v[248:249], 0, s[2:3]
	s_mov_b32 m0, s14
	s_nop 0
	global_load_lds_dwordx4 v[162:163], off
	s_waitcnt vmcnt(6)
	s_barrier
	s_setprio 1
	v_mfma_f32_16x16x32_bf16 v[28:31], v[230:233], v[198:201], v[28:31]
	v_mfma_f32_16x16x32_bf16 v[24:27], v[238:241], v[198:201], v[24:27]
	v_mfma_f32_16x16x32_bf16 v[16:19], v[238:241], v[206:209], v[16:19]
	v_mfma_f32_16x16x32_bf16 v[20:23], v[230:233], v[206:209], v[20:23]
	v_mfma_f32_16x16x32_bf16 v[12:15], v[230:233], v[214:217], v[12:15]
	v_mfma_f32_16x16x32_bf16 v[8:11], v[238:241], v[214:217], v[8:11]
	v_mfma_f32_16x16x32_bf16 v[0:3], v[238:241], v[222:225], v[0:3]
	v_mfma_f32_16x16x32_bf16 v[4:7], v[230:233], v[222:225], v[4:7]
	v_mfma_f32_16x16x32_bf16 v[28:31], v[234:237], v[202:205], v[28:31]
	v_mfma_f32_16x16x32_bf16 v[24:27], v[242:245], v[202:205], v[24:27]
	v_mfma_f32_16x16x32_bf16 v[16:19], v[242:245], v[210:213], v[16:19]
	v_mfma_f32_16x16x32_bf16 v[20:23], v[234:237], v[210:213], v[20:23]
	v_mfma_f32_16x16x32_bf16 v[12:15], v[234:237], v[218:221], v[12:15]
	v_mfma_f32_16x16x32_bf16 v[8:11], v[242:245], v[218:221], v[8:11]
	v_mfma_f32_16x16x32_bf16 v[0:3], v[242:245], v[226:229], v[0:3]
	v_mfma_f32_16x16x32_bf16 v[4:7], v[234:237], v[226:229], v[4:7]
	s_setprio 0
	s_add_i32 s11, s11, 2
	v_lshl_add_u64 v[136:137], v[136:137], 0, s[44:45]
	v_lshl_add_u64 v[138:139], v[138:139], 0, s[44:45]
	v_lshl_add_u64 v[140:141], v[140:141], 0, s[44:45]
	s_cmp_lt_u32 s11, 12
	v_lshl_add_u64 v[142:143], v[142:143], 0, s[44:45]
	s_barrier
	s_cbranch_scc1 .LBB0_844
	s_add_u32 s12, s12, 0x40780
	s_addc_u32 s13, s13, 0
	v_lshl_add_u64 v[130:131], s[12:13], 0, v[130:131]
	v_readfirstlane_b32 s11, v160
	v_lshl_add_u64 v[128:129], v[128:129], 1, v[130:131]
	s_mov_b32 m0, s11
	ds_read_b128 v[136:139], v159
	ds_read_b128 v[140:143], v159 offset:1024
	ds_read_b128 v[154:157], v159 offset:2048
	ds_read_b128 v[162:165], v159 offset:3072
	ds_read_b128 v[166:169], v151
	ds_read_b128 v[170:173], v151 offset:1024
	ds_read_b128 v[174:177], v150
	ds_read_b128 v[198:201], v150 offset:1024
	ds_read_b128 v[202:205], v149
	ds_read_b128 v[206:209], v149 offset:1024
	ds_read_b128 v[210:213], v148
	ds_read_b128 v[214:217], v148 offset:1024
	global_load_lds_dwordx4 v[128:129], off
	v_lshl_add_u64 v[128:129], s[12:13], 0, v[134:135]
	v_readfirstlane_b32 s11, v161
	v_lshl_add_u64 v[128:129], v[132:133], 1, v[128:129]
	s_mov_b32 m0, s11
	s_nop 0
	global_load_lds_dwordx4 v[128:129], off
	s_barrier
	s_waitcnt lgkmcnt(0)
	s_setprio 1
	s_waitcnt lgkmcnt(0)
	v_mfma_f32_16x16x32_bf16 v[124:127], v[136:139], v[166:169], v[124:127]
	v_mfma_f32_16x16x32_bf16 v[120:123], v[154:157], v[166:169], v[120:123]
	v_mfma_f32_16x16x32_bf16 v[112:115], v[154:157], v[174:177], v[112:115]
	v_mfma_f32_16x16x32_bf16 v[116:119], v[136:139], v[174:177], v[116:119]
	v_mfma_f32_16x16x32_bf16 v[108:111], v[136:139], v[202:205], v[108:111]
	v_mfma_f32_16x16x32_bf16 v[104:107], v[154:157], v[202:205], v[104:107]
	v_mfma_f32_16x16x32_bf16 v[96:99], v[154:157], v[210:213], v[96:99]
	v_mfma_f32_16x16x32_bf16 v[100:103], v[136:139], v[210:213], v[100:103]
	v_mfma_f32_16x16x32_bf16 v[124:127], v[140:143], v[170:173], v[124:127]
	v_mfma_f32_16x16x32_bf16 v[120:123], v[162:165], v[170:173], v[120:123]
	v_mfma_f32_16x16x32_bf16 v[112:115], v[162:165], v[198:201], v[112:115]
	v_mfma_f32_16x16x32_bf16 v[116:119], v[140:143], v[198:201], v[116:119]
	v_mfma_f32_16x16x32_bf16 v[108:111], v[140:143], v[206:209], v[108:111]
	v_mfma_f32_16x16x32_bf16 v[104:107], v[162:165], v[206:209], v[104:107]
	v_mfma_f32_16x16x32_bf16 v[96:99], v[162:165], v[214:217], v[96:99]
	v_mfma_f32_16x16x32_bf16 v[100:103], v[140:143], v[214:217], v[100:103]
	s_setprio 0
	s_barrier
; #define WAIT_V(n) asm volatile("s_waitcnt vmcnt(" #n ")" ::: "memory")
; #define WAIT_L(n) asm volatile("s_waitcnt lgkmcnt(" #n ")" ::: "memory")
; #define BAR __builtin_amdgcn_s_barrier()
; #define LDA(dst, b, h)                                                                            \
;   _Pragma("unroll") for (int m = 0; m < 4; ++m) _Pragma("unroll") for (int k = 0; k < 2; ++k)                                         \
;     dst[m][k] = *reinterpret_cast<const bf16x8*>((char*)SA(b, h) + lds_byte(wr * 64 + m * 16 + fr, k * 32 + fq * 8))
; #define LDB(dst, b, h)                                                                            \
;   _Pragma("unroll") for (int n = 0; n < 2; ++n) _Pragma("unroll") for (int k = 0; k < 2; ++k)                                         \
;     dst[n][k] = *reinterpret_cast<const bf16x8*>((char*)SB(b, h) + lds_byte(wc * 32 + n * 16 + fr, k * 32 + fq * 8))
; template <int K, bool SWAP>
; __device__ __forceinline__ void gemm_kloop(const bf16* __restrict__ A, const bf16* __restrict__ Bt,
;                                            f32x4 (&acc)[2][2][4][2], bool pref = false) {
;     ...
;     BAR; WAIT_L(0); MMA(0, 0, At, B0); BAR;
;     LDB(B1, 0, 1); BAR; WAIT_L(0); MMA(0, 1, At, B1); BAR;
;     LDA(At, 0, 1); WAIT_V(4); BAR; WAIT_L(0); MMA(1, 0, At, B0); MMA(1, 1, At, B1); BAR; }
;   { LDB(B0, 1, 0); LDA(At, 1, 0); WAIT_V(2); BAR; WAIT_L(0); MMA(0, 0, At, B0); BAR;
	ds_read_b128 v[128:131], v158
	ds_read_b128 v[132:135], v158 offset:1024
	ds_read_b128 v[218:221], v158 offset:2048
	ds_read_b128 v[158:161], v158 offset:3072
	s_barrier
	s_waitcnt lgkmcnt(0)
	s_setprio 1
	s_waitcnt lgkmcnt(0)
	v_mfma_f32_16x16x32_bf16 v[88:91], v[218:221], v[166:169], v[88:91]
	v_mfma_f32_16x16x32_bf16 v[84:87], v[128:131], v[174:177], v[84:87]
	v_mfma_f32_16x16x32_bf16 v[80:83], v[218:221], v[174:177], v[80:83]
	v_mfma_f32_16x16x32_bf16 v[76:79], v[128:131], v[202:205], v[76:79]
	v_mfma_f32_16x16x32_bf16 v[72:75], v[218:221], v[202:205], v[72:75]
	v_mfma_f32_16x16x32_bf16 v[68:71], v[128:131], v[210:213], v[68:71]
	v_mfma_f32_16x16x32_bf16 v[64:67], v[218:221], v[210:213], v[64:67]
	v_mfma_f32_16x16x32_bf16 v[92:95], v[128:131], v[166:169], v[92:95]
	v_mfma_f32_16x16x32_bf16 v[88:91], v[158:161], v[170:173], v[88:91]
	v_mfma_f32_16x16x32_bf16 v[84:87], v[132:135], v[198:201], v[84:87]
	v_mfma_f32_16x16x32_bf16 v[80:83], v[158:161], v[198:201], v[80:83]
	v_mfma_f32_16x16x32_bf16 v[76:79], v[132:135], v[206:209], v[76:79]
	v_mfma_f32_16x16x32_bf16 v[72:75], v[158:161], v[206:209], v[72:75]
	v_mfma_f32_16x16x32_bf16 v[68:71], v[132:135], v[214:217], v[68:71]
	v_mfma_f32_16x16x32_bf16 v[64:67], v[158:161], v[214:217], v[64:67]
	v_mfma_f32_16x16x32_bf16 v[222:225], v[132:135], v[170:173], v[92:95]
	s_setprio 0
	s_barrier
	s_nop 0
	ds_read_b128 v[92:95], v151 offset:16384
	ds_read_b128 v[166:169], v151 offset:17408
	ds_read_b128 v[170:173], v150 offset:16384
	ds_read_b128 v[174:177], v150 offset:17408
	ds_read_b128 v[198:201], v149 offset:16384
	ds_read_b128 v[202:205], v149 offset:17408
	ds_read_b128 v[206:209], v148 offset:16384
	ds_read_b128 v[210:213], v148 offset:17408
	s_waitcnt vmcnt(4)
	s_barrier
	s_waitcnt lgkmcnt(0)
	s_setprio 1
	s_waitcnt lgkmcnt(0)
	v_mfma_f32_16x16x32_bf16 v[60:63], v[136:139], v[92:95], v[60:63]
	v_mfma_f32_16x16x32_bf16 v[56:59], v[154:157], v[92:95], v[56:59]
	v_mfma_f32_16x16x32_bf16 v[48:51], v[154:157], v[170:173], v[48:51]
	v_mfma_f32_16x16x32_bf16 v[52:55], v[136:139], v[170:173], v[52:55]
	v_mfma_f32_16x16x32_bf16 v[44:47], v[136:139], v[198:201], v[44:47]
	v_mfma_f32_16x16x32_bf16 v[40:43], v[154:157], v[198:201], v[40:43]
	v_mfma_f32_16x16x32_bf16 v[32:35], v[154:157], v[206:209], v[32:35]
	v_mfma_f32_16x16x32_bf16 v[36:39], v[136:139], v[206:209], v[36:39]
	v_mfma_f32_16x16x32_bf16 v[60:63], v[140:143], v[166:169], v[60:63]
	v_mfma_f32_16x16x32_bf16 v[56:59], v[162:165], v[166:169], v[56:59]
	v_mfma_f32_16x16x32_bf16 v[48:51], v[162:165], v[174:177], v[48:51]
	v_mfma_f32_16x16x32_bf16 v[52:55], v[140:143], v[174:177], v[52:55]
	v_mfma_f32_16x16x32_bf16 v[44:47], v[140:143], v[202:205], v[44:47]
	v_mfma_f32_16x16x32_bf16 v[40:43], v[162:165], v[202:205], v[40:43]
	v_mfma_f32_16x16x32_bf16 v[32:35], v[162:165], v[210:213], v[32:35]
	v_mfma_f32_16x16x32_bf16 v[36:39], v[140:143], v[210:213], v[36:39]
	s_setprio 0
	s_setprio 1
	v_mfma_f32_16x16x32_bf16 v[28:31], v[128:131], v[92:95], v[28:31]
	v_mfma_f32_16x16x32_bf16 v[24:27], v[218:221], v[92:95], v[24:27]
	v_mfma_f32_16x16x32_bf16 v[16:19], v[218:221], v[170:173], v[16:19]
	v_mfma_f32_16x16x32_bf16 v[20:23], v[128:131], v[170:173], v[20:23]
	v_mfma_f32_16x16x32_bf16 v[12:15], v[128:131], v[198:201], v[12:15]
	v_mfma_f32_16x16x32_bf16 v[8:11], v[218:221], v[198:201], v[8:11]
	v_mfma_f32_16x16x32_bf16 v[0:3], v[218:221], v[206:209], v[0:3]
	v_mfma_f32_16x16x32_bf16 v[4:7], v[128:131], v[206:209], v[4:7]
	v_mfma_f32_16x16x32_bf16 v[28:31], v[132:135], v[166:169], v[28:31]
	v_mfma_f32_16x16x32_bf16 v[24:27], v[158:161], v[166:169], v[24:27]
	v_mfma_f32_16x16x32_bf16 v[16:19], v[158:161], v[174:177], v[16:19]
	v_mfma_f32_16x16x32_bf16 v[20:23], v[132:135], v[174:177], v[20:23]
	v_mfma_f32_16x16x32_bf16 v[12:15], v[132:135], v[202:205], v[12:15]
	v_mfma_f32_16x16x32_bf16 v[8:11], v[158:161], v[202:205], v[8:11]
	v_mfma_f32_16x16x32_bf16 v[0:3], v[158:161], v[210:213], v[0:3]
	v_mfma_f32_16x16x32_bf16 v[4:7], v[132:135], v[210:213], v[4:7]
	s_setprio 0
	s_barrier
	ds_read_b128 v[128:131], v153
	ds_read_b128 v[132:135], v153 offset:1024
	ds_read_b128 v[136:139], v153 offset:2048
	ds_read_b128 v[140:143], v153 offset:3072
	ds_read_b128 v[154:157], v151 offset:32768
	ds_read_b128 v[158:161], v151 offset:33792
	ds_read_b128 v[162:165], v150 offset:32768
	ds_read_b128 v[166:169], v150 offset:33792
	ds_read_b128 v[170:173], v149 offset:32768
	ds_read_b128 v[174:177], v149 offset:33792
	ds_read_b128 v[198:201], v148 offset:32768
	ds_read_b128 v[202:205], v148 offset:33792
	s_waitcnt vmcnt(2)
	s_barrier
; #define WAIT_V(n) asm volatile("s_waitcnt vmcnt(" #n ")" ::: "memory")
; #define WAIT_L(n) asm volatile("s_waitcnt lgkmcnt(" #n ")" ::: "memory")
; #define BAR __builtin_amdgcn_s_barrier()
; #define LDA(dst, b, h)                                                                            \
;   _Pragma("unroll") for (int m = 0; m < 4; ++m) _Pragma("unroll") for (int k = 0; k < 2; ++k)                                         \
;     dst[m][k] = *reinterpret_cast<const bf16x8*>((char*)SA(b, h) + lds_byte(wr * 64 + m * 16 + fr, k * 32 + fq * 8))
; #define LDB(dst, b, h)                                                                            \
;   _Pragma("unroll") for (int n = 0; n < 2; ++n) _Pragma("unroll") for (int k = 0; k < 2; ++k)                                         \
;     dst[n][k] = *reinterpret_cast<const bf16x8*>((char*)SB(b, h) + lds_byte(wc * 32 + n * 16 + fr, k * 32 + fq * 8))
; template <int K, bool SWAP>
; __device__ __forceinline__ void gemm_kloop(const bf16* __restrict__ A, const bf16* __restrict__ Bt,
;                                            f32x4 (&acc)[2][2][4][2], bool pref = false) {
;     ...
;   { LDB(B0, 1, 0); LDA(At, 1, 0); WAIT_V(2); BAR; WAIT_L(0); MMA(0, 0, At, B0); BAR;
;     LDB(B1, 1, 1); WAIT_V(0); BAR; WAIT_L(0); MMA(0, 1, At, B1); BAR;
;     LDA(At, 1, 1); BAR; WAIT_L(0); MMA(1, 0, At, B0); MMA(1, 1, At, B1); BAR; }
;   if (wr == 0) BAR;
	s_waitcnt lgkmcnt(0)
	s_setprio 1
	s_waitcnt lgkmcnt(0)
	v_mfma_f32_16x16x32_bf16 v[92:95], v[128:131], v[154:157], v[124:127]
	v_mfma_f32_16x16x32_bf16 v[124:127], v[132:135], v[158:161], v[92:95]
	v_mfma_f32_16x16x32_bf16 v[92:95], v[136:139], v[154:157], v[120:123]
	v_mfma_f32_16x16x32_bf16 v[120:123], v[140:143], v[158:161], v[92:95]
	v_mfma_f32_16x16x32_bf16 v[92:95], v[128:131], v[162:165], v[116:119]
	v_mfma_f32_16x16x32_bf16 v[116:119], v[132:135], v[166:169], v[92:95]
	v_mfma_f32_16x16x32_bf16 v[92:95], v[136:139], v[162:165], v[112:115]
	v_mfma_f32_16x16x32_bf16 v[112:115], v[140:143], v[166:169], v[92:95]
	v_mfma_f32_16x16x32_bf16 v[92:95], v[128:131], v[170:173], v[108:111]
	v_mfma_f32_16x16x32_bf16 v[108:111], v[132:135], v[174:177], v[92:95]
	v_mfma_f32_16x16x32_bf16 v[92:95], v[136:139], v[170:173], v[104:107]
	v_mfma_f32_16x16x32_bf16 v[104:107], v[140:143], v[174:177], v[92:95]
	v_mfma_f32_16x16x32_bf16 v[92:95], v[128:131], v[198:201], v[100:103]
	v_mfma_f32_16x16x32_bf16 v[100:103], v[132:135], v[202:205], v[92:95]
	v_mfma_f32_16x16x32_bf16 v[92:95], v[136:139], v[198:201], v[96:99]
	v_mfma_f32_16x16x32_bf16 v[92:95], v[140:143], v[202:205], v[92:95]
	s_setprio 0
	s_barrier
	ds_read_b128 v[206:209], v152
	ds_read_b128 v[210:213], v152 offset:1024
	ds_read_b128 v[214:217], v152 offset:2048
	ds_read_b128 v[218:221], v152 offset:3072
	s_waitcnt vmcnt(0)
	s_barrier
	s_waitcnt lgkmcnt(0)
	s_setprio 1
	s_waitcnt lgkmcnt(0)
	v_mfma_f32_16x16x32_bf16 v[96:99], v[206:209], v[154:157], v[222:225]
	v_mfma_f32_16x16x32_bf16 v[88:91], v[214:217], v[154:157], v[88:91]
	v_mfma_f32_16x16x32_bf16 v[84:87], v[206:209], v[162:165], v[84:87]
	v_mfma_f32_16x16x32_bf16 v[80:83], v[214:217], v[162:165], v[80:83]
	v_mfma_f32_16x16x32_bf16 v[76:79], v[206:209], v[170:173], v[76:79]
	v_mfma_f32_16x16x32_bf16 v[72:75], v[214:217], v[170:173], v[72:75]
	v_mfma_f32_16x16x32_bf16 v[68:71], v[206:209], v[198:201], v[68:71]
	v_mfma_f32_16x16x32_bf16 v[64:67], v[214:217], v[198:201], v[64:67]
	v_mfma_f32_16x16x32_bf16 v[96:99], v[210:213], v[158:161], v[96:99]
	v_mfma_f32_16x16x32_bf16 v[88:91], v[218:221], v[158:161], v[88:91]
	v_mfma_f32_16x16x32_bf16 v[84:87], v[210:213], v[166:169], v[84:87]
	v_mfma_f32_16x16x32_bf16 v[80:83], v[218:221], v[166:169], v[80:83]
	v_mfma_f32_16x16x32_bf16 v[76:79], v[210:213], v[174:177], v[76:79]
	v_mfma_f32_16x16x32_bf16 v[72:75], v[218:221], v[174:177], v[72:75]
	v_mfma_f32_16x16x32_bf16 v[68:71], v[210:213], v[202:205], v[68:71]
	v_mfma_f32_16x16x32_bf16 v[64:67], v[218:221], v[202:205], v[64:67]
	s_setprio 0
	s_barrier
	ds_read_b128 v[152:155], v151 offset:49152
	ds_read_b128 v[156:159], v151 offset:50176
	ds_read_b128 v[160:163], v150 offset:49152
	ds_read_b128 v[164:167], v150 offset:50176
	ds_read_b128 v[168:171], v149 offset:49152
	ds_read_b128 v[172:175], v149 offset:50176
	ds_read_b128 v[176:179], v148 offset:49152
	ds_read_b128 v[146:149], v148 offset:50176
	s_barrier
	s_waitcnt lgkmcnt(0)
	s_setprio 1
	s_waitcnt lgkmcnt(0)
	v_mfma_f32_16x16x32_bf16 v[60:63], v[128:131], v[152:155], v[60:63]
	v_mfma_f32_16x16x32_bf16 v[56:59], v[136:139], v[152:155], v[56:59]
	v_mfma_f32_16x16x32_bf16 v[48:51], v[136:139], v[160:163], v[48:51]
	v_mfma_f32_16x16x32_bf16 v[52:55], v[128:131], v[160:163], v[52:55]
	v_mfma_f32_16x16x32_bf16 v[44:47], v[128:131], v[168:171], v[44:47]
	v_mfma_f32_16x16x32_bf16 v[40:43], v[136:139], v[168:171], v[40:43]
	v_mfma_f32_16x16x32_bf16 v[32:35], v[136:139], v[176:179], v[32:35]
	v_mfma_f32_16x16x32_bf16 v[36:39], v[128:131], v[176:179], v[36:39]
	v_mfma_f32_16x16x32_bf16 v[60:63], v[132:135], v[156:159], v[60:63]
	v_mfma_f32_16x16x32_bf16 v[56:59], v[140:143], v[156:159], v[56:59]
	v_mfma_f32_16x16x32_bf16 v[48:51], v[140:143], v[164:167], v[48:51]
	v_mfma_f32_16x16x32_bf16 v[52:55], v[132:135], v[164:167], v[52:55]
	v_mfma_f32_16x16x32_bf16 v[44:47], v[132:135], v[172:175], v[44:47]
	v_mfma_f32_16x16x32_bf16 v[40:43], v[140:143], v[172:175], v[40:43]
	v_mfma_f32_16x16x32_bf16 v[32:35], v[140:143], v[146:149], v[32:35]
	v_mfma_f32_16x16x32_bf16 v[36:39], v[132:135], v[146:149], v[36:39]
	s_setprio 0
	s_setprio 1
	v_mfma_f32_16x16x32_bf16 v[28:31], v[206:209], v[152:155], v[28:31]
	v_mfma_f32_16x16x32_bf16 v[24:27], v[214:217], v[152:155], v[24:27]
	v_mfma_f32_16x16x32_bf16 v[16:19], v[214:217], v[160:163], v[16:19]
	v_mfma_f32_16x16x32_bf16 v[20:23], v[206:209], v[160:163], v[20:23]
	v_mfma_f32_16x16x32_bf16 v[12:15], v[206:209], v[168:171], v[12:15]
	v_mfma_f32_16x16x32_bf16 v[8:11], v[214:217], v[168:171], v[8:11]
	v_mfma_f32_16x16x32_bf16 v[0:3], v[214:217], v[176:179], v[0:3]
	v_mfma_f32_16x16x32_bf16 v[4:7], v[206:209], v[176:179], v[4:7]
	v_mfma_f32_16x16x32_bf16 v[28:31], v[210:213], v[156:159], v[28:31]
	v_mfma_f32_16x16x32_bf16 v[24:27], v[218:221], v[156:159], v[24:27]
	v_mfma_f32_16x16x32_bf16 v[16:19], v[218:221], v[164:167], v[16:19]
	v_mfma_f32_16x16x32_bf16 v[20:23], v[210:213], v[164:167], v[20:23]
	v_mfma_f32_16x16x32_bf16 v[12:15], v[210:213], v[172:175], v[12:15]
	v_mfma_f32_16x16x32_bf16 v[8:11], v[218:221], v[172:175], v[8:11]
	v_mfma_f32_16x16x32_bf16 v[0:3], v[218:221], v[146:149], v[0:3]
	v_mfma_f32_16x16x32_bf16 v[4:7], v[210:213], v[146:149], v[4:7]
	s_setprio 0
	s_movk_i32 s11, 0x100
	v_cmp_gt_u32_e32 vcc, s11, v144
	s_barrier
	s_and_saveexec_b64 s[12:13], vcc
	s_cbranch_execz .LBB0_847
	s_barrier
